# batched loads in GEMM epilogues (Epi3/Epi4), rescheduled scan stepper, mix/post phases with contiguous token blocks + nt loads, LN gamma/beta in registers, attn RMW loads hoisted
# speedup vs baseline: 1.1458x; 1.0235x over previous
.LBB0_222:
	s_mov_b64 s[4:5], s[0:1]
	s_load_dword s3, s[4:5], 0xe8
	s_waitcnt lgkmcnt(0)
	s_cmp_gt_i32 s3, 2
	s_cbranch_scc1 .LBB0_230
	s_mov_b64 s[4:5], s[0:1]
	s_load_dword s3, s[4:5], 0xec
	s_waitcnt lgkmcnt(0)
	s_cmp_lt_i32 s3, 3
	s_cbranch_scc1 .LBB0_230
	s_cmp_eq_u32 s24, 0x100
	s_cbranch_scc0 .Lmix2_orig
	s_load_dwordx2 s[16:17], s[0:1], 0x8
	s_load_dwordx2 s[18:19], s[0:1], 0x0
	s_load_dwordx2 s[20:21], s[0:1], 0xe0
	v_lshlrev_b32_e32 v1, 4, v190
	v_lshlrev_b32_e32 v2, 3, v190
	s_lshl_b32 s3, s2, 19
	s_lshl_b32 s22, s2, 18
	s_waitcnt lgkmcnt(0)
	s_add_u32 s12, s16, 0x2000
	s_addc_u32 s13, s17, 0
	global_load_dwordx4 v[4:7], v1, s[12:13]
	s_add_u32 s12, s16, 0x8000
	s_addc_u32 s13, s17, 0
	global_load_dwordx4 v[8:11], v1, s[12:13]
	s_add_u32 s12, s16, 0xa000
	s_addc_u32 s13, s17, 0
	global_load_dwordx4 v[12:15], v1, s[12:13]
	s_add_u32 s4, s18, s3
	s_addc_u32 s5, s19, 0
	s_add_u32 s6, s20, 0x8100000
	s_addc_u32 s7, s21, 0
	s_add_u32 s6, s6, s22
	s_addc_u32 s7, s7, 0
	s_add_u32 s8, s6, 0x4000000
	s_addc_u32 s9, s7, 0
	s_add_u32 s10, s6, 0x8000000
	s_addc_u32 s11, s7, 0
	v_mov_b32_e32 v16, 0
	v_mov_b32_e32 v17, 0
	v_mov_b32_e32 v18, 0
	v_mov_b32_e32 v19, 0
	s_and_b32 s3, s2, 63
	s_cmp_eq_u32 s3, 0
	s_cbranch_scc1 .Lmix2_noprev
	s_sub_u32 s22, s4, 0x2000
	s_subb_u32 s23, s5, 0
	global_load_dwordx4 v[16:19], v1, s[22:23] nt
.Lmix2_noprev:
	global_load_dwordx4 v[20:23], v1, s[4:5] nt
	s_add_u32 s4, s4, 0x2000
	s_addc_u32 s5, s5, 0
	global_load_dwordx4 v[24:27], v1, s[4:5] nt
	s_add_u32 s4, s4, 0x2000
	s_addc_u32 s5, s5, 0
	global_load_dwordx4 v[28:31], v1, s[4:5] nt
	s_add_u32 s4, s4, 0x2000
	s_addc_u32 s5, s5, 0
	global_load_dwordx4 v[32:35], v1, s[4:5] nt
	s_add_u32 s4, s4, 0x2000
	s_addc_u32 s5, s5, 0
	global_load_dwordx4 v[36:39], v1, s[4:5] nt
	s_add_u32 s4, s4, 0x2000
	s_addc_u32 s5, s5, 0
	global_load_dwordx4 v[40:43], v1, s[4:5] nt
	s_add_u32 s4, s4, 0x2000
	s_addc_u32 s5, s5, 0
	global_load_dwordx4 v[44:47], v1, s[4:5] nt
	s_add_u32 s4, s4, 0x2000
	s_addc_u32 s5, s5, 0
	global_load_dwordx4 v[48:51], v1, s[4:5] nt
	s_add_u32 s4, s4, 0x2000
	s_addc_u32 s5, s5, 0
	global_load_dwordx4 v[52:55], v1, s[4:5] nt
	s_add_u32 s4, s4, 0x2000
	s_addc_u32 s5, s5, 0
	global_load_dwordx4 v[56:59], v1, s[4:5] nt
	s_add_u32 s4, s4, 0x2000
	s_addc_u32 s5, s5, 0
	global_load_dwordx4 v[60:63], v1, s[4:5] nt
	s_add_u32 s4, s4, 0x2000
	s_addc_u32 s5, s5, 0
	global_load_dwordx4 v[64:67], v1, s[4:5] nt
	s_add_u32 s4, s4, 0x2000
	s_addc_u32 s5, s5, 0
	global_load_dwordx4 v[68:71], v1, s[4:5] nt
	s_add_u32 s4, s4, 0x2000
	s_addc_u32 s5, s5, 0
	global_load_dwordx4 v[72:75], v1, s[4:5] nt
	s_add_u32 s4, s4, 0x2000
	s_addc_u32 s5, s5, 0
	global_load_dwordx4 v[76:79], v1, s[4:5] nt
	s_add_u32 s4, s4, 0x2000
	s_addc_u32 s5, s5, 0
	global_load_dwordx4 v[80:83], v1, s[4:5] nt
	s_add_u32 s4, s4, 0x2000
	s_addc_u32 s5, s5, 0
	s_waitcnt vmcnt(15)
	v_sub_f32_e32 v84, v16, v20
	v_sub_f32_e32 v85, v17, v21
	v_sub_f32_e32 v86, v18, v22
	v_sub_f32_e32 v87, v19, v23
	v_pk_fma_f32 v[88:89], v[84:85], v[4:5], v[20:21]
	v_pk_fma_f32 v[90:91], v[86:87], v[6:7], v[22:23]
	v_pk_fma_f32 v[92:93], v[84:85], v[8:9], v[20:21]
	v_pk_fma_f32 v[94:95], v[86:87], v[10:11], v[22:23]
	v_pk_fma_f32 v[96:97], v[84:85], v[12:13], v[20:21]
	v_pk_fma_f32 v[98:99], v[86:87], v[14:15], v[22:23]
	v_cvt_pk_bf16_f32 v100, v88, v89
	v_cvt_pk_bf16_f32 v101, v90, v91
	v_cvt_pk_bf16_f32 v102, v92, v93
	v_cvt_pk_bf16_f32 v103, v94, v95
	v_cvt_pk_bf16_f32 v104, v96, v97
	v_cvt_pk_bf16_f32 v105, v98, v99
	global_store_dwordx2 v2, v[100:101], s[6:7]
	global_store_dwordx2 v2, v[102:103], s[8:9]
	global_store_dwordx2 v2, v[104:105], s[10:11]
	s_add_u32 s6, s6, 0x1000
	s_addc_u32 s7, s7, 0
	s_add_u32 s8, s8, 0x1000
	s_addc_u32 s9, s9, 0
	s_add_u32 s10, s10, 0x1000
	s_addc_u32 s11, s11, 0
	s_waitcnt vmcnt(17)
	v_sub_f32_e32 v84, v20, v24
	v_sub_f32_e32 v85, v21, v25
	v_sub_f32_e32 v86, v22, v26
	v_sub_f32_e32 v87, v23, v27
	v_pk_fma_f32 v[88:89], v[84:85], v[4:5], v[24:25]
	v_pk_fma_f32 v[90:91], v[86:87], v[6:7], v[26:27]
	v_pk_fma_f32 v[92:93], v[84:85], v[8:9], v[24:25]
	v_pk_fma_f32 v[94:95], v[86:87], v[10:11], v[26:27]
	v_pk_fma_f32 v[96:97], v[84:85], v[12:13], v[24:25]
	v_pk_fma_f32 v[98:99], v[86:87], v[14:15], v[26:27]
	v_cvt_pk_bf16_f32 v106, v88, v89
	v_cvt_pk_bf16_f32 v107, v90, v91
	v_cvt_pk_bf16_f32 v108, v92, v93
	v_cvt_pk_bf16_f32 v109, v94, v95
	v_cvt_pk_bf16_f32 v110, v96, v97
	v_cvt_pk_bf16_f32 v111, v98, v99
	global_store_dwordx2 v2, v[106:107], s[6:7]
	global_store_dwordx2 v2, v[108:109], s[8:9]
	global_store_dwordx2 v2, v[110:111], s[10:11]
	s_add_u32 s6, s6, 0x1000
	s_addc_u32 s7, s7, 0
	s_add_u32 s8, s8, 0x1000
	s_addc_u32 s9, s9, 0
	s_add_u32 s10, s10, 0x1000
	s_addc_u32 s11, s11, 0
	s_waitcnt vmcnt(19)
	v_sub_f32_e32 v84, v24, v28
	v_sub_f32_e32 v85, v25, v29
	v_sub_f32_e32 v86, v26, v30
	v_sub_f32_e32 v87, v27, v31
	v_pk_fma_f32 v[88:89], v[84:85], v[4:5], v[28:29]
	v_pk_fma_f32 v[90:91], v[86:87], v[6:7], v[30:31]
	v_pk_fma_f32 v[92:93], v[84:85], v[8:9], v[28:29]
	v_pk_fma_f32 v[94:95], v[86:87], v[10:11], v[30:31]
	v_pk_fma_f32 v[96:97], v[84:85], v[12:13], v[28:29]
	v_pk_fma_f32 v[98:99], v[86:87], v[14:15], v[30:31]
	v_cvt_pk_bf16_f32 v100, v88, v89
	v_cvt_pk_bf16_f32 v101, v90, v91
	v_cvt_pk_bf16_f32 v102, v92, v93
	v_cvt_pk_bf16_f32 v103, v94, v95
	v_cvt_pk_bf16_f32 v104, v96, v97
	v_cvt_pk_bf16_f32 v105, v98, v99
	global_store_dwordx2 v2, v[100:101], s[6:7]
	global_store_dwordx2 v2, v[102:103], s[8:9]
	global_store_dwordx2 v2, v[104:105], s[10:11]
	s_add_u32 s6, s6, 0x1000
	s_addc_u32 s7, s7, 0
	s_add_u32 s8, s8, 0x1000
	s_addc_u32 s9, s9, 0
	s_add_u32 s10, s10, 0x1000
	s_addc_u32 s11, s11, 0
	s_waitcnt vmcnt(21)
	v_sub_f32_e32 v84, v28, v32
	v_sub_f32_e32 v85, v29, v33
	v_sub_f32_e32 v86, v30, v34
	v_sub_f32_e32 v87, v31, v35
	v_pk_fma_f32 v[88:89], v[84:85], v[4:5], v[32:33]
	v_pk_fma_f32 v[90:91], v[86:87], v[6:7], v[34:35]
	v_pk_fma_f32 v[92:93], v[84:85], v[8:9], v[32:33]
	v_pk_fma_f32 v[94:95], v[86:87], v[10:11], v[34:35]
	v_pk_fma_f32 v[96:97], v[84:85], v[12:13], v[32:33]
	v_pk_fma_f32 v[98:99], v[86:87], v[14:15], v[34:35]
	v_cvt_pk_bf16_f32 v106, v88, v89
	v_cvt_pk_bf16_f32 v107, v90, v91
	v_cvt_pk_bf16_f32 v108, v92, v93
	v_cvt_pk_bf16_f32 v109, v94, v95
	v_cvt_pk_bf16_f32 v110, v96, v97
	v_cvt_pk_bf16_f32 v111, v98, v99
	global_store_dwordx2 v2, v[106:107], s[6:7]
	global_store_dwordx2 v2, v[108:109], s[8:9]
	global_store_dwordx2 v2, v[110:111], s[10:11]
	s_add_u32 s6, s6, 0x1000
	s_addc_u32 s7, s7, 0
	s_add_u32 s8, s8, 0x1000
	s_addc_u32 s9, s9, 0
	s_add_u32 s10, s10, 0x1000
	s_addc_u32 s11, s11, 0
	s_waitcnt vmcnt(23)
	v_sub_f32_e32 v84, v32, v36
	v_sub_f32_e32 v85, v33, v37
	v_sub_f32_e32 v86, v34, v38
	v_sub_f32_e32 v87, v35, v39
	v_pk_fma_f32 v[88:89], v[84:85], v[4:5], v[36:37]
	v_pk_fma_f32 v[90:91], v[86:87], v[6:7], v[38:39]
	v_pk_fma_f32 v[92:93], v[84:85], v[8:9], v[36:37]
	v_pk_fma_f32 v[94:95], v[86:87], v[10:11], v[38:39]
	v_pk_fma_f32 v[96:97], v[84:85], v[12:13], v[36:37]
	v_pk_fma_f32 v[98:99], v[86:87], v[14:15], v[38:39]
	v_cvt_pk_bf16_f32 v100, v88, v89
	v_cvt_pk_bf16_f32 v101, v90, v91
	v_cvt_pk_bf16_f32 v102, v92, v93
	v_cvt_pk_bf16_f32 v103, v94, v95
	v_cvt_pk_bf16_f32 v104, v96, v97
	v_cvt_pk_bf16_f32 v105, v98, v99
	global_store_dwordx2 v2, v[100:101], s[6:7]
	global_store_dwordx2 v2, v[102:103], s[8:9]
	global_store_dwordx2 v2, v[104:105], s[10:11]
	s_add_u32 s6, s6, 0x1000
	s_addc_u32 s7, s7, 0
	s_add_u32 s8, s8, 0x1000
	s_addc_u32 s9, s9, 0
	s_add_u32 s10, s10, 0x1000
	s_addc_u32 s11, s11, 0
	s_waitcnt vmcnt(25)
	v_sub_f32_e32 v84, v36, v40
	v_sub_f32_e32 v85, v37, v41
	v_sub_f32_e32 v86, v38, v42
	v_sub_f32_e32 v87, v39, v43
	v_pk_fma_f32 v[88:89], v[84:85], v[4:5], v[40:41]
	v_pk_fma_f32 v[90:91], v[86:87], v[6:7], v[42:43]
	v_pk_fma_f32 v[92:93], v[84:85], v[8:9], v[40:41]
	v_pk_fma_f32 v[94:95], v[86:87], v[10:11], v[42:43]
	v_pk_fma_f32 v[96:97], v[84:85], v[12:13], v[40:41]
	v_pk_fma_f32 v[98:99], v[86:87], v[14:15], v[42:43]
	v_cvt_pk_bf16_f32 v106, v88, v89
	v_cvt_pk_bf16_f32 v107, v90, v91
	v_cvt_pk_bf16_f32 v108, v92, v93
	v_cvt_pk_bf16_f32 v109, v94, v95
	v_cvt_pk_bf16_f32 v110, v96, v97
	v_cvt_pk_bf16_f32 v111, v98, v99
	global_store_dwordx2 v2, v[106:107], s[6:7]
	global_store_dwordx2 v2, v[108:109], s[8:9]
	global_store_dwordx2 v2, v[110:111], s[10:11]
	s_add_u32 s6, s6, 0x1000
	s_addc_u32 s7, s7, 0
	s_add_u32 s8, s8, 0x1000
	s_addc_u32 s9, s9, 0
	s_add_u32 s10, s10, 0x1000
	s_addc_u32 s11, s11, 0
	s_waitcnt vmcnt(27)
	v_sub_f32_e32 v84, v40, v44
	v_sub_f32_e32 v85, v41, v45
	v_sub_f32_e32 v86, v42, v46
	v_sub_f32_e32 v87, v43, v47
	v_pk_fma_f32 v[88:89], v[84:85], v[4:5], v[44:45]
	v_pk_fma_f32 v[90:91], v[86:87], v[6:7], v[46:47]
	v_pk_fma_f32 v[92:93], v[84:85], v[8:9], v[44:45]
	v_pk_fma_f32 v[94:95], v[86:87], v[10:11], v[46:47]
	v_pk_fma_f32 v[96:97], v[84:85], v[12:13], v[44:45]
	v_pk_fma_f32 v[98:99], v[86:87], v[14:15], v[46:47]
	v_cvt_pk_bf16_f32 v100, v88, v89
	v_cvt_pk_bf16_f32 v101, v90, v91
	v_cvt_pk_bf16_f32 v102, v92, v93
	v_cvt_pk_bf16_f32 v103, v94, v95
	v_cvt_pk_bf16_f32 v104, v96, v97
	v_cvt_pk_bf16_f32 v105, v98, v99
	global_store_dwordx2 v2, v[100:101], s[6:7]
	global_store_dwordx2 v2, v[102:103], s[8:9]
	global_store_dwordx2 v2, v[104:105], s[10:11]
	s_add_u32 s6, s6, 0x1000
	s_addc_u32 s7, s7, 0
	s_add_u32 s8, s8, 0x1000
	s_addc_u32 s9, s9, 0
	s_add_u32 s10, s10, 0x1000
	s_addc_u32 s11, s11, 0
	s_waitcnt vmcnt(29)
	v_sub_f32_e32 v84, v44, v48
	v_sub_f32_e32 v85, v45, v49
	v_sub_f32_e32 v86, v46, v50
	v_sub_f32_e32 v87, v47, v51
	v_pk_fma_f32 v[88:89], v[84:85], v[4:5], v[48:49]
	v_pk_fma_f32 v[90:91], v[86:87], v[6:7], v[50:51]
	v_pk_fma_f32 v[92:93], v[84:85], v[8:9], v[48:49]
	v_pk_fma_f32 v[94:95], v[86:87], v[10:11], v[50:51]
	v_pk_fma_f32 v[96:97], v[84:85], v[12:13], v[48:49]
	v_pk_fma_f32 v[98:99], v[86:87], v[14:15], v[50:51]
	v_cvt_pk_bf16_f32 v106, v88, v89
	v_cvt_pk_bf16_f32 v107, v90, v91
	v_cvt_pk_bf16_f32 v108, v92, v93
	v_cvt_pk_bf16_f32 v109, v94, v95
	v_cvt_pk_bf16_f32 v110, v96, v97
	v_cvt_pk_bf16_f32 v111, v98, v99
	global_store_dwordx2 v2, v[106:107], s[6:7]
	global_store_dwordx2 v2, v[108:109], s[8:9]
	global_store_dwordx2 v2, v[110:111], s[10:11]
	s_add_u32 s6, s6, 0x1000
	s_addc_u32 s7, s7, 0
	s_add_u32 s8, s8, 0x1000
	s_addc_u32 s9, s9, 0
	s_add_u32 s10, s10, 0x1000
	s_addc_u32 s11, s11, 0
	v_mov_b32_e32 v16, v48
	v_mov_b32_e32 v17, v49
	v_mov_b32_e32 v18, v50
	v_mov_b32_e32 v19, v51
	global_load_dwordx4 v[20:23], v1, s[4:5] nt
	s_add_u32 s4, s4, 0x2000
	s_addc_u32 s5, s5, 0
	global_load_dwordx4 v[24:27], v1, s[4:5] nt
	s_add_u32 s4, s4, 0x2000
	s_addc_u32 s5, s5, 0
	global_load_dwordx4 v[28:31], v1, s[4:5] nt
	s_add_u32 s4, s4, 0x2000
	s_addc_u32 s5, s5, 0
	global_load_dwordx4 v[32:35], v1, s[4:5] nt
	s_add_u32 s4, s4, 0x2000
	s_addc_u32 s5, s5, 0
	global_load_dwordx4 v[36:39], v1, s[4:5] nt
	s_add_u32 s4, s4, 0x2000
	s_addc_u32 s5, s5, 0
	global_load_dwordx4 v[40:43], v1, s[4:5] nt
	s_add_u32 s4, s4, 0x2000
	s_addc_u32 s5, s5, 0
	global_load_dwordx4 v[44:47], v1, s[4:5] nt
	s_add_u32 s4, s4, 0x2000
	s_addc_u32 s5, s5, 0
	global_load_dwordx4 v[48:51], v1, s[4:5] nt
	s_add_u32 s4, s4, 0x2000
	s_addc_u32 s5, s5, 0
	s_waitcnt vmcnt(39)
	v_sub_f32_e32 v84, v16, v52
	v_sub_f32_e32 v85, v17, v53
	v_sub_f32_e32 v86, v18, v54
	v_sub_f32_e32 v87, v19, v55
	v_pk_fma_f32 v[88:89], v[84:85], v[4:5], v[52:53]
	v_pk_fma_f32 v[90:91], v[86:87], v[6:7], v[54:55]
	v_pk_fma_f32 v[92:93], v[84:85], v[8:9], v[52:53]
	v_pk_fma_f32 v[94:95], v[86:87], v[10:11], v[54:55]
	v_pk_fma_f32 v[96:97], v[84:85], v[12:13], v[52:53]
	v_pk_fma_f32 v[98:99], v[86:87], v[14:15], v[54:55]
	v_cvt_pk_bf16_f32 v100, v88, v89
	v_cvt_pk_bf16_f32 v101, v90, v91
	v_cvt_pk_bf16_f32 v102, v92, v93
	v_cvt_pk_bf16_f32 v103, v94, v95
	v_cvt_pk_bf16_f32 v104, v96, v97
	v_cvt_pk_bf16_f32 v105, v98, v99
	global_store_dwordx2 v2, v[100:101], s[6:7]
	global_store_dwordx2 v2, v[102:103], s[8:9]
	global_store_dwordx2 v2, v[104:105], s[10:11]
	s_add_u32 s6, s6, 0x1000
	s_addc_u32 s7, s7, 0
	s_add_u32 s8, s8, 0x1000
	s_addc_u32 s9, s9, 0
	s_add_u32 s10, s10, 0x1000
	s_addc_u32 s11, s11, 0
	s_waitcnt vmcnt(41)
	v_sub_f32_e32 v84, v52, v56
	v_sub_f32_e32 v85, v53, v57
	v_sub_f32_e32 v86, v54, v58
	v_sub_f32_e32 v87, v55, v59
	v_pk_fma_f32 v[88:89], v[84:85], v[4:5], v[56:57]
	v_pk_fma_f32 v[90:91], v[86:87], v[6:7], v[58:59]
	v_pk_fma_f32 v[92:93], v[84:85], v[8:9], v[56:57]
	v_pk_fma_f32 v[94:95], v[86:87], v[10:11], v[58:59]
	v_pk_fma_f32 v[96:97], v[84:85], v[12:13], v[56:57]
	v_pk_fma_f32 v[98:99], v[86:87], v[14:15], v[58:59]
	v_cvt_pk_bf16_f32 v106, v88, v89
	v_cvt_pk_bf16_f32 v107, v90, v91
	v_cvt_pk_bf16_f32 v108, v92, v93
	v_cvt_pk_bf16_f32 v109, v94, v95
	v_cvt_pk_bf16_f32 v110, v96, v97
	v_cvt_pk_bf16_f32 v111, v98, v99
	global_store_dwordx2 v2, v[106:107], s[6:7]
	global_store_dwordx2 v2, v[108:109], s[8:9]
	global_store_dwordx2 v2, v[110:111], s[10:11]
	s_add_u32 s6, s6, 0x1000
	s_addc_u32 s7, s7, 0
	s_add_u32 s8, s8, 0x1000
	s_addc_u32 s9, s9, 0
	s_add_u32 s10, s10, 0x1000
	s_addc_u32 s11, s11, 0
	s_waitcnt vmcnt(43)
	v_sub_f32_e32 v84, v56, v60
	v_sub_f32_e32 v85, v57, v61
	v_sub_f32_e32 v86, v58, v62
	v_sub_f32_e32 v87, v59, v63
	v_pk_fma_f32 v[88:89], v[84:85], v[4:5], v[60:61]
	v_pk_fma_f32 v[90:91], v[86:87], v[6:7], v[62:63]
	v_pk_fma_f32 v[92:93], v[84:85], v[8:9], v[60:61]
	v_pk_fma_f32 v[94:95], v[86:87], v[10:11], v[62:63]
	v_pk_fma_f32 v[96:97], v[84:85], v[12:13], v[60:61]
	v_pk_fma_f32 v[98:99], v[86:87], v[14:15], v[62:63]
	v_cvt_pk_bf16_f32 v100, v88, v89
	v_cvt_pk_bf16_f32 v101, v90, v91
	v_cvt_pk_bf16_f32 v102, v92, v93
	v_cvt_pk_bf16_f32 v103, v94, v95
	v_cvt_pk_bf16_f32 v104, v96, v97
	v_cvt_pk_bf16_f32 v105, v98, v99
	global_store_dwordx2 v2, v[100:101], s[6:7]
	global_store_dwordx2 v2, v[102:103], s[8:9]
	global_store_dwordx2 v2, v[104:105], s[10:11]
	s_add_u32 s6, s6, 0x1000
	s_addc_u32 s7, s7, 0
	s_add_u32 s8, s8, 0x1000
	s_addc_u32 s9, s9, 0
	s_add_u32 s10, s10, 0x1000
	s_addc_u32 s11, s11, 0
	s_waitcnt vmcnt(45)
	v_sub_f32_e32 v84, v60, v64
	v_sub_f32_e32 v85, v61, v65
	v_sub_f32_e32 v86, v62, v66
	v_sub_f32_e32 v87, v63, v67
	v_pk_fma_f32 v[88:89], v[84:85], v[4:5], v[64:65]
	v_pk_fma_f32 v[90:91], v[86:87], v[6:7], v[66:67]
	v_pk_fma_f32 v[92:93], v[84:85], v[8:9], v[64:65]
	v_pk_fma_f32 v[94:95], v[86:87], v[10:11], v[66:67]
	v_pk_fma_f32 v[96:97], v[84:85], v[12:13], v[64:65]
	v_pk_fma_f32 v[98:99], v[86:87], v[14:15], v[66:67]
	v_cvt_pk_bf16_f32 v106, v88, v89
	v_cvt_pk_bf16_f32 v107, v90, v91
	v_cvt_pk_bf16_f32 v108, v92, v93
	v_cvt_pk_bf16_f32 v109, v94, v95
	v_cvt_pk_bf16_f32 v110, v96, v97
	v_cvt_pk_bf16_f32 v111, v98, v99
	global_store_dwordx2 v2, v[106:107], s[6:7]
	global_store_dwordx2 v2, v[108:109], s[8:9]
	global_store_dwordx2 v2, v[110:111], s[10:11]
	s_add_u32 s6, s6, 0x1000
	s_addc_u32 s7, s7, 0
	s_add_u32 s8, s8, 0x1000
	s_addc_u32 s9, s9, 0
	s_add_u32 s10, s10, 0x1000
	s_addc_u32 s11, s11, 0
	s_waitcnt vmcnt(47)
	v_sub_f32_e32 v84, v64, v68
	v_sub_f32_e32 v85, v65, v69
	v_sub_f32_e32 v86, v66, v70
	v_sub_f32_e32 v87, v67, v71
	v_pk_fma_f32 v[88:89], v[84:85], v[4:5], v[68:69]
	v_pk_fma_f32 v[90:91], v[86:87], v[6:7], v[70:71]
	v_pk_fma_f32 v[92:93], v[84:85], v[8:9], v[68:69]
	v_pk_fma_f32 v[94:95], v[86:87], v[10:11], v[70:71]
	v_pk_fma_f32 v[96:97], v[84:85], v[12:13], v[68:69]
	v_pk_fma_f32 v[98:99], v[86:87], v[14:15], v[70:71]
	v_cvt_pk_bf16_f32 v100, v88, v89
	v_cvt_pk_bf16_f32 v101, v90, v91
	v_cvt_pk_bf16_f32 v102, v92, v93
	v_cvt_pk_bf16_f32 v103, v94, v95
	v_cvt_pk_bf16_f32 v104, v96, v97
	v_cvt_pk_bf16_f32 v105, v98, v99
	global_store_dwordx2 v2, v[100:101], s[6:7]
	global_store_dwordx2 v2, v[102:103], s[8:9]
	global_store_dwordx2 v2, v[104:105], s[10:11]
	s_add_u32 s6, s6, 0x1000
	s_addc_u32 s7, s7, 0
	s_add_u32 s8, s8, 0x1000
	s_addc_u32 s9, s9, 0
	s_add_u32 s10, s10, 0x1000
	s_addc_u32 s11, s11, 0
	s_waitcnt vmcnt(49)
	v_sub_f32_e32 v84, v68, v72
	v_sub_f32_e32 v85, v69, v73
	v_sub_f32_e32 v86, v70, v74
	v_sub_f32_e32 v87, v71, v75
	v_pk_fma_f32 v[88:89], v[84:85], v[4:5], v[72:73]
	v_pk_fma_f32 v[90:91], v[86:87], v[6:7], v[74:75]
	v_pk_fma_f32 v[92:93], v[84:85], v[8:9], v[72:73]
	v_pk_fma_f32 v[94:95], v[86:87], v[10:11], v[74:75]
	v_pk_fma_f32 v[96:97], v[84:85], v[12:13], v[72:73]
	v_pk_fma_f32 v[98:99], v[86:87], v[14:15], v[74:75]
	v_cvt_pk_bf16_f32 v106, v88, v89
	v_cvt_pk_bf16_f32 v107, v90, v91
	v_cvt_pk_bf16_f32 v108, v92, v93
	v_cvt_pk_bf16_f32 v109, v94, v95
	v_cvt_pk_bf16_f32 v110, v96, v97
	v_cvt_pk_bf16_f32 v111, v98, v99
	global_store_dwordx2 v2, v[106:107], s[6:7]
	global_store_dwordx2 v2, v[108:109], s[8:9]
	global_store_dwordx2 v2, v[110:111], s[10:11]
	s_add_u32 s6, s6, 0x1000
	s_addc_u32 s7, s7, 0
	s_add_u32 s8, s8, 0x1000
	s_addc_u32 s9, s9, 0
	s_add_u32 s10, s10, 0x1000
	s_addc_u32 s11, s11, 0
	s_waitcnt vmcnt(51)
	v_sub_f32_e32 v84, v72, v76
	v_sub_f32_e32 v85, v73, v77
	v_sub_f32_e32 v86, v74, v78
	v_sub_f32_e32 v87, v75, v79
	v_pk_fma_f32 v[88:89], v[84:85], v[4:5], v[76:77]
	v_pk_fma_f32 v[90:91], v[86:87], v[6:7], v[78:79]
	v_pk_fma_f32 v[92:93], v[84:85], v[8:9], v[76:77]
	v_pk_fma_f32 v[94:95], v[86:87], v[10:11], v[78:79]
	v_pk_fma_f32 v[96:97], v[84:85], v[12:13], v[76:77]
	v_pk_fma_f32 v[98:99], v[86:87], v[14:15], v[78:79]
	v_cvt_pk_bf16_f32 v100, v88, v89
	v_cvt_pk_bf16_f32 v101, v90, v91
	v_cvt_pk_bf16_f32 v102, v92, v93
	v_cvt_pk_bf16_f32 v103, v94, v95
	v_cvt_pk_bf16_f32 v104, v96, v97
	v_cvt_pk_bf16_f32 v105, v98, v99
	global_store_dwordx2 v2, v[100:101], s[6:7]
	global_store_dwordx2 v2, v[102:103], s[8:9]
	global_store_dwordx2 v2, v[104:105], s[10:11]
	s_add_u32 s6, s6, 0x1000
	s_addc_u32 s7, s7, 0
	s_add_u32 s8, s8, 0x1000
	s_addc_u32 s9, s9, 0
	s_add_u32 s10, s10, 0x1000
	s_addc_u32 s11, s11, 0
	s_waitcnt vmcnt(53)
	v_sub_f32_e32 v84, v76, v80
	v_sub_f32_e32 v85, v77, v81
	v_sub_f32_e32 v86, v78, v82
	v_sub_f32_e32 v87, v79, v83
	v_pk_fma_f32 v[88:89], v[84:85], v[4:5], v[80:81]
	v_pk_fma_f32 v[90:91], v[86:87], v[6:7], v[82:83]
	v_pk_fma_f32 v[92:93], v[84:85], v[8:9], v[80:81]
	v_pk_fma_f32 v[94:95], v[86:87], v[10:11], v[82:83]
	v_pk_fma_f32 v[96:97], v[84:85], v[12:13], v[80:81]
	v_pk_fma_f32 v[98:99], v[86:87], v[14:15], v[82:83]
	v_cvt_pk_bf16_f32 v106, v88, v89
	v_cvt_pk_bf16_f32 v107, v90, v91
	v_cvt_pk_bf16_f32 v108, v92, v93
	v_cvt_pk_bf16_f32 v109, v94, v95
	v_cvt_pk_bf16_f32 v110, v96, v97
	v_cvt_pk_bf16_f32 v111, v98, v99
	global_store_dwordx2 v2, v[106:107], s[6:7]
	global_store_dwordx2 v2, v[108:109], s[8:9]
	global_store_dwordx2 v2, v[110:111], s[10:11]
	s_add_u32 s6, s6, 0x1000
	s_addc_u32 s7, s7, 0
	s_add_u32 s8, s8, 0x1000
	s_addc_u32 s9, s9, 0
	s_add_u32 s10, s10, 0x1000
	s_addc_u32 s11, s11, 0
	v_mov_b32_e32 v16, v80
	v_mov_b32_e32 v17, v81
	v_mov_b32_e32 v18, v82
	v_mov_b32_e32 v19, v83
	global_load_dwordx4 v[52:55], v1, s[4:5] nt
	s_add_u32 s4, s4, 0x2000
	s_addc_u32 s5, s5, 0
	global_load_dwordx4 v[56:59], v1, s[4:5] nt
	s_add_u32 s4, s4, 0x2000
	s_addc_u32 s5, s5, 0
	global_load_dwordx4 v[60:63], v1, s[4:5] nt
	s_add_u32 s4, s4, 0x2000
	s_addc_u32 s5, s5, 0
	global_load_dwordx4 v[64:67], v1, s[4:5] nt
	s_add_u32 s4, s4, 0x2000
	s_addc_u32 s5, s5, 0
	global_load_dwordx4 v[68:71], v1, s[4:5] nt
	s_add_u32 s4, s4, 0x2000
	s_addc_u32 s5, s5, 0
	global_load_dwordx4 v[72:75], v1, s[4:5] nt
	s_add_u32 s4, s4, 0x2000
	s_addc_u32 s5, s5, 0
	global_load_dwordx4 v[76:79], v1, s[4:5] nt
	s_add_u32 s4, s4, 0x2000
	s_addc_u32 s5, s5, 0
	global_load_dwordx4 v[80:83], v1, s[4:5] nt
	s_add_u32 s4, s4, 0x2000
	s_addc_u32 s5, s5, 0
	s_waitcnt vmcnt(39)
	v_sub_f32_e32 v84, v16, v20
	v_sub_f32_e32 v85, v17, v21
	v_sub_f32_e32 v86, v18, v22
	v_sub_f32_e32 v87, v19, v23
	v_pk_fma_f32 v[88:89], v[84:85], v[4:5], v[20:21]
	v_pk_fma_f32 v[90:91], v[86:87], v[6:7], v[22:23]
	v_pk_fma_f32 v[92:93], v[84:85], v[8:9], v[20:21]
	v_pk_fma_f32 v[94:95], v[86:87], v[10:11], v[22:23]
	v_pk_fma_f32 v[96:97], v[84:85], v[12:13], v[20:21]
	v_pk_fma_f32 v[98:99], v[86:87], v[14:15], v[22:23]
	v_cvt_pk_bf16_f32 v100, v88, v89
	v_cvt_pk_bf16_f32 v101, v90, v91
	v_cvt_pk_bf16_f32 v102, v92, v93
	v_cvt_pk_bf16_f32 v103, v94, v95
	v_cvt_pk_bf16_f32 v104, v96, v97
	v_cvt_pk_bf16_f32 v105, v98, v99
	global_store_dwordx2 v2, v[100:101], s[6:7]
	global_store_dwordx2 v2, v[102:103], s[8:9]
	global_store_dwordx2 v2, v[104:105], s[10:11]
	s_add_u32 s6, s6, 0x1000
	s_addc_u32 s7, s7, 0
	s_add_u32 s8, s8, 0x1000
	s_addc_u32 s9, s9, 0
	s_add_u32 s10, s10, 0x1000
	s_addc_u32 s11, s11, 0
	s_waitcnt vmcnt(41)
	v_sub_f32_e32 v84, v20, v24
	v_sub_f32_e32 v85, v21, v25
	v_sub_f32_e32 v86, v22, v26
	v_sub_f32_e32 v87, v23, v27
	v_pk_fma_f32 v[88:89], v[84:85], v[4:5], v[24:25]
	v_pk_fma_f32 v[90:91], v[86:87], v[6:7], v[26:27]
	v_pk_fma_f32 v[92:93], v[84:85], v[8:9], v[24:25]
	v_pk_fma_f32 v[94:95], v[86:87], v[10:11], v[26:27]
	v_pk_fma_f32 v[96:97], v[84:85], v[12:13], v[24:25]
	v_pk_fma_f32 v[98:99], v[86:87], v[14:15], v[26:27]
	v_cvt_pk_bf16_f32 v106, v88, v89
	v_cvt_pk_bf16_f32 v107, v90, v91
	v_cvt_pk_bf16_f32 v108, v92, v93
	v_cvt_pk_bf16_f32 v109, v94, v95
	v_cvt_pk_bf16_f32 v110, v96, v97
	v_cvt_pk_bf16_f32 v111, v98, v99
	global_store_dwordx2 v2, v[106:107], s[6:7]
	global_store_dwordx2 v2, v[108:109], s[8:9]
	global_store_dwordx2 v2, v[110:111], s[10:11]
	s_add_u32 s6, s6, 0x1000
	s_addc_u32 s7, s7, 0
	s_add_u32 s8, s8, 0x1000
	s_addc_u32 s9, s9, 0
	s_add_u32 s10, s10, 0x1000
	s_addc_u32 s11, s11, 0
	s_waitcnt vmcnt(43)
	v_sub_f32_e32 v84, v24, v28
	v_sub_f32_e32 v85, v25, v29
	v_sub_f32_e32 v86, v26, v30
	v_sub_f32_e32 v87, v27, v31
	v_pk_fma_f32 v[88:89], v[84:85], v[4:5], v[28:29]
	v_pk_fma_f32 v[90:91], v[86:87], v[6:7], v[30:31]
	v_pk_fma_f32 v[92:93], v[84:85], v[8:9], v[28:29]
	v_pk_fma_f32 v[94:95], v[86:87], v[10:11], v[30:31]
	v_pk_fma_f32 v[96:97], v[84:85], v[12:13], v[28:29]
	v_pk_fma_f32 v[98:99], v[86:87], v[14:15], v[30:31]
	v_cvt_pk_bf16_f32 v100, v88, v89
	v_cvt_pk_bf16_f32 v101, v90, v91
	v_cvt_pk_bf16_f32 v102, v92, v93
	v_cvt_pk_bf16_f32 v103, v94, v95
	v_cvt_pk_bf16_f32 v104, v96, v97
	v_cvt_pk_bf16_f32 v105, v98, v99
	global_store_dwordx2 v2, v[100:101], s[6:7]
	global_store_dwordx2 v2, v[102:103], s[8:9]
	global_store_dwordx2 v2, v[104:105], s[10:11]
	s_add_u32 s6, s6, 0x1000
	s_addc_u32 s7, s7, 0
	s_add_u32 s8, s8, 0x1000
	s_addc_u32 s9, s9, 0
	s_add_u32 s10, s10, 0x1000
	s_addc_u32 s11, s11, 0
	s_waitcnt vmcnt(45)
	v_sub_f32_e32 v84, v28, v32
	v_sub_f32_e32 v85, v29, v33
	v_sub_f32_e32 v86, v30, v34
	v_sub_f32_e32 v87, v31, v35
	v_pk_fma_f32 v[88:89], v[84:85], v[4:5], v[32:33]
	v_pk_fma_f32 v[90:91], v[86:87], v[6:7], v[34:35]
	v_pk_fma_f32 v[92:93], v[84:85], v[8:9], v[32:33]
	v_pk_fma_f32 v[94:95], v[86:87], v[10:11], v[34:35]
	v_pk_fma_f32 v[96:97], v[84:85], v[12:13], v[32:33]
	v_pk_fma_f32 v[98:99], v[86:87], v[14:15], v[34:35]
	v_cvt_pk_bf16_f32 v106, v88, v89
	v_cvt_pk_bf16_f32 v107, v90, v91
	v_cvt_pk_bf16_f32 v108, v92, v93
	v_cvt_pk_bf16_f32 v109, v94, v95
	v_cvt_pk_bf16_f32 v110, v96, v97
	v_cvt_pk_bf16_f32 v111, v98, v99
	global_store_dwordx2 v2, v[106:107], s[6:7]
	global_store_dwordx2 v2, v[108:109], s[8:9]
	global_store_dwordx2 v2, v[110:111], s[10:11]
	s_add_u32 s6, s6, 0x1000
	s_addc_u32 s7, s7, 0
	s_add_u32 s8, s8, 0x1000
	s_addc_u32 s9, s9, 0
	s_add_u32 s10, s10, 0x1000
	s_addc_u32 s11, s11, 0
	s_waitcnt vmcnt(47)
	v_sub_f32_e32 v84, v32, v36
	v_sub_f32_e32 v85, v33, v37
	v_sub_f32_e32 v86, v34, v38
	v_sub_f32_e32 v87, v35, v39
	v_pk_fma_f32 v[88:89], v[84:85], v[4:5], v[36:37]
	v_pk_fma_f32 v[90:91], v[86:87], v[6:7], v[38:39]
	v_pk_fma_f32 v[92:93], v[84:85], v[8:9], v[36:37]
	v_pk_fma_f32 v[94:95], v[86:87], v[10:11], v[38:39]
	v_pk_fma_f32 v[96:97], v[84:85], v[12:13], v[36:37]
	v_pk_fma_f32 v[98:99], v[86:87], v[14:15], v[38:39]
	v_cvt_pk_bf16_f32 v100, v88, v89
	v_cvt_pk_bf16_f32 v101, v90, v91
	v_cvt_pk_bf16_f32 v102, v92, v93
	v_cvt_pk_bf16_f32 v103, v94, v95
	v_cvt_pk_bf16_f32 v104, v96, v97
	v_cvt_pk_bf16_f32 v105, v98, v99
	global_store_dwordx2 v2, v[100:101], s[6:7]
	global_store_dwordx2 v2, v[102:103], s[8:9]
	global_store_dwordx2 v2, v[104:105], s[10:11]
	s_add_u32 s6, s6, 0x1000
	s_addc_u32 s7, s7, 0
	s_add_u32 s8, s8, 0x1000
	s_addc_u32 s9, s9, 0
	s_add_u32 s10, s10, 0x1000
	s_addc_u32 s11, s11, 0
	s_waitcnt vmcnt(49)
	v_sub_f32_e32 v84, v36, v40
	v_sub_f32_e32 v85, v37, v41
	v_sub_f32_e32 v86, v38, v42
	v_sub_f32_e32 v87, v39, v43
	v_pk_fma_f32 v[88:89], v[84:85], v[4:5], v[40:41]
	v_pk_fma_f32 v[90:91], v[86:87], v[6:7], v[42:43]
	v_pk_fma_f32 v[92:93], v[84:85], v[8:9], v[40:41]
	v_pk_fma_f32 v[94:95], v[86:87], v[10:11], v[42:43]
	v_pk_fma_f32 v[96:97], v[84:85], v[12:13], v[40:41]
	v_pk_fma_f32 v[98:99], v[86:87], v[14:15], v[42:43]
	v_cvt_pk_bf16_f32 v106, v88, v89
	v_cvt_pk_bf16_f32 v107, v90, v91
	v_cvt_pk_bf16_f32 v108, v92, v93
	v_cvt_pk_bf16_f32 v109, v94, v95
	v_cvt_pk_bf16_f32 v110, v96, v97
	v_cvt_pk_bf16_f32 v111, v98, v99
	global_store_dwordx2 v2, v[106:107], s[6:7]
	global_store_dwordx2 v2, v[108:109], s[8:9]
	global_store_dwordx2 v2, v[110:111], s[10:11]
	s_add_u32 s6, s6, 0x1000
	s_addc_u32 s7, s7, 0
	s_add_u32 s8, s8, 0x1000
	s_addc_u32 s9, s9, 0
	s_add_u32 s10, s10, 0x1000
	s_addc_u32 s11, s11, 0
	s_waitcnt vmcnt(51)
	v_sub_f32_e32 v84, v40, v44
	v_sub_f32_e32 v85, v41, v45
	v_sub_f32_e32 v86, v42, v46
	v_sub_f32_e32 v87, v43, v47
	v_pk_fma_f32 v[88:89], v[84:85], v[4:5], v[44:45]
	v_pk_fma_f32 v[90:91], v[86:87], v[6:7], v[46:47]
	v_pk_fma_f32 v[92:93], v[84:85], v[8:9], v[44:45]
	v_pk_fma_f32 v[94:95], v[86:87], v[10:11], v[46:47]
	v_pk_fma_f32 v[96:97], v[84:85], v[12:13], v[44:45]
	v_pk_fma_f32 v[98:99], v[86:87], v[14:15], v[46:47]
	v_cvt_pk_bf16_f32 v100, v88, v89
	v_cvt_pk_bf16_f32 v101, v90, v91
	v_cvt_pk_bf16_f32 v102, v92, v93
	v_cvt_pk_bf16_f32 v103, v94, v95
	v_cvt_pk_bf16_f32 v104, v96, v97
	v_cvt_pk_bf16_f32 v105, v98, v99
	global_store_dwordx2 v2, v[100:101], s[6:7]
	global_store_dwordx2 v2, v[102:103], s[8:9]
	global_store_dwordx2 v2, v[104:105], s[10:11]
	s_add_u32 s6, s6, 0x1000
	s_addc_u32 s7, s7, 0
	s_add_u32 s8, s8, 0x1000
	s_addc_u32 s9, s9, 0
	s_add_u32 s10, s10, 0x1000
	s_addc_u32 s11, s11, 0
	s_waitcnt vmcnt(53)
	v_sub_f32_e32 v84, v44, v48
	v_sub_f32_e32 v85, v45, v49
	v_sub_f32_e32 v86, v46, v50
	v_sub_f32_e32 v87, v47, v51
	v_pk_fma_f32 v[88:89], v[84:85], v[4:5], v[48:49]
	v_pk_fma_f32 v[90:91], v[86:87], v[6:7], v[50:51]
	v_pk_fma_f32 v[92:93], v[84:85], v[8:9], v[48:49]
	v_pk_fma_f32 v[94:95], v[86:87], v[10:11], v[50:51]
	v_pk_fma_f32 v[96:97], v[84:85], v[12:13], v[48:49]
	v_pk_fma_f32 v[98:99], v[86:87], v[14:15], v[50:51]
	v_cvt_pk_bf16_f32 v106, v88, v89
	v_cvt_pk_bf16_f32 v107, v90, v91
	v_cvt_pk_bf16_f32 v108, v92, v93
	v_cvt_pk_bf16_f32 v109, v94, v95
	v_cvt_pk_bf16_f32 v110, v96, v97
	v_cvt_pk_bf16_f32 v111, v98, v99
	global_store_dwordx2 v2, v[106:107], s[6:7]
	global_store_dwordx2 v2, v[108:109], s[8:9]
	global_store_dwordx2 v2, v[110:111], s[10:11]
	s_add_u32 s6, s6, 0x1000
	s_addc_u32 s7, s7, 0
	s_add_u32 s8, s8, 0x1000
	s_addc_u32 s9, s9, 0
	s_add_u32 s10, s10, 0x1000
	s_addc_u32 s11, s11, 0
	v_mov_b32_e32 v16, v48
	v_mov_b32_e32 v17, v49
	v_mov_b32_e32 v18, v50
	v_mov_b32_e32 v19, v51
	global_load_dwordx4 v[20:23], v1, s[4:5] nt
	s_add_u32 s4, s4, 0x2000
	s_addc_u32 s5, s5, 0
	global_load_dwordx4 v[24:27], v1, s[4:5] nt
	s_add_u32 s4, s4, 0x2000
	s_addc_u32 s5, s5, 0
	global_load_dwordx4 v[28:31], v1, s[4:5] nt
	s_add_u32 s4, s4, 0x2000
	s_addc_u32 s5, s5, 0
	global_load_dwordx4 v[32:35], v1, s[4:5] nt
	s_add_u32 s4, s4, 0x2000
	s_addc_u32 s5, s5, 0
	global_load_dwordx4 v[36:39], v1, s[4:5] nt
	s_add_u32 s4, s4, 0x2000
	s_addc_u32 s5, s5, 0
	global_load_dwordx4 v[40:43], v1, s[4:5] nt
	s_add_u32 s4, s4, 0x2000
	s_addc_u32 s5, s5, 0
	global_load_dwordx4 v[44:47], v1, s[4:5] nt
	s_add_u32 s4, s4, 0x2000
	s_addc_u32 s5, s5, 0
	global_load_dwordx4 v[48:51], v1, s[4:5] nt
	s_add_u32 s4, s4, 0x2000
	s_addc_u32 s5, s5, 0
	s_waitcnt vmcnt(39)
	v_sub_f32_e32 v84, v16, v52
	v_sub_f32_e32 v85, v17, v53
	v_sub_f32_e32 v86, v18, v54
	v_sub_f32_e32 v87, v19, v55
	v_pk_fma_f32 v[88:89], v[84:85], v[4:5], v[52:53]
	v_pk_fma_f32 v[90:91], v[86:87], v[6:7], v[54:55]
	v_pk_fma_f32 v[92:93], v[84:85], v[8:9], v[52:53]
	v_pk_fma_f32 v[94:95], v[86:87], v[10:11], v[54:55]
	v_pk_fma_f32 v[96:97], v[84:85], v[12:13], v[52:53]
	v_pk_fma_f32 v[98:99], v[86:87], v[14:15], v[54:55]
	v_cvt_pk_bf16_f32 v100, v88, v89
	v_cvt_pk_bf16_f32 v101, v90, v91
	v_cvt_pk_bf16_f32 v102, v92, v93
	v_cvt_pk_bf16_f32 v103, v94, v95
	v_cvt_pk_bf16_f32 v104, v96, v97
	v_cvt_pk_bf16_f32 v105, v98, v99
	global_store_dwordx2 v2, v[100:101], s[6:7]
	global_store_dwordx2 v2, v[102:103], s[8:9]
	global_store_dwordx2 v2, v[104:105], s[10:11]
	s_add_u32 s6, s6, 0x1000
	s_addc_u32 s7, s7, 0
	s_add_u32 s8, s8, 0x1000
	s_addc_u32 s9, s9, 0
	s_add_u32 s10, s10, 0x1000
	s_addc_u32 s11, s11, 0
	s_waitcnt vmcnt(41)
	v_sub_f32_e32 v84, v52, v56
	v_sub_f32_e32 v85, v53, v57
	v_sub_f32_e32 v86, v54, v58
	v_sub_f32_e32 v87, v55, v59
	v_pk_fma_f32 v[88:89], v[84:85], v[4:5], v[56:57]
	v_pk_fma_f32 v[90:91], v[86:87], v[6:7], v[58:59]
	v_pk_fma_f32 v[92:93], v[84:85], v[8:9], v[56:57]
	v_pk_fma_f32 v[94:95], v[86:87], v[10:11], v[58:59]
	v_pk_fma_f32 v[96:97], v[84:85], v[12:13], v[56:57]
	v_pk_fma_f32 v[98:99], v[86:87], v[14:15], v[58:59]
	v_cvt_pk_bf16_f32 v106, v88, v89
	v_cvt_pk_bf16_f32 v107, v90, v91
	v_cvt_pk_bf16_f32 v108, v92, v93
	v_cvt_pk_bf16_f32 v109, v94, v95
	v_cvt_pk_bf16_f32 v110, v96, v97
	v_cvt_pk_bf16_f32 v111, v98, v99
	global_store_dwordx2 v2, v[106:107], s[6:7]
	global_store_dwordx2 v2, v[108:109], s[8:9]
	global_store_dwordx2 v2, v[110:111], s[10:11]
	s_add_u32 s6, s6, 0x1000
	s_addc_u32 s7, s7, 0
	s_add_u32 s8, s8, 0x1000
	s_addc_u32 s9, s9, 0
	s_add_u32 s10, s10, 0x1000
	s_addc_u32 s11, s11, 0
	s_waitcnt vmcnt(43)
	v_sub_f32_e32 v84, v56, v60
	v_sub_f32_e32 v85, v57, v61
	v_sub_f32_e32 v86, v58, v62
	v_sub_f32_e32 v87, v59, v63
	v_pk_fma_f32 v[88:89], v[84:85], v[4:5], v[60:61]
	v_pk_fma_f32 v[90:91], v[86:87], v[6:7], v[62:63]
	v_pk_fma_f32 v[92:93], v[84:85], v[8:9], v[60:61]
	v_pk_fma_f32 v[94:95], v[86:87], v[10:11], v[62:63]
	v_pk_fma_f32 v[96:97], v[84:85], v[12:13], v[60:61]
	v_pk_fma_f32 v[98:99], v[86:87], v[14:15], v[62:63]
	v_cvt_pk_bf16_f32 v100, v88, v89
	v_cvt_pk_bf16_f32 v101, v90, v91
	v_cvt_pk_bf16_f32 v102, v92, v93
	v_cvt_pk_bf16_f32 v103, v94, v95
	v_cvt_pk_bf16_f32 v104, v96, v97
	v_cvt_pk_bf16_f32 v105, v98, v99
	global_store_dwordx2 v2, v[100:101], s[6:7]
	global_store_dwordx2 v2, v[102:103], s[8:9]
	global_store_dwordx2 v2, v[104:105], s[10:11]
	s_add_u32 s6, s6, 0x1000
	s_addc_u32 s7, s7, 0
	s_add_u32 s8, s8, 0x1000
	s_addc_u32 s9, s9, 0
	s_add_u32 s10, s10, 0x1000
	s_addc_u32 s11, s11, 0
	s_waitcnt vmcnt(45)
	v_sub_f32_e32 v84, v60, v64
	v_sub_f32_e32 v85, v61, v65
	v_sub_f32_e32 v86, v62, v66
	v_sub_f32_e32 v87, v63, v67
	v_pk_fma_f32 v[88:89], v[84:85], v[4:5], v[64:65]
	v_pk_fma_f32 v[90:91], v[86:87], v[6:7], v[66:67]
	v_pk_fma_f32 v[92:93], v[84:85], v[8:9], v[64:65]
	v_pk_fma_f32 v[94:95], v[86:87], v[10:11], v[66:67]
	v_pk_fma_f32 v[96:97], v[84:85], v[12:13], v[64:65]
	v_pk_fma_f32 v[98:99], v[86:87], v[14:15], v[66:67]
	v_cvt_pk_bf16_f32 v106, v88, v89
	v_cvt_pk_bf16_f32 v107, v90, v91
	v_cvt_pk_bf16_f32 v108, v92, v93
	v_cvt_pk_bf16_f32 v109, v94, v95
	v_cvt_pk_bf16_f32 v110, v96, v97
	v_cvt_pk_bf16_f32 v111, v98, v99
	global_store_dwordx2 v2, v[106:107], s[6:7]
	global_store_dwordx2 v2, v[108:109], s[8:9]
	global_store_dwordx2 v2, v[110:111], s[10:11]
	s_add_u32 s6, s6, 0x1000
	s_addc_u32 s7, s7, 0
	s_add_u32 s8, s8, 0x1000
	s_addc_u32 s9, s9, 0
	s_add_u32 s10, s10, 0x1000
	s_addc_u32 s11, s11, 0
	s_waitcnt vmcnt(47)
	v_sub_f32_e32 v84, v64, v68
	v_sub_f32_e32 v85, v65, v69
	v_sub_f32_e32 v86, v66, v70
	v_sub_f32_e32 v87, v67, v71
	v_pk_fma_f32 v[88:89], v[84:85], v[4:5], v[68:69]
	v_pk_fma_f32 v[90:91], v[86:87], v[6:7], v[70:71]
	v_pk_fma_f32 v[92:93], v[84:85], v[8:9], v[68:69]
	v_pk_fma_f32 v[94:95], v[86:87], v[10:11], v[70:71]
	v_pk_fma_f32 v[96:97], v[84:85], v[12:13], v[68:69]
	v_pk_fma_f32 v[98:99], v[86:87], v[14:15], v[70:71]
	v_cvt_pk_bf16_f32 v100, v88, v89
	v_cvt_pk_bf16_f32 v101, v90, v91
	v_cvt_pk_bf16_f32 v102, v92, v93
	v_cvt_pk_bf16_f32 v103, v94, v95
	v_cvt_pk_bf16_f32 v104, v96, v97
	v_cvt_pk_bf16_f32 v105, v98, v99
	global_store_dwordx2 v2, v[100:101], s[6:7]
	global_store_dwordx2 v2, v[102:103], s[8:9]
	global_store_dwordx2 v2, v[104:105], s[10:11]
	s_add_u32 s6, s6, 0x1000
	s_addc_u32 s7, s7, 0
	s_add_u32 s8, s8, 0x1000
	s_addc_u32 s9, s9, 0
	s_add_u32 s10, s10, 0x1000
	s_addc_u32 s11, s11, 0
	s_waitcnt vmcnt(49)
	v_sub_f32_e32 v84, v68, v72
	v_sub_f32_e32 v85, v69, v73
	v_sub_f32_e32 v86, v70, v74
	v_sub_f32_e32 v87, v71, v75
	v_pk_fma_f32 v[88:89], v[84:85], v[4:5], v[72:73]
	v_pk_fma_f32 v[90:91], v[86:87], v[6:7], v[74:75]
	v_pk_fma_f32 v[92:93], v[84:85], v[8:9], v[72:73]
	v_pk_fma_f32 v[94:95], v[86:87], v[10:11], v[74:75]
	v_pk_fma_f32 v[96:97], v[84:85], v[12:13], v[72:73]
	v_pk_fma_f32 v[98:99], v[86:87], v[14:15], v[74:75]
	v_cvt_pk_bf16_f32 v106, v88, v89
	v_cvt_pk_bf16_f32 v107, v90, v91
	v_cvt_pk_bf16_f32 v108, v92, v93
	v_cvt_pk_bf16_f32 v109, v94, v95
	v_cvt_pk_bf16_f32 v110, v96, v97
	v_cvt_pk_bf16_f32 v111, v98, v99
	global_store_dwordx2 v2, v[106:107], s[6:7]
	global_store_dwordx2 v2, v[108:109], s[8:9]
	global_store_dwordx2 v2, v[110:111], s[10:11]
	s_add_u32 s6, s6, 0x1000
	s_addc_u32 s7, s7, 0
	s_add_u32 s8, s8, 0x1000
	s_addc_u32 s9, s9, 0
	s_add_u32 s10, s10, 0x1000
	s_addc_u32 s11, s11, 0
	s_waitcnt vmcnt(51)
	v_sub_f32_e32 v84, v72, v76
	v_sub_f32_e32 v85, v73, v77
	v_sub_f32_e32 v86, v74, v78
	v_sub_f32_e32 v87, v75, v79
	v_pk_fma_f32 v[88:89], v[84:85], v[4:5], v[76:77]
	v_pk_fma_f32 v[90:91], v[86:87], v[6:7], v[78:79]
	v_pk_fma_f32 v[92:93], v[84:85], v[8:9], v[76:77]
	v_pk_fma_f32 v[94:95], v[86:87], v[10:11], v[78:79]
	v_pk_fma_f32 v[96:97], v[84:85], v[12:13], v[76:77]
	v_pk_fma_f32 v[98:99], v[86:87], v[14:15], v[78:79]
	v_cvt_pk_bf16_f32 v100, v88, v89
	v_cvt_pk_bf16_f32 v101, v90, v91
	v_cvt_pk_bf16_f32 v102, v92, v93
	v_cvt_pk_bf16_f32 v103, v94, v95
	v_cvt_pk_bf16_f32 v104, v96, v97
	v_cvt_pk_bf16_f32 v105, v98, v99
	global_store_dwordx2 v2, v[100:101], s[6:7]
	global_store_dwordx2 v2, v[102:103], s[8:9]
	global_store_dwordx2 v2, v[104:105], s[10:11]
	s_add_u32 s6, s6, 0x1000
	s_addc_u32 s7, s7, 0
	s_add_u32 s8, s8, 0x1000
	s_addc_u32 s9, s9, 0
	s_add_u32 s10, s10, 0x1000
	s_addc_u32 s11, s11, 0
	s_waitcnt vmcnt(53)
	v_sub_f32_e32 v84, v76, v80
	v_sub_f32_e32 v85, v77, v81
	v_sub_f32_e32 v86, v78, v82
	v_sub_f32_e32 v87, v79, v83
	v_pk_fma_f32 v[88:89], v[84:85], v[4:5], v[80:81]
	v_pk_fma_f32 v[90:91], v[86:87], v[6:7], v[82:83]
	v_pk_fma_f32 v[92:93], v[84:85], v[8:9], v[80:81]
	v_pk_fma_f32 v[94:95], v[86:87], v[10:11], v[82:83]
	v_pk_fma_f32 v[96:97], v[84:85], v[12:13], v[80:81]
	v_pk_fma_f32 v[98:99], v[86:87], v[14:15], v[82:83]
	v_cvt_pk_bf16_f32 v106, v88, v89
	v_cvt_pk_bf16_f32 v107, v90, v91
	v_cvt_pk_bf16_f32 v108, v92, v93
	v_cvt_pk_bf16_f32 v109, v94, v95
	v_cvt_pk_bf16_f32 v110, v96, v97
	v_cvt_pk_bf16_f32 v111, v98, v99
	global_store_dwordx2 v2, v[106:107], s[6:7]
	global_store_dwordx2 v2, v[108:109], s[8:9]
	global_store_dwordx2 v2, v[110:111], s[10:11]
	s_add_u32 s6, s6, 0x1000
	s_addc_u32 s7, s7, 0
	s_add_u32 s8, s8, 0x1000
	s_addc_u32 s9, s9, 0
	s_add_u32 s10, s10, 0x1000
	s_addc_u32 s11, s11, 0
	v_mov_b32_e32 v16, v80
	v_mov_b32_e32 v17, v81
	v_mov_b32_e32 v18, v82
	v_mov_b32_e32 v19, v83
	global_load_dwordx4 v[52:55], v1, s[4:5] nt
	s_add_u32 s4, s4, 0x2000
	s_addc_u32 s5, s5, 0
	global_load_dwordx4 v[56:59], v1, s[4:5] nt
	s_add_u32 s4, s4, 0x2000
	s_addc_u32 s5, s5, 0
	global_load_dwordx4 v[60:63], v1, s[4:5] nt
	s_add_u32 s4, s4, 0x2000
	s_addc_u32 s5, s5, 0
	global_load_dwordx4 v[64:67], v1, s[4:5] nt
	s_add_u32 s4, s4, 0x2000
	s_addc_u32 s5, s5, 0
	global_load_dwordx4 v[68:71], v1, s[4:5] nt
	s_add_u32 s4, s4, 0x2000
	s_addc_u32 s5, s5, 0
	global_load_dwordx4 v[72:75], v1, s[4:5] nt
	s_add_u32 s4, s4, 0x2000
	s_addc_u32 s5, s5, 0
	global_load_dwordx4 v[76:79], v1, s[4:5] nt
	s_add_u32 s4, s4, 0x2000
	s_addc_u32 s5, s5, 0
	global_load_dwordx4 v[80:83], v1, s[4:5] nt
	s_add_u32 s4, s4, 0x2000
	s_addc_u32 s5, s5, 0
	s_waitcnt vmcnt(39)
	v_sub_f32_e32 v84, v16, v20
	v_sub_f32_e32 v85, v17, v21
	v_sub_f32_e32 v86, v18, v22
	v_sub_f32_e32 v87, v19, v23
	v_pk_fma_f32 v[88:89], v[84:85], v[4:5], v[20:21]
	v_pk_fma_f32 v[90:91], v[86:87], v[6:7], v[22:23]
	v_pk_fma_f32 v[92:93], v[84:85], v[8:9], v[20:21]
	v_pk_fma_f32 v[94:95], v[86:87], v[10:11], v[22:23]
	v_pk_fma_f32 v[96:97], v[84:85], v[12:13], v[20:21]
	v_pk_fma_f32 v[98:99], v[86:87], v[14:15], v[22:23]
	v_cvt_pk_bf16_f32 v100, v88, v89
	v_cvt_pk_bf16_f32 v101, v90, v91
	v_cvt_pk_bf16_f32 v102, v92, v93
	v_cvt_pk_bf16_f32 v103, v94, v95
	v_cvt_pk_bf16_f32 v104, v96, v97
	v_cvt_pk_bf16_f32 v105, v98, v99
	global_store_dwordx2 v2, v[100:101], s[6:7]
	global_store_dwordx2 v2, v[102:103], s[8:9]
	global_store_dwordx2 v2, v[104:105], s[10:11]
	s_add_u32 s6, s6, 0x1000
	s_addc_u32 s7, s7, 0
	s_add_u32 s8, s8, 0x1000
	s_addc_u32 s9, s9, 0
	s_add_u32 s10, s10, 0x1000
	s_addc_u32 s11, s11, 0
	s_waitcnt vmcnt(41)
	v_sub_f32_e32 v84, v20, v24
	v_sub_f32_e32 v85, v21, v25
	v_sub_f32_e32 v86, v22, v26
	v_sub_f32_e32 v87, v23, v27
	v_pk_fma_f32 v[88:89], v[84:85], v[4:5], v[24:25]
	v_pk_fma_f32 v[90:91], v[86:87], v[6:7], v[26:27]
	v_pk_fma_f32 v[92:93], v[84:85], v[8:9], v[24:25]
	v_pk_fma_f32 v[94:95], v[86:87], v[10:11], v[26:27]
	v_pk_fma_f32 v[96:97], v[84:85], v[12:13], v[24:25]
	v_pk_fma_f32 v[98:99], v[86:87], v[14:15], v[26:27]
	v_cvt_pk_bf16_f32 v106, v88, v89
	v_cvt_pk_bf16_f32 v107, v90, v91
	v_cvt_pk_bf16_f32 v108, v92, v93
	v_cvt_pk_bf16_f32 v109, v94, v95
	v_cvt_pk_bf16_f32 v110, v96, v97
	v_cvt_pk_bf16_f32 v111, v98, v99
	global_store_dwordx2 v2, v[106:107], s[6:7]
	global_store_dwordx2 v2, v[108:109], s[8:9]
	global_store_dwordx2 v2, v[110:111], s[10:11]
	s_add_u32 s6, s6, 0x1000
	s_addc_u32 s7, s7, 0
	s_add_u32 s8, s8, 0x1000
	s_addc_u32 s9, s9, 0
	s_add_u32 s10, s10, 0x1000
	s_addc_u32 s11, s11, 0
	s_waitcnt vmcnt(43)
	v_sub_f32_e32 v84, v24, v28
	v_sub_f32_e32 v85, v25, v29
	v_sub_f32_e32 v86, v26, v30
	v_sub_f32_e32 v87, v27, v31
	v_pk_fma_f32 v[88:89], v[84:85], v[4:5], v[28:29]
	v_pk_fma_f32 v[90:91], v[86:87], v[6:7], v[30:31]
	v_pk_fma_f32 v[92:93], v[84:85], v[8:9], v[28:29]
	v_pk_fma_f32 v[94:95], v[86:87], v[10:11], v[30:31]
	v_pk_fma_f32 v[96:97], v[84:85], v[12:13], v[28:29]
	v_pk_fma_f32 v[98:99], v[86:87], v[14:15], v[30:31]
	v_cvt_pk_bf16_f32 v100, v88, v89
	v_cvt_pk_bf16_f32 v101, v90, v91
	v_cvt_pk_bf16_f32 v102, v92, v93
	v_cvt_pk_bf16_f32 v103, v94, v95
	v_cvt_pk_bf16_f32 v104, v96, v97
	v_cvt_pk_bf16_f32 v105, v98, v99
	global_store_dwordx2 v2, v[100:101], s[6:7]
	global_store_dwordx2 v2, v[102:103], s[8:9]
	global_store_dwordx2 v2, v[104:105], s[10:11]
	s_add_u32 s6, s6, 0x1000
	s_addc_u32 s7, s7, 0
	s_add_u32 s8, s8, 0x1000
	s_addc_u32 s9, s9, 0
	s_add_u32 s10, s10, 0x1000
	s_addc_u32 s11, s11, 0
	s_waitcnt vmcnt(45)
	v_sub_f32_e32 v84, v28, v32
	v_sub_f32_e32 v85, v29, v33
	v_sub_f32_e32 v86, v30, v34
	v_sub_f32_e32 v87, v31, v35
	v_pk_fma_f32 v[88:89], v[84:85], v[4:5], v[32:33]
	v_pk_fma_f32 v[90:91], v[86:87], v[6:7], v[34:35]
	v_pk_fma_f32 v[92:93], v[84:85], v[8:9], v[32:33]
	v_pk_fma_f32 v[94:95], v[86:87], v[10:11], v[34:35]
	v_pk_fma_f32 v[96:97], v[84:85], v[12:13], v[32:33]
	v_pk_fma_f32 v[98:99], v[86:87], v[14:15], v[34:35]
	v_cvt_pk_bf16_f32 v106, v88, v89
	v_cvt_pk_bf16_f32 v107, v90, v91
	v_cvt_pk_bf16_f32 v108, v92, v93
	v_cvt_pk_bf16_f32 v109, v94, v95
	v_cvt_pk_bf16_f32 v110, v96, v97
	v_cvt_pk_bf16_f32 v111, v98, v99
	global_store_dwordx2 v2, v[106:107], s[6:7]
	global_store_dwordx2 v2, v[108:109], s[8:9]
	global_store_dwordx2 v2, v[110:111], s[10:11]
	s_add_u32 s6, s6, 0x1000
	s_addc_u32 s7, s7, 0
	s_add_u32 s8, s8, 0x1000
	s_addc_u32 s9, s9, 0
	s_add_u32 s10, s10, 0x1000
	s_addc_u32 s11, s11, 0
	s_waitcnt vmcnt(47)
	v_sub_f32_e32 v84, v32, v36
	v_sub_f32_e32 v85, v33, v37
	v_sub_f32_e32 v86, v34, v38
	v_sub_f32_e32 v87, v35, v39
	v_pk_fma_f32 v[88:89], v[84:85], v[4:5], v[36:37]
	v_pk_fma_f32 v[90:91], v[86:87], v[6:7], v[38:39]
	v_pk_fma_f32 v[92:93], v[84:85], v[8:9], v[36:37]
	v_pk_fma_f32 v[94:95], v[86:87], v[10:11], v[38:39]
	v_pk_fma_f32 v[96:97], v[84:85], v[12:13], v[36:37]
	v_pk_fma_f32 v[98:99], v[86:87], v[14:15], v[38:39]
	v_cvt_pk_bf16_f32 v100, v88, v89
	v_cvt_pk_bf16_f32 v101, v90, v91
	v_cvt_pk_bf16_f32 v102, v92, v93
	v_cvt_pk_bf16_f32 v103, v94, v95
	v_cvt_pk_bf16_f32 v104, v96, v97
	v_cvt_pk_bf16_f32 v105, v98, v99
	global_store_dwordx2 v2, v[100:101], s[6:7]
	global_store_dwordx2 v2, v[102:103], s[8:9]
	global_store_dwordx2 v2, v[104:105], s[10:11]
	s_add_u32 s6, s6, 0x1000
	s_addc_u32 s7, s7, 0
	s_add_u32 s8, s8, 0x1000
	s_addc_u32 s9, s9, 0
	s_add_u32 s10, s10, 0x1000
	s_addc_u32 s11, s11, 0
	s_waitcnt vmcnt(49)
	v_sub_f32_e32 v84, v36, v40
	v_sub_f32_e32 v85, v37, v41
	v_sub_f32_e32 v86, v38, v42
	v_sub_f32_e32 v87, v39, v43
	v_pk_fma_f32 v[88:89], v[84:85], v[4:5], v[40:41]
	v_pk_fma_f32 v[90:91], v[86:87], v[6:7], v[42:43]
	v_pk_fma_f32 v[92:93], v[84:85], v[8:9], v[40:41]
	v_pk_fma_f32 v[94:95], v[86:87], v[10:11], v[42:43]
	v_pk_fma_f32 v[96:97], v[84:85], v[12:13], v[40:41]
	v_pk_fma_f32 v[98:99], v[86:87], v[14:15], v[42:43]
	v_cvt_pk_bf16_f32 v106, v88, v89
	v_cvt_pk_bf16_f32 v107, v90, v91
	v_cvt_pk_bf16_f32 v108, v92, v93
	v_cvt_pk_bf16_f32 v109, v94, v95
	v_cvt_pk_bf16_f32 v110, v96, v97
	v_cvt_pk_bf16_f32 v111, v98, v99
	global_store_dwordx2 v2, v[106:107], s[6:7]
	global_store_dwordx2 v2, v[108:109], s[8:9]
	global_store_dwordx2 v2, v[110:111], s[10:11]
	s_add_u32 s6, s6, 0x1000
	s_addc_u32 s7, s7, 0
	s_add_u32 s8, s8, 0x1000
	s_addc_u32 s9, s9, 0
	s_add_u32 s10, s10, 0x1000
	s_addc_u32 s11, s11, 0
	s_waitcnt vmcnt(51)
	v_sub_f32_e32 v84, v40, v44
	v_sub_f32_e32 v85, v41, v45
	v_sub_f32_e32 v86, v42, v46
	v_sub_f32_e32 v87, v43, v47
	v_pk_fma_f32 v[88:89], v[84:85], v[4:5], v[44:45]
	v_pk_fma_f32 v[90:91], v[86:87], v[6:7], v[46:47]
	v_pk_fma_f32 v[92:93], v[84:85], v[8:9], v[44:45]
	v_pk_fma_f32 v[94:95], v[86:87], v[10:11], v[46:47]
	v_pk_fma_f32 v[96:97], v[84:85], v[12:13], v[44:45]
	v_pk_fma_f32 v[98:99], v[86:87], v[14:15], v[46:47]
	v_cvt_pk_bf16_f32 v100, v88, v89
	v_cvt_pk_bf16_f32 v101, v90, v91
	v_cvt_pk_bf16_f32 v102, v92, v93
	v_cvt_pk_bf16_f32 v103, v94, v95
	v_cvt_pk_bf16_f32 v104, v96, v97
	v_cvt_pk_bf16_f32 v105, v98, v99
	global_store_dwordx2 v2, v[100:101], s[6:7]
	global_store_dwordx2 v2, v[102:103], s[8:9]
	global_store_dwordx2 v2, v[104:105], s[10:11]
	s_add_u32 s6, s6, 0x1000
	s_addc_u32 s7, s7, 0
	s_add_u32 s8, s8, 0x1000
	s_addc_u32 s9, s9, 0
	s_add_u32 s10, s10, 0x1000
	s_addc_u32 s11, s11, 0
	s_waitcnt vmcnt(53)
	v_sub_f32_e32 v84, v44, v48
	v_sub_f32_e32 v85, v45, v49
	v_sub_f32_e32 v86, v46, v50
	v_sub_f32_e32 v87, v47, v51
	v_pk_fma_f32 v[88:89], v[84:85], v[4:5], v[48:49]
	v_pk_fma_f32 v[90:91], v[86:87], v[6:7], v[50:51]
	v_pk_fma_f32 v[92:93], v[84:85], v[8:9], v[48:49]
	v_pk_fma_f32 v[94:95], v[86:87], v[10:11], v[50:51]
	v_pk_fma_f32 v[96:97], v[84:85], v[12:13], v[48:49]
	v_pk_fma_f32 v[98:99], v[86:87], v[14:15], v[50:51]
	v_cvt_pk_bf16_f32 v106, v88, v89
	v_cvt_pk_bf16_f32 v107, v90, v91
	v_cvt_pk_bf16_f32 v108, v92, v93
	v_cvt_pk_bf16_f32 v109, v94, v95
	v_cvt_pk_bf16_f32 v110, v96, v97
	v_cvt_pk_bf16_f32 v111, v98, v99
	global_store_dwordx2 v2, v[106:107], s[6:7]
	global_store_dwordx2 v2, v[108:109], s[8:9]
	global_store_dwordx2 v2, v[110:111], s[10:11]
	s_add_u32 s6, s6, 0x1000
	s_addc_u32 s7, s7, 0
	s_add_u32 s8, s8, 0x1000
	s_addc_u32 s9, s9, 0
	s_add_u32 s10, s10, 0x1000
	s_addc_u32 s11, s11, 0
	v_mov_b32_e32 v16, v48
	v_mov_b32_e32 v17, v49
	v_mov_b32_e32 v18, v50
	v_mov_b32_e32 v19, v51
	global_load_dwordx4 v[20:23], v1, s[4:5] nt
	s_add_u32 s4, s4, 0x2000
	s_addc_u32 s5, s5, 0
	global_load_dwordx4 v[24:27], v1, s[4:5] nt
	s_add_u32 s4, s4, 0x2000
	s_addc_u32 s5, s5, 0
	global_load_dwordx4 v[28:31], v1, s[4:5] nt
	s_add_u32 s4, s4, 0x2000
	s_addc_u32 s5, s5, 0
	global_load_dwordx4 v[32:35], v1, s[4:5] nt
	s_add_u32 s4, s4, 0x2000
	s_addc_u32 s5, s5, 0
	global_load_dwordx4 v[36:39], v1, s[4:5] nt
	s_add_u32 s4, s4, 0x2000
	s_addc_u32 s5, s5, 0
	global_load_dwordx4 v[40:43], v1, s[4:5] nt
	s_add_u32 s4, s4, 0x2000
	s_addc_u32 s5, s5, 0
	global_load_dwordx4 v[44:47], v1, s[4:5] nt
	s_add_u32 s4, s4, 0x2000
	s_addc_u32 s5, s5, 0
	global_load_dwordx4 v[48:51], v1, s[4:5] nt
	s_add_u32 s4, s4, 0x2000
	s_addc_u32 s5, s5, 0
	s_waitcnt vmcnt(39)
	v_sub_f32_e32 v84, v16, v52
	v_sub_f32_e32 v85, v17, v53
	v_sub_f32_e32 v86, v18, v54
	v_sub_f32_e32 v87, v19, v55
	v_pk_fma_f32 v[88:89], v[84:85], v[4:5], v[52:53]
	v_pk_fma_f32 v[90:91], v[86:87], v[6:7], v[54:55]
	v_pk_fma_f32 v[92:93], v[84:85], v[8:9], v[52:53]
	v_pk_fma_f32 v[94:95], v[86:87], v[10:11], v[54:55]
	v_pk_fma_f32 v[96:97], v[84:85], v[12:13], v[52:53]
	v_pk_fma_f32 v[98:99], v[86:87], v[14:15], v[54:55]
	v_cvt_pk_bf16_f32 v100, v88, v89
	v_cvt_pk_bf16_f32 v101, v90, v91
	v_cvt_pk_bf16_f32 v102, v92, v93
	v_cvt_pk_bf16_f32 v103, v94, v95
	v_cvt_pk_bf16_f32 v104, v96, v97
	v_cvt_pk_bf16_f32 v105, v98, v99
	global_store_dwordx2 v2, v[100:101], s[6:7]
	global_store_dwordx2 v2, v[102:103], s[8:9]
	global_store_dwordx2 v2, v[104:105], s[10:11]
	s_add_u32 s6, s6, 0x1000
	s_addc_u32 s7, s7, 0
	s_add_u32 s8, s8, 0x1000
	s_addc_u32 s9, s9, 0
	s_add_u32 s10, s10, 0x1000
	s_addc_u32 s11, s11, 0
	s_waitcnt vmcnt(41)
	v_sub_f32_e32 v84, v52, v56
	v_sub_f32_e32 v85, v53, v57
	v_sub_f32_e32 v86, v54, v58
	v_sub_f32_e32 v87, v55, v59
	v_pk_fma_f32 v[88:89], v[84:85], v[4:5], v[56:57]
	v_pk_fma_f32 v[90:91], v[86:87], v[6:7], v[58:59]
	v_pk_fma_f32 v[92:93], v[84:85], v[8:9], v[56:57]
	v_pk_fma_f32 v[94:95], v[86:87], v[10:11], v[58:59]
	v_pk_fma_f32 v[96:97], v[84:85], v[12:13], v[56:57]
	v_pk_fma_f32 v[98:99], v[86:87], v[14:15], v[58:59]
	v_cvt_pk_bf16_f32 v106, v88, v89
	v_cvt_pk_bf16_f32 v107, v90, v91
	v_cvt_pk_bf16_f32 v108, v92, v93
	v_cvt_pk_bf16_f32 v109, v94, v95
	v_cvt_pk_bf16_f32 v110, v96, v97
	v_cvt_pk_bf16_f32 v111, v98, v99
	global_store_dwordx2 v2, v[106:107], s[6:7]
	global_store_dwordx2 v2, v[108:109], s[8:9]
	global_store_dwordx2 v2, v[110:111], s[10:11]
	s_add_u32 s6, s6, 0x1000
	s_addc_u32 s7, s7, 0
	s_add_u32 s8, s8, 0x1000
	s_addc_u32 s9, s9, 0
	s_add_u32 s10, s10, 0x1000
	s_addc_u32 s11, s11, 0
	s_waitcnt vmcnt(43)
	v_sub_f32_e32 v84, v56, v60
	v_sub_f32_e32 v85, v57, v61
	v_sub_f32_e32 v86, v58, v62
	v_sub_f32_e32 v87, v59, v63
	v_pk_fma_f32 v[88:89], v[84:85], v[4:5], v[60:61]
	v_pk_fma_f32 v[90:91], v[86:87], v[6:7], v[62:63]
	v_pk_fma_f32 v[92:93], v[84:85], v[8:9], v[60:61]
	v_pk_fma_f32 v[94:95], v[86:87], v[10:11], v[62:63]
	v_pk_fma_f32 v[96:97], v[84:85], v[12:13], v[60:61]
	v_pk_fma_f32 v[98:99], v[86:87], v[14:15], v[62:63]
	v_cvt_pk_bf16_f32 v100, v88, v89
	v_cvt_pk_bf16_f32 v101, v90, v91
	v_cvt_pk_bf16_f32 v102, v92, v93
	v_cvt_pk_bf16_f32 v103, v94, v95
	v_cvt_pk_bf16_f32 v104, v96, v97
	v_cvt_pk_bf16_f32 v105, v98, v99
	global_store_dwordx2 v2, v[100:101], s[6:7]
	global_store_dwordx2 v2, v[102:103], s[8:9]
	global_store_dwordx2 v2, v[104:105], s[10:11]
	s_add_u32 s6, s6, 0x1000
	s_addc_u32 s7, s7, 0
	s_add_u32 s8, s8, 0x1000
	s_addc_u32 s9, s9, 0
	s_add_u32 s10, s10, 0x1000
	s_addc_u32 s11, s11, 0
	s_waitcnt vmcnt(45)
	v_sub_f32_e32 v84, v60, v64
	v_sub_f32_e32 v85, v61, v65
	v_sub_f32_e32 v86, v62, v66
	v_sub_f32_e32 v87, v63, v67
	v_pk_fma_f32 v[88:89], v[84:85], v[4:5], v[64:65]
	v_pk_fma_f32 v[90:91], v[86:87], v[6:7], v[66:67]
	v_pk_fma_f32 v[92:93], v[84:85], v[8:9], v[64:65]
	v_pk_fma_f32 v[94:95], v[86:87], v[10:11], v[66:67]
	v_pk_fma_f32 v[96:97], v[84:85], v[12:13], v[64:65]
	v_pk_fma_f32 v[98:99], v[86:87], v[14:15], v[66:67]
	v_cvt_pk_bf16_f32 v106, v88, v89
	v_cvt_pk_bf16_f32 v107, v90, v91
	v_cvt_pk_bf16_f32 v108, v92, v93
	v_cvt_pk_bf16_f32 v109, v94, v95
	v_cvt_pk_bf16_f32 v110, v96, v97
	v_cvt_pk_bf16_f32 v111, v98, v99
	global_store_dwordx2 v2, v[106:107], s[6:7]
	global_store_dwordx2 v2, v[108:109], s[8:9]
	global_store_dwordx2 v2, v[110:111], s[10:11]
	s_add_u32 s6, s6, 0x1000
	s_addc_u32 s7, s7, 0
	s_add_u32 s8, s8, 0x1000
	s_addc_u32 s9, s9, 0
	s_add_u32 s10, s10, 0x1000
	s_addc_u32 s11, s11, 0
	s_waitcnt vmcnt(47)
	v_sub_f32_e32 v84, v64, v68
	v_sub_f32_e32 v85, v65, v69
	v_sub_f32_e32 v86, v66, v70
	v_sub_f32_e32 v87, v67, v71
	v_pk_fma_f32 v[88:89], v[84:85], v[4:5], v[68:69]
	v_pk_fma_f32 v[90:91], v[86:87], v[6:7], v[70:71]
	v_pk_fma_f32 v[92:93], v[84:85], v[8:9], v[68:69]
	v_pk_fma_f32 v[94:95], v[86:87], v[10:11], v[70:71]
	v_pk_fma_f32 v[96:97], v[84:85], v[12:13], v[68:69]
	v_pk_fma_f32 v[98:99], v[86:87], v[14:15], v[70:71]
	v_cvt_pk_bf16_f32 v100, v88, v89
	v_cvt_pk_bf16_f32 v101, v90, v91
	v_cvt_pk_bf16_f32 v102, v92, v93
	v_cvt_pk_bf16_f32 v103, v94, v95
	v_cvt_pk_bf16_f32 v104, v96, v97
	v_cvt_pk_bf16_f32 v105, v98, v99
	global_store_dwordx2 v2, v[100:101], s[6:7]
	global_store_dwordx2 v2, v[102:103], s[8:9]
	global_store_dwordx2 v2, v[104:105], s[10:11]
	s_add_u32 s6, s6, 0x1000
	s_addc_u32 s7, s7, 0
	s_add_u32 s8, s8, 0x1000
	s_addc_u32 s9, s9, 0
	s_add_u32 s10, s10, 0x1000
	s_addc_u32 s11, s11, 0
	s_waitcnt vmcnt(49)
	v_sub_f32_e32 v84, v68, v72
	v_sub_f32_e32 v85, v69, v73
	v_sub_f32_e32 v86, v70, v74
	v_sub_f32_e32 v87, v71, v75
	v_pk_fma_f32 v[88:89], v[84:85], v[4:5], v[72:73]
	v_pk_fma_f32 v[90:91], v[86:87], v[6:7], v[74:75]
	v_pk_fma_f32 v[92:93], v[84:85], v[8:9], v[72:73]
	v_pk_fma_f32 v[94:95], v[86:87], v[10:11], v[74:75]
	v_pk_fma_f32 v[96:97], v[84:85], v[12:13], v[72:73]
	v_pk_fma_f32 v[98:99], v[86:87], v[14:15], v[74:75]
	v_cvt_pk_bf16_f32 v106, v88, v89
	v_cvt_pk_bf16_f32 v107, v90, v91
	v_cvt_pk_bf16_f32 v108, v92, v93
	v_cvt_pk_bf16_f32 v109, v94, v95
	v_cvt_pk_bf16_f32 v110, v96, v97
	v_cvt_pk_bf16_f32 v111, v98, v99
	global_store_dwordx2 v2, v[106:107], s[6:7]
	global_store_dwordx2 v2, v[108:109], s[8:9]
	global_store_dwordx2 v2, v[110:111], s[10:11]
	s_add_u32 s6, s6, 0x1000
	s_addc_u32 s7, s7, 0
	s_add_u32 s8, s8, 0x1000
	s_addc_u32 s9, s9, 0
	s_add_u32 s10, s10, 0x1000
	s_addc_u32 s11, s11, 0
	s_waitcnt vmcnt(51)
	v_sub_f32_e32 v84, v72, v76
	v_sub_f32_e32 v85, v73, v77
	v_sub_f32_e32 v86, v74, v78
	v_sub_f32_e32 v87, v75, v79
	v_pk_fma_f32 v[88:89], v[84:85], v[4:5], v[76:77]
	v_pk_fma_f32 v[90:91], v[86:87], v[6:7], v[78:79]
	v_pk_fma_f32 v[92:93], v[84:85], v[8:9], v[76:77]
	v_pk_fma_f32 v[94:95], v[86:87], v[10:11], v[78:79]
	v_pk_fma_f32 v[96:97], v[84:85], v[12:13], v[76:77]
	v_pk_fma_f32 v[98:99], v[86:87], v[14:15], v[78:79]
	v_cvt_pk_bf16_f32 v100, v88, v89
	v_cvt_pk_bf16_f32 v101, v90, v91
	v_cvt_pk_bf16_f32 v102, v92, v93
	v_cvt_pk_bf16_f32 v103, v94, v95
	v_cvt_pk_bf16_f32 v104, v96, v97
	v_cvt_pk_bf16_f32 v105, v98, v99
	global_store_dwordx2 v2, v[100:101], s[6:7]
	global_store_dwordx2 v2, v[102:103], s[8:9]
	global_store_dwordx2 v2, v[104:105], s[10:11]
	s_add_u32 s6, s6, 0x1000
	s_addc_u32 s7, s7, 0
	s_add_u32 s8, s8, 0x1000
	s_addc_u32 s9, s9, 0
	s_add_u32 s10, s10, 0x1000
	s_addc_u32 s11, s11, 0
	s_waitcnt vmcnt(53)
	v_sub_f32_e32 v84, v76, v80
	v_sub_f32_e32 v85, v77, v81
	v_sub_f32_e32 v86, v78, v82
	v_sub_f32_e32 v87, v79, v83
	v_pk_fma_f32 v[88:89], v[84:85], v[4:5], v[80:81]
	v_pk_fma_f32 v[90:91], v[86:87], v[6:7], v[82:83]
	v_pk_fma_f32 v[92:93], v[84:85], v[8:9], v[80:81]
	v_pk_fma_f32 v[94:95], v[86:87], v[10:11], v[82:83]
	v_pk_fma_f32 v[96:97], v[84:85], v[12:13], v[80:81]
	v_pk_fma_f32 v[98:99], v[86:87], v[14:15], v[82:83]
	v_cvt_pk_bf16_f32 v106, v88, v89
	v_cvt_pk_bf16_f32 v107, v90, v91
	v_cvt_pk_bf16_f32 v108, v92, v93
	v_cvt_pk_bf16_f32 v109, v94, v95
	v_cvt_pk_bf16_f32 v110, v96, v97
	v_cvt_pk_bf16_f32 v111, v98, v99
	global_store_dwordx2 v2, v[106:107], s[6:7]
	global_store_dwordx2 v2, v[108:109], s[8:9]
	global_store_dwordx2 v2, v[110:111], s[10:11]
	s_add_u32 s6, s6, 0x1000
	s_addc_u32 s7, s7, 0
	s_add_u32 s8, s8, 0x1000
	s_addc_u32 s9, s9, 0
	s_add_u32 s10, s10, 0x1000
	s_addc_u32 s11, s11, 0
	v_mov_b32_e32 v16, v80
	v_mov_b32_e32 v17, v81
	v_mov_b32_e32 v18, v82
	v_mov_b32_e32 v19, v83
	global_load_dwordx4 v[52:55], v1, s[4:5] nt
	s_add_u32 s4, s4, 0x2000
	s_addc_u32 s5, s5, 0
	global_load_dwordx4 v[56:59], v1, s[4:5] nt
	s_add_u32 s4, s4, 0x2000
	s_addc_u32 s5, s5, 0
	global_load_dwordx4 v[60:63], v1, s[4:5] nt
	s_add_u32 s4, s4, 0x2000
	s_addc_u32 s5, s5, 0
	global_load_dwordx4 v[64:67], v1, s[4:5] nt
	s_add_u32 s4, s4, 0x2000
	s_addc_u32 s5, s5, 0
	global_load_dwordx4 v[68:71], v1, s[4:5] nt
	s_add_u32 s4, s4, 0x2000
	s_addc_u32 s5, s5, 0
	global_load_dwordx4 v[72:75], v1, s[4:5] nt
	s_add_u32 s4, s4, 0x2000
	s_addc_u32 s5, s5, 0
	global_load_dwordx4 v[76:79], v1, s[4:5] nt
	s_add_u32 s4, s4, 0x2000
	s_addc_u32 s5, s5, 0
	global_load_dwordx4 v[80:83], v1, s[4:5] nt
	s_add_u32 s4, s4, 0x2000
	s_addc_u32 s5, s5, 0
	s_waitcnt vmcnt(39)
	v_sub_f32_e32 v84, v16, v20
	v_sub_f32_e32 v85, v17, v21
	v_sub_f32_e32 v86, v18, v22
	v_sub_f32_e32 v87, v19, v23
	v_pk_fma_f32 v[88:89], v[84:85], v[4:5], v[20:21]
	v_pk_fma_f32 v[90:91], v[86:87], v[6:7], v[22:23]
	v_pk_fma_f32 v[92:93], v[84:85], v[8:9], v[20:21]
	v_pk_fma_f32 v[94:95], v[86:87], v[10:11], v[22:23]
	v_pk_fma_f32 v[96:97], v[84:85], v[12:13], v[20:21]
	v_pk_fma_f32 v[98:99], v[86:87], v[14:15], v[22:23]
	v_cvt_pk_bf16_f32 v100, v88, v89
	v_cvt_pk_bf16_f32 v101, v90, v91
	v_cvt_pk_bf16_f32 v102, v92, v93
	v_cvt_pk_bf16_f32 v103, v94, v95
	v_cvt_pk_bf16_f32 v104, v96, v97
	v_cvt_pk_bf16_f32 v105, v98, v99
	global_store_dwordx2 v2, v[100:101], s[6:7]
	global_store_dwordx2 v2, v[102:103], s[8:9]
	global_store_dwordx2 v2, v[104:105], s[10:11]
	s_add_u32 s6, s6, 0x1000
	s_addc_u32 s7, s7, 0
	s_add_u32 s8, s8, 0x1000
	s_addc_u32 s9, s9, 0
	s_add_u32 s10, s10, 0x1000
	s_addc_u32 s11, s11, 0
	s_waitcnt vmcnt(41)
	v_sub_f32_e32 v84, v20, v24
	v_sub_f32_e32 v85, v21, v25
	v_sub_f32_e32 v86, v22, v26
	v_sub_f32_e32 v87, v23, v27
	v_pk_fma_f32 v[88:89], v[84:85], v[4:5], v[24:25]
	v_pk_fma_f32 v[90:91], v[86:87], v[6:7], v[26:27]
	v_pk_fma_f32 v[92:93], v[84:85], v[8:9], v[24:25]
	v_pk_fma_f32 v[94:95], v[86:87], v[10:11], v[26:27]
	v_pk_fma_f32 v[96:97], v[84:85], v[12:13], v[24:25]
	v_pk_fma_f32 v[98:99], v[86:87], v[14:15], v[26:27]
	v_cvt_pk_bf16_f32 v106, v88, v89
	v_cvt_pk_bf16_f32 v107, v90, v91
	v_cvt_pk_bf16_f32 v108, v92, v93
	v_cvt_pk_bf16_f32 v109, v94, v95
	v_cvt_pk_bf16_f32 v110, v96, v97
	v_cvt_pk_bf16_f32 v111, v98, v99
	global_store_dwordx2 v2, v[106:107], s[6:7]
	global_store_dwordx2 v2, v[108:109], s[8:9]
	global_store_dwordx2 v2, v[110:111], s[10:11]
	s_add_u32 s6, s6, 0x1000
	s_addc_u32 s7, s7, 0
	s_add_u32 s8, s8, 0x1000
	s_addc_u32 s9, s9, 0
	s_add_u32 s10, s10, 0x1000
	s_addc_u32 s11, s11, 0
	s_waitcnt vmcnt(43)
	v_sub_f32_e32 v84, v24, v28
	v_sub_f32_e32 v85, v25, v29
	v_sub_f32_e32 v86, v26, v30
	v_sub_f32_e32 v87, v27, v31
	v_pk_fma_f32 v[88:89], v[84:85], v[4:5], v[28:29]
	v_pk_fma_f32 v[90:91], v[86:87], v[6:7], v[30:31]
	v_pk_fma_f32 v[92:93], v[84:85], v[8:9], v[28:29]
	v_pk_fma_f32 v[94:95], v[86:87], v[10:11], v[30:31]
	v_pk_fma_f32 v[96:97], v[84:85], v[12:13], v[28:29]
	v_pk_fma_f32 v[98:99], v[86:87], v[14:15], v[30:31]
	v_cvt_pk_bf16_f32 v100, v88, v89
	v_cvt_pk_bf16_f32 v101, v90, v91
	v_cvt_pk_bf16_f32 v102, v92, v93
	v_cvt_pk_bf16_f32 v103, v94, v95
	v_cvt_pk_bf16_f32 v104, v96, v97
	v_cvt_pk_bf16_f32 v105, v98, v99
	global_store_dwordx2 v2, v[100:101], s[6:7]
	global_store_dwordx2 v2, v[102:103], s[8:9]
	global_store_dwordx2 v2, v[104:105], s[10:11]
	s_add_u32 s6, s6, 0x1000
	s_addc_u32 s7, s7, 0
	s_add_u32 s8, s8, 0x1000
	s_addc_u32 s9, s9, 0
	s_add_u32 s10, s10, 0x1000
	s_addc_u32 s11, s11, 0
	s_waitcnt vmcnt(45)
	v_sub_f32_e32 v84, v28, v32
	v_sub_f32_e32 v85, v29, v33
	v_sub_f32_e32 v86, v30, v34
	v_sub_f32_e32 v87, v31, v35
	v_pk_fma_f32 v[88:89], v[84:85], v[4:5], v[32:33]
	v_pk_fma_f32 v[90:91], v[86:87], v[6:7], v[34:35]
	v_pk_fma_f32 v[92:93], v[84:85], v[8:9], v[32:33]
	v_pk_fma_f32 v[94:95], v[86:87], v[10:11], v[34:35]
	v_pk_fma_f32 v[96:97], v[84:85], v[12:13], v[32:33]
	v_pk_fma_f32 v[98:99], v[86:87], v[14:15], v[34:35]
	v_cvt_pk_bf16_f32 v106, v88, v89
	v_cvt_pk_bf16_f32 v107, v90, v91
	v_cvt_pk_bf16_f32 v108, v92, v93
	v_cvt_pk_bf16_f32 v109, v94, v95
	v_cvt_pk_bf16_f32 v110, v96, v97
	v_cvt_pk_bf16_f32 v111, v98, v99
	global_store_dwordx2 v2, v[106:107], s[6:7]
	global_store_dwordx2 v2, v[108:109], s[8:9]
	global_store_dwordx2 v2, v[110:111], s[10:11]
	s_add_u32 s6, s6, 0x1000
	s_addc_u32 s7, s7, 0
	s_add_u32 s8, s8, 0x1000
	s_addc_u32 s9, s9, 0
	s_add_u32 s10, s10, 0x1000
	s_addc_u32 s11, s11, 0
	s_waitcnt vmcnt(47)
	v_sub_f32_e32 v84, v32, v36
	v_sub_f32_e32 v85, v33, v37
	v_sub_f32_e32 v86, v34, v38
	v_sub_f32_e32 v87, v35, v39
	v_pk_fma_f32 v[88:89], v[84:85], v[4:5], v[36:37]
	v_pk_fma_f32 v[90:91], v[86:87], v[6:7], v[38:39]
	v_pk_fma_f32 v[92:93], v[84:85], v[8:9], v[36:37]
	v_pk_fma_f32 v[94:95], v[86:87], v[10:11], v[38:39]
	v_pk_fma_f32 v[96:97], v[84:85], v[12:13], v[36:37]
	v_pk_fma_f32 v[98:99], v[86:87], v[14:15], v[38:39]
	v_cvt_pk_bf16_f32 v100, v88, v89
	v_cvt_pk_bf16_f32 v101, v90, v91
	v_cvt_pk_bf16_f32 v102, v92, v93
	v_cvt_pk_bf16_f32 v103, v94, v95
	v_cvt_pk_bf16_f32 v104, v96, v97
	v_cvt_pk_bf16_f32 v105, v98, v99
	global_store_dwordx2 v2, v[100:101], s[6:7]
	global_store_dwordx2 v2, v[102:103], s[8:9]
	global_store_dwordx2 v2, v[104:105], s[10:11]
	s_add_u32 s6, s6, 0x1000
	s_addc_u32 s7, s7, 0
	s_add_u32 s8, s8, 0x1000
	s_addc_u32 s9, s9, 0
	s_add_u32 s10, s10, 0x1000
	s_addc_u32 s11, s11, 0
	s_waitcnt vmcnt(49)
	v_sub_f32_e32 v84, v36, v40
	v_sub_f32_e32 v85, v37, v41
	v_sub_f32_e32 v86, v38, v42
	v_sub_f32_e32 v87, v39, v43
	v_pk_fma_f32 v[88:89], v[84:85], v[4:5], v[40:41]
	v_pk_fma_f32 v[90:91], v[86:87], v[6:7], v[42:43]
	v_pk_fma_f32 v[92:93], v[84:85], v[8:9], v[40:41]
	v_pk_fma_f32 v[94:95], v[86:87], v[10:11], v[42:43]
	v_pk_fma_f32 v[96:97], v[84:85], v[12:13], v[40:41]
	v_pk_fma_f32 v[98:99], v[86:87], v[14:15], v[42:43]
	v_cvt_pk_bf16_f32 v106, v88, v89
	v_cvt_pk_bf16_f32 v107, v90, v91
	v_cvt_pk_bf16_f32 v108, v92, v93
	v_cvt_pk_bf16_f32 v109, v94, v95
	v_cvt_pk_bf16_f32 v110, v96, v97
	v_cvt_pk_bf16_f32 v111, v98, v99
	global_store_dwordx2 v2, v[106:107], s[6:7]
	global_store_dwordx2 v2, v[108:109], s[8:9]
	global_store_dwordx2 v2, v[110:111], s[10:11]
	s_add_u32 s6, s6, 0x1000
	s_addc_u32 s7, s7, 0
	s_add_u32 s8, s8, 0x1000
	s_addc_u32 s9, s9, 0
	s_add_u32 s10, s10, 0x1000
	s_addc_u32 s11, s11, 0
	s_waitcnt vmcnt(51)
	v_sub_f32_e32 v84, v40, v44
	v_sub_f32_e32 v85, v41, v45
	v_sub_f32_e32 v86, v42, v46
	v_sub_f32_e32 v87, v43, v47
	v_pk_fma_f32 v[88:89], v[84:85], v[4:5], v[44:45]
	v_pk_fma_f32 v[90:91], v[86:87], v[6:7], v[46:47]
	v_pk_fma_f32 v[92:93], v[84:85], v[8:9], v[44:45]
	v_pk_fma_f32 v[94:95], v[86:87], v[10:11], v[46:47]
	v_pk_fma_f32 v[96:97], v[84:85], v[12:13], v[44:45]
	v_pk_fma_f32 v[98:99], v[86:87], v[14:15], v[46:47]
	v_cvt_pk_bf16_f32 v100, v88, v89
	v_cvt_pk_bf16_f32 v101, v90, v91
	v_cvt_pk_bf16_f32 v102, v92, v93
	v_cvt_pk_bf16_f32 v103, v94, v95
	v_cvt_pk_bf16_f32 v104, v96, v97
	v_cvt_pk_bf16_f32 v105, v98, v99
	global_store_dwordx2 v2, v[100:101], s[6:7]
	global_store_dwordx2 v2, v[102:103], s[8:9]
	global_store_dwordx2 v2, v[104:105], s[10:11]
	s_add_u32 s6, s6, 0x1000
	s_addc_u32 s7, s7, 0
	s_add_u32 s8, s8, 0x1000
	s_addc_u32 s9, s9, 0
	s_add_u32 s10, s10, 0x1000
	s_addc_u32 s11, s11, 0
	s_waitcnt vmcnt(53)
	v_sub_f32_e32 v84, v44, v48
	v_sub_f32_e32 v85, v45, v49
	v_sub_f32_e32 v86, v46, v50
	v_sub_f32_e32 v87, v47, v51
	v_pk_fma_f32 v[88:89], v[84:85], v[4:5], v[48:49]
	v_pk_fma_f32 v[90:91], v[86:87], v[6:7], v[50:51]
	v_pk_fma_f32 v[92:93], v[84:85], v[8:9], v[48:49]
	v_pk_fma_f32 v[94:95], v[86:87], v[10:11], v[50:51]
	v_pk_fma_f32 v[96:97], v[84:85], v[12:13], v[48:49]
	v_pk_fma_f32 v[98:99], v[86:87], v[14:15], v[50:51]
	v_cvt_pk_bf16_f32 v106, v88, v89
	v_cvt_pk_bf16_f32 v107, v90, v91
	v_cvt_pk_bf16_f32 v108, v92, v93
	v_cvt_pk_bf16_f32 v109, v94, v95
	v_cvt_pk_bf16_f32 v110, v96, v97
	v_cvt_pk_bf16_f32 v111, v98, v99
	global_store_dwordx2 v2, v[106:107], s[6:7]
	global_store_dwordx2 v2, v[108:109], s[8:9]
	global_store_dwordx2 v2, v[110:111], s[10:11]
	s_add_u32 s6, s6, 0x1000
	s_addc_u32 s7, s7, 0
	s_add_u32 s8, s8, 0x1000
	s_addc_u32 s9, s9, 0
	s_add_u32 s10, s10, 0x1000
	s_addc_u32 s11, s11, 0
	v_mov_b32_e32 v16, v48
	v_mov_b32_e32 v17, v49
	v_mov_b32_e32 v18, v50
	v_mov_b32_e32 v19, v51
	s_waitcnt vmcnt(31)
	v_sub_f32_e32 v84, v16, v52
	v_sub_f32_e32 v85, v17, v53
	v_sub_f32_e32 v86, v18, v54
	v_sub_f32_e32 v87, v19, v55
	v_pk_fma_f32 v[88:89], v[84:85], v[4:5], v[52:53]
	v_pk_fma_f32 v[90:91], v[86:87], v[6:7], v[54:55]
	v_pk_fma_f32 v[92:93], v[84:85], v[8:9], v[52:53]
	v_pk_fma_f32 v[94:95], v[86:87], v[10:11], v[54:55]
	v_pk_fma_f32 v[96:97], v[84:85], v[12:13], v[52:53]
	v_pk_fma_f32 v[98:99], v[86:87], v[14:15], v[54:55]
	v_cvt_pk_bf16_f32 v100, v88, v89
	v_cvt_pk_bf16_f32 v101, v90, v91
	v_cvt_pk_bf16_f32 v102, v92, v93
	v_cvt_pk_bf16_f32 v103, v94, v95
	v_cvt_pk_bf16_f32 v104, v96, v97
	v_cvt_pk_bf16_f32 v105, v98, v99
	global_store_dwordx2 v2, v[100:101], s[6:7]
	global_store_dwordx2 v2, v[102:103], s[8:9]
	global_store_dwordx2 v2, v[104:105], s[10:11]
	s_add_u32 s6, s6, 0x1000
	s_addc_u32 s7, s7, 0
	s_add_u32 s8, s8, 0x1000
	s_addc_u32 s9, s9, 0
	s_add_u32 s10, s10, 0x1000
	s_addc_u32 s11, s11, 0
	s_waitcnt vmcnt(33)
	v_sub_f32_e32 v84, v52, v56
	v_sub_f32_e32 v85, v53, v57
	v_sub_f32_e32 v86, v54, v58
	v_sub_f32_e32 v87, v55, v59
	v_pk_fma_f32 v[88:89], v[84:85], v[4:5], v[56:57]
	v_pk_fma_f32 v[90:91], v[86:87], v[6:7], v[58:59]
	v_pk_fma_f32 v[92:93], v[84:85], v[8:9], v[56:57]
	v_pk_fma_f32 v[94:95], v[86:87], v[10:11], v[58:59]
	v_pk_fma_f32 v[96:97], v[84:85], v[12:13], v[56:57]
	v_pk_fma_f32 v[98:99], v[86:87], v[14:15], v[58:59]
	v_cvt_pk_bf16_f32 v106, v88, v89
	v_cvt_pk_bf16_f32 v107, v90, v91
	v_cvt_pk_bf16_f32 v108, v92, v93
	v_cvt_pk_bf16_f32 v109, v94, v95
	v_cvt_pk_bf16_f32 v110, v96, v97
	v_cvt_pk_bf16_f32 v111, v98, v99
	global_store_dwordx2 v2, v[106:107], s[6:7]
	global_store_dwordx2 v2, v[108:109], s[8:9]
	global_store_dwordx2 v2, v[110:111], s[10:11]
	s_add_u32 s6, s6, 0x1000
	s_addc_u32 s7, s7, 0
	s_add_u32 s8, s8, 0x1000
	s_addc_u32 s9, s9, 0
	s_add_u32 s10, s10, 0x1000
	s_addc_u32 s11, s11, 0
	s_waitcnt vmcnt(35)
	v_sub_f32_e32 v84, v56, v60
	v_sub_f32_e32 v85, v57, v61
	v_sub_f32_e32 v86, v58, v62
	v_sub_f32_e32 v87, v59, v63
	v_pk_fma_f32 v[88:89], v[84:85], v[4:5], v[60:61]
	v_pk_fma_f32 v[90:91], v[86:87], v[6:7], v[62:63]
	v_pk_fma_f32 v[92:93], v[84:85], v[8:9], v[60:61]
	v_pk_fma_f32 v[94:95], v[86:87], v[10:11], v[62:63]
	v_pk_fma_f32 v[96:97], v[84:85], v[12:13], v[60:61]
	v_pk_fma_f32 v[98:99], v[86:87], v[14:15], v[62:63]
	v_cvt_pk_bf16_f32 v100, v88, v89
	v_cvt_pk_bf16_f32 v101, v90, v91
	v_cvt_pk_bf16_f32 v102, v92, v93
	v_cvt_pk_bf16_f32 v103, v94, v95
	v_cvt_pk_bf16_f32 v104, v96, v97
	v_cvt_pk_bf16_f32 v105, v98, v99
	global_store_dwordx2 v2, v[100:101], s[6:7]
	global_store_dwordx2 v2, v[102:103], s[8:9]
	global_store_dwordx2 v2, v[104:105], s[10:11]
	s_add_u32 s6, s6, 0x1000
	s_addc_u32 s7, s7, 0
	s_add_u32 s8, s8, 0x1000
	s_addc_u32 s9, s9, 0
	s_add_u32 s10, s10, 0x1000
	s_addc_u32 s11, s11, 0
	s_waitcnt vmcnt(37)
	v_sub_f32_e32 v84, v60, v64
	v_sub_f32_e32 v85, v61, v65
	v_sub_f32_e32 v86, v62, v66
	v_sub_f32_e32 v87, v63, v67
	v_pk_fma_f32 v[88:89], v[84:85], v[4:5], v[64:65]
	v_pk_fma_f32 v[90:91], v[86:87], v[6:7], v[66:67]
	v_pk_fma_f32 v[92:93], v[84:85], v[8:9], v[64:65]
	v_pk_fma_f32 v[94:95], v[86:87], v[10:11], v[66:67]
	v_pk_fma_f32 v[96:97], v[84:85], v[12:13], v[64:65]
	v_pk_fma_f32 v[98:99], v[86:87], v[14:15], v[66:67]
	v_cvt_pk_bf16_f32 v106, v88, v89
	v_cvt_pk_bf16_f32 v107, v90, v91
	v_cvt_pk_bf16_f32 v108, v92, v93
	v_cvt_pk_bf16_f32 v109, v94, v95
	v_cvt_pk_bf16_f32 v110, v96, v97
	v_cvt_pk_bf16_f32 v111, v98, v99
	global_store_dwordx2 v2, v[106:107], s[6:7]
	global_store_dwordx2 v2, v[108:109], s[8:9]
	global_store_dwordx2 v2, v[110:111], s[10:11]
	s_add_u32 s6, s6, 0x1000
	s_addc_u32 s7, s7, 0
	s_add_u32 s8, s8, 0x1000
	s_addc_u32 s9, s9, 0
	s_add_u32 s10, s10, 0x1000
	s_addc_u32 s11, s11, 0
	s_waitcnt vmcnt(39)
	v_sub_f32_e32 v84, v64, v68
	v_sub_f32_e32 v85, v65, v69
	v_sub_f32_e32 v86, v66, v70
	v_sub_f32_e32 v87, v67, v71
	v_pk_fma_f32 v[88:89], v[84:85], v[4:5], v[68:69]
	v_pk_fma_f32 v[90:91], v[86:87], v[6:7], v[70:71]
	v_pk_fma_f32 v[92:93], v[84:85], v[8:9], v[68:69]
	v_pk_fma_f32 v[94:95], v[86:87], v[10:11], v[70:71]
	v_pk_fma_f32 v[96:97], v[84:85], v[12:13], v[68:69]
	v_pk_fma_f32 v[98:99], v[86:87], v[14:15], v[70:71]
	v_cvt_pk_bf16_f32 v100, v88, v89
	v_cvt_pk_bf16_f32 v101, v90, v91
	v_cvt_pk_bf16_f32 v102, v92, v93
	v_cvt_pk_bf16_f32 v103, v94, v95
	v_cvt_pk_bf16_f32 v104, v96, v97
	v_cvt_pk_bf16_f32 v105, v98, v99
	global_store_dwordx2 v2, v[100:101], s[6:7]
	global_store_dwordx2 v2, v[102:103], s[8:9]
	global_store_dwordx2 v2, v[104:105], s[10:11]
	s_add_u32 s6, s6, 0x1000
	s_addc_u32 s7, s7, 0
	s_add_u32 s8, s8, 0x1000
	s_addc_u32 s9, s9, 0
	s_add_u32 s10, s10, 0x1000
	s_addc_u32 s11, s11, 0
	s_waitcnt vmcnt(41)
	v_sub_f32_e32 v84, v68, v72
	v_sub_f32_e32 v85, v69, v73
	v_sub_f32_e32 v86, v70, v74
	v_sub_f32_e32 v87, v71, v75
	v_pk_fma_f32 v[88:89], v[84:85], v[4:5], v[72:73]
	v_pk_fma_f32 v[90:91], v[86:87], v[6:7], v[74:75]
	v_pk_fma_f32 v[92:93], v[84:85], v[8:9], v[72:73]
	v_pk_fma_f32 v[94:95], v[86:87], v[10:11], v[74:75]
	v_pk_fma_f32 v[96:97], v[84:85], v[12:13], v[72:73]
	v_pk_fma_f32 v[98:99], v[86:87], v[14:15], v[74:75]
	v_cvt_pk_bf16_f32 v106, v88, v89
	v_cvt_pk_bf16_f32 v107, v90, v91
	v_cvt_pk_bf16_f32 v108, v92, v93
	v_cvt_pk_bf16_f32 v109, v94, v95
	v_cvt_pk_bf16_f32 v110, v96, v97
	v_cvt_pk_bf16_f32 v111, v98, v99
	global_store_dwordx2 v2, v[106:107], s[6:7]
	global_store_dwordx2 v2, v[108:109], s[8:9]
	global_store_dwordx2 v2, v[110:111], s[10:11]
	s_add_u32 s6, s6, 0x1000
	s_addc_u32 s7, s7, 0
	s_add_u32 s8, s8, 0x1000
	s_addc_u32 s9, s9, 0
	s_add_u32 s10, s10, 0x1000
	s_addc_u32 s11, s11, 0
	s_waitcnt vmcnt(43)
	v_sub_f32_e32 v84, v72, v76
	v_sub_f32_e32 v85, v73, v77
	v_sub_f32_e32 v86, v74, v78
	v_sub_f32_e32 v87, v75, v79
	v_pk_fma_f32 v[88:89], v[84:85], v[4:5], v[76:77]
	v_pk_fma_f32 v[90:91], v[86:87], v[6:7], v[78:79]
	v_pk_fma_f32 v[92:93], v[84:85], v[8:9], v[76:77]
	v_pk_fma_f32 v[94:95], v[86:87], v[10:11], v[78:79]
	v_pk_fma_f32 v[96:97], v[84:85], v[12:13], v[76:77]
	v_pk_fma_f32 v[98:99], v[86:87], v[14:15], v[78:79]
	v_cvt_pk_bf16_f32 v100, v88, v89
	v_cvt_pk_bf16_f32 v101, v90, v91
	v_cvt_pk_bf16_f32 v102, v92, v93
	v_cvt_pk_bf16_f32 v103, v94, v95
	v_cvt_pk_bf16_f32 v104, v96, v97
	v_cvt_pk_bf16_f32 v105, v98, v99
	global_store_dwordx2 v2, v[100:101], s[6:7]
	global_store_dwordx2 v2, v[102:103], s[8:9]
	global_store_dwordx2 v2, v[104:105], s[10:11]
	s_add_u32 s6, s6, 0x1000
	s_addc_u32 s7, s7, 0
	s_add_u32 s8, s8, 0x1000
	s_addc_u32 s9, s9, 0
	s_add_u32 s10, s10, 0x1000
	s_addc_u32 s11, s11, 0
	s_waitcnt vmcnt(45)
	v_sub_f32_e32 v84, v76, v80
	v_sub_f32_e32 v85, v77, v81
	v_sub_f32_e32 v86, v78, v82
	v_sub_f32_e32 v87, v79, v83
	v_pk_fma_f32 v[88:89], v[84:85], v[4:5], v[80:81]
	v_pk_fma_f32 v[90:91], v[86:87], v[6:7], v[82:83]
	v_pk_fma_f32 v[92:93], v[84:85], v[8:9], v[80:81]
	v_pk_fma_f32 v[94:95], v[86:87], v[10:11], v[82:83]
	v_pk_fma_f32 v[96:97], v[84:85], v[12:13], v[80:81]
	v_pk_fma_f32 v[98:99], v[86:87], v[14:15], v[82:83]
	v_cvt_pk_bf16_f32 v106, v88, v89
	v_cvt_pk_bf16_f32 v107, v90, v91
	v_cvt_pk_bf16_f32 v108, v92, v93
	v_cvt_pk_bf16_f32 v109, v94, v95
	v_cvt_pk_bf16_f32 v110, v96, v97
	v_cvt_pk_bf16_f32 v111, v98, v99
	global_store_dwordx2 v2, v[106:107], s[6:7]
	global_store_dwordx2 v2, v[108:109], s[8:9]
	global_store_dwordx2 v2, v[110:111], s[10:11]
	s_add_u32 s6, s6, 0x1000
	s_addc_u32 s7, s7, 0
	s_add_u32 s8, s8, 0x1000
	s_addc_u32 s9, s9, 0
	s_add_u32 s10, s10, 0x1000
	s_addc_u32 s11, s11, 0
	v_mov_b32_e32 v16, v80
	v_mov_b32_e32 v17, v81
	v_mov_b32_e32 v18, v82
	v_mov_b32_e32 v19, v83
	s_branch .LBB0_230

.LBB0_639:
	s_and_b32 s20, s95, 1
	s_and_saveexec_b64 s[4:5], s[8:9]
	s_xor_b64 s[18:19], exec, s[4:5]
	s_cbranch_execz .LBB0_641
	s_mul_i32 s4, s20, 0xb400
	s_add_i32 s4, s4, 0
	v_add_u32_e32 v2, s4, v108
	v_lshl_add_u32 v104, v48, 2, s4
	v_lshl_add_u32 v105, s20, 12, v117
	ds_read_b128 v[134:137], v2 offset:256
	ds_read_b128 v[138:141], v2 offset:272
	ds_read_b128 v[142:145], v2 offset:512
	ds_read_b128 v[146:149], v2 offset:528
	ds_read_b128 v[150:153], v2 offset:768
	ds_read_b128 v[154:157], v2 offset:784
	ds_read_b32 v210, v104 offset:1280
	ds_read_b128 v[126:129], v2 offset:0
	ds_read_b128 v[130:133], v2 offset:16
	ds_read_b128 v[158:161], v2 offset:1024
	ds_read_b128 v[162:165], v2 offset:1040
	s_waitcnt lgkmcnt(9)
	v_pk_mul_f32 v[134:135], v[96:97], v[134:135]
	v_pk_mul_f32 v[138:139], v[100:101], v[138:139]
	v_pk_fma_f32 v[134:135], v[98:99], v[136:137], v[134:135]
	v_pk_fma_f32 v[138:139], v[102:103], v[140:141], v[138:139]
	s_nop 0
	v_pk_add_f32 v[134:135], v[134:135], v[138:139]
	s_nop 0
	v_add_f32_e32 v136, v134, v135
	ds_read_b128 v[174:177], v2 offset:1696
	s_nop 0
	v_add_f32_dpp v136, v136, v136 quad_perm:[1,0,3,2] row_mask:0xf bank_mask:0xf bound_ctrl:1
	ds_read_b128 v[178:181], v2 offset:1712
	ds_read_b128 v[182:185], v2 offset:1952
	v_add_f32_dpp v136, v136, v136 quad_perm:[2,3,0,1] row_mask:0xf bank_mask:0xf bound_ctrl:1
	ds_read_b128 v[186:189], v2 offset:1968
	ds_read_b128 v[192:195], v2 offset:2208
	v_add_f32_dpp v136, v136, v136 row_half_mirror row_mask:0xf bank_mask:0xf bound_ctrl:1
	s_waitcnt lgkmcnt(12)
	v_pk_mul_f32 v[142:143], v[142:143], v[136:137] op_sel_hi:[1,0]
	v_pk_mul_f32 v[144:145], v[144:145], v[136:137] op_sel_hi:[1,0]
	v_pk_mul_f32 v[146:147], v[146:147], v[136:137] op_sel_hi:[1,0]
	v_pk_mul_f32 v[148:149], v[148:149], v[136:137] op_sel_hi:[1,0]
	ds_read_b128 v[196:199], v2 offset:2224
	s_waitcnt lgkmcnt(10)
	v_pk_fma_f32 v[142:143], v[150:151], v[210:211], v[142:143] op_sel_hi:[1,0,1]
	v_pk_fma_f32 v[144:145], v[152:153], v[210:211], v[144:145] op_sel_hi:[1,0,1]
	v_pk_fma_f32 v[146:147], v[154:155], v[210:211], v[146:147] op_sel_hi:[1,0,1]
	v_pk_fma_f32 v[148:149], v[156:157], v[210:211], v[148:149] op_sel_hi:[1,0,1]
	ds_read_b32 v212, v104 offset:2720
	ds_read_b128 v[166:169], v2 offset:1440
	s_waitcnt lgkmcnt(10)
	v_pk_fma_f32 v[96:97], v[96:97], v[126:127], v[142:143]
	v_pk_fma_f32 v[98:99], v[98:99], v[128:129], v[144:145]
	v_pk_fma_f32 v[100:101], v[100:101], v[130:131], v[146:147]
	v_pk_fma_f32 v[102:103], v[102:103], v[132:133], v[148:149]
	ds_read_b128 v[170:173], v2 offset:1456
	ds_read_b128 v[200:203], v2 offset:2464
	ds_read_b128 v[204:207], v2 offset:2480
	s_waitcnt lgkmcnt(9)
	v_pk_mul_f32 v[174:175], v[96:97], v[174:175]
	v_pk_mul_f32 v[158:159], v[96:97], v[158:159]
	v_pk_mul_f32 v[178:179], v[100:101], v[178:179]
	v_pk_mul_f32 v[162:163], v[100:101], v[162:163]
	v_pk_fma_f32 v[174:175], v[98:99], v[176:177], v[174:175]
	v_pk_fma_f32 v[158:159], v[98:99], v[160:161], v[158:159]
	v_pk_fma_f32 v[178:179], v[102:103], v[180:181], v[178:179]
	v_pk_fma_f32 v[162:163], v[102:103], v[164:165], v[162:163]
	v_pk_add_f32 v[174:175], v[174:175], v[178:179]
	v_pk_add_f32 v[158:159], v[158:159], v[162:163]
	v_add_f32_e32 v176, v174, v175
	v_add_f32_e32 v211, v158, v159
	ds_read_b128 v[134:137], v2 offset:3136
	v_add_f32_dpp v176, v176, v176 quad_perm:[1,0,3,2] row_mask:0xf bank_mask:0xf bound_ctrl:1
	ds_read_b128 v[138:141], v2 offset:3152
	ds_read_b128 v[142:145], v2 offset:3392
	v_add_f32_dpp v176, v176, v176 quad_perm:[2,3,0,1] row_mask:0xf bank_mask:0xf bound_ctrl:1
	ds_read_b128 v[146:149], v2 offset:3408
	ds_read_b128 v[150:153], v2 offset:3648
	v_add_f32_dpp v176, v176, v176 row_half_mirror row_mask:0xf bank_mask:0xf bound_ctrl:1
	s_waitcnt lgkmcnt(12)
	v_pk_mul_f32 v[182:183], v[182:183], v[176:177] op_sel_hi:[1,0]
	v_pk_mul_f32 v[184:185], v[184:185], v[176:177] op_sel_hi:[1,0]
	v_pk_mul_f32 v[186:187], v[186:187], v[176:177] op_sel_hi:[1,0]
	v_pk_mul_f32 v[188:189], v[188:189], v[176:177] op_sel_hi:[1,0]
	ds_read_b128 v[154:157], v2 offset:3664
	s_waitcnt lgkmcnt(10)
	v_pk_fma_f32 v[182:183], v[192:193], v[212:213], v[182:183] op_sel_hi:[1,0,1]
	v_pk_fma_f32 v[184:185], v[194:195], v[212:213], v[184:185] op_sel_hi:[1,0,1]
	v_pk_fma_f32 v[186:187], v[196:197], v[212:213], v[186:187] op_sel_hi:[1,0,1]
	v_pk_fma_f32 v[188:189], v[198:199], v[212:213], v[188:189] op_sel_hi:[1,0,1]
	ds_read_b32 v210, v104 offset:4160
	ds_read_b128 v[126:129], v2 offset:2880
	s_waitcnt lgkmcnt(10)
	v_pk_fma_f32 v[96:97], v[96:97], v[166:167], v[182:183]
	v_pk_fma_f32 v[98:99], v[98:99], v[168:169], v[184:185]
	v_pk_fma_f32 v[100:101], v[100:101], v[170:171], v[186:187]
	v_pk_fma_f32 v[102:103], v[102:103], v[172:173], v[188:189]
	ds_read_b128 v[130:133], v2 offset:2896
	ds_read_b128 v[158:161], v2 offset:3904
	ds_read_b128 v[162:165], v2 offset:3920
	s_waitcnt lgkmcnt(9)
	v_pk_mul_f32 v[134:135], v[96:97], v[134:135]
	v_pk_mul_f32 v[200:201], v[96:97], v[200:201]
	v_pk_mul_f32 v[138:139], v[100:101], v[138:139]
	v_pk_mul_f32 v[204:205], v[100:101], v[204:205]
	v_pk_fma_f32 v[134:135], v[98:99], v[136:137], v[134:135]
	v_pk_fma_f32 v[200:201], v[98:99], v[202:203], v[200:201]
	v_pk_fma_f32 v[138:139], v[102:103], v[140:141], v[138:139]
	v_pk_fma_f32 v[204:205], v[102:103], v[206:207], v[204:205]
	v_pk_add_f32 v[134:135], v[134:135], v[138:139]
	v_pk_add_f32 v[200:201], v[200:201], v[204:205]
	v_add_f32_e32 v136, v134, v135
	v_add_f32_e32 v213, v200, v201
	ds_read_b128 v[174:177], v2 offset:4576
	v_add_f32_dpp v136, v136, v136 quad_perm:[1,0,3,2] row_mask:0xf bank_mask:0xf bound_ctrl:1
	ds_read_b128 v[178:181], v2 offset:4592
	ds_read_b128 v[182:185], v2 offset:4832
	v_add_f32_dpp v136, v136, v136 quad_perm:[2,3,0,1] row_mask:0xf bank_mask:0xf bound_ctrl:1
	ds_read_b128 v[186:189], v2 offset:4848
	ds_read_b128 v[192:195], v2 offset:5088
	v_add_f32_dpp v136, v136, v136 row_half_mirror row_mask:0xf bank_mask:0xf bound_ctrl:1
	s_waitcnt lgkmcnt(12)
	v_pk_mul_f32 v[142:143], v[142:143], v[136:137] op_sel_hi:[1,0]
	v_pk_mul_f32 v[144:145], v[144:145], v[136:137] op_sel_hi:[1,0]
	v_pk_mul_f32 v[146:147], v[146:147], v[136:137] op_sel_hi:[1,0]
	v_pk_mul_f32 v[148:149], v[148:149], v[136:137] op_sel_hi:[1,0]
	ds_read_b128 v[196:199], v2 offset:5104
	s_waitcnt lgkmcnt(10)
	v_pk_fma_f32 v[142:143], v[150:151], v[210:211], v[142:143] op_sel_hi:[1,0,1]
	v_pk_fma_f32 v[144:145], v[152:153], v[210:211], v[144:145] op_sel_hi:[1,0,1]
	v_pk_fma_f32 v[146:147], v[154:155], v[210:211], v[146:147] op_sel_hi:[1,0,1]
	v_pk_fma_f32 v[148:149], v[156:157], v[210:211], v[148:149] op_sel_hi:[1,0,1]
	ds_read_b32 v212, v104 offset:5600
	ds_read_b128 v[166:169], v2 offset:4320
	s_waitcnt lgkmcnt(10)
	v_pk_fma_f32 v[96:97], v[96:97], v[126:127], v[142:143]
	v_pk_fma_f32 v[98:99], v[98:99], v[128:129], v[144:145]
	v_pk_fma_f32 v[100:101], v[100:101], v[130:131], v[146:147]
	v_pk_fma_f32 v[102:103], v[102:103], v[132:133], v[148:149]
	ds_read_b128 v[170:173], v2 offset:4336
	ds_read_b128 v[200:203], v2 offset:5344
	ds_read_b128 v[204:207], v2 offset:5360
	s_waitcnt lgkmcnt(9)
	v_pk_mul_f32 v[174:175], v[96:97], v[174:175]
	v_pk_mul_f32 v[158:159], v[96:97], v[158:159]
	v_pk_mul_f32 v[178:179], v[100:101], v[178:179]
	v_pk_mul_f32 v[162:163], v[100:101], v[162:163]
	v_pk_fma_f32 v[174:175], v[98:99], v[176:177], v[174:175]
	v_pk_fma_f32 v[158:159], v[98:99], v[160:161], v[158:159]
	v_pk_fma_f32 v[178:179], v[102:103], v[180:181], v[178:179]
	v_pk_fma_f32 v[162:163], v[102:103], v[164:165], v[162:163]
	v_pk_add_f32 v[174:175], v[174:175], v[178:179]
	v_pk_add_f32 v[158:159], v[158:159], v[162:163]
	v_add_f32_e32 v176, v174, v175
	v_add_f32_e32 v214, v158, v159
	ds_read_b128 v[134:137], v2 offset:6016
	v_add_f32_dpp v176, v176, v176 quad_perm:[1,0,3,2] row_mask:0xf bank_mask:0xf bound_ctrl:1
	ds_read_b128 v[138:141], v2 offset:6032
	ds_read_b128 v[142:145], v2 offset:6272
	v_add_f32_dpp v176, v176, v176 quad_perm:[2,3,0,1] row_mask:0xf bank_mask:0xf bound_ctrl:1
	ds_read_b128 v[146:149], v2 offset:6288
	ds_read_b128 v[150:153], v2 offset:6528
	v_add_f32_dpp v176, v176, v176 row_half_mirror row_mask:0xf bank_mask:0xf bound_ctrl:1
	s_waitcnt lgkmcnt(12)
	v_pk_mul_f32 v[182:183], v[182:183], v[176:177] op_sel_hi:[1,0]
	v_pk_mul_f32 v[184:185], v[184:185], v[176:177] op_sel_hi:[1,0]
	v_pk_mul_f32 v[186:187], v[186:187], v[176:177] op_sel_hi:[1,0]
	v_pk_mul_f32 v[188:189], v[188:189], v[176:177] op_sel_hi:[1,0]
	ds_read_b128 v[154:157], v2 offset:6544
	s_waitcnt lgkmcnt(10)
	v_pk_fma_f32 v[182:183], v[192:193], v[212:213], v[182:183] op_sel_hi:[1,0,1]
	v_pk_fma_f32 v[184:185], v[194:195], v[212:213], v[184:185] op_sel_hi:[1,0,1]
	v_pk_fma_f32 v[186:187], v[196:197], v[212:213], v[186:187] op_sel_hi:[1,0,1]
	v_pk_fma_f32 v[188:189], v[198:199], v[212:213], v[188:189] op_sel_hi:[1,0,1]
	ds_read_b32 v210, v104 offset:7040
	ds_read_b128 v[126:129], v2 offset:5760
	s_waitcnt lgkmcnt(10)
	v_pk_fma_f32 v[96:97], v[96:97], v[166:167], v[182:183]
	v_pk_fma_f32 v[98:99], v[98:99], v[168:169], v[184:185]
	v_pk_fma_f32 v[100:101], v[100:101], v[170:171], v[186:187]
	v_pk_fma_f32 v[102:103], v[102:103], v[172:173], v[188:189]
	ds_read_b128 v[130:133], v2 offset:5776
	ds_read_b128 v[158:161], v2 offset:6784
	ds_read_b128 v[162:165], v2 offset:6800
	s_waitcnt lgkmcnt(9)
	v_pk_mul_f32 v[134:135], v[96:97], v[134:135]
	v_pk_mul_f32 v[200:201], v[96:97], v[200:201]
	v_pk_mul_f32 v[138:139], v[100:101], v[138:139]
	v_pk_mul_f32 v[204:205], v[100:101], v[204:205]
	v_pk_fma_f32 v[134:135], v[98:99], v[136:137], v[134:135]
	v_pk_fma_f32 v[200:201], v[98:99], v[202:203], v[200:201]
	v_pk_fma_f32 v[138:139], v[102:103], v[140:141], v[138:139]
	v_pk_fma_f32 v[204:205], v[102:103], v[206:207], v[204:205]
	v_pk_add_f32 v[134:135], v[134:135], v[138:139]
	v_pk_add_f32 v[200:201], v[200:201], v[204:205]
	v_add_f32_e32 v136, v134, v135
	v_add_f32_e32 v215, v200, v201
	ds_read_b128 v[174:177], v2 offset:7456
	v_add_f32_dpp v136, v136, v136 quad_perm:[1,0,3,2] row_mask:0xf bank_mask:0xf bound_ctrl:1
	ds_read_b128 v[178:181], v2 offset:7472
	ds_read_b128 v[182:185], v2 offset:7712
	v_add_f32_dpp v136, v136, v136 quad_perm:[2,3,0,1] row_mask:0xf bank_mask:0xf bound_ctrl:1
	ds_read_b128 v[186:189], v2 offset:7728
	ds_read_b128 v[192:195], v2 offset:7968
	v_add_f32_dpp v136, v136, v136 row_half_mirror row_mask:0xf bank_mask:0xf bound_ctrl:1
	s_waitcnt lgkmcnt(12)
	v_pk_mul_f32 v[142:143], v[142:143], v[136:137] op_sel_hi:[1,0]
	v_pk_mul_f32 v[144:145], v[144:145], v[136:137] op_sel_hi:[1,0]
	v_pk_mul_f32 v[146:147], v[146:147], v[136:137] op_sel_hi:[1,0]
	v_pk_mul_f32 v[148:149], v[148:149], v[136:137] op_sel_hi:[1,0]
	ds_read_b128 v[196:199], v2 offset:7984
	s_waitcnt lgkmcnt(10)
	v_pk_fma_f32 v[142:143], v[150:151], v[210:211], v[142:143] op_sel_hi:[1,0,1]
	v_pk_fma_f32 v[144:145], v[152:153], v[210:211], v[144:145] op_sel_hi:[1,0,1]
	v_pk_fma_f32 v[146:147], v[154:155], v[210:211], v[146:147] op_sel_hi:[1,0,1]
	v_pk_fma_f32 v[148:149], v[156:157], v[210:211], v[148:149] op_sel_hi:[1,0,1]
	ds_read_b32 v212, v104 offset:8480
	ds_read_b128 v[166:169], v2 offset:7200
	s_waitcnt lgkmcnt(10)
	v_pk_fma_f32 v[96:97], v[96:97], v[126:127], v[142:143]
	v_pk_fma_f32 v[98:99], v[98:99], v[128:129], v[144:145]
	v_pk_fma_f32 v[100:101], v[100:101], v[130:131], v[146:147]
	v_pk_fma_f32 v[102:103], v[102:103], v[132:133], v[148:149]
	ds_read_b128 v[170:173], v2 offset:7216
	ds_read_b128 v[200:203], v2 offset:8224
	ds_read_b128 v[204:207], v2 offset:8240
	s_waitcnt lgkmcnt(9)
	v_pk_mul_f32 v[174:175], v[96:97], v[174:175]
	v_pk_mul_f32 v[158:159], v[96:97], v[158:159]
	v_pk_mul_f32 v[178:179], v[100:101], v[178:179]
	v_pk_mul_f32 v[162:163], v[100:101], v[162:163]
	v_pk_fma_f32 v[174:175], v[98:99], v[176:177], v[174:175]
	v_pk_fma_f32 v[158:159], v[98:99], v[160:161], v[158:159]
	v_pk_fma_f32 v[178:179], v[102:103], v[180:181], v[178:179]
	v_pk_fma_f32 v[162:163], v[102:103], v[164:165], v[162:163]
	v_pk_add_f32 v[174:175], v[174:175], v[178:179]
	v_pk_add_f32 v[158:159], v[158:159], v[162:163]
	v_add_f32_e32 v176, v174, v175
	v_add_f32_e32 v216, v158, v159
	ds_read_b128 v[134:137], v2 offset:8896
	v_add_f32_dpp v176, v176, v176 quad_perm:[1,0,3,2] row_mask:0xf bank_mask:0xf bound_ctrl:1
	ds_read_b128 v[138:141], v2 offset:8912
	ds_read_b128 v[142:145], v2 offset:9152
	v_add_f32_dpp v176, v176, v176 quad_perm:[2,3,0,1] row_mask:0xf bank_mask:0xf bound_ctrl:1
	ds_read_b128 v[146:149], v2 offset:9168
	ds_read_b128 v[150:153], v2 offset:9408
	v_add_f32_dpp v176, v176, v176 row_half_mirror row_mask:0xf bank_mask:0xf bound_ctrl:1
	s_waitcnt lgkmcnt(12)
	v_pk_mul_f32 v[182:183], v[182:183], v[176:177] op_sel_hi:[1,0]
	v_pk_mul_f32 v[184:185], v[184:185], v[176:177] op_sel_hi:[1,0]
	v_pk_mul_f32 v[186:187], v[186:187], v[176:177] op_sel_hi:[1,0]
	v_pk_mul_f32 v[188:189], v[188:189], v[176:177] op_sel_hi:[1,0]
	ds_read_b128 v[154:157], v2 offset:9424
	s_waitcnt lgkmcnt(10)
	v_pk_fma_f32 v[182:183], v[192:193], v[212:213], v[182:183] op_sel_hi:[1,0,1]
	v_pk_fma_f32 v[184:185], v[194:195], v[212:213], v[184:185] op_sel_hi:[1,0,1]
	v_pk_fma_f32 v[186:187], v[196:197], v[212:213], v[186:187] op_sel_hi:[1,0,1]
	v_pk_fma_f32 v[188:189], v[198:199], v[212:213], v[188:189] op_sel_hi:[1,0,1]
	ds_read_b32 v210, v104 offset:9920
	ds_read_b128 v[126:129], v2 offset:8640
	s_waitcnt lgkmcnt(10)
	v_pk_fma_f32 v[96:97], v[96:97], v[166:167], v[182:183]
	v_pk_fma_f32 v[98:99], v[98:99], v[168:169], v[184:185]
	v_pk_fma_f32 v[100:101], v[100:101], v[170:171], v[186:187]
	v_pk_fma_f32 v[102:103], v[102:103], v[172:173], v[188:189]
	ds_read_b128 v[130:133], v2 offset:8656
	ds_read_b128 v[158:161], v2 offset:9664
	ds_read_b128 v[162:165], v2 offset:9680
	s_waitcnt lgkmcnt(9)
	v_pk_mul_f32 v[134:135], v[96:97], v[134:135]
	v_pk_mul_f32 v[200:201], v[96:97], v[200:201]
	v_pk_mul_f32 v[138:139], v[100:101], v[138:139]
	v_pk_mul_f32 v[204:205], v[100:101], v[204:205]
	v_pk_fma_f32 v[134:135], v[98:99], v[136:137], v[134:135]
	v_pk_fma_f32 v[200:201], v[98:99], v[202:203], v[200:201]
	v_pk_fma_f32 v[138:139], v[102:103], v[140:141], v[138:139]
	v_pk_fma_f32 v[204:205], v[102:103], v[206:207], v[204:205]
	v_pk_add_f32 v[134:135], v[134:135], v[138:139]
	v_pk_add_f32 v[200:201], v[200:201], v[204:205]
	v_add_f32_e32 v136, v134, v135
	v_add_f32_e32 v208, v200, v201
	ds_read_b128 v[174:177], v2 offset:10336
	v_add_f32_dpp v136, v136, v136 quad_perm:[1,0,3,2] row_mask:0xf bank_mask:0xf bound_ctrl:1
	ds_read_b128 v[178:181], v2 offset:10352
	ds_read_b128 v[182:185], v2 offset:10592
	v_add_f32_dpp v136, v136, v136 quad_perm:[2,3,0,1] row_mask:0xf bank_mask:0xf bound_ctrl:1
	ds_read_b128 v[186:189], v2 offset:10608
	ds_read_b128 v[192:195], v2 offset:10848
	v_add_f32_dpp v136, v136, v136 row_half_mirror row_mask:0xf bank_mask:0xf bound_ctrl:1
	s_waitcnt lgkmcnt(12)
	v_pk_mul_f32 v[142:143], v[142:143], v[136:137] op_sel_hi:[1,0]
	v_pk_mul_f32 v[144:145], v[144:145], v[136:137] op_sel_hi:[1,0]
	v_pk_mul_f32 v[146:147], v[146:147], v[136:137] op_sel_hi:[1,0]
	v_pk_mul_f32 v[148:149], v[148:149], v[136:137] op_sel_hi:[1,0]
	ds_read_b128 v[196:199], v2 offset:10864
	s_waitcnt lgkmcnt(10)
	v_pk_fma_f32 v[142:143], v[150:151], v[210:211], v[142:143] op_sel_hi:[1,0,1]
	v_pk_fma_f32 v[144:145], v[152:153], v[210:211], v[144:145] op_sel_hi:[1,0,1]
	v_pk_fma_f32 v[146:147], v[154:155], v[210:211], v[146:147] op_sel_hi:[1,0,1]
	v_pk_fma_f32 v[148:149], v[156:157], v[210:211], v[148:149] op_sel_hi:[1,0,1]
	ds_read_b32 v212, v104 offset:11360
	ds_read_b128 v[166:169], v2 offset:10080
	s_waitcnt lgkmcnt(10)
	v_pk_fma_f32 v[96:97], v[96:97], v[126:127], v[142:143]
	v_pk_fma_f32 v[98:99], v[98:99], v[128:129], v[144:145]
	v_pk_fma_f32 v[100:101], v[100:101], v[130:131], v[146:147]
	v_pk_fma_f32 v[102:103], v[102:103], v[132:133], v[148:149]
	ds_read_b128 v[170:173], v2 offset:10096
	ds_read_b128 v[200:203], v2 offset:11104
	ds_read_b128 v[204:207], v2 offset:11120
	s_waitcnt lgkmcnt(9)
	v_pk_mul_f32 v[174:175], v[96:97], v[174:175]
	v_pk_mul_f32 v[158:159], v[96:97], v[158:159]
	v_pk_mul_f32 v[178:179], v[100:101], v[178:179]
	v_pk_mul_f32 v[162:163], v[100:101], v[162:163]
	v_pk_fma_f32 v[174:175], v[98:99], v[176:177], v[174:175]
	v_pk_fma_f32 v[158:159], v[98:99], v[160:161], v[158:159]
	v_pk_fma_f32 v[178:179], v[102:103], v[180:181], v[178:179]
	v_pk_fma_f32 v[162:163], v[102:103], v[164:165], v[162:163]
	v_pk_add_f32 v[174:175], v[174:175], v[178:179]
	v_pk_add_f32 v[158:159], v[158:159], v[162:163]
	v_add_f32_e32 v176, v174, v175
	v_add_f32_e32 v191, v158, v159
	ds_read_b128 v[134:137], v2 offset:11776
	v_add_f32_dpp v176, v176, v176 quad_perm:[1,0,3,2] row_mask:0xf bank_mask:0xf bound_ctrl:1
	ds_read_b128 v[138:141], v2 offset:11792
	ds_read_b128 v[142:145], v2 offset:12032
	v_add_f32_dpp v176, v176, v176 quad_perm:[2,3,0,1] row_mask:0xf bank_mask:0xf bound_ctrl:1
	ds_read_b128 v[146:149], v2 offset:12048
	ds_read_b128 v[150:153], v2 offset:12288
	v_add_f32_dpp v176, v176, v176 row_half_mirror row_mask:0xf bank_mask:0xf bound_ctrl:1
	s_waitcnt lgkmcnt(12)
	v_pk_mul_f32 v[182:183], v[182:183], v[176:177] op_sel_hi:[1,0]
	v_pk_mul_f32 v[184:185], v[184:185], v[176:177] op_sel_hi:[1,0]
	v_pk_mul_f32 v[186:187], v[186:187], v[176:177] op_sel_hi:[1,0]
	v_pk_mul_f32 v[188:189], v[188:189], v[176:177] op_sel_hi:[1,0]
	ds_read_b128 v[154:157], v2 offset:12304
	s_waitcnt lgkmcnt(10)
	v_pk_fma_f32 v[182:183], v[192:193], v[212:213], v[182:183] op_sel_hi:[1,0,1]
	v_pk_fma_f32 v[184:185], v[194:195], v[212:213], v[184:185] op_sel_hi:[1,0,1]
	v_pk_fma_f32 v[186:187], v[196:197], v[212:213], v[186:187] op_sel_hi:[1,0,1]
	v_pk_fma_f32 v[188:189], v[198:199], v[212:213], v[188:189] op_sel_hi:[1,0,1]
	ds_read_b32 v210, v104 offset:12800
	ds_read_b128 v[126:129], v2 offset:11520
	s_waitcnt lgkmcnt(10)
	v_pk_fma_f32 v[96:97], v[96:97], v[166:167], v[182:183]
	v_pk_fma_f32 v[98:99], v[98:99], v[168:169], v[184:185]
	v_pk_fma_f32 v[100:101], v[100:101], v[170:171], v[186:187]
	v_pk_fma_f32 v[102:103], v[102:103], v[172:173], v[188:189]
	ds_read_b128 v[130:133], v2 offset:11536
	ds_read_b128 v[158:161], v2 offset:12544
	ds_read_b128 v[162:165], v2 offset:12560
	s_waitcnt lgkmcnt(9)
	v_pk_mul_f32 v[134:135], v[96:97], v[134:135]
	v_pk_mul_f32 v[200:201], v[96:97], v[200:201]
	v_pk_mul_f32 v[138:139], v[100:101], v[138:139]
	v_pk_mul_f32 v[204:205], v[100:101], v[204:205]
	v_pk_fma_f32 v[134:135], v[98:99], v[136:137], v[134:135]
	v_pk_fma_f32 v[200:201], v[98:99], v[202:203], v[200:201]
	v_pk_fma_f32 v[138:139], v[102:103], v[140:141], v[138:139]
	v_pk_fma_f32 v[204:205], v[102:103], v[206:207], v[204:205]
	v_pk_add_f32 v[134:135], v[134:135], v[138:139]
	v_pk_add_f32 v[200:201], v[200:201], v[204:205]
	v_add_f32_e32 v136, v134, v135
	v_add_f32_e32 v59, v200, v201
	ds_read_b128 v[174:177], v2 offset:13216
	v_add_f32_dpp v136, v136, v136 quad_perm:[1,0,3,2] row_mask:0xf bank_mask:0xf bound_ctrl:1
	ds_read_b128 v[178:181], v2 offset:13232
	ds_read_b128 v[182:185], v2 offset:13472
	v_add_f32_dpp v136, v136, v136 quad_perm:[2,3,0,1] row_mask:0xf bank_mask:0xf bound_ctrl:1
	ds_read_b128 v[186:189], v2 offset:13488
	ds_read_b128 v[192:195], v2 offset:13728
	v_add_f32_dpp v136, v136, v136 row_half_mirror row_mask:0xf bank_mask:0xf bound_ctrl:1
	v_cndmask_b32_e64 v200, v213, v211, s[10:11]
	v_cndmask_b32_e64 v204, v211, v213, s[10:11]
	v_cndmask_b32_e64 v201, v215, v214, s[10:11]
	v_cndmask_b32_e64 v205, v214, v215, s[10:11]
	v_cndmask_b32_e64 v202, v208, v216, s[10:11]
	v_cndmask_b32_e64 v206, v216, v208, s[10:11]
	v_cndmask_b32_e64 v203, v59, v191, s[10:11]
	v_cndmask_b32_e64 v207, v191, v59, s[10:11]
	v_add_f32_dpp v200, v204, v200 quad_perm:[1,0,3,2] row_mask:0xf bank_mask:0xf bound_ctrl:1
	v_add_f32_dpp v201, v205, v201 quad_perm:[1,0,3,2] row_mask:0xf bank_mask:0xf bound_ctrl:1
	v_add_f32_dpp v202, v206, v202 quad_perm:[1,0,3,2] row_mask:0xf bank_mask:0xf bound_ctrl:1
	v_add_f32_dpp v203, v207, v203 quad_perm:[1,0,3,2] row_mask:0xf bank_mask:0xf bound_ctrl:1
	v_cndmask_b32_e64 v204, v201, v200, s[12:13]
	v_cndmask_b32_e64 v206, v200, v201, s[12:13]
	v_cndmask_b32_e64 v205, v203, v202, s[12:13]
	v_cndmask_b32_e64 v207, v202, v203, s[12:13]
	v_add_f32_dpp v204, v206, v204 quad_perm:[2,3,0,1] row_mask:0xf bank_mask:0xf bound_ctrl:1
	s_nop 0
	v_add_f32_dpp v205, v207, v205 quad_perm:[2,3,0,1] row_mask:0xf bank_mask:0xf bound_ctrl:1
	v_xor_b32_e32 v202, 4, v121
	v_cndmask_b32_e64 v200, v205, v204, s[14:15]
	v_cndmask_b32_e64 v201, v204, v205, s[14:15]
	v_lshlrev_b32_e32 v202, 2, v202
	ds_bpermute_b32 v201, v202, v201
	s_waitcnt lgkmcnt(0)
	v_add_f32_e32 v200, v200, v201
	ds_write_b32 v105, v200
	v_pk_mul_f32 v[142:143], v[142:143], v[136:137] op_sel_hi:[1,0]
	v_pk_mul_f32 v[144:145], v[144:145], v[136:137] op_sel_hi:[1,0]
	v_pk_mul_f32 v[146:147], v[146:147], v[136:137] op_sel_hi:[1,0]
	v_pk_mul_f32 v[148:149], v[148:149], v[136:137] op_sel_hi:[1,0]
	ds_read_b128 v[196:199], v2 offset:13744
	v_pk_fma_f32 v[142:143], v[150:151], v[210:211], v[142:143] op_sel_hi:[1,0,1]
	v_pk_fma_f32 v[144:145], v[152:153], v[210:211], v[144:145] op_sel_hi:[1,0,1]
	v_pk_fma_f32 v[146:147], v[154:155], v[210:211], v[146:147] op_sel_hi:[1,0,1]
	v_pk_fma_f32 v[148:149], v[156:157], v[210:211], v[148:149] op_sel_hi:[1,0,1]
	ds_read_b32 v212, v104 offset:14240
	ds_read_b128 v[166:169], v2 offset:12960
	v_pk_fma_f32 v[96:97], v[96:97], v[126:127], v[142:143]
	v_pk_fma_f32 v[98:99], v[98:99], v[128:129], v[144:145]
	v_pk_fma_f32 v[100:101], v[100:101], v[130:131], v[146:147]
	v_pk_fma_f32 v[102:103], v[102:103], v[132:133], v[148:149]
	ds_read_b128 v[170:173], v2 offset:12976
	ds_read_b128 v[200:203], v2 offset:13984
	ds_read_b128 v[204:207], v2 offset:14000
	v_pk_mul_f32 v[174:175], v[96:97], v[174:175]
	v_pk_mul_f32 v[158:159], v[96:97], v[158:159]
	v_pk_mul_f32 v[178:179], v[100:101], v[178:179]
	v_pk_mul_f32 v[162:163], v[100:101], v[162:163]
	v_pk_fma_f32 v[174:175], v[98:99], v[176:177], v[174:175]
	v_pk_fma_f32 v[158:159], v[98:99], v[160:161], v[158:159]
	v_pk_fma_f32 v[178:179], v[102:103], v[180:181], v[178:179]
	v_pk_fma_f32 v[162:163], v[102:103], v[164:165], v[162:163]
	v_pk_add_f32 v[174:175], v[174:175], v[178:179]
	v_pk_add_f32 v[158:159], v[158:159], v[162:163]
	v_add_f32_e32 v176, v174, v175
	v_add_f32_e32 v211, v158, v159
	ds_read_b128 v[134:137], v2 offset:14656
	v_add_f32_dpp v176, v176, v176 quad_perm:[1,0,3,2] row_mask:0xf bank_mask:0xf bound_ctrl:1
	ds_read_b128 v[138:141], v2 offset:14672
	ds_read_b128 v[142:145], v2 offset:14912
	v_add_f32_dpp v176, v176, v176 quad_perm:[2,3,0,1] row_mask:0xf bank_mask:0xf bound_ctrl:1
	ds_read_b128 v[146:149], v2 offset:14928
	ds_read_b128 v[150:153], v2 offset:15168
	v_add_f32_dpp v176, v176, v176 row_half_mirror row_mask:0xf bank_mask:0xf bound_ctrl:1
	v_pk_mul_f32 v[182:183], v[182:183], v[176:177] op_sel_hi:[1,0]
	v_pk_mul_f32 v[184:185], v[184:185], v[176:177] op_sel_hi:[1,0]
	v_pk_mul_f32 v[186:187], v[186:187], v[176:177] op_sel_hi:[1,0]
	v_pk_mul_f32 v[188:189], v[188:189], v[176:177] op_sel_hi:[1,0]
	ds_read_b128 v[154:157], v2 offset:15184
	s_waitcnt lgkmcnt(10)
	v_pk_fma_f32 v[182:183], v[192:193], v[212:213], v[182:183] op_sel_hi:[1,0,1]
	v_pk_fma_f32 v[184:185], v[194:195], v[212:213], v[184:185] op_sel_hi:[1,0,1]
	v_pk_fma_f32 v[186:187], v[196:197], v[212:213], v[186:187] op_sel_hi:[1,0,1]
	v_pk_fma_f32 v[188:189], v[198:199], v[212:213], v[188:189] op_sel_hi:[1,0,1]
	ds_read_b32 v210, v104 offset:15680
	ds_read_b128 v[126:129], v2 offset:14400
	s_waitcnt lgkmcnt(10)
	v_pk_fma_f32 v[96:97], v[96:97], v[166:167], v[182:183]
	v_pk_fma_f32 v[98:99], v[98:99], v[168:169], v[184:185]
	v_pk_fma_f32 v[100:101], v[100:101], v[170:171], v[186:187]
	v_pk_fma_f32 v[102:103], v[102:103], v[172:173], v[188:189]
	ds_read_b128 v[130:133], v2 offset:14416
	ds_read_b128 v[158:161], v2 offset:15424
	ds_read_b128 v[162:165], v2 offset:15440
	s_waitcnt lgkmcnt(9)
	v_pk_mul_f32 v[134:135], v[96:97], v[134:135]
	v_pk_mul_f32 v[200:201], v[96:97], v[200:201]
	v_pk_mul_f32 v[138:139], v[100:101], v[138:139]
	v_pk_mul_f32 v[204:205], v[100:101], v[204:205]
	v_pk_fma_f32 v[134:135], v[98:99], v[136:137], v[134:135]
	v_pk_fma_f32 v[200:201], v[98:99], v[202:203], v[200:201]
	v_pk_fma_f32 v[138:139], v[102:103], v[140:141], v[138:139]
	v_pk_fma_f32 v[204:205], v[102:103], v[206:207], v[204:205]
	v_pk_add_f32 v[134:135], v[134:135], v[138:139]
	v_pk_add_f32 v[200:201], v[200:201], v[204:205]
	v_add_f32_e32 v136, v134, v135
	v_add_f32_e32 v213, v200, v201
	ds_read_b128 v[174:177], v2 offset:16096
	v_add_f32_dpp v136, v136, v136 quad_perm:[1,0,3,2] row_mask:0xf bank_mask:0xf bound_ctrl:1
	ds_read_b128 v[178:181], v2 offset:16112
	ds_read_b128 v[182:185], v2 offset:16352
	v_add_f32_dpp v136, v136, v136 quad_perm:[2,3,0,1] row_mask:0xf bank_mask:0xf bound_ctrl:1
	ds_read_b128 v[186:189], v2 offset:16368
	ds_read_b128 v[192:195], v2 offset:16608
	v_add_f32_dpp v136, v136, v136 row_half_mirror row_mask:0xf bank_mask:0xf bound_ctrl:1
	s_waitcnt lgkmcnt(12)
	v_pk_mul_f32 v[142:143], v[142:143], v[136:137] op_sel_hi:[1,0]
	v_pk_mul_f32 v[144:145], v[144:145], v[136:137] op_sel_hi:[1,0]
	v_pk_mul_f32 v[146:147], v[146:147], v[136:137] op_sel_hi:[1,0]
	v_pk_mul_f32 v[148:149], v[148:149], v[136:137] op_sel_hi:[1,0]
	ds_read_b128 v[196:199], v2 offset:16624
	s_waitcnt lgkmcnt(10)
	v_pk_fma_f32 v[142:143], v[150:151], v[210:211], v[142:143] op_sel_hi:[1,0,1]
	v_pk_fma_f32 v[144:145], v[152:153], v[210:211], v[144:145] op_sel_hi:[1,0,1]
	v_pk_fma_f32 v[146:147], v[154:155], v[210:211], v[146:147] op_sel_hi:[1,0,1]
	v_pk_fma_f32 v[148:149], v[156:157], v[210:211], v[148:149] op_sel_hi:[1,0,1]
	ds_read_b32 v212, v104 offset:17120
	ds_read_b128 v[166:169], v2 offset:15840
	s_waitcnt lgkmcnt(10)
	v_pk_fma_f32 v[96:97], v[96:97], v[126:127], v[142:143]
	v_pk_fma_f32 v[98:99], v[98:99], v[128:129], v[144:145]
	v_pk_fma_f32 v[100:101], v[100:101], v[130:131], v[146:147]
	v_pk_fma_f32 v[102:103], v[102:103], v[132:133], v[148:149]
	ds_read_b128 v[170:173], v2 offset:15856
	ds_read_b128 v[200:203], v2 offset:16864
	ds_read_b128 v[204:207], v2 offset:16880
	s_waitcnt lgkmcnt(9)
	v_pk_mul_f32 v[174:175], v[96:97], v[174:175]
	v_pk_mul_f32 v[158:159], v[96:97], v[158:159]
	v_pk_mul_f32 v[178:179], v[100:101], v[178:179]
	v_pk_mul_f32 v[162:163], v[100:101], v[162:163]
	v_pk_fma_f32 v[174:175], v[98:99], v[176:177], v[174:175]
	v_pk_fma_f32 v[158:159], v[98:99], v[160:161], v[158:159]
	v_pk_fma_f32 v[178:179], v[102:103], v[180:181], v[178:179]
	v_pk_fma_f32 v[162:163], v[102:103], v[164:165], v[162:163]
	v_pk_add_f32 v[174:175], v[174:175], v[178:179]
	v_pk_add_f32 v[158:159], v[158:159], v[162:163]
	v_add_f32_e32 v176, v174, v175
	v_add_f32_e32 v214, v158, v159
	ds_read_b128 v[134:137], v2 offset:17536
	v_add_f32_dpp v176, v176, v176 quad_perm:[1,0,3,2] row_mask:0xf bank_mask:0xf bound_ctrl:1
	ds_read_b128 v[138:141], v2 offset:17552
	ds_read_b128 v[142:145], v2 offset:17792
	v_add_f32_dpp v176, v176, v176 quad_perm:[2,3,0,1] row_mask:0xf bank_mask:0xf bound_ctrl:1
	ds_read_b128 v[146:149], v2 offset:17808
	ds_read_b128 v[150:153], v2 offset:18048
	v_add_f32_dpp v176, v176, v176 row_half_mirror row_mask:0xf bank_mask:0xf bound_ctrl:1
	s_waitcnt lgkmcnt(12)
	v_pk_mul_f32 v[182:183], v[182:183], v[176:177] op_sel_hi:[1,0]
	v_pk_mul_f32 v[184:185], v[184:185], v[176:177] op_sel_hi:[1,0]
	v_pk_mul_f32 v[186:187], v[186:187], v[176:177] op_sel_hi:[1,0]
	v_pk_mul_f32 v[188:189], v[188:189], v[176:177] op_sel_hi:[1,0]
	ds_read_b128 v[154:157], v2 offset:18064
	s_waitcnt lgkmcnt(10)
	v_pk_fma_f32 v[182:183], v[192:193], v[212:213], v[182:183] op_sel_hi:[1,0,1]
	v_pk_fma_f32 v[184:185], v[194:195], v[212:213], v[184:185] op_sel_hi:[1,0,1]
	v_pk_fma_f32 v[186:187], v[196:197], v[212:213], v[186:187] op_sel_hi:[1,0,1]
	v_pk_fma_f32 v[188:189], v[198:199], v[212:213], v[188:189] op_sel_hi:[1,0,1]
	ds_read_b32 v210, v104 offset:18560
	ds_read_b128 v[126:129], v2 offset:17280
	s_waitcnt lgkmcnt(10)
	v_pk_fma_f32 v[96:97], v[96:97], v[166:167], v[182:183]
	v_pk_fma_f32 v[98:99], v[98:99], v[168:169], v[184:185]
	v_pk_fma_f32 v[100:101], v[100:101], v[170:171], v[186:187]
	v_pk_fma_f32 v[102:103], v[102:103], v[172:173], v[188:189]
	ds_read_b128 v[130:133], v2 offset:17296
	ds_read_b128 v[158:161], v2 offset:18304
	ds_read_b128 v[162:165], v2 offset:18320
	s_waitcnt lgkmcnt(9)
	v_pk_mul_f32 v[134:135], v[96:97], v[134:135]
	v_pk_mul_f32 v[200:201], v[96:97], v[200:201]
	v_pk_mul_f32 v[138:139], v[100:101], v[138:139]
	v_pk_mul_f32 v[204:205], v[100:101], v[204:205]
	v_pk_fma_f32 v[134:135], v[98:99], v[136:137], v[134:135]
	v_pk_fma_f32 v[200:201], v[98:99], v[202:203], v[200:201]
	v_pk_fma_f32 v[138:139], v[102:103], v[140:141], v[138:139]
	v_pk_fma_f32 v[204:205], v[102:103], v[206:207], v[204:205]
	v_pk_add_f32 v[134:135], v[134:135], v[138:139]
	v_pk_add_f32 v[200:201], v[200:201], v[204:205]
	v_add_f32_e32 v136, v134, v135
	v_add_f32_e32 v215, v200, v201
	ds_read_b128 v[174:177], v2 offset:18976
	v_add_f32_dpp v136, v136, v136 quad_perm:[1,0,3,2] row_mask:0xf bank_mask:0xf bound_ctrl:1
	ds_read_b128 v[178:181], v2 offset:18992
	ds_read_b128 v[182:185], v2 offset:19232
	v_add_f32_dpp v136, v136, v136 quad_perm:[2,3,0,1] row_mask:0xf bank_mask:0xf bound_ctrl:1
	ds_read_b128 v[186:189], v2 offset:19248
	ds_read_b128 v[192:195], v2 offset:19488
	v_add_f32_dpp v136, v136, v136 row_half_mirror row_mask:0xf bank_mask:0xf bound_ctrl:1
	s_waitcnt lgkmcnt(12)
	v_pk_mul_f32 v[142:143], v[142:143], v[136:137] op_sel_hi:[1,0]
	v_pk_mul_f32 v[144:145], v[144:145], v[136:137] op_sel_hi:[1,0]
	v_pk_mul_f32 v[146:147], v[146:147], v[136:137] op_sel_hi:[1,0]
	v_pk_mul_f32 v[148:149], v[148:149], v[136:137] op_sel_hi:[1,0]
	ds_read_b128 v[196:199], v2 offset:19504
	s_waitcnt lgkmcnt(10)
	v_pk_fma_f32 v[142:143], v[150:151], v[210:211], v[142:143] op_sel_hi:[1,0,1]
	v_pk_fma_f32 v[144:145], v[152:153], v[210:211], v[144:145] op_sel_hi:[1,0,1]
	v_pk_fma_f32 v[146:147], v[154:155], v[210:211], v[146:147] op_sel_hi:[1,0,1]
	v_pk_fma_f32 v[148:149], v[156:157], v[210:211], v[148:149] op_sel_hi:[1,0,1]
	ds_read_b32 v212, v104 offset:20000
	ds_read_b128 v[166:169], v2 offset:18720
	s_waitcnt lgkmcnt(10)
	v_pk_fma_f32 v[96:97], v[96:97], v[126:127], v[142:143]
	v_pk_fma_f32 v[98:99], v[98:99], v[128:129], v[144:145]
	v_pk_fma_f32 v[100:101], v[100:101], v[130:131], v[146:147]
	v_pk_fma_f32 v[102:103], v[102:103], v[132:133], v[148:149]
	ds_read_b128 v[170:173], v2 offset:18736
	ds_read_b128 v[200:203], v2 offset:19744
	ds_read_b128 v[204:207], v2 offset:19760
	s_waitcnt lgkmcnt(9)
	v_pk_mul_f32 v[174:175], v[96:97], v[174:175]
	v_pk_mul_f32 v[158:159], v[96:97], v[158:159]
	v_pk_mul_f32 v[178:179], v[100:101], v[178:179]
	v_pk_mul_f32 v[162:163], v[100:101], v[162:163]
	v_pk_fma_f32 v[174:175], v[98:99], v[176:177], v[174:175]
	v_pk_fma_f32 v[158:159], v[98:99], v[160:161], v[158:159]
	v_pk_fma_f32 v[178:179], v[102:103], v[180:181], v[178:179]
	v_pk_fma_f32 v[162:163], v[102:103], v[164:165], v[162:163]
	v_pk_add_f32 v[174:175], v[174:175], v[178:179]
	v_pk_add_f32 v[158:159], v[158:159], v[162:163]
	v_add_f32_e32 v176, v174, v175
	v_add_f32_e32 v216, v158, v159
	ds_read_b128 v[134:137], v2 offset:20416
	v_add_f32_dpp v176, v176, v176 quad_perm:[1,0,3,2] row_mask:0xf bank_mask:0xf bound_ctrl:1
	ds_read_b128 v[138:141], v2 offset:20432
	ds_read_b128 v[142:145], v2 offset:20672
	v_add_f32_dpp v176, v176, v176 quad_perm:[2,3,0,1] row_mask:0xf bank_mask:0xf bound_ctrl:1
	ds_read_b128 v[146:149], v2 offset:20688
	ds_read_b128 v[150:153], v2 offset:20928
	v_add_f32_dpp v176, v176, v176 row_half_mirror row_mask:0xf bank_mask:0xf bound_ctrl:1
	s_waitcnt lgkmcnt(12)
	v_pk_mul_f32 v[182:183], v[182:183], v[176:177] op_sel_hi:[1,0]
	v_pk_mul_f32 v[184:185], v[184:185], v[176:177] op_sel_hi:[1,0]
	v_pk_mul_f32 v[186:187], v[186:187], v[176:177] op_sel_hi:[1,0]
	v_pk_mul_f32 v[188:189], v[188:189], v[176:177] op_sel_hi:[1,0]
	ds_read_b128 v[154:157], v2 offset:20944
	s_waitcnt lgkmcnt(10)
	v_pk_fma_f32 v[182:183], v[192:193], v[212:213], v[182:183] op_sel_hi:[1,0,1]
	v_pk_fma_f32 v[184:185], v[194:195], v[212:213], v[184:185] op_sel_hi:[1,0,1]
	v_pk_fma_f32 v[186:187], v[196:197], v[212:213], v[186:187] op_sel_hi:[1,0,1]
	v_pk_fma_f32 v[188:189], v[198:199], v[212:213], v[188:189] op_sel_hi:[1,0,1]
	ds_read_b32 v210, v104 offset:21440
	ds_read_b128 v[126:129], v2 offset:20160
	s_waitcnt lgkmcnt(10)
	v_pk_fma_f32 v[96:97], v[96:97], v[166:167], v[182:183]
	v_pk_fma_f32 v[98:99], v[98:99], v[168:169], v[184:185]
	v_pk_fma_f32 v[100:101], v[100:101], v[170:171], v[186:187]
	v_pk_fma_f32 v[102:103], v[102:103], v[172:173], v[188:189]
	ds_read_b128 v[130:133], v2 offset:20176
	ds_read_b128 v[158:161], v2 offset:21184
	ds_read_b128 v[162:165], v2 offset:21200
	s_waitcnt lgkmcnt(9)
	v_pk_mul_f32 v[134:135], v[96:97], v[134:135]
	v_pk_mul_f32 v[200:201], v[96:97], v[200:201]
	v_pk_mul_f32 v[138:139], v[100:101], v[138:139]
	v_pk_mul_f32 v[204:205], v[100:101], v[204:205]
	v_pk_fma_f32 v[134:135], v[98:99], v[136:137], v[134:135]
	v_pk_fma_f32 v[200:201], v[98:99], v[202:203], v[200:201]
	v_pk_fma_f32 v[138:139], v[102:103], v[140:141], v[138:139]
	v_pk_fma_f32 v[204:205], v[102:103], v[206:207], v[204:205]
	v_pk_add_f32 v[134:135], v[134:135], v[138:139]
	v_pk_add_f32 v[200:201], v[200:201], v[204:205]
	v_add_f32_e32 v136, v134, v135
	v_add_f32_e32 v208, v200, v201
	ds_read_b128 v[174:177], v2 offset:21856
	v_add_f32_dpp v136, v136, v136 quad_perm:[1,0,3,2] row_mask:0xf bank_mask:0xf bound_ctrl:1
	ds_read_b128 v[178:181], v2 offset:21872
	ds_read_b128 v[182:185], v2 offset:22112
	v_add_f32_dpp v136, v136, v136 quad_perm:[2,3,0,1] row_mask:0xf bank_mask:0xf bound_ctrl:1
	ds_read_b128 v[186:189], v2 offset:22128
	ds_read_b128 v[192:195], v2 offset:22368
	v_add_f32_dpp v136, v136, v136 row_half_mirror row_mask:0xf bank_mask:0xf bound_ctrl:1
	s_waitcnt lgkmcnt(12)
	v_pk_mul_f32 v[142:143], v[142:143], v[136:137] op_sel_hi:[1,0]
	v_pk_mul_f32 v[144:145], v[144:145], v[136:137] op_sel_hi:[1,0]
	v_pk_mul_f32 v[146:147], v[146:147], v[136:137] op_sel_hi:[1,0]
	v_pk_mul_f32 v[148:149], v[148:149], v[136:137] op_sel_hi:[1,0]
	ds_read_b128 v[196:199], v2 offset:22384
	s_waitcnt lgkmcnt(10)
	v_pk_fma_f32 v[142:143], v[150:151], v[210:211], v[142:143] op_sel_hi:[1,0,1]
	v_pk_fma_f32 v[144:145], v[152:153], v[210:211], v[144:145] op_sel_hi:[1,0,1]
	v_pk_fma_f32 v[146:147], v[154:155], v[210:211], v[146:147] op_sel_hi:[1,0,1]
	v_pk_fma_f32 v[148:149], v[156:157], v[210:211], v[148:149] op_sel_hi:[1,0,1]
	ds_read_b32 v212, v104 offset:22880
	ds_read_b128 v[166:169], v2 offset:21600
	s_waitcnt lgkmcnt(10)
	v_pk_fma_f32 v[96:97], v[96:97], v[126:127], v[142:143]
	v_pk_fma_f32 v[98:99], v[98:99], v[128:129], v[144:145]
	v_pk_fma_f32 v[100:101], v[100:101], v[130:131], v[146:147]
	v_pk_fma_f32 v[102:103], v[102:103], v[132:133], v[148:149]
	ds_read_b128 v[170:173], v2 offset:21616
	ds_read_b128 v[200:203], v2 offset:22624
	ds_read_b128 v[204:207], v2 offset:22640
	s_waitcnt lgkmcnt(9)
	v_pk_mul_f32 v[174:175], v[96:97], v[174:175]
	v_pk_mul_f32 v[158:159], v[96:97], v[158:159]
	v_pk_mul_f32 v[178:179], v[100:101], v[178:179]
	v_pk_mul_f32 v[162:163], v[100:101], v[162:163]
	v_pk_fma_f32 v[174:175], v[98:99], v[176:177], v[174:175]
	v_pk_fma_f32 v[158:159], v[98:99], v[160:161], v[158:159]
	v_pk_fma_f32 v[178:179], v[102:103], v[180:181], v[178:179]
	v_pk_fma_f32 v[162:163], v[102:103], v[164:165], v[162:163]
	v_pk_add_f32 v[174:175], v[174:175], v[178:179]
	v_pk_add_f32 v[158:159], v[158:159], v[162:163]
	v_add_f32_e32 v176, v174, v175
	v_add_f32_e32 v191, v158, v159
	ds_read_b128 v[134:137], v2 offset:23296
	v_add_f32_dpp v176, v176, v176 quad_perm:[1,0,3,2] row_mask:0xf bank_mask:0xf bound_ctrl:1
	ds_read_b128 v[138:141], v2 offset:23312
	ds_read_b128 v[142:145], v2 offset:23552
	v_add_f32_dpp v176, v176, v176 quad_perm:[2,3,0,1] row_mask:0xf bank_mask:0xf bound_ctrl:1
	ds_read_b128 v[146:149], v2 offset:23568
	ds_read_b128 v[150:153], v2 offset:23808
	v_add_f32_dpp v176, v176, v176 row_half_mirror row_mask:0xf bank_mask:0xf bound_ctrl:1
	s_waitcnt lgkmcnt(12)
	v_pk_mul_f32 v[182:183], v[182:183], v[176:177] op_sel_hi:[1,0]
	v_pk_mul_f32 v[184:185], v[184:185], v[176:177] op_sel_hi:[1,0]
	v_pk_mul_f32 v[186:187], v[186:187], v[176:177] op_sel_hi:[1,0]
	v_pk_mul_f32 v[188:189], v[188:189], v[176:177] op_sel_hi:[1,0]
	ds_read_b128 v[154:157], v2 offset:23824
	s_waitcnt lgkmcnt(10)
	v_pk_fma_f32 v[182:183], v[192:193], v[212:213], v[182:183] op_sel_hi:[1,0,1]
	v_pk_fma_f32 v[184:185], v[194:195], v[212:213], v[184:185] op_sel_hi:[1,0,1]
	v_pk_fma_f32 v[186:187], v[196:197], v[212:213], v[186:187] op_sel_hi:[1,0,1]
	v_pk_fma_f32 v[188:189], v[198:199], v[212:213], v[188:189] op_sel_hi:[1,0,1]
	ds_read_b32 v210, v104 offset:24320
	ds_read_b128 v[126:129], v2 offset:23040
	s_waitcnt lgkmcnt(10)
	v_pk_fma_f32 v[96:97], v[96:97], v[166:167], v[182:183]
	v_pk_fma_f32 v[98:99], v[98:99], v[168:169], v[184:185]
	v_pk_fma_f32 v[100:101], v[100:101], v[170:171], v[186:187]
	v_pk_fma_f32 v[102:103], v[102:103], v[172:173], v[188:189]
	ds_read_b128 v[130:133], v2 offset:23056
	ds_read_b128 v[158:161], v2 offset:24064
	ds_read_b128 v[162:165], v2 offset:24080
	s_waitcnt lgkmcnt(9)
	v_pk_mul_f32 v[134:135], v[96:97], v[134:135]
	v_pk_mul_f32 v[200:201], v[96:97], v[200:201]
	v_pk_mul_f32 v[138:139], v[100:101], v[138:139]
	v_pk_mul_f32 v[204:205], v[100:101], v[204:205]
	v_pk_fma_f32 v[134:135], v[98:99], v[136:137], v[134:135]
	v_pk_fma_f32 v[200:201], v[98:99], v[202:203], v[200:201]
	v_pk_fma_f32 v[138:139], v[102:103], v[140:141], v[138:139]
	v_pk_fma_f32 v[204:205], v[102:103], v[206:207], v[204:205]
	v_pk_add_f32 v[134:135], v[134:135], v[138:139]
	v_pk_add_f32 v[200:201], v[200:201], v[204:205]
	v_add_f32_e32 v136, v134, v135
	v_add_f32_e32 v59, v200, v201
	ds_read_b128 v[174:177], v2 offset:24736
	v_add_f32_dpp v136, v136, v136 quad_perm:[1,0,3,2] row_mask:0xf bank_mask:0xf bound_ctrl:1
	ds_read_b128 v[178:181], v2 offset:24752
	ds_read_b128 v[182:185], v2 offset:24992
	v_add_f32_dpp v136, v136, v136 quad_perm:[2,3,0,1] row_mask:0xf bank_mask:0xf bound_ctrl:1
	ds_read_b128 v[186:189], v2 offset:25008
	ds_read_b128 v[192:195], v2 offset:25248
	v_add_f32_dpp v136, v136, v136 row_half_mirror row_mask:0xf bank_mask:0xf bound_ctrl:1
	v_cndmask_b32_e64 v200, v213, v211, s[10:11]
	v_cndmask_b32_e64 v204, v211, v213, s[10:11]
	v_cndmask_b32_e64 v201, v215, v214, s[10:11]
	v_cndmask_b32_e64 v205, v214, v215, s[10:11]
	v_cndmask_b32_e64 v202, v208, v216, s[10:11]
	v_cndmask_b32_e64 v206, v216, v208, s[10:11]
	v_cndmask_b32_e64 v203, v59, v191, s[10:11]
	v_cndmask_b32_e64 v207, v191, v59, s[10:11]
	v_add_f32_dpp v200, v204, v200 quad_perm:[1,0,3,2] row_mask:0xf bank_mask:0xf bound_ctrl:1
	v_add_f32_dpp v201, v205, v201 quad_perm:[1,0,3,2] row_mask:0xf bank_mask:0xf bound_ctrl:1
	v_add_f32_dpp v202, v206, v202 quad_perm:[1,0,3,2] row_mask:0xf bank_mask:0xf bound_ctrl:1
	v_add_f32_dpp v203, v207, v203 quad_perm:[1,0,3,2] row_mask:0xf bank_mask:0xf bound_ctrl:1
	v_cndmask_b32_e64 v204, v201, v200, s[12:13]
	v_cndmask_b32_e64 v206, v200, v201, s[12:13]
	v_cndmask_b32_e64 v205, v203, v202, s[12:13]
	v_cndmask_b32_e64 v207, v202, v203, s[12:13]
	v_add_f32_dpp v204, v206, v204 quad_perm:[2,3,0,1] row_mask:0xf bank_mask:0xf bound_ctrl:1
	s_nop 0
	v_add_f32_dpp v205, v207, v205 quad_perm:[2,3,0,1] row_mask:0xf bank_mask:0xf bound_ctrl:1
	v_xor_b32_e32 v202, 4, v121
	v_cndmask_b32_e64 v200, v205, v204, s[14:15]
	v_cndmask_b32_e64 v201, v204, v205, s[14:15]
	v_lshlrev_b32_e32 v202, 2, v202
	ds_bpermute_b32 v201, v202, v201
	s_waitcnt lgkmcnt(0)
	v_add_f32_e32 v200, v200, v201
	ds_write_b32 v105, v200 offset:1024
	v_pk_mul_f32 v[142:143], v[142:143], v[136:137] op_sel_hi:[1,0]
	v_pk_mul_f32 v[144:145], v[144:145], v[136:137] op_sel_hi:[1,0]
	v_pk_mul_f32 v[146:147], v[146:147], v[136:137] op_sel_hi:[1,0]
	v_pk_mul_f32 v[148:149], v[148:149], v[136:137] op_sel_hi:[1,0]
	ds_read_b128 v[196:199], v2 offset:25264
	v_pk_fma_f32 v[142:143], v[150:151], v[210:211], v[142:143] op_sel_hi:[1,0,1]
	v_pk_fma_f32 v[144:145], v[152:153], v[210:211], v[144:145] op_sel_hi:[1,0,1]
	v_pk_fma_f32 v[146:147], v[154:155], v[210:211], v[146:147] op_sel_hi:[1,0,1]
	v_pk_fma_f32 v[148:149], v[156:157], v[210:211], v[148:149] op_sel_hi:[1,0,1]
	ds_read_b32 v212, v104 offset:25760
	ds_read_b128 v[166:169], v2 offset:24480
	v_pk_fma_f32 v[96:97], v[96:97], v[126:127], v[142:143]
	v_pk_fma_f32 v[98:99], v[98:99], v[128:129], v[144:145]
	v_pk_fma_f32 v[100:101], v[100:101], v[130:131], v[146:147]
	v_pk_fma_f32 v[102:103], v[102:103], v[132:133], v[148:149]
	ds_read_b128 v[170:173], v2 offset:24496
	ds_read_b128 v[200:203], v2 offset:25504
	ds_read_b128 v[204:207], v2 offset:25520
	v_pk_mul_f32 v[174:175], v[96:97], v[174:175]
	v_pk_mul_f32 v[158:159], v[96:97], v[158:159]
	v_pk_mul_f32 v[178:179], v[100:101], v[178:179]
	v_pk_mul_f32 v[162:163], v[100:101], v[162:163]
	v_pk_fma_f32 v[174:175], v[98:99], v[176:177], v[174:175]
	v_pk_fma_f32 v[158:159], v[98:99], v[160:161], v[158:159]
	v_pk_fma_f32 v[178:179], v[102:103], v[180:181], v[178:179]
	v_pk_fma_f32 v[162:163], v[102:103], v[164:165], v[162:163]
	v_pk_add_f32 v[174:175], v[174:175], v[178:179]
	v_pk_add_f32 v[158:159], v[158:159], v[162:163]
	v_add_f32_e32 v176, v174, v175
	v_add_f32_e32 v211, v158, v159
	ds_read_b128 v[134:137], v2 offset:26176
	v_add_f32_dpp v176, v176, v176 quad_perm:[1,0,3,2] row_mask:0xf bank_mask:0xf bound_ctrl:1
	ds_read_b128 v[138:141], v2 offset:26192
	ds_read_b128 v[142:145], v2 offset:26432
	v_add_f32_dpp v176, v176, v176 quad_perm:[2,3,0,1] row_mask:0xf bank_mask:0xf bound_ctrl:1
	ds_read_b128 v[146:149], v2 offset:26448
	ds_read_b128 v[150:153], v2 offset:26688
	v_add_f32_dpp v176, v176, v176 row_half_mirror row_mask:0xf bank_mask:0xf bound_ctrl:1
	v_pk_mul_f32 v[182:183], v[182:183], v[176:177] op_sel_hi:[1,0]
	v_pk_mul_f32 v[184:185], v[184:185], v[176:177] op_sel_hi:[1,0]
	v_pk_mul_f32 v[186:187], v[186:187], v[176:177] op_sel_hi:[1,0]
	v_pk_mul_f32 v[188:189], v[188:189], v[176:177] op_sel_hi:[1,0]
	ds_read_b128 v[154:157], v2 offset:26704
	s_waitcnt lgkmcnt(10)
	v_pk_fma_f32 v[182:183], v[192:193], v[212:213], v[182:183] op_sel_hi:[1,0,1]
	v_pk_fma_f32 v[184:185], v[194:195], v[212:213], v[184:185] op_sel_hi:[1,0,1]
	v_pk_fma_f32 v[186:187], v[196:197], v[212:213], v[186:187] op_sel_hi:[1,0,1]
	v_pk_fma_f32 v[188:189], v[198:199], v[212:213], v[188:189] op_sel_hi:[1,0,1]
	ds_read_b32 v210, v104 offset:27200
	ds_read_b128 v[126:129], v2 offset:25920
	s_waitcnt lgkmcnt(10)
	v_pk_fma_f32 v[96:97], v[96:97], v[166:167], v[182:183]
	v_pk_fma_f32 v[98:99], v[98:99], v[168:169], v[184:185]
	v_pk_fma_f32 v[100:101], v[100:101], v[170:171], v[186:187]
	v_pk_fma_f32 v[102:103], v[102:103], v[172:173], v[188:189]
	ds_read_b128 v[130:133], v2 offset:25936
	ds_read_b128 v[158:161], v2 offset:26944
	ds_read_b128 v[162:165], v2 offset:26960
	s_waitcnt lgkmcnt(9)
	v_pk_mul_f32 v[134:135], v[96:97], v[134:135]
	v_pk_mul_f32 v[200:201], v[96:97], v[200:201]
	v_pk_mul_f32 v[138:139], v[100:101], v[138:139]
	v_pk_mul_f32 v[204:205], v[100:101], v[204:205]
	v_pk_fma_f32 v[134:135], v[98:99], v[136:137], v[134:135]
	v_pk_fma_f32 v[200:201], v[98:99], v[202:203], v[200:201]
	v_pk_fma_f32 v[138:139], v[102:103], v[140:141], v[138:139]
	v_pk_fma_f32 v[204:205], v[102:103], v[206:207], v[204:205]
	v_pk_add_f32 v[134:135], v[134:135], v[138:139]
	v_pk_add_f32 v[200:201], v[200:201], v[204:205]
	v_add_f32_e32 v136, v134, v135
	v_add_f32_e32 v213, v200, v201
	ds_read_b128 v[174:177], v2 offset:27616
	v_add_f32_dpp v136, v136, v136 quad_perm:[1,0,3,2] row_mask:0xf bank_mask:0xf bound_ctrl:1
	ds_read_b128 v[178:181], v2 offset:27632
	ds_read_b128 v[182:185], v2 offset:27872
	v_add_f32_dpp v136, v136, v136 quad_perm:[2,3,0,1] row_mask:0xf bank_mask:0xf bound_ctrl:1
	ds_read_b128 v[186:189], v2 offset:27888
	ds_read_b128 v[192:195], v2 offset:28128
	v_add_f32_dpp v136, v136, v136 row_half_mirror row_mask:0xf bank_mask:0xf bound_ctrl:1
	s_waitcnt lgkmcnt(12)
	v_pk_mul_f32 v[142:143], v[142:143], v[136:137] op_sel_hi:[1,0]
	v_pk_mul_f32 v[144:145], v[144:145], v[136:137] op_sel_hi:[1,0]
	v_pk_mul_f32 v[146:147], v[146:147], v[136:137] op_sel_hi:[1,0]
	v_pk_mul_f32 v[148:149], v[148:149], v[136:137] op_sel_hi:[1,0]
	ds_read_b128 v[196:199], v2 offset:28144
	s_waitcnt lgkmcnt(10)
	v_pk_fma_f32 v[142:143], v[150:151], v[210:211], v[142:143] op_sel_hi:[1,0,1]
	v_pk_fma_f32 v[144:145], v[152:153], v[210:211], v[144:145] op_sel_hi:[1,0,1]
	v_pk_fma_f32 v[146:147], v[154:155], v[210:211], v[146:147] op_sel_hi:[1,0,1]
	v_pk_fma_f32 v[148:149], v[156:157], v[210:211], v[148:149] op_sel_hi:[1,0,1]
	ds_read_b32 v212, v104 offset:28640
	ds_read_b128 v[166:169], v2 offset:27360
	s_waitcnt lgkmcnt(10)
	v_pk_fma_f32 v[96:97], v[96:97], v[126:127], v[142:143]
	v_pk_fma_f32 v[98:99], v[98:99], v[128:129], v[144:145]
	v_pk_fma_f32 v[100:101], v[100:101], v[130:131], v[146:147]
	v_pk_fma_f32 v[102:103], v[102:103], v[132:133], v[148:149]
	ds_read_b128 v[170:173], v2 offset:27376
	ds_read_b128 v[200:203], v2 offset:28384
	ds_read_b128 v[204:207], v2 offset:28400
	s_waitcnt lgkmcnt(9)
	v_pk_mul_f32 v[174:175], v[96:97], v[174:175]
	v_pk_mul_f32 v[158:159], v[96:97], v[158:159]
	v_pk_mul_f32 v[178:179], v[100:101], v[178:179]
	v_pk_mul_f32 v[162:163], v[100:101], v[162:163]
	v_pk_fma_f32 v[174:175], v[98:99], v[176:177], v[174:175]
	v_pk_fma_f32 v[158:159], v[98:99], v[160:161], v[158:159]
	v_pk_fma_f32 v[178:179], v[102:103], v[180:181], v[178:179]
	v_pk_fma_f32 v[162:163], v[102:103], v[164:165], v[162:163]
	v_pk_add_f32 v[174:175], v[174:175], v[178:179]
	v_pk_add_f32 v[158:159], v[158:159], v[162:163]
	v_add_f32_e32 v176, v174, v175
	v_add_f32_e32 v214, v158, v159
	ds_read_b128 v[134:137], v2 offset:29056
	v_add_f32_dpp v176, v176, v176 quad_perm:[1,0,3,2] row_mask:0xf bank_mask:0xf bound_ctrl:1
	ds_read_b128 v[138:141], v2 offset:29072
	ds_read_b128 v[142:145], v2 offset:29312
	v_add_f32_dpp v176, v176, v176 quad_perm:[2,3,0,1] row_mask:0xf bank_mask:0xf bound_ctrl:1
	ds_read_b128 v[146:149], v2 offset:29328
	ds_read_b128 v[150:153], v2 offset:29568
	v_add_f32_dpp v176, v176, v176 row_half_mirror row_mask:0xf bank_mask:0xf bound_ctrl:1
	s_waitcnt lgkmcnt(12)
	v_pk_mul_f32 v[182:183], v[182:183], v[176:177] op_sel_hi:[1,0]
	v_pk_mul_f32 v[184:185], v[184:185], v[176:177] op_sel_hi:[1,0]
	v_pk_mul_f32 v[186:187], v[186:187], v[176:177] op_sel_hi:[1,0]
	v_pk_mul_f32 v[188:189], v[188:189], v[176:177] op_sel_hi:[1,0]
	ds_read_b128 v[154:157], v2 offset:29584
	s_waitcnt lgkmcnt(10)
	v_pk_fma_f32 v[182:183], v[192:193], v[212:213], v[182:183] op_sel_hi:[1,0,1]
	v_pk_fma_f32 v[184:185], v[194:195], v[212:213], v[184:185] op_sel_hi:[1,0,1]
	v_pk_fma_f32 v[186:187], v[196:197], v[212:213], v[186:187] op_sel_hi:[1,0,1]
	v_pk_fma_f32 v[188:189], v[198:199], v[212:213], v[188:189] op_sel_hi:[1,0,1]
	ds_read_b32 v210, v104 offset:30080
	ds_read_b128 v[126:129], v2 offset:28800
	s_waitcnt lgkmcnt(10)
	v_pk_fma_f32 v[96:97], v[96:97], v[166:167], v[182:183]
	v_pk_fma_f32 v[98:99], v[98:99], v[168:169], v[184:185]
	v_pk_fma_f32 v[100:101], v[100:101], v[170:171], v[186:187]
	v_pk_fma_f32 v[102:103], v[102:103], v[172:173], v[188:189]
	ds_read_b128 v[130:133], v2 offset:28816
	ds_read_b128 v[158:161], v2 offset:29824
	ds_read_b128 v[162:165], v2 offset:29840
	s_waitcnt lgkmcnt(9)
	v_pk_mul_f32 v[134:135], v[96:97], v[134:135]
	v_pk_mul_f32 v[200:201], v[96:97], v[200:201]
	v_pk_mul_f32 v[138:139], v[100:101], v[138:139]
	v_pk_mul_f32 v[204:205], v[100:101], v[204:205]
	v_pk_fma_f32 v[134:135], v[98:99], v[136:137], v[134:135]
	v_pk_fma_f32 v[200:201], v[98:99], v[202:203], v[200:201]
	v_pk_fma_f32 v[138:139], v[102:103], v[140:141], v[138:139]
	v_pk_fma_f32 v[204:205], v[102:103], v[206:207], v[204:205]
	v_pk_add_f32 v[134:135], v[134:135], v[138:139]
	v_pk_add_f32 v[200:201], v[200:201], v[204:205]
	v_add_f32_e32 v136, v134, v135
	v_add_f32_e32 v215, v200, v201
	ds_read_b128 v[174:177], v2 offset:30496
	v_add_f32_dpp v136, v136, v136 quad_perm:[1,0,3,2] row_mask:0xf bank_mask:0xf bound_ctrl:1
	ds_read_b128 v[178:181], v2 offset:30512
	ds_read_b128 v[182:185], v2 offset:30752
	v_add_f32_dpp v136, v136, v136 quad_perm:[2,3,0,1] row_mask:0xf bank_mask:0xf bound_ctrl:1
	ds_read_b128 v[186:189], v2 offset:30768
	ds_read_b128 v[192:195], v2 offset:31008
	v_add_f32_dpp v136, v136, v136 row_half_mirror row_mask:0xf bank_mask:0xf bound_ctrl:1
	s_waitcnt lgkmcnt(12)
	v_pk_mul_f32 v[142:143], v[142:143], v[136:137] op_sel_hi:[1,0]
	v_pk_mul_f32 v[144:145], v[144:145], v[136:137] op_sel_hi:[1,0]
	v_pk_mul_f32 v[146:147], v[146:147], v[136:137] op_sel_hi:[1,0]
	v_pk_mul_f32 v[148:149], v[148:149], v[136:137] op_sel_hi:[1,0]
	ds_read_b128 v[196:199], v2 offset:31024
	s_waitcnt lgkmcnt(10)
	v_pk_fma_f32 v[142:143], v[150:151], v[210:211], v[142:143] op_sel_hi:[1,0,1]
	v_pk_fma_f32 v[144:145], v[152:153], v[210:211], v[144:145] op_sel_hi:[1,0,1]
	v_pk_fma_f32 v[146:147], v[154:155], v[210:211], v[146:147] op_sel_hi:[1,0,1]
	v_pk_fma_f32 v[148:149], v[156:157], v[210:211], v[148:149] op_sel_hi:[1,0,1]
	ds_read_b32 v212, v104 offset:31520
	ds_read_b128 v[166:169], v2 offset:30240
	s_waitcnt lgkmcnt(10)
	v_pk_fma_f32 v[96:97], v[96:97], v[126:127], v[142:143]
	v_pk_fma_f32 v[98:99], v[98:99], v[128:129], v[144:145]
	v_pk_fma_f32 v[100:101], v[100:101], v[130:131], v[146:147]
	v_pk_fma_f32 v[102:103], v[102:103], v[132:133], v[148:149]
	ds_read_b128 v[170:173], v2 offset:30256
	ds_read_b128 v[200:203], v2 offset:31264
	ds_read_b128 v[204:207], v2 offset:31280
	s_waitcnt lgkmcnt(9)
	v_pk_mul_f32 v[174:175], v[96:97], v[174:175]
	v_pk_mul_f32 v[158:159], v[96:97], v[158:159]
	v_pk_mul_f32 v[178:179], v[100:101], v[178:179]
	v_pk_mul_f32 v[162:163], v[100:101], v[162:163]
	v_pk_fma_f32 v[174:175], v[98:99], v[176:177], v[174:175]
	v_pk_fma_f32 v[158:159], v[98:99], v[160:161], v[158:159]
	v_pk_fma_f32 v[178:179], v[102:103], v[180:181], v[178:179]
	v_pk_fma_f32 v[162:163], v[102:103], v[164:165], v[162:163]
	v_pk_add_f32 v[174:175], v[174:175], v[178:179]
	v_pk_add_f32 v[158:159], v[158:159], v[162:163]
	v_add_f32_e32 v176, v174, v175
	v_add_f32_e32 v216, v158, v159
	ds_read_b128 v[134:137], v2 offset:31936
	v_add_f32_dpp v176, v176, v176 quad_perm:[1,0,3,2] row_mask:0xf bank_mask:0xf bound_ctrl:1
	ds_read_b128 v[138:141], v2 offset:31952
	ds_read_b128 v[142:145], v2 offset:32192
	v_add_f32_dpp v176, v176, v176 quad_perm:[2,3,0,1] row_mask:0xf bank_mask:0xf bound_ctrl:1
	ds_read_b128 v[146:149], v2 offset:32208
	ds_read_b128 v[150:153], v2 offset:32448
	v_add_f32_dpp v176, v176, v176 row_half_mirror row_mask:0xf bank_mask:0xf bound_ctrl:1
	s_waitcnt lgkmcnt(12)
	v_pk_mul_f32 v[182:183], v[182:183], v[176:177] op_sel_hi:[1,0]
	v_pk_mul_f32 v[184:185], v[184:185], v[176:177] op_sel_hi:[1,0]
	v_pk_mul_f32 v[186:187], v[186:187], v[176:177] op_sel_hi:[1,0]
	v_pk_mul_f32 v[188:189], v[188:189], v[176:177] op_sel_hi:[1,0]
	ds_read_b128 v[154:157], v2 offset:32464
	s_waitcnt lgkmcnt(10)
	v_pk_fma_f32 v[182:183], v[192:193], v[212:213], v[182:183] op_sel_hi:[1,0,1]
	v_pk_fma_f32 v[184:185], v[194:195], v[212:213], v[184:185] op_sel_hi:[1,0,1]
	v_pk_fma_f32 v[186:187], v[196:197], v[212:213], v[186:187] op_sel_hi:[1,0,1]
	v_pk_fma_f32 v[188:189], v[198:199], v[212:213], v[188:189] op_sel_hi:[1,0,1]
	ds_read_b32 v210, v104 offset:32960
	ds_read_b128 v[126:129], v2 offset:31680
	s_waitcnt lgkmcnt(10)
	v_pk_fma_f32 v[96:97], v[96:97], v[166:167], v[182:183]
	v_pk_fma_f32 v[98:99], v[98:99], v[168:169], v[184:185]
	v_pk_fma_f32 v[100:101], v[100:101], v[170:171], v[186:187]
	v_pk_fma_f32 v[102:103], v[102:103], v[172:173], v[188:189]
	ds_read_b128 v[130:133], v2 offset:31696
	ds_read_b128 v[158:161], v2 offset:32704
	ds_read_b128 v[162:165], v2 offset:32720
	s_waitcnt lgkmcnt(9)
	v_pk_mul_f32 v[134:135], v[96:97], v[134:135]
	v_pk_mul_f32 v[200:201], v[96:97], v[200:201]
	v_pk_mul_f32 v[138:139], v[100:101], v[138:139]
	v_pk_mul_f32 v[204:205], v[100:101], v[204:205]
	v_pk_fma_f32 v[134:135], v[98:99], v[136:137], v[134:135]
	v_pk_fma_f32 v[200:201], v[98:99], v[202:203], v[200:201]
	v_pk_fma_f32 v[138:139], v[102:103], v[140:141], v[138:139]
	v_pk_fma_f32 v[204:205], v[102:103], v[206:207], v[204:205]
	v_pk_add_f32 v[134:135], v[134:135], v[138:139]
	v_pk_add_f32 v[200:201], v[200:201], v[204:205]
	v_add_f32_e32 v136, v134, v135
	v_add_f32_e32 v208, v200, v201
	ds_read_b128 v[174:177], v2 offset:33376
	v_add_f32_dpp v136, v136, v136 quad_perm:[1,0,3,2] row_mask:0xf bank_mask:0xf bound_ctrl:1
	ds_read_b128 v[178:181], v2 offset:33392
	ds_read_b128 v[182:185], v2 offset:33632
	v_add_f32_dpp v136, v136, v136 quad_perm:[2,3,0,1] row_mask:0xf bank_mask:0xf bound_ctrl:1
	ds_read_b128 v[186:189], v2 offset:33648
	ds_read_b128 v[192:195], v2 offset:33888
	v_add_f32_dpp v136, v136, v136 row_half_mirror row_mask:0xf bank_mask:0xf bound_ctrl:1
	s_waitcnt lgkmcnt(12)
	v_pk_mul_f32 v[142:143], v[142:143], v[136:137] op_sel_hi:[1,0]
	v_pk_mul_f32 v[144:145], v[144:145], v[136:137] op_sel_hi:[1,0]
	v_pk_mul_f32 v[146:147], v[146:147], v[136:137] op_sel_hi:[1,0]
	v_pk_mul_f32 v[148:149], v[148:149], v[136:137] op_sel_hi:[1,0]
	ds_read_b128 v[196:199], v2 offset:33904
	s_waitcnt lgkmcnt(10)
	v_pk_fma_f32 v[142:143], v[150:151], v[210:211], v[142:143] op_sel_hi:[1,0,1]
	v_pk_fma_f32 v[144:145], v[152:153], v[210:211], v[144:145] op_sel_hi:[1,0,1]
	v_pk_fma_f32 v[146:147], v[154:155], v[210:211], v[146:147] op_sel_hi:[1,0,1]
	v_pk_fma_f32 v[148:149], v[156:157], v[210:211], v[148:149] op_sel_hi:[1,0,1]
	ds_read_b32 v212, v104 offset:34400
	ds_read_b128 v[166:169], v2 offset:33120
	s_waitcnt lgkmcnt(10)
	v_pk_fma_f32 v[96:97], v[96:97], v[126:127], v[142:143]
	v_pk_fma_f32 v[98:99], v[98:99], v[128:129], v[144:145]
	v_pk_fma_f32 v[100:101], v[100:101], v[130:131], v[146:147]
	v_pk_fma_f32 v[102:103], v[102:103], v[132:133], v[148:149]
	ds_read_b128 v[170:173], v2 offset:33136
	ds_read_b128 v[200:203], v2 offset:34144
	ds_read_b128 v[204:207], v2 offset:34160
	s_waitcnt lgkmcnt(9)
	v_pk_mul_f32 v[174:175], v[96:97], v[174:175]
	v_pk_mul_f32 v[158:159], v[96:97], v[158:159]
	v_pk_mul_f32 v[178:179], v[100:101], v[178:179]
	v_pk_mul_f32 v[162:163], v[100:101], v[162:163]
	v_pk_fma_f32 v[174:175], v[98:99], v[176:177], v[174:175]
	v_pk_fma_f32 v[158:159], v[98:99], v[160:161], v[158:159]
	v_pk_fma_f32 v[178:179], v[102:103], v[180:181], v[178:179]
	v_pk_fma_f32 v[162:163], v[102:103], v[164:165], v[162:163]
	v_pk_add_f32 v[174:175], v[174:175], v[178:179]
	v_pk_add_f32 v[158:159], v[158:159], v[162:163]
	v_add_f32_e32 v176, v174, v175
	v_add_f32_e32 v191, v158, v159
	ds_read_b128 v[134:137], v2 offset:34816
	v_add_f32_dpp v176, v176, v176 quad_perm:[1,0,3,2] row_mask:0xf bank_mask:0xf bound_ctrl:1
	ds_read_b128 v[138:141], v2 offset:34832
	ds_read_b128 v[142:145], v2 offset:35072
	v_add_f32_dpp v176, v176, v176 quad_perm:[2,3,0,1] row_mask:0xf bank_mask:0xf bound_ctrl:1
	ds_read_b128 v[146:149], v2 offset:35088
	ds_read_b128 v[150:153], v2 offset:35328
	v_add_f32_dpp v176, v176, v176 row_half_mirror row_mask:0xf bank_mask:0xf bound_ctrl:1
	s_waitcnt lgkmcnt(12)
	v_pk_mul_f32 v[182:183], v[182:183], v[176:177] op_sel_hi:[1,0]
	v_pk_mul_f32 v[184:185], v[184:185], v[176:177] op_sel_hi:[1,0]
	v_pk_mul_f32 v[186:187], v[186:187], v[176:177] op_sel_hi:[1,0]
	v_pk_mul_f32 v[188:189], v[188:189], v[176:177] op_sel_hi:[1,0]
	ds_read_b128 v[154:157], v2 offset:35344
	s_waitcnt lgkmcnt(10)
	v_pk_fma_f32 v[182:183], v[192:193], v[212:213], v[182:183] op_sel_hi:[1,0,1]
	v_pk_fma_f32 v[184:185], v[194:195], v[212:213], v[184:185] op_sel_hi:[1,0,1]
	v_pk_fma_f32 v[186:187], v[196:197], v[212:213], v[186:187] op_sel_hi:[1,0,1]
	v_pk_fma_f32 v[188:189], v[198:199], v[212:213], v[188:189] op_sel_hi:[1,0,1]
	ds_read_b32 v210, v104 offset:35840
	ds_read_b128 v[126:129], v2 offset:34560
	s_waitcnt lgkmcnt(10)
	v_pk_fma_f32 v[96:97], v[96:97], v[166:167], v[182:183]
	v_pk_fma_f32 v[98:99], v[98:99], v[168:169], v[184:185]
	v_pk_fma_f32 v[100:101], v[100:101], v[170:171], v[186:187]
	v_pk_fma_f32 v[102:103], v[102:103], v[172:173], v[188:189]
	ds_read_b128 v[130:133], v2 offset:34576
	ds_read_b128 v[158:161], v2 offset:35584
	ds_read_b128 v[162:165], v2 offset:35600
	s_waitcnt lgkmcnt(9)
	v_pk_mul_f32 v[134:135], v[96:97], v[134:135]
	v_pk_mul_f32 v[200:201], v[96:97], v[200:201]
	v_pk_mul_f32 v[138:139], v[100:101], v[138:139]
	v_pk_mul_f32 v[204:205], v[100:101], v[204:205]
	v_pk_fma_f32 v[134:135], v[98:99], v[136:137], v[134:135]
	v_pk_fma_f32 v[200:201], v[98:99], v[202:203], v[200:201]
	v_pk_fma_f32 v[138:139], v[102:103], v[140:141], v[138:139]
	v_pk_fma_f32 v[204:205], v[102:103], v[206:207], v[204:205]
	v_pk_add_f32 v[134:135], v[134:135], v[138:139]
	v_pk_add_f32 v[200:201], v[200:201], v[204:205]
	v_add_f32_e32 v136, v134, v135
	v_add_f32_e32 v59, v200, v201
	ds_read_b128 v[174:177], v2 offset:36256
	v_add_f32_dpp v136, v136, v136 quad_perm:[1,0,3,2] row_mask:0xf bank_mask:0xf bound_ctrl:1
	ds_read_b128 v[178:181], v2 offset:36272
	ds_read_b128 v[182:185], v2 offset:36512
	v_add_f32_dpp v136, v136, v136 quad_perm:[2,3,0,1] row_mask:0xf bank_mask:0xf bound_ctrl:1
	ds_read_b128 v[186:189], v2 offset:36528
	ds_read_b128 v[192:195], v2 offset:36768
	v_add_f32_dpp v136, v136, v136 row_half_mirror row_mask:0xf bank_mask:0xf bound_ctrl:1
	v_cndmask_b32_e64 v200, v213, v211, s[10:11]
	v_cndmask_b32_e64 v204, v211, v213, s[10:11]
	v_cndmask_b32_e64 v201, v215, v214, s[10:11]
	v_cndmask_b32_e64 v205, v214, v215, s[10:11]
	v_cndmask_b32_e64 v202, v208, v216, s[10:11]
	v_cndmask_b32_e64 v206, v216, v208, s[10:11]
	v_cndmask_b32_e64 v203, v59, v191, s[10:11]
	v_cndmask_b32_e64 v207, v191, v59, s[10:11]
	v_add_f32_dpp v200, v204, v200 quad_perm:[1,0,3,2] row_mask:0xf bank_mask:0xf bound_ctrl:1
	v_add_f32_dpp v201, v205, v201 quad_perm:[1,0,3,2] row_mask:0xf bank_mask:0xf bound_ctrl:1
	v_add_f32_dpp v202, v206, v202 quad_perm:[1,0,3,2] row_mask:0xf bank_mask:0xf bound_ctrl:1
	v_add_f32_dpp v203, v207, v203 quad_perm:[1,0,3,2] row_mask:0xf bank_mask:0xf bound_ctrl:1
	v_cndmask_b32_e64 v204, v201, v200, s[12:13]
	v_cndmask_b32_e64 v206, v200, v201, s[12:13]
	v_cndmask_b32_e64 v205, v203, v202, s[12:13]
	v_cndmask_b32_e64 v207, v202, v203, s[12:13]
	v_add_f32_dpp v204, v206, v204 quad_perm:[2,3,0,1] row_mask:0xf bank_mask:0xf bound_ctrl:1
	s_nop 0
	v_add_f32_dpp v205, v207, v205 quad_perm:[2,3,0,1] row_mask:0xf bank_mask:0xf bound_ctrl:1
	v_xor_b32_e32 v202, 4, v121
	v_cndmask_b32_e64 v200, v205, v204, s[14:15]
	v_cndmask_b32_e64 v201, v204, v205, s[14:15]
	v_lshlrev_b32_e32 v202, 2, v202
	ds_bpermute_b32 v201, v202, v201
	s_waitcnt lgkmcnt(0)
	v_add_f32_e32 v200, v200, v201
	ds_write_b32 v105, v200 offset:2048
	v_pk_mul_f32 v[142:143], v[142:143], v[136:137] op_sel_hi:[1,0]
	v_pk_mul_f32 v[144:145], v[144:145], v[136:137] op_sel_hi:[1,0]
	v_pk_mul_f32 v[146:147], v[146:147], v[136:137] op_sel_hi:[1,0]
	v_pk_mul_f32 v[148:149], v[148:149], v[136:137] op_sel_hi:[1,0]
	ds_read_b128 v[196:199], v2 offset:36784
	v_pk_fma_f32 v[142:143], v[150:151], v[210:211], v[142:143] op_sel_hi:[1,0,1]
	v_pk_fma_f32 v[144:145], v[152:153], v[210:211], v[144:145] op_sel_hi:[1,0,1]
	v_pk_fma_f32 v[146:147], v[154:155], v[210:211], v[146:147] op_sel_hi:[1,0,1]
	v_pk_fma_f32 v[148:149], v[156:157], v[210:211], v[148:149] op_sel_hi:[1,0,1]
	ds_read_b32 v212, v104 offset:37280
	ds_read_b128 v[166:169], v2 offset:36000
	v_pk_fma_f32 v[96:97], v[96:97], v[126:127], v[142:143]
	v_pk_fma_f32 v[98:99], v[98:99], v[128:129], v[144:145]
	v_pk_fma_f32 v[100:101], v[100:101], v[130:131], v[146:147]
	v_pk_fma_f32 v[102:103], v[102:103], v[132:133], v[148:149]
	ds_read_b128 v[170:173], v2 offset:36016
	ds_read_b128 v[200:203], v2 offset:37024
	ds_read_b128 v[204:207], v2 offset:37040
	v_pk_mul_f32 v[174:175], v[96:97], v[174:175]
	v_pk_mul_f32 v[158:159], v[96:97], v[158:159]
	v_pk_mul_f32 v[178:179], v[100:101], v[178:179]
	v_pk_mul_f32 v[162:163], v[100:101], v[162:163]
	v_pk_fma_f32 v[174:175], v[98:99], v[176:177], v[174:175]
	v_pk_fma_f32 v[158:159], v[98:99], v[160:161], v[158:159]
	v_pk_fma_f32 v[178:179], v[102:103], v[180:181], v[178:179]
	v_pk_fma_f32 v[162:163], v[102:103], v[164:165], v[162:163]
	v_pk_add_f32 v[174:175], v[174:175], v[178:179]
	v_pk_add_f32 v[158:159], v[158:159], v[162:163]
	v_add_f32_e32 v176, v174, v175
	v_add_f32_e32 v211, v158, v159
	ds_read_b128 v[134:137], v2 offset:37696
	v_add_f32_dpp v176, v176, v176 quad_perm:[1,0,3,2] row_mask:0xf bank_mask:0xf bound_ctrl:1
	ds_read_b128 v[138:141], v2 offset:37712
	ds_read_b128 v[142:145], v2 offset:37952
	v_add_f32_dpp v176, v176, v176 quad_perm:[2,3,0,1] row_mask:0xf bank_mask:0xf bound_ctrl:1
	ds_read_b128 v[146:149], v2 offset:37968
	ds_read_b128 v[150:153], v2 offset:38208
	v_add_f32_dpp v176, v176, v176 row_half_mirror row_mask:0xf bank_mask:0xf bound_ctrl:1
	v_pk_mul_f32 v[182:183], v[182:183], v[176:177] op_sel_hi:[1,0]
	v_pk_mul_f32 v[184:185], v[184:185], v[176:177] op_sel_hi:[1,0]
	v_pk_mul_f32 v[186:187], v[186:187], v[176:177] op_sel_hi:[1,0]
	v_pk_mul_f32 v[188:189], v[188:189], v[176:177] op_sel_hi:[1,0]
	ds_read_b128 v[154:157], v2 offset:38224
	s_waitcnt lgkmcnt(10)
	v_pk_fma_f32 v[182:183], v[192:193], v[212:213], v[182:183] op_sel_hi:[1,0,1]
	v_pk_fma_f32 v[184:185], v[194:195], v[212:213], v[184:185] op_sel_hi:[1,0,1]
	v_pk_fma_f32 v[186:187], v[196:197], v[212:213], v[186:187] op_sel_hi:[1,0,1]
	v_pk_fma_f32 v[188:189], v[198:199], v[212:213], v[188:189] op_sel_hi:[1,0,1]
	ds_read_b32 v210, v104 offset:38720
	ds_read_b128 v[126:129], v2 offset:37440
	s_waitcnt lgkmcnt(10)
	v_pk_fma_f32 v[96:97], v[96:97], v[166:167], v[182:183]
	v_pk_fma_f32 v[98:99], v[98:99], v[168:169], v[184:185]
	v_pk_fma_f32 v[100:101], v[100:101], v[170:171], v[186:187]
	v_pk_fma_f32 v[102:103], v[102:103], v[172:173], v[188:189]
	ds_read_b128 v[130:133], v2 offset:37456
	ds_read_b128 v[158:161], v2 offset:38464
	ds_read_b128 v[162:165], v2 offset:38480
	s_waitcnt lgkmcnt(9)
	v_pk_mul_f32 v[134:135], v[96:97], v[134:135]
	v_pk_mul_f32 v[200:201], v[96:97], v[200:201]
	v_pk_mul_f32 v[138:139], v[100:101], v[138:139]
	v_pk_mul_f32 v[204:205], v[100:101], v[204:205]
	v_pk_fma_f32 v[134:135], v[98:99], v[136:137], v[134:135]
	v_pk_fma_f32 v[200:201], v[98:99], v[202:203], v[200:201]
	v_pk_fma_f32 v[138:139], v[102:103], v[140:141], v[138:139]
	v_pk_fma_f32 v[204:205], v[102:103], v[206:207], v[204:205]
	v_pk_add_f32 v[134:135], v[134:135], v[138:139]
	v_pk_add_f32 v[200:201], v[200:201], v[204:205]
	v_add_f32_e32 v136, v134, v135
	v_add_f32_e32 v213, v200, v201
	ds_read_b128 v[174:177], v2 offset:39136
	v_add_f32_dpp v136, v136, v136 quad_perm:[1,0,3,2] row_mask:0xf bank_mask:0xf bound_ctrl:1
	ds_read_b128 v[178:181], v2 offset:39152
	ds_read_b128 v[182:185], v2 offset:39392
	v_add_f32_dpp v136, v136, v136 quad_perm:[2,3,0,1] row_mask:0xf bank_mask:0xf bound_ctrl:1
	ds_read_b128 v[186:189], v2 offset:39408
	ds_read_b128 v[192:195], v2 offset:39648
	v_add_f32_dpp v136, v136, v136 row_half_mirror row_mask:0xf bank_mask:0xf bound_ctrl:1
	s_waitcnt lgkmcnt(12)
	v_pk_mul_f32 v[142:143], v[142:143], v[136:137] op_sel_hi:[1,0]
	v_pk_mul_f32 v[144:145], v[144:145], v[136:137] op_sel_hi:[1,0]
	v_pk_mul_f32 v[146:147], v[146:147], v[136:137] op_sel_hi:[1,0]
	v_pk_mul_f32 v[148:149], v[148:149], v[136:137] op_sel_hi:[1,0]
	ds_read_b128 v[196:199], v2 offset:39664
	s_waitcnt lgkmcnt(10)
	v_pk_fma_f32 v[142:143], v[150:151], v[210:211], v[142:143] op_sel_hi:[1,0,1]
	v_pk_fma_f32 v[144:145], v[152:153], v[210:211], v[144:145] op_sel_hi:[1,0,1]
	v_pk_fma_f32 v[146:147], v[154:155], v[210:211], v[146:147] op_sel_hi:[1,0,1]
	v_pk_fma_f32 v[148:149], v[156:157], v[210:211], v[148:149] op_sel_hi:[1,0,1]
	ds_read_b32 v212, v104 offset:40160
	ds_read_b128 v[166:169], v2 offset:38880
	s_waitcnt lgkmcnt(10)
	v_pk_fma_f32 v[96:97], v[96:97], v[126:127], v[142:143]
	v_pk_fma_f32 v[98:99], v[98:99], v[128:129], v[144:145]
	v_pk_fma_f32 v[100:101], v[100:101], v[130:131], v[146:147]
	v_pk_fma_f32 v[102:103], v[102:103], v[132:133], v[148:149]
	ds_read_b128 v[170:173], v2 offset:38896
	ds_read_b128 v[200:203], v2 offset:39904
	ds_read_b128 v[204:207], v2 offset:39920
	s_waitcnt lgkmcnt(9)
	v_pk_mul_f32 v[174:175], v[96:97], v[174:175]
	v_pk_mul_f32 v[158:159], v[96:97], v[158:159]
	v_pk_mul_f32 v[178:179], v[100:101], v[178:179]
	v_pk_mul_f32 v[162:163], v[100:101], v[162:163]
	v_pk_fma_f32 v[174:175], v[98:99], v[176:177], v[174:175]
	v_pk_fma_f32 v[158:159], v[98:99], v[160:161], v[158:159]
	v_pk_fma_f32 v[178:179], v[102:103], v[180:181], v[178:179]
	v_pk_fma_f32 v[162:163], v[102:103], v[164:165], v[162:163]
	v_pk_add_f32 v[174:175], v[174:175], v[178:179]
	v_pk_add_f32 v[158:159], v[158:159], v[162:163]
	v_add_f32_e32 v176, v174, v175
	v_add_f32_e32 v214, v158, v159
	ds_read_b128 v[134:137], v2 offset:40576
	v_add_f32_dpp v176, v176, v176 quad_perm:[1,0,3,2] row_mask:0xf bank_mask:0xf bound_ctrl:1
	ds_read_b128 v[138:141], v2 offset:40592
	ds_read_b128 v[142:145], v2 offset:40832
	v_add_f32_dpp v176, v176, v176 quad_perm:[2,3,0,1] row_mask:0xf bank_mask:0xf bound_ctrl:1
	ds_read_b128 v[146:149], v2 offset:40848
	ds_read_b128 v[150:153], v2 offset:41088
	v_add_f32_dpp v176, v176, v176 row_half_mirror row_mask:0xf bank_mask:0xf bound_ctrl:1
	s_waitcnt lgkmcnt(12)
	v_pk_mul_f32 v[182:183], v[182:183], v[176:177] op_sel_hi:[1,0]
	v_pk_mul_f32 v[184:185], v[184:185], v[176:177] op_sel_hi:[1,0]
	v_pk_mul_f32 v[186:187], v[186:187], v[176:177] op_sel_hi:[1,0]
	v_pk_mul_f32 v[188:189], v[188:189], v[176:177] op_sel_hi:[1,0]
	ds_read_b128 v[154:157], v2 offset:41104
	s_waitcnt lgkmcnt(10)
	v_pk_fma_f32 v[182:183], v[192:193], v[212:213], v[182:183] op_sel_hi:[1,0,1]
	v_pk_fma_f32 v[184:185], v[194:195], v[212:213], v[184:185] op_sel_hi:[1,0,1]
	v_pk_fma_f32 v[186:187], v[196:197], v[212:213], v[186:187] op_sel_hi:[1,0,1]
	v_pk_fma_f32 v[188:189], v[198:199], v[212:213], v[188:189] op_sel_hi:[1,0,1]
	ds_read_b32 v210, v104 offset:41600
	ds_read_b128 v[126:129], v2 offset:40320
	s_waitcnt lgkmcnt(10)
	v_pk_fma_f32 v[96:97], v[96:97], v[166:167], v[182:183]
	v_pk_fma_f32 v[98:99], v[98:99], v[168:169], v[184:185]
	v_pk_fma_f32 v[100:101], v[100:101], v[170:171], v[186:187]
	v_pk_fma_f32 v[102:103], v[102:103], v[172:173], v[188:189]
	ds_read_b128 v[130:133], v2 offset:40336
	ds_read_b128 v[158:161], v2 offset:41344
	ds_read_b128 v[162:165], v2 offset:41360
	s_waitcnt lgkmcnt(9)
	v_pk_mul_f32 v[134:135], v[96:97], v[134:135]
	v_pk_mul_f32 v[200:201], v[96:97], v[200:201]
	v_pk_mul_f32 v[138:139], v[100:101], v[138:139]
	v_pk_mul_f32 v[204:205], v[100:101], v[204:205]
	v_pk_fma_f32 v[134:135], v[98:99], v[136:137], v[134:135]
	v_pk_fma_f32 v[200:201], v[98:99], v[202:203], v[200:201]
	v_pk_fma_f32 v[138:139], v[102:103], v[140:141], v[138:139]
	v_pk_fma_f32 v[204:205], v[102:103], v[206:207], v[204:205]
	v_pk_add_f32 v[134:135], v[134:135], v[138:139]
	v_pk_add_f32 v[200:201], v[200:201], v[204:205]
	v_add_f32_e32 v136, v134, v135
	v_add_f32_e32 v215, v200, v201
	ds_read_b128 v[174:177], v2 offset:42016
	v_add_f32_dpp v136, v136, v136 quad_perm:[1,0,3,2] row_mask:0xf bank_mask:0xf bound_ctrl:1
	ds_read_b128 v[178:181], v2 offset:42032
	ds_read_b128 v[182:185], v2 offset:42272
	v_add_f32_dpp v136, v136, v136 quad_perm:[2,3,0,1] row_mask:0xf bank_mask:0xf bound_ctrl:1
	ds_read_b128 v[186:189], v2 offset:42288
	ds_read_b128 v[192:195], v2 offset:42528
	v_add_f32_dpp v136, v136, v136 row_half_mirror row_mask:0xf bank_mask:0xf bound_ctrl:1
	s_waitcnt lgkmcnt(12)
	v_pk_mul_f32 v[142:143], v[142:143], v[136:137] op_sel_hi:[1,0]
	v_pk_mul_f32 v[144:145], v[144:145], v[136:137] op_sel_hi:[1,0]
	v_pk_mul_f32 v[146:147], v[146:147], v[136:137] op_sel_hi:[1,0]
	v_pk_mul_f32 v[148:149], v[148:149], v[136:137] op_sel_hi:[1,0]
	ds_read_b128 v[196:199], v2 offset:42544
	s_waitcnt lgkmcnt(10)
	v_pk_fma_f32 v[142:143], v[150:151], v[210:211], v[142:143] op_sel_hi:[1,0,1]
	v_pk_fma_f32 v[144:145], v[152:153], v[210:211], v[144:145] op_sel_hi:[1,0,1]
	v_pk_fma_f32 v[146:147], v[154:155], v[210:211], v[146:147] op_sel_hi:[1,0,1]
	v_pk_fma_f32 v[148:149], v[156:157], v[210:211], v[148:149] op_sel_hi:[1,0,1]
	ds_read_b32 v212, v104 offset:43040
	ds_read_b128 v[166:169], v2 offset:41760
	s_waitcnt lgkmcnt(10)
	v_pk_fma_f32 v[96:97], v[96:97], v[126:127], v[142:143]
	v_pk_fma_f32 v[98:99], v[98:99], v[128:129], v[144:145]
	v_pk_fma_f32 v[100:101], v[100:101], v[130:131], v[146:147]
	v_pk_fma_f32 v[102:103], v[102:103], v[132:133], v[148:149]
	ds_read_b128 v[170:173], v2 offset:41776
	ds_read_b128 v[200:203], v2 offset:42784
	ds_read_b128 v[204:207], v2 offset:42800
	s_waitcnt lgkmcnt(9)
	v_pk_mul_f32 v[174:175], v[96:97], v[174:175]
	v_pk_mul_f32 v[158:159], v[96:97], v[158:159]
	v_pk_mul_f32 v[178:179], v[100:101], v[178:179]
	v_pk_mul_f32 v[162:163], v[100:101], v[162:163]
	v_pk_fma_f32 v[174:175], v[98:99], v[176:177], v[174:175]
	v_pk_fma_f32 v[158:159], v[98:99], v[160:161], v[158:159]
	v_pk_fma_f32 v[178:179], v[102:103], v[180:181], v[178:179]
	v_pk_fma_f32 v[162:163], v[102:103], v[164:165], v[162:163]
	v_pk_add_f32 v[174:175], v[174:175], v[178:179]
	v_pk_add_f32 v[158:159], v[158:159], v[162:163]
	v_add_f32_e32 v176, v174, v175
	v_add_f32_e32 v216, v158, v159
	ds_read_b128 v[134:137], v2 offset:43456
	v_add_f32_dpp v176, v176, v176 quad_perm:[1,0,3,2] row_mask:0xf bank_mask:0xf bound_ctrl:1
	ds_read_b128 v[138:141], v2 offset:43472
	ds_read_b128 v[142:145], v2 offset:43712
	v_add_f32_dpp v176, v176, v176 quad_perm:[2,3,0,1] row_mask:0xf bank_mask:0xf bound_ctrl:1
	ds_read_b128 v[146:149], v2 offset:43728
	ds_read_b128 v[150:153], v2 offset:43968
	v_add_f32_dpp v176, v176, v176 row_half_mirror row_mask:0xf bank_mask:0xf bound_ctrl:1
	s_waitcnt lgkmcnt(12)
	v_pk_mul_f32 v[182:183], v[182:183], v[176:177] op_sel_hi:[1,0]
	v_pk_mul_f32 v[184:185], v[184:185], v[176:177] op_sel_hi:[1,0]
	v_pk_mul_f32 v[186:187], v[186:187], v[176:177] op_sel_hi:[1,0]
	v_pk_mul_f32 v[188:189], v[188:189], v[176:177] op_sel_hi:[1,0]
	ds_read_b128 v[154:157], v2 offset:43984
	s_waitcnt lgkmcnt(10)
	v_pk_fma_f32 v[182:183], v[192:193], v[212:213], v[182:183] op_sel_hi:[1,0,1]
	v_pk_fma_f32 v[184:185], v[194:195], v[212:213], v[184:185] op_sel_hi:[1,0,1]
	v_pk_fma_f32 v[186:187], v[196:197], v[212:213], v[186:187] op_sel_hi:[1,0,1]
	v_pk_fma_f32 v[188:189], v[198:199], v[212:213], v[188:189] op_sel_hi:[1,0,1]
	ds_read_b32 v210, v104 offset:44480
	ds_read_b128 v[126:129], v2 offset:43200
	s_waitcnt lgkmcnt(10)
	v_pk_fma_f32 v[96:97], v[96:97], v[166:167], v[182:183]
	v_pk_fma_f32 v[98:99], v[98:99], v[168:169], v[184:185]
	v_pk_fma_f32 v[100:101], v[100:101], v[170:171], v[186:187]
	v_pk_fma_f32 v[102:103], v[102:103], v[172:173], v[188:189]
	ds_read_b128 v[130:133], v2 offset:43216
	ds_read_b128 v[158:161], v2 offset:44224
	ds_read_b128 v[162:165], v2 offset:44240
	s_waitcnt lgkmcnt(9)
	v_pk_mul_f32 v[134:135], v[96:97], v[134:135]
	v_pk_mul_f32 v[200:201], v[96:97], v[200:201]
	v_pk_mul_f32 v[138:139], v[100:101], v[138:139]
	v_pk_mul_f32 v[204:205], v[100:101], v[204:205]
	v_pk_fma_f32 v[134:135], v[98:99], v[136:137], v[134:135]
	v_pk_fma_f32 v[200:201], v[98:99], v[202:203], v[200:201]
	v_pk_fma_f32 v[138:139], v[102:103], v[140:141], v[138:139]
	v_pk_fma_f32 v[204:205], v[102:103], v[206:207], v[204:205]
	v_pk_add_f32 v[134:135], v[134:135], v[138:139]
	v_pk_add_f32 v[200:201], v[200:201], v[204:205]
	v_add_f32_e32 v136, v134, v135
	v_add_f32_e32 v208, v200, v201
	ds_read_b128 v[174:177], v2 offset:44896
	v_add_f32_dpp v136, v136, v136 quad_perm:[1,0,3,2] row_mask:0xf bank_mask:0xf bound_ctrl:1
	ds_read_b128 v[178:181], v2 offset:44912
	ds_read_b128 v[182:185], v2 offset:45152
	v_add_f32_dpp v136, v136, v136 quad_perm:[2,3,0,1] row_mask:0xf bank_mask:0xf bound_ctrl:1
	ds_read_b128 v[186:189], v2 offset:45168
	ds_read_b128 v[192:195], v2 offset:45408
	v_add_f32_dpp v136, v136, v136 row_half_mirror row_mask:0xf bank_mask:0xf bound_ctrl:1
	s_waitcnt lgkmcnt(12)
	v_pk_mul_f32 v[142:143], v[142:143], v[136:137] op_sel_hi:[1,0]
	v_pk_mul_f32 v[144:145], v[144:145], v[136:137] op_sel_hi:[1,0]
	v_pk_mul_f32 v[146:147], v[146:147], v[136:137] op_sel_hi:[1,0]
	v_pk_mul_f32 v[148:149], v[148:149], v[136:137] op_sel_hi:[1,0]
	ds_read_b128 v[196:199], v2 offset:45424
	s_waitcnt lgkmcnt(10)
	v_pk_fma_f32 v[142:143], v[150:151], v[210:211], v[142:143] op_sel_hi:[1,0,1]
	v_pk_fma_f32 v[144:145], v[152:153], v[210:211], v[144:145] op_sel_hi:[1,0,1]
	v_pk_fma_f32 v[146:147], v[154:155], v[210:211], v[146:147] op_sel_hi:[1,0,1]
	v_pk_fma_f32 v[148:149], v[156:157], v[210:211], v[148:149] op_sel_hi:[1,0,1]
	ds_read_b32 v212, v104 offset:45920
	ds_read_b128 v[166:169], v2 offset:44640
	s_waitcnt lgkmcnt(10)
	v_pk_fma_f32 v[96:97], v[96:97], v[126:127], v[142:143]
	v_pk_fma_f32 v[98:99], v[98:99], v[128:129], v[144:145]
	v_pk_fma_f32 v[100:101], v[100:101], v[130:131], v[146:147]
	v_pk_fma_f32 v[102:103], v[102:103], v[132:133], v[148:149]
	ds_read_b128 v[170:173], v2 offset:44656
	ds_read_b128 v[200:203], v2 offset:45664
	ds_read_b128 v[204:207], v2 offset:45680
	s_waitcnt lgkmcnt(0)
	v_pk_mul_f32 v[174:175], v[96:97], v[174:175]
	v_pk_mul_f32 v[158:159], v[96:97], v[158:159]
	v_pk_mul_f32 v[178:179], v[100:101], v[178:179]
	v_pk_mul_f32 v[162:163], v[100:101], v[162:163]
	v_pk_fma_f32 v[174:175], v[98:99], v[176:177], v[174:175]
	v_pk_fma_f32 v[158:159], v[98:99], v[160:161], v[158:159]
	v_pk_fma_f32 v[178:179], v[102:103], v[180:181], v[178:179]
	v_pk_fma_f32 v[162:163], v[102:103], v[164:165], v[162:163]
	v_pk_add_f32 v[174:175], v[174:175], v[178:179]
	v_pk_add_f32 v[158:159], v[158:159], v[162:163]
	v_add_f32_e32 v176, v174, v175
	v_add_f32_e32 v191, v158, v159
	s_nop 0
	v_add_f32_dpp v176, v176, v176 quad_perm:[1,0,3,2] row_mask:0xf bank_mask:0xf bound_ctrl:1
	s_nop 1
	v_add_f32_dpp v176, v176, v176 quad_perm:[2,3,0,1] row_mask:0xf bank_mask:0xf bound_ctrl:1
	s_nop 1
	v_add_f32_dpp v176, v176, v176 row_half_mirror row_mask:0xf bank_mask:0xf bound_ctrl:1
	v_pk_mul_f32 v[182:183], v[182:183], v[176:177] op_sel_hi:[1,0]
	v_pk_mul_f32 v[184:185], v[184:185], v[176:177] op_sel_hi:[1,0]
	v_pk_mul_f32 v[186:187], v[186:187], v[176:177] op_sel_hi:[1,0]
	v_pk_mul_f32 v[188:189], v[188:189], v[176:177] op_sel_hi:[1,0]
	v_pk_fma_f32 v[182:183], v[192:193], v[212:213], v[182:183] op_sel_hi:[1,0,1]
	v_pk_fma_f32 v[184:185], v[194:195], v[212:213], v[184:185] op_sel_hi:[1,0,1]
	v_pk_fma_f32 v[186:187], v[196:197], v[212:213], v[186:187] op_sel_hi:[1,0,1]
	v_pk_fma_f32 v[188:189], v[198:199], v[212:213], v[188:189] op_sel_hi:[1,0,1]
	v_pk_fma_f32 v[96:97], v[96:97], v[166:167], v[182:183]
	v_pk_fma_f32 v[98:99], v[98:99], v[168:169], v[184:185]
	v_pk_fma_f32 v[100:101], v[100:101], v[170:171], v[186:187]
	v_pk_fma_f32 v[102:103], v[102:103], v[172:173], v[188:189]
	v_pk_mul_f32 v[200:201], v[96:97], v[200:201]
	v_pk_mul_f32 v[204:205], v[100:101], v[204:205]
	v_pk_fma_f32 v[200:201], v[98:99], v[202:203], v[200:201]
	v_pk_fma_f32 v[204:205], v[102:103], v[206:207], v[204:205]
	s_nop 0
	v_pk_add_f32 v[200:201], v[200:201], v[204:205]
	s_nop 0
	v_add_f32_e32 v59, v200, v201
	v_cndmask_b32_e64 v200, v213, v211, s[10:11]
	v_cndmask_b32_e64 v204, v211, v213, s[10:11]
	v_cndmask_b32_e64 v201, v215, v214, s[10:11]
	v_cndmask_b32_e64 v205, v214, v215, s[10:11]
	v_cndmask_b32_e64 v202, v208, v216, s[10:11]
	v_cndmask_b32_e64 v206, v216, v208, s[10:11]
	v_cndmask_b32_e64 v203, v59, v191, s[10:11]
	v_cndmask_b32_e64 v207, v191, v59, s[10:11]
	v_add_f32_dpp v200, v204, v200 quad_perm:[1,0,3,2] row_mask:0xf bank_mask:0xf bound_ctrl:1
	v_add_f32_dpp v201, v205, v201 quad_perm:[1,0,3,2] row_mask:0xf bank_mask:0xf bound_ctrl:1
	v_add_f32_dpp v202, v206, v202 quad_perm:[1,0,3,2] row_mask:0xf bank_mask:0xf bound_ctrl:1
	v_add_f32_dpp v203, v207, v203 quad_perm:[1,0,3,2] row_mask:0xf bank_mask:0xf bound_ctrl:1
	v_cndmask_b32_e64 v204, v201, v200, s[12:13]
	v_cndmask_b32_e64 v206, v200, v201, s[12:13]
	v_cndmask_b32_e64 v205, v203, v202, s[12:13]
	v_cndmask_b32_e64 v207, v202, v203, s[12:13]
	v_add_f32_dpp v204, v206, v204 quad_perm:[2,3,0,1] row_mask:0xf bank_mask:0xf bound_ctrl:1
	s_nop 0
	v_add_f32_dpp v205, v207, v205 quad_perm:[2,3,0,1] row_mask:0xf bank_mask:0xf bound_ctrl:1
	v_xor_b32_e32 v202, 4, v121
	v_cndmask_b32_e64 v200, v205, v204, s[14:15]
	v_cndmask_b32_e64 v201, v204, v205, s[14:15]
	v_lshlrev_b32_e32 v202, 2, v202
	ds_bpermute_b32 v201, v202, v201
	s_waitcnt lgkmcnt(0)
	v_add_f32_e32 v200, v200, v201
	ds_write_b32 v105, v200 offset:3072

.LBB0_758:
	s_mov_b64 s[4:5], s[0:1]
	s_load_dword s3, s[4:5], 0xe8
	s_waitcnt lgkmcnt(0)
	s_cmp_gt_i32 s3, 6
	s_cbranch_scc1 .LBB0_764
	s_mov_b64 s[4:5], s[0:1]
	s_load_dword s3, s[4:5], 0xec
	s_waitcnt lgkmcnt(0)
	s_cmp_lt_i32 s3, 7
	s_cbranch_scc1 .LBB0_764
	s_cmp_eq_u32 s24, 0x100
	s_cbranch_scc0 .Lpost_orig
	s_load_dwordx2 s[16:17], s[0:1], 0xe0
	s_load_dwordx2 s[4:5], s[0:1], 0xd8
	s_load_dwordx2 s[18:19], s[0:1], 0x70
	s_load_dwordx2 s[20:21], s[0:1], 0x78
	v_lshlrev_b32_e32 v1, 3, v190
	v_lshrrev_b32_e32 v2, 4, v190
	v_lshlrev_b32_e32 v2, 2, v2
	v_lshlrev_b32_e32 v5, 4, v190
	v_mov_b32_e32 v3, 0x260
	v_mov_b32_e32 v4, 0x3a27c5ac
	s_mov_b32 s3, 0xf800000
	s_lshl_b32 s22, s2, 18
	s_lshl_b32 s23, s2, 13
	s_waitcnt lgkmcnt(0)
	global_load_dwordx4 v[8:11], v5, s[18:19]
	global_load_dwordx4 v[12:15], v5, s[20:21]
	s_add_u32 s4, s4, s22
	s_addc_u32 s5, s5, 0
	s_add_u32 s8, s16, 0x1c100000
	s_addc_u32 s9, s17, 0
	s_add_u32 s8, s8, s22
	s_addc_u32 s9, s9, 0
	s_add_u32 s10, s16, 0x20100000
	s_addc_u32 s11, s17, 0
	s_add_u32 s10, s10, s22
	s_addc_u32 s11, s11, 0
	s_add_u32 s12, s16, 0x24100000
	s_addc_u32 s13, s17, 0
	s_add_u32 s12, s12, s23
	s_addc_u32 s13, s13, 0
	s_add_u32 s14, s16, 0x24300000
	s_addc_u32 s15, s17, 0
	s_add_u32 s14, s14, s22
	s_addc_u32 s15, s15, 0
	global_load_dwordx2 v[16:17], v1, s[4:5] nt
	global_load_dwordx2 v[18:19], v1, s[8:9] nt
	global_load_dwordx2 v[20:21], v1, s[10:11] nt
	global_load_dword v22, v2, s[12:13] nt
	s_add_u32 s4, s4, 0x1000
	s_addc_u32 s5, s5, 0
	s_add_u32 s8, s8, 0x1000
	s_addc_u32 s9, s9, 0
	s_add_u32 s10, s10, 0x1000
	s_addc_u32 s11, s11, 0
	s_add_u32 s12, s12, 0x80
	s_addc_u32 s13, s13, 0
	global_load_dwordx2 v[24:25], v1, s[4:5] nt
	global_load_dwordx2 v[26:27], v1, s[8:9] nt
	global_load_dwordx2 v[28:29], v1, s[10:11] nt
	global_load_dword v30, v2, s[12:13] nt
	s_add_u32 s4, s4, 0x1000
	s_addc_u32 s5, s5, 0
	s_add_u32 s8, s8, 0x1000
	s_addc_u32 s9, s9, 0
	s_add_u32 s10, s10, 0x1000
	s_addc_u32 s11, s11, 0
	s_add_u32 s12, s12, 0x80
	s_addc_u32 s13, s13, 0
	global_load_dwordx2 v[32:33], v1, s[4:5] nt
	global_load_dwordx2 v[34:35], v1, s[8:9] nt
	global_load_dwordx2 v[36:37], v1, s[10:11] nt
	global_load_dword v38, v2, s[12:13] nt
	s_add_u32 s4, s4, 0x1000
	s_addc_u32 s5, s5, 0
	s_add_u32 s8, s8, 0x1000
	s_addc_u32 s9, s9, 0
	s_add_u32 s10, s10, 0x1000
	s_addc_u32 s11, s11, 0
	s_add_u32 s12, s12, 0x80
	s_addc_u32 s13, s13, 0
	global_load_dwordx2 v[40:41], v1, s[4:5] nt
	global_load_dwordx2 v[42:43], v1, s[8:9] nt
	global_load_dwordx2 v[44:45], v1, s[10:11] nt
	global_load_dword v46, v2, s[12:13] nt
	s_add_u32 s4, s4, 0x1000
	s_addc_u32 s5, s5, 0
	s_add_u32 s8, s8, 0x1000
	s_addc_u32 s9, s9, 0
	s_add_u32 s10, s10, 0x1000
	s_addc_u32 s11, s11, 0
	s_add_u32 s12, s12, 0x80
	s_addc_u32 s13, s13, 0
	global_load_dword v80, v2, s[12:13]
	global_load_dword v81, v2, s[12:13]
	global_load_dword v82, v2, s[12:13]
	global_load_dword v83, v2, s[12:13]
	s_mov_b32 s26, 8
.Lpost_loop:
	global_load_dwordx2 v[48:49], v1, s[4:5] nt
	global_load_dwordx2 v[50:51], v1, s[8:9] nt
	global_load_dwordx2 v[52:53], v1, s[10:11] nt
	global_load_dword v54, v2, s[12:13] nt
	s_add_u32 s4, s4, 0x1000
	s_addc_u32 s5, s5, 0
	s_add_u32 s8, s8, 0x1000
	s_addc_u32 s9, s9, 0
	s_add_u32 s10, s10, 0x1000
	s_addc_u32 s11, s11, 0
	s_add_u32 s12, s12, 0x80
	s_addc_u32 s13, s13, 0
	global_load_dwordx2 v[56:57], v1, s[4:5] nt
	global_load_dwordx2 v[58:59], v1, s[8:9] nt
	global_load_dwordx2 v[60:61], v1, s[10:11] nt
	global_load_dword v62, v2, s[12:13] nt
	s_add_u32 s4, s4, 0x1000
	s_addc_u32 s5, s5, 0
	s_add_u32 s8, s8, 0x1000
	s_addc_u32 s9, s9, 0
	s_add_u32 s10, s10, 0x1000
	s_addc_u32 s11, s11, 0
	s_add_u32 s12, s12, 0x80
	s_addc_u32 s13, s13, 0
	global_load_dwordx2 v[64:65], v1, s[4:5] nt
	global_load_dwordx2 v[66:67], v1, s[8:9] nt
	global_load_dwordx2 v[68:69], v1, s[10:11] nt
	global_load_dword v70, v2, s[12:13] nt
	s_add_u32 s4, s4, 0x1000
	s_addc_u32 s5, s5, 0
	s_add_u32 s8, s8, 0x1000
	s_addc_u32 s9, s9, 0
	s_add_u32 s10, s10, 0x1000
	s_addc_u32 s11, s11, 0
	s_add_u32 s12, s12, 0x80
	s_addc_u32 s13, s13, 0
	global_load_dwordx2 v[72:73], v1, s[4:5] nt
	global_load_dwordx2 v[74:75], v1, s[8:9] nt
	global_load_dwordx2 v[76:77], v1, s[10:11] nt
	global_load_dword v78, v2, s[12:13] nt
	s_add_u32 s4, s4, 0x1000
	s_addc_u32 s5, s5, 0
	s_add_u32 s8, s8, 0x1000
	s_addc_u32 s9, s9, 0
	s_add_u32 s10, s10, 0x1000
	s_addc_u32 s11, s11, 0
	s_add_u32 s12, s12, 0x80
	s_addc_u32 s13, s13, 0
	s_waitcnt vmcnt(32)
	v_lshlrev_b32_e32 v85, 16, v17
	v_lshlrev_b32_e32 v84, 16, v16
	v_and_b32_e32 v17, 0xffff0000, v17
	v_and_b32_e32 v16, 0xffff0000, v16
	v_pk_add_f32 v[86:87], v[84:85], v[16:17]
	v_lshlrev_b32_e32 v88, 16, v18
	v_add_f32_e32 v86, v86, v87
	v_and_b32_e32 v89, 0xffff0000, v18
	v_lshlrev_b32_e32 v90, 16, v19
	v_add_f32_dpp v86, v86, v86 quad_perm:[1,0,3,2] row_mask:0xf bank_mask:0xf bound_ctrl:1
	v_and_b32_e32 v91, 0xffff0000, v19
	v_lshlrev_b32_e32 v92, 16, v20
	v_add_f32_dpp v86, v86, v86 quad_perm:[2,3,0,1] row_mask:0xf bank_mask:0xf bound_ctrl:1
	v_and_b32_e32 v93, 0xffff0000, v20
	v_lshlrev_b32_e32 v94, 16, v21
	v_add_f32_dpp v86, v86, v86 row_half_mirror row_mask:0xf bank_mask:0xf bound_ctrl:1
	v_and_b32_e32 v95, 0xffff0000, v21
	s_nop 0
	v_add_f32_dpp v86, v86, v86 row_ror:8 row_mask:0xf bank_mask:0xf bound_ctrl:1
	v_fmac_f32_e32 v16, 0xbc800000, v86
	v_fmac_f32_e32 v17, 0xbc800000, v86
	v_fmac_f32_e32 v85, 0xbc800000, v86
	v_fmac_f32_e32 v84, 0xbc800000, v86
	v_mov_b32_e32 v86, v85
	v_mov_b32_e32 v87, v17
	v_mov_b32_e32 v85, v16
	v_pk_mul_f32 v[96:97], v[86:87], v[86:87]
	v_pk_mul_f32 v[98:99], v[84:85], v[84:85]
	s_nop 0
	v_pk_mov_b32 v[100:101], v[98:99], v[96:97] op_sel:[1,0]
	v_mov_b32_e32 v99, v97
	v_pk_add_f32 v[96:97], v[100:101], v[98:99]
	s_nop 0
	v_add_f32_e32 v96, v96, v97
	s_nop 1
	v_add_f32_dpp v96, v96, v96 quad_perm:[1,0,3,2] row_mask:0xf bank_mask:0xf bound_ctrl:1
	s_nop 1
	v_add_f32_dpp v96, v96, v96 quad_perm:[2,3,0,1] row_mask:0xf bank_mask:0xf bound_ctrl:1
	s_nop 1
	v_add_f32_dpp v96, v96, v96 row_half_mirror row_mask:0xf bank_mask:0xf bound_ctrl:1
	s_nop 1
	v_add_f32_dpp v96, v96, v96 row_ror:8 row_mask:0xf bank_mask:0xf bound_ctrl:1
	v_fmamk_f32 v96, v96, 0x3c800000, v4
	v_mul_f32_e32 v97, 0x4f800000, v96
	v_cmp_gt_f32_e32 vcc, s3, v96
	s_nop 1
	v_cndmask_b32_e32 v96, v96, v97, vcc
	v_sqrt_f32_e32 v97, v96
	s_nop 0
	v_add_u32_e32 v98, -1, v97
	v_add_u32_e32 v99, 1, v97
	v_fma_f32 v100, -v98, v97, v96
	v_fma_f32 v101, -v99, v97, v96
	v_cmp_ge_f32_e64 s[6:7], 0, v100
	s_nop 1
	v_cndmask_b32_e64 v97, v97, v98, s[6:7]
	v_cmp_lt_f32_e64 s[6:7], 0, v101
	s_nop 1
	v_cndmask_b32_e64 v97, v97, v99, s[6:7]
	v_mul_f32_e32 v98, 0x37800000, v97
	v_cndmask_b32_e32 v97, v97, v98, vcc
	v_cmp_class_f32_e32 vcc, v96, v3
	s_nop 1
	v_cndmask_b32_e32 v96, v97, v96, vcc
	v_div_scale_f32 v97, s[6:7], v96, v96, 1.0
	v_rcp_f32_e32 v99, v97
	v_div_scale_f32 v98, vcc, 1.0, v96, 1.0
	v_fma_f32 v100, -v97, v99, 1.0
	v_fmac_f32_e32 v99, v100, v99
	v_mul_f32_e32 v100, v98, v99
	v_fma_f32 v101, -v97, v100, v98
	v_fmac_f32_e32 v100, v101, v99
	v_fma_f32 v97, -v97, v100, v98
	v_div_fmas_f32 v97, v97, v99, v100
	v_div_fixup_f32 v96, v97, v96, 1.0
	v_pk_mul_f32 v[84:85], v[84:85], v[96:97] op_sel_hi:[1,0]
	v_pk_mul_f32 v[96:97], v[86:87], v[96:97] op_sel_hi:[1,0]
	s_nop 0
	v_pk_fma_f32 v[102:103], v[8:9], v[84:85], v[12:13]
	v_pk_fma_f32 v[104:105], v[10:11], v[96:97], v[14:15]
	s_nop 0
	v_pk_fma_f32 v[102:103], v[22:23], v[88:89], v[102:103] op_sel_hi:[0,1,1]
	v_pk_fma_f32 v[104:105], v[22:23], v[90:91], v[104:105] op_sel_hi:[0,1,1]
	s_nop 0
	v_pk_mul_f32 v[104:105], v[104:105], v[94:95]
	v_pk_mul_f32 v[102:103], v[102:103], v[92:93]
	s_nop 0
	v_cvt_pk_bf16_f32 v102, v102, v103
	v_cvt_pk_bf16_f32 v103, v104, v105
	global_store_dwordx2 v1, v[102:103], s[14:15]
	s_add_u32 s14, s14, 0x1000
	s_addc_u32 s15, s15, 0
	s_waitcnt vmcnt(29)
	v_lshlrev_b32_e32 v85, 16, v25
	v_lshlrev_b32_e32 v84, 16, v24
	v_and_b32_e32 v25, 0xffff0000, v25
	v_and_b32_e32 v24, 0xffff0000, v24
	v_pk_add_f32 v[86:87], v[84:85], v[24:25]
	v_lshlrev_b32_e32 v88, 16, v26
	v_add_f32_e32 v86, v86, v87
	v_and_b32_e32 v89, 0xffff0000, v26
	v_lshlrev_b32_e32 v90, 16, v27
	v_add_f32_dpp v86, v86, v86 quad_perm:[1,0,3,2] row_mask:0xf bank_mask:0xf bound_ctrl:1
	v_and_b32_e32 v91, 0xffff0000, v27
	v_lshlrev_b32_e32 v92, 16, v28
	v_add_f32_dpp v86, v86, v86 quad_perm:[2,3,0,1] row_mask:0xf bank_mask:0xf bound_ctrl:1
	v_and_b32_e32 v93, 0xffff0000, v28
	v_lshlrev_b32_e32 v94, 16, v29
	v_add_f32_dpp v86, v86, v86 row_half_mirror row_mask:0xf bank_mask:0xf bound_ctrl:1
	v_and_b32_e32 v95, 0xffff0000, v29
	s_nop 0
	v_add_f32_dpp v86, v86, v86 row_ror:8 row_mask:0xf bank_mask:0xf bound_ctrl:1
	v_fmac_f32_e32 v24, 0xbc800000, v86
	v_fmac_f32_e32 v25, 0xbc800000, v86
	v_fmac_f32_e32 v85, 0xbc800000, v86
	v_fmac_f32_e32 v84, 0xbc800000, v86
	v_mov_b32_e32 v86, v85
	v_mov_b32_e32 v87, v25
	v_mov_b32_e32 v85, v24
	v_pk_mul_f32 v[96:97], v[86:87], v[86:87]
	v_pk_mul_f32 v[98:99], v[84:85], v[84:85]
	s_nop 0
	v_pk_mov_b32 v[100:101], v[98:99], v[96:97] op_sel:[1,0]
	v_mov_b32_e32 v99, v97
	v_pk_add_f32 v[96:97], v[100:101], v[98:99]
	s_nop 0
	v_add_f32_e32 v96, v96, v97
	s_nop 1
	v_add_f32_dpp v96, v96, v96 quad_perm:[1,0,3,2] row_mask:0xf bank_mask:0xf bound_ctrl:1
	s_nop 1
	v_add_f32_dpp v96, v96, v96 quad_perm:[2,3,0,1] row_mask:0xf bank_mask:0xf bound_ctrl:1
	s_nop 1
	v_add_f32_dpp v96, v96, v96 row_half_mirror row_mask:0xf bank_mask:0xf bound_ctrl:1
	s_nop 1
	v_add_f32_dpp v96, v96, v96 row_ror:8 row_mask:0xf bank_mask:0xf bound_ctrl:1
	v_fmamk_f32 v96, v96, 0x3c800000, v4
	v_mul_f32_e32 v97, 0x4f800000, v96
	v_cmp_gt_f32_e32 vcc, s3, v96
	s_nop 1
	v_cndmask_b32_e32 v96, v96, v97, vcc
	v_sqrt_f32_e32 v97, v96
	s_nop 0
	v_add_u32_e32 v98, -1, v97
	v_add_u32_e32 v99, 1, v97
	v_fma_f32 v100, -v98, v97, v96
	v_fma_f32 v101, -v99, v97, v96
	v_cmp_ge_f32_e64 s[6:7], 0, v100
	s_nop 1
	v_cndmask_b32_e64 v97, v97, v98, s[6:7]
	v_cmp_lt_f32_e64 s[6:7], 0, v101
	s_nop 1
	v_cndmask_b32_e64 v97, v97, v99, s[6:7]
	v_mul_f32_e32 v98, 0x37800000, v97
	v_cndmask_b32_e32 v97, v97, v98, vcc
	v_cmp_class_f32_e32 vcc, v96, v3
	s_nop 1
	v_cndmask_b32_e32 v96, v97, v96, vcc
	v_div_scale_f32 v97, s[6:7], v96, v96, 1.0
	v_rcp_f32_e32 v99, v97
	v_div_scale_f32 v98, vcc, 1.0, v96, 1.0
	v_fma_f32 v100, -v97, v99, 1.0
	v_fmac_f32_e32 v99, v100, v99
	v_mul_f32_e32 v100, v98, v99
	v_fma_f32 v101, -v97, v100, v98
	v_fmac_f32_e32 v100, v101, v99
	v_fma_f32 v97, -v97, v100, v98
	v_div_fmas_f32 v97, v97, v99, v100
	v_div_fixup_f32 v96, v97, v96, 1.0
	v_pk_mul_f32 v[84:85], v[84:85], v[96:97] op_sel_hi:[1,0]
	v_pk_mul_f32 v[96:97], v[86:87], v[96:97] op_sel_hi:[1,0]
	s_nop 0
	v_pk_fma_f32 v[102:103], v[8:9], v[84:85], v[12:13]
	v_pk_fma_f32 v[104:105], v[10:11], v[96:97], v[14:15]
	s_nop 0
	v_pk_fma_f32 v[102:103], v[30:31], v[88:89], v[102:103] op_sel_hi:[0,1,1]
	v_pk_fma_f32 v[104:105], v[30:31], v[90:91], v[104:105] op_sel_hi:[0,1,1]
	s_nop 0
	v_pk_mul_f32 v[104:105], v[104:105], v[94:95]
	v_pk_mul_f32 v[102:103], v[102:103], v[92:93]
	s_nop 0
	v_cvt_pk_bf16_f32 v102, v102, v103
	v_cvt_pk_bf16_f32 v103, v104, v105
	global_store_dwordx2 v1, v[102:103], s[14:15]
	s_add_u32 s14, s14, 0x1000
	s_addc_u32 s15, s15, 0
	s_waitcnt vmcnt(26)
	v_lshlrev_b32_e32 v85, 16, v33
	v_lshlrev_b32_e32 v84, 16, v32
	v_and_b32_e32 v33, 0xffff0000, v33
	v_and_b32_e32 v32, 0xffff0000, v32
	v_pk_add_f32 v[86:87], v[84:85], v[32:33]
	v_lshlrev_b32_e32 v88, 16, v34
	v_add_f32_e32 v86, v86, v87
	v_and_b32_e32 v89, 0xffff0000, v34
	v_lshlrev_b32_e32 v90, 16, v35
	v_add_f32_dpp v86, v86, v86 quad_perm:[1,0,3,2] row_mask:0xf bank_mask:0xf bound_ctrl:1
	v_and_b32_e32 v91, 0xffff0000, v35
	v_lshlrev_b32_e32 v92, 16, v36
	v_add_f32_dpp v86, v86, v86 quad_perm:[2,3,0,1] row_mask:0xf bank_mask:0xf bound_ctrl:1
	v_and_b32_e32 v93, 0xffff0000, v36
	v_lshlrev_b32_e32 v94, 16, v37
	v_add_f32_dpp v86, v86, v86 row_half_mirror row_mask:0xf bank_mask:0xf bound_ctrl:1
	v_and_b32_e32 v95, 0xffff0000, v37
	s_nop 0
	v_add_f32_dpp v86, v86, v86 row_ror:8 row_mask:0xf bank_mask:0xf bound_ctrl:1
	v_fmac_f32_e32 v32, 0xbc800000, v86
	v_fmac_f32_e32 v33, 0xbc800000, v86
	v_fmac_f32_e32 v85, 0xbc800000, v86
	v_fmac_f32_e32 v84, 0xbc800000, v86
	v_mov_b32_e32 v86, v85
	v_mov_b32_e32 v87, v33
	v_mov_b32_e32 v85, v32
	v_pk_mul_f32 v[96:97], v[86:87], v[86:87]
	v_pk_mul_f32 v[98:99], v[84:85], v[84:85]
	s_nop 0
	v_pk_mov_b32 v[100:101], v[98:99], v[96:97] op_sel:[1,0]
	v_mov_b32_e32 v99, v97
	v_pk_add_f32 v[96:97], v[100:101], v[98:99]
	s_nop 0
	v_add_f32_e32 v96, v96, v97
	s_nop 1
	v_add_f32_dpp v96, v96, v96 quad_perm:[1,0,3,2] row_mask:0xf bank_mask:0xf bound_ctrl:1
	s_nop 1
	v_add_f32_dpp v96, v96, v96 quad_perm:[2,3,0,1] row_mask:0xf bank_mask:0xf bound_ctrl:1
	s_nop 1
	v_add_f32_dpp v96, v96, v96 row_half_mirror row_mask:0xf bank_mask:0xf bound_ctrl:1
	s_nop 1
	v_add_f32_dpp v96, v96, v96 row_ror:8 row_mask:0xf bank_mask:0xf bound_ctrl:1
	v_fmamk_f32 v96, v96, 0x3c800000, v4
	v_mul_f32_e32 v97, 0x4f800000, v96
	v_cmp_gt_f32_e32 vcc, s3, v96
	s_nop 1
	v_cndmask_b32_e32 v96, v96, v97, vcc
	v_sqrt_f32_e32 v97, v96
	s_nop 0
	v_add_u32_e32 v98, -1, v97
	v_add_u32_e32 v99, 1, v97
	v_fma_f32 v100, -v98, v97, v96
	v_fma_f32 v101, -v99, v97, v96
	v_cmp_ge_f32_e64 s[6:7], 0, v100
	s_nop 1
	v_cndmask_b32_e64 v97, v97, v98, s[6:7]
	v_cmp_lt_f32_e64 s[6:7], 0, v101
	s_nop 1
	v_cndmask_b32_e64 v97, v97, v99, s[6:7]
	v_mul_f32_e32 v98, 0x37800000, v97
	v_cndmask_b32_e32 v97, v97, v98, vcc
	v_cmp_class_f32_e32 vcc, v96, v3
	s_nop 1
	v_cndmask_b32_e32 v96, v97, v96, vcc
	v_div_scale_f32 v97, s[6:7], v96, v96, 1.0
	v_rcp_f32_e32 v99, v97
	v_div_scale_f32 v98, vcc, 1.0, v96, 1.0
	v_fma_f32 v100, -v97, v99, 1.0
	v_fmac_f32_e32 v99, v100, v99
	v_mul_f32_e32 v100, v98, v99
	v_fma_f32 v101, -v97, v100, v98
	v_fmac_f32_e32 v100, v101, v99
	v_fma_f32 v97, -v97, v100, v98
	v_div_fmas_f32 v97, v97, v99, v100
	v_div_fixup_f32 v96, v97, v96, 1.0
	v_pk_mul_f32 v[84:85], v[84:85], v[96:97] op_sel_hi:[1,0]
	v_pk_mul_f32 v[96:97], v[86:87], v[96:97] op_sel_hi:[1,0]
	s_nop 0
	v_pk_fma_f32 v[102:103], v[8:9], v[84:85], v[12:13]
	v_pk_fma_f32 v[104:105], v[10:11], v[96:97], v[14:15]
	s_nop 0
	v_pk_fma_f32 v[102:103], v[38:39], v[88:89], v[102:103] op_sel_hi:[0,1,1]
	v_pk_fma_f32 v[104:105], v[38:39], v[90:91], v[104:105] op_sel_hi:[0,1,1]
	s_nop 0
	v_pk_mul_f32 v[104:105], v[104:105], v[94:95]
	v_pk_mul_f32 v[102:103], v[102:103], v[92:93]
	s_nop 0
	v_cvt_pk_bf16_f32 v102, v102, v103
	v_cvt_pk_bf16_f32 v103, v104, v105
	global_store_dwordx2 v1, v[102:103], s[14:15]
	s_add_u32 s14, s14, 0x1000
	s_addc_u32 s15, s15, 0
	s_waitcnt vmcnt(23)
	v_lshlrev_b32_e32 v85, 16, v41
	v_lshlrev_b32_e32 v84, 16, v40
	v_and_b32_e32 v41, 0xffff0000, v41
	v_and_b32_e32 v40, 0xffff0000, v40
	v_pk_add_f32 v[86:87], v[84:85], v[40:41]
	v_lshlrev_b32_e32 v88, 16, v42
	v_add_f32_e32 v86, v86, v87
	v_and_b32_e32 v89, 0xffff0000, v42
	v_lshlrev_b32_e32 v90, 16, v43
	v_add_f32_dpp v86, v86, v86 quad_perm:[1,0,3,2] row_mask:0xf bank_mask:0xf bound_ctrl:1
	v_and_b32_e32 v91, 0xffff0000, v43
	v_lshlrev_b32_e32 v92, 16, v44
	v_add_f32_dpp v86, v86, v86 quad_perm:[2,3,0,1] row_mask:0xf bank_mask:0xf bound_ctrl:1
	v_and_b32_e32 v93, 0xffff0000, v44
	v_lshlrev_b32_e32 v94, 16, v45
	v_add_f32_dpp v86, v86, v86 row_half_mirror row_mask:0xf bank_mask:0xf bound_ctrl:1
	v_and_b32_e32 v95, 0xffff0000, v45
	s_nop 0
	v_add_f32_dpp v86, v86, v86 row_ror:8 row_mask:0xf bank_mask:0xf bound_ctrl:1
	v_fmac_f32_e32 v40, 0xbc800000, v86
	v_fmac_f32_e32 v41, 0xbc800000, v86
	v_fmac_f32_e32 v85, 0xbc800000, v86
	v_fmac_f32_e32 v84, 0xbc800000, v86
	v_mov_b32_e32 v86, v85
	v_mov_b32_e32 v87, v41
	v_mov_b32_e32 v85, v40
	v_pk_mul_f32 v[96:97], v[86:87], v[86:87]
	v_pk_mul_f32 v[98:99], v[84:85], v[84:85]
	s_nop 0
	v_pk_mov_b32 v[100:101], v[98:99], v[96:97] op_sel:[1,0]
	v_mov_b32_e32 v99, v97
	v_pk_add_f32 v[96:97], v[100:101], v[98:99]
	s_nop 0
	v_add_f32_e32 v96, v96, v97
	s_nop 1
	v_add_f32_dpp v96, v96, v96 quad_perm:[1,0,3,2] row_mask:0xf bank_mask:0xf bound_ctrl:1
	s_nop 1
	v_add_f32_dpp v96, v96, v96 quad_perm:[2,3,0,1] row_mask:0xf bank_mask:0xf bound_ctrl:1
	s_nop 1
	v_add_f32_dpp v96, v96, v96 row_half_mirror row_mask:0xf bank_mask:0xf bound_ctrl:1
	s_nop 1
	v_add_f32_dpp v96, v96, v96 row_ror:8 row_mask:0xf bank_mask:0xf bound_ctrl:1
	v_fmamk_f32 v96, v96, 0x3c800000, v4
	v_mul_f32_e32 v97, 0x4f800000, v96
	v_cmp_gt_f32_e32 vcc, s3, v96
	s_nop 1
	v_cndmask_b32_e32 v96, v96, v97, vcc
	v_sqrt_f32_e32 v97, v96
	s_nop 0
	v_add_u32_e32 v98, -1, v97
	v_add_u32_e32 v99, 1, v97
	v_fma_f32 v100, -v98, v97, v96
	v_fma_f32 v101, -v99, v97, v96
	v_cmp_ge_f32_e64 s[6:7], 0, v100
	s_nop 1
	v_cndmask_b32_e64 v97, v97, v98, s[6:7]
	v_cmp_lt_f32_e64 s[6:7], 0, v101
	s_nop 1
	v_cndmask_b32_e64 v97, v97, v99, s[6:7]
	v_mul_f32_e32 v98, 0x37800000, v97
	v_cndmask_b32_e32 v97, v97, v98, vcc
	v_cmp_class_f32_e32 vcc, v96, v3
	s_nop 1
	v_cndmask_b32_e32 v96, v97, v96, vcc
	v_div_scale_f32 v97, s[6:7], v96, v96, 1.0
	v_rcp_f32_e32 v99, v97
	v_div_scale_f32 v98, vcc, 1.0, v96, 1.0
	v_fma_f32 v100, -v97, v99, 1.0
	v_fmac_f32_e32 v99, v100, v99
	v_mul_f32_e32 v100, v98, v99
	v_fma_f32 v101, -v97, v100, v98
	v_fmac_f32_e32 v100, v101, v99
	v_fma_f32 v97, -v97, v100, v98
	v_div_fmas_f32 v97, v97, v99, v100
	v_div_fixup_f32 v96, v97, v96, 1.0
	v_pk_mul_f32 v[84:85], v[84:85], v[96:97] op_sel_hi:[1,0]
	v_pk_mul_f32 v[96:97], v[86:87], v[96:97] op_sel_hi:[1,0]
	s_nop 0
	v_pk_fma_f32 v[102:103], v[8:9], v[84:85], v[12:13]
	v_pk_fma_f32 v[104:105], v[10:11], v[96:97], v[14:15]
	s_nop 0
	v_pk_fma_f32 v[102:103], v[46:47], v[88:89], v[102:103] op_sel_hi:[0,1,1]
	v_pk_fma_f32 v[104:105], v[46:47], v[90:91], v[104:105] op_sel_hi:[0,1,1]
	s_nop 0
	v_pk_mul_f32 v[104:105], v[104:105], v[94:95]
	v_pk_mul_f32 v[102:103], v[102:103], v[92:93]
	s_nop 0
	v_cvt_pk_bf16_f32 v102, v102, v103
	v_cvt_pk_bf16_f32 v103, v104, v105
	global_store_dwordx2 v1, v[102:103], s[14:15]
	s_add_u32 s14, s14, 0x1000
	s_addc_u32 s15, s15, 0
	global_load_dwordx2 v[16:17], v1, s[4:5] nt
	global_load_dwordx2 v[18:19], v1, s[8:9] nt
	global_load_dwordx2 v[20:21], v1, s[10:11] nt
	global_load_dword v22, v2, s[12:13] nt
	s_add_u32 s4, s4, 0x1000
	s_addc_u32 s5, s5, 0
	s_add_u32 s8, s8, 0x1000
	s_addc_u32 s9, s9, 0
	s_add_u32 s10, s10, 0x1000
	s_addc_u32 s11, s11, 0
	s_add_u32 s12, s12, 0x80
	s_addc_u32 s13, s13, 0
	global_load_dwordx2 v[24:25], v1, s[4:5] nt
	global_load_dwordx2 v[26:27], v1, s[8:9] nt
	global_load_dwordx2 v[28:29], v1, s[10:11] nt
	global_load_dword v30, v2, s[12:13] nt
	s_add_u32 s4, s4, 0x1000
	s_addc_u32 s5, s5, 0
	s_add_u32 s8, s8, 0x1000
	s_addc_u32 s9, s9, 0
	s_add_u32 s10, s10, 0x1000
	s_addc_u32 s11, s11, 0
	s_add_u32 s12, s12, 0x80
	s_addc_u32 s13, s13, 0
	global_load_dwordx2 v[32:33], v1, s[4:5] nt
	global_load_dwordx2 v[34:35], v1, s[8:9] nt
	global_load_dwordx2 v[36:37], v1, s[10:11] nt
	global_load_dword v38, v2, s[12:13] nt
	s_add_u32 s4, s4, 0x1000
	s_addc_u32 s5, s5, 0
	s_add_u32 s8, s8, 0x1000
	s_addc_u32 s9, s9, 0
	s_add_u32 s10, s10, 0x1000
	s_addc_u32 s11, s11, 0
	s_add_u32 s12, s12, 0x80
	s_addc_u32 s13, s13, 0
	global_load_dwordx2 v[40:41], v1, s[4:5] nt
	global_load_dwordx2 v[42:43], v1, s[8:9] nt
	global_load_dwordx2 v[44:45], v1, s[10:11] nt
	global_load_dword v46, v2, s[12:13] nt
	s_add_u32 s4, s4, 0x1000
	s_addc_u32 s5, s5, 0
	s_add_u32 s8, s8, 0x1000
	s_addc_u32 s9, s9, 0
	s_add_u32 s10, s10, 0x1000
	s_addc_u32 s11, s11, 0
	s_add_u32 s12, s12, 0x80
	s_addc_u32 s13, s13, 0
	s_waitcnt vmcnt(32)
	v_lshlrev_b32_e32 v85, 16, v49
	v_lshlrev_b32_e32 v84, 16, v48
	v_and_b32_e32 v49, 0xffff0000, v49
	v_and_b32_e32 v48, 0xffff0000, v48
	v_pk_add_f32 v[86:87], v[84:85], v[48:49]
	v_lshlrev_b32_e32 v88, 16, v50
	v_add_f32_e32 v86, v86, v87
	v_and_b32_e32 v89, 0xffff0000, v50
	v_lshlrev_b32_e32 v90, 16, v51
	v_add_f32_dpp v86, v86, v86 quad_perm:[1,0,3,2] row_mask:0xf bank_mask:0xf bound_ctrl:1
	v_and_b32_e32 v91, 0xffff0000, v51
	v_lshlrev_b32_e32 v92, 16, v52
	v_add_f32_dpp v86, v86, v86 quad_perm:[2,3,0,1] row_mask:0xf bank_mask:0xf bound_ctrl:1
	v_and_b32_e32 v93, 0xffff0000, v52
	v_lshlrev_b32_e32 v94, 16, v53
	v_add_f32_dpp v86, v86, v86 row_half_mirror row_mask:0xf bank_mask:0xf bound_ctrl:1
	v_and_b32_e32 v95, 0xffff0000, v53
	s_nop 0
	v_add_f32_dpp v86, v86, v86 row_ror:8 row_mask:0xf bank_mask:0xf bound_ctrl:1
	v_fmac_f32_e32 v48, 0xbc800000, v86
	v_fmac_f32_e32 v49, 0xbc800000, v86
	v_fmac_f32_e32 v85, 0xbc800000, v86
	v_fmac_f32_e32 v84, 0xbc800000, v86
	v_mov_b32_e32 v86, v85
	v_mov_b32_e32 v87, v49
	v_mov_b32_e32 v85, v48
	v_pk_mul_f32 v[96:97], v[86:87], v[86:87]
	v_pk_mul_f32 v[98:99], v[84:85], v[84:85]
	s_nop 0
	v_pk_mov_b32 v[100:101], v[98:99], v[96:97] op_sel:[1,0]
	v_mov_b32_e32 v99, v97
	v_pk_add_f32 v[96:97], v[100:101], v[98:99]
	s_nop 0
	v_add_f32_e32 v96, v96, v97
	s_nop 1
	v_add_f32_dpp v96, v96, v96 quad_perm:[1,0,3,2] row_mask:0xf bank_mask:0xf bound_ctrl:1
	s_nop 1
	v_add_f32_dpp v96, v96, v96 quad_perm:[2,3,0,1] row_mask:0xf bank_mask:0xf bound_ctrl:1
	s_nop 1
	v_add_f32_dpp v96, v96, v96 row_half_mirror row_mask:0xf bank_mask:0xf bound_ctrl:1
	s_nop 1
	v_add_f32_dpp v96, v96, v96 row_ror:8 row_mask:0xf bank_mask:0xf bound_ctrl:1
	v_fmamk_f32 v96, v96, 0x3c800000, v4
	v_mul_f32_e32 v97, 0x4f800000, v96
	v_cmp_gt_f32_e32 vcc, s3, v96
	s_nop 1
	v_cndmask_b32_e32 v96, v96, v97, vcc
	v_sqrt_f32_e32 v97, v96
	s_nop 0
	v_add_u32_e32 v98, -1, v97
	v_add_u32_e32 v99, 1, v97
	v_fma_f32 v100, -v98, v97, v96
	v_fma_f32 v101, -v99, v97, v96
	v_cmp_ge_f32_e64 s[6:7], 0, v100
	s_nop 1
	v_cndmask_b32_e64 v97, v97, v98, s[6:7]
	v_cmp_lt_f32_e64 s[6:7], 0, v101
	s_nop 1
	v_cndmask_b32_e64 v97, v97, v99, s[6:7]
	v_mul_f32_e32 v98, 0x37800000, v97
	v_cndmask_b32_e32 v97, v97, v98, vcc
	v_cmp_class_f32_e32 vcc, v96, v3
	s_nop 1
	v_cndmask_b32_e32 v96, v97, v96, vcc
	v_div_scale_f32 v97, s[6:7], v96, v96, 1.0
	v_rcp_f32_e32 v99, v97
	v_div_scale_f32 v98, vcc, 1.0, v96, 1.0
	v_fma_f32 v100, -v97, v99, 1.0
	v_fmac_f32_e32 v99, v100, v99
	v_mul_f32_e32 v100, v98, v99
	v_fma_f32 v101, -v97, v100, v98
	v_fmac_f32_e32 v100, v101, v99
	v_fma_f32 v97, -v97, v100, v98
	v_div_fmas_f32 v97, v97, v99, v100
	v_div_fixup_f32 v96, v97, v96, 1.0
	v_pk_mul_f32 v[84:85], v[84:85], v[96:97] op_sel_hi:[1,0]
	v_pk_mul_f32 v[96:97], v[86:87], v[96:97] op_sel_hi:[1,0]
	s_nop 0
	v_pk_fma_f32 v[102:103], v[8:9], v[84:85], v[12:13]
	v_pk_fma_f32 v[104:105], v[10:11], v[96:97], v[14:15]
	s_nop 0
	v_pk_fma_f32 v[102:103], v[54:55], v[88:89], v[102:103] op_sel_hi:[0,1,1]
	v_pk_fma_f32 v[104:105], v[54:55], v[90:91], v[104:105] op_sel_hi:[0,1,1]
	s_nop 0
	v_pk_mul_f32 v[104:105], v[104:105], v[94:95]
	v_pk_mul_f32 v[102:103], v[102:103], v[92:93]
	s_nop 0
	v_cvt_pk_bf16_f32 v102, v102, v103
	v_cvt_pk_bf16_f32 v103, v104, v105
	global_store_dwordx2 v1, v[102:103], s[14:15]
	s_add_u32 s14, s14, 0x1000
	s_addc_u32 s15, s15, 0
	s_waitcnt vmcnt(29)
	v_lshlrev_b32_e32 v85, 16, v57
	v_lshlrev_b32_e32 v84, 16, v56
	v_and_b32_e32 v57, 0xffff0000, v57
	v_and_b32_e32 v56, 0xffff0000, v56
	v_pk_add_f32 v[86:87], v[84:85], v[56:57]
	v_lshlrev_b32_e32 v88, 16, v58
	v_add_f32_e32 v86, v86, v87
	v_and_b32_e32 v89, 0xffff0000, v58
	v_lshlrev_b32_e32 v90, 16, v59
	v_add_f32_dpp v86, v86, v86 quad_perm:[1,0,3,2] row_mask:0xf bank_mask:0xf bound_ctrl:1
	v_and_b32_e32 v91, 0xffff0000, v59
	v_lshlrev_b32_e32 v92, 16, v60
	v_add_f32_dpp v86, v86, v86 quad_perm:[2,3,0,1] row_mask:0xf bank_mask:0xf bound_ctrl:1
	v_and_b32_e32 v93, 0xffff0000, v60
	v_lshlrev_b32_e32 v94, 16, v61
	v_add_f32_dpp v86, v86, v86 row_half_mirror row_mask:0xf bank_mask:0xf bound_ctrl:1
	v_and_b32_e32 v95, 0xffff0000, v61
	s_nop 0
	v_add_f32_dpp v86, v86, v86 row_ror:8 row_mask:0xf bank_mask:0xf bound_ctrl:1
	v_fmac_f32_e32 v56, 0xbc800000, v86
	v_fmac_f32_e32 v57, 0xbc800000, v86
	v_fmac_f32_e32 v85, 0xbc800000, v86
	v_fmac_f32_e32 v84, 0xbc800000, v86
	v_mov_b32_e32 v86, v85
	v_mov_b32_e32 v87, v57
	v_mov_b32_e32 v85, v56
	v_pk_mul_f32 v[96:97], v[86:87], v[86:87]
	v_pk_mul_f32 v[98:99], v[84:85], v[84:85]
	s_nop 0
	v_pk_mov_b32 v[100:101], v[98:99], v[96:97] op_sel:[1,0]
	v_mov_b32_e32 v99, v97
	v_pk_add_f32 v[96:97], v[100:101], v[98:99]
	s_nop 0
	v_add_f32_e32 v96, v96, v97
	s_nop 1
	v_add_f32_dpp v96, v96, v96 quad_perm:[1,0,3,2] row_mask:0xf bank_mask:0xf bound_ctrl:1
	s_nop 1
	v_add_f32_dpp v96, v96, v96 quad_perm:[2,3,0,1] row_mask:0xf bank_mask:0xf bound_ctrl:1
	s_nop 1
	v_add_f32_dpp v96, v96, v96 row_half_mirror row_mask:0xf bank_mask:0xf bound_ctrl:1
	s_nop 1
	v_add_f32_dpp v96, v96, v96 row_ror:8 row_mask:0xf bank_mask:0xf bound_ctrl:1
	v_fmamk_f32 v96, v96, 0x3c800000, v4
	v_mul_f32_e32 v97, 0x4f800000, v96
	v_cmp_gt_f32_e32 vcc, s3, v96
	s_nop 1
	v_cndmask_b32_e32 v96, v96, v97, vcc
	v_sqrt_f32_e32 v97, v96
	s_nop 0
	v_add_u32_e32 v98, -1, v97
	v_add_u32_e32 v99, 1, v97
	v_fma_f32 v100, -v98, v97, v96
	v_fma_f32 v101, -v99, v97, v96
	v_cmp_ge_f32_e64 s[6:7], 0, v100
	s_nop 1
	v_cndmask_b32_e64 v97, v97, v98, s[6:7]
	v_cmp_lt_f32_e64 s[6:7], 0, v101
	s_nop 1
	v_cndmask_b32_e64 v97, v97, v99, s[6:7]
	v_mul_f32_e32 v98, 0x37800000, v97
	v_cndmask_b32_e32 v97, v97, v98, vcc
	v_cmp_class_f32_e32 vcc, v96, v3
	s_nop 1
	v_cndmask_b32_e32 v96, v97, v96, vcc
	v_div_scale_f32 v97, s[6:7], v96, v96, 1.0
	v_rcp_f32_e32 v99, v97
	v_div_scale_f32 v98, vcc, 1.0, v96, 1.0
	v_fma_f32 v100, -v97, v99, 1.0
	v_fmac_f32_e32 v99, v100, v99
	v_mul_f32_e32 v100, v98, v99
	v_fma_f32 v101, -v97, v100, v98
	v_fmac_f32_e32 v100, v101, v99
	v_fma_f32 v97, -v97, v100, v98
	v_div_fmas_f32 v97, v97, v99, v100
	v_div_fixup_f32 v96, v97, v96, 1.0
	v_pk_mul_f32 v[84:85], v[84:85], v[96:97] op_sel_hi:[1,0]
	v_pk_mul_f32 v[96:97], v[86:87], v[96:97] op_sel_hi:[1,0]
	s_nop 0
	v_pk_fma_f32 v[102:103], v[8:9], v[84:85], v[12:13]
	v_pk_fma_f32 v[104:105], v[10:11], v[96:97], v[14:15]
	s_nop 0
	v_pk_fma_f32 v[102:103], v[62:63], v[88:89], v[102:103] op_sel_hi:[0,1,1]
	v_pk_fma_f32 v[104:105], v[62:63], v[90:91], v[104:105] op_sel_hi:[0,1,1]
	s_nop 0
	v_pk_mul_f32 v[104:105], v[104:105], v[94:95]
	v_pk_mul_f32 v[102:103], v[102:103], v[92:93]
	s_nop 0
	v_cvt_pk_bf16_f32 v102, v102, v103
	v_cvt_pk_bf16_f32 v103, v104, v105
	global_store_dwordx2 v1, v[102:103], s[14:15]
	s_add_u32 s14, s14, 0x1000
	s_addc_u32 s15, s15, 0
	s_waitcnt vmcnt(26)
	v_lshlrev_b32_e32 v85, 16, v65
	v_lshlrev_b32_e32 v84, 16, v64
	v_and_b32_e32 v65, 0xffff0000, v65
	v_and_b32_e32 v64, 0xffff0000, v64
	v_pk_add_f32 v[86:87], v[84:85], v[64:65]
	v_lshlrev_b32_e32 v88, 16, v66
	v_add_f32_e32 v86, v86, v87
	v_and_b32_e32 v89, 0xffff0000, v66
	v_lshlrev_b32_e32 v90, 16, v67
	v_add_f32_dpp v86, v86, v86 quad_perm:[1,0,3,2] row_mask:0xf bank_mask:0xf bound_ctrl:1
	v_and_b32_e32 v91, 0xffff0000, v67
	v_lshlrev_b32_e32 v92, 16, v68
	v_add_f32_dpp v86, v86, v86 quad_perm:[2,3,0,1] row_mask:0xf bank_mask:0xf bound_ctrl:1
	v_and_b32_e32 v93, 0xffff0000, v68
	v_lshlrev_b32_e32 v94, 16, v69
	v_add_f32_dpp v86, v86, v86 row_half_mirror row_mask:0xf bank_mask:0xf bound_ctrl:1
	v_and_b32_e32 v95, 0xffff0000, v69
	s_nop 0
	v_add_f32_dpp v86, v86, v86 row_ror:8 row_mask:0xf bank_mask:0xf bound_ctrl:1
	v_fmac_f32_e32 v64, 0xbc800000, v86
	v_fmac_f32_e32 v65, 0xbc800000, v86
	v_fmac_f32_e32 v85, 0xbc800000, v86
	v_fmac_f32_e32 v84, 0xbc800000, v86
	v_mov_b32_e32 v86, v85
	v_mov_b32_e32 v87, v65
	v_mov_b32_e32 v85, v64
	v_pk_mul_f32 v[96:97], v[86:87], v[86:87]
	v_pk_mul_f32 v[98:99], v[84:85], v[84:85]
	s_nop 0
	v_pk_mov_b32 v[100:101], v[98:99], v[96:97] op_sel:[1,0]
	v_mov_b32_e32 v99, v97
	v_pk_add_f32 v[96:97], v[100:101], v[98:99]
	s_nop 0
	v_add_f32_e32 v96, v96, v97
	s_nop 1
	v_add_f32_dpp v96, v96, v96 quad_perm:[1,0,3,2] row_mask:0xf bank_mask:0xf bound_ctrl:1
	s_nop 1
	v_add_f32_dpp v96, v96, v96 quad_perm:[2,3,0,1] row_mask:0xf bank_mask:0xf bound_ctrl:1
	s_nop 1
	v_add_f32_dpp v96, v96, v96 row_half_mirror row_mask:0xf bank_mask:0xf bound_ctrl:1
	s_nop 1
	v_add_f32_dpp v96, v96, v96 row_ror:8 row_mask:0xf bank_mask:0xf bound_ctrl:1
	v_fmamk_f32 v96, v96, 0x3c800000, v4
	v_mul_f32_e32 v97, 0x4f800000, v96
	v_cmp_gt_f32_e32 vcc, s3, v96
	s_nop 1
	v_cndmask_b32_e32 v96, v96, v97, vcc
	v_sqrt_f32_e32 v97, v96
	s_nop 0
	v_add_u32_e32 v98, -1, v97
	v_add_u32_e32 v99, 1, v97
	v_fma_f32 v100, -v98, v97, v96
	v_fma_f32 v101, -v99, v97, v96
	v_cmp_ge_f32_e64 s[6:7], 0, v100
	s_nop 1
	v_cndmask_b32_e64 v97, v97, v98, s[6:7]
	v_cmp_lt_f32_e64 s[6:7], 0, v101
	s_nop 1
	v_cndmask_b32_e64 v97, v97, v99, s[6:7]
	v_mul_f32_e32 v98, 0x37800000, v97
	v_cndmask_b32_e32 v97, v97, v98, vcc
	v_cmp_class_f32_e32 vcc, v96, v3
	s_nop 1
	v_cndmask_b32_e32 v96, v97, v96, vcc
	v_div_scale_f32 v97, s[6:7], v96, v96, 1.0
	v_rcp_f32_e32 v99, v97
	v_div_scale_f32 v98, vcc, 1.0, v96, 1.0
	v_fma_f32 v100, -v97, v99, 1.0
	v_fmac_f32_e32 v99, v100, v99
	v_mul_f32_e32 v100, v98, v99
	v_fma_f32 v101, -v97, v100, v98
	v_fmac_f32_e32 v100, v101, v99
	v_fma_f32 v97, -v97, v100, v98
	v_div_fmas_f32 v97, v97, v99, v100
	v_div_fixup_f32 v96, v97, v96, 1.0
	v_pk_mul_f32 v[84:85], v[84:85], v[96:97] op_sel_hi:[1,0]
	v_pk_mul_f32 v[96:97], v[86:87], v[96:97] op_sel_hi:[1,0]
	s_nop 0
	v_pk_fma_f32 v[102:103], v[8:9], v[84:85], v[12:13]
	v_pk_fma_f32 v[104:105], v[10:11], v[96:97], v[14:15]
	s_nop 0
	v_pk_fma_f32 v[102:103], v[70:71], v[88:89], v[102:103] op_sel_hi:[0,1,1]
	v_pk_fma_f32 v[104:105], v[70:71], v[90:91], v[104:105] op_sel_hi:[0,1,1]
	s_nop 0
	v_pk_mul_f32 v[104:105], v[104:105], v[94:95]
	v_pk_mul_f32 v[102:103], v[102:103], v[92:93]
	s_nop 0
	v_cvt_pk_bf16_f32 v102, v102, v103
	v_cvt_pk_bf16_f32 v103, v104, v105
	global_store_dwordx2 v1, v[102:103], s[14:15]
	s_add_u32 s14, s14, 0x1000
	s_addc_u32 s15, s15, 0
	s_waitcnt vmcnt(23)
	v_lshlrev_b32_e32 v85, 16, v73
	v_lshlrev_b32_e32 v84, 16, v72
	v_and_b32_e32 v73, 0xffff0000, v73
	v_and_b32_e32 v72, 0xffff0000, v72
	v_pk_add_f32 v[86:87], v[84:85], v[72:73]
	v_lshlrev_b32_e32 v88, 16, v74
	v_add_f32_e32 v86, v86, v87
	v_and_b32_e32 v89, 0xffff0000, v74
	v_lshlrev_b32_e32 v90, 16, v75
	v_add_f32_dpp v86, v86, v86 quad_perm:[1,0,3,2] row_mask:0xf bank_mask:0xf bound_ctrl:1
	v_and_b32_e32 v91, 0xffff0000, v75
	v_lshlrev_b32_e32 v92, 16, v76
	v_add_f32_dpp v86, v86, v86 quad_perm:[2,3,0,1] row_mask:0xf bank_mask:0xf bound_ctrl:1
	v_and_b32_e32 v93, 0xffff0000, v76
	v_lshlrev_b32_e32 v94, 16, v77
	v_add_f32_dpp v86, v86, v86 row_half_mirror row_mask:0xf bank_mask:0xf bound_ctrl:1
	v_and_b32_e32 v95, 0xffff0000, v77
	s_nop 0
	v_add_f32_dpp v86, v86, v86 row_ror:8 row_mask:0xf bank_mask:0xf bound_ctrl:1
	v_fmac_f32_e32 v72, 0xbc800000, v86
	v_fmac_f32_e32 v73, 0xbc800000, v86
	v_fmac_f32_e32 v85, 0xbc800000, v86
	v_fmac_f32_e32 v84, 0xbc800000, v86
	v_mov_b32_e32 v86, v85
	v_mov_b32_e32 v87, v73
	v_mov_b32_e32 v85, v72
	v_pk_mul_f32 v[96:97], v[86:87], v[86:87]
	v_pk_mul_f32 v[98:99], v[84:85], v[84:85]
	s_nop 0
	v_pk_mov_b32 v[100:101], v[98:99], v[96:97] op_sel:[1,0]
	v_mov_b32_e32 v99, v97
	v_pk_add_f32 v[96:97], v[100:101], v[98:99]
	s_nop 0
	v_add_f32_e32 v96, v96, v97
	s_nop 1
	v_add_f32_dpp v96, v96, v96 quad_perm:[1,0,3,2] row_mask:0xf bank_mask:0xf bound_ctrl:1
	s_nop 1
	v_add_f32_dpp v96, v96, v96 quad_perm:[2,3,0,1] row_mask:0xf bank_mask:0xf bound_ctrl:1
	s_nop 1
	v_add_f32_dpp v96, v96, v96 row_half_mirror row_mask:0xf bank_mask:0xf bound_ctrl:1
	s_nop 1
	v_add_f32_dpp v96, v96, v96 row_ror:8 row_mask:0xf bank_mask:0xf bound_ctrl:1
	v_fmamk_f32 v96, v96, 0x3c800000, v4
	v_mul_f32_e32 v97, 0x4f800000, v96
	v_cmp_gt_f32_e32 vcc, s3, v96
	s_nop 1
	v_cndmask_b32_e32 v96, v96, v97, vcc
	v_sqrt_f32_e32 v97, v96
	s_nop 0
	v_add_u32_e32 v98, -1, v97
	v_add_u32_e32 v99, 1, v97
	v_fma_f32 v100, -v98, v97, v96
	v_fma_f32 v101, -v99, v97, v96
	v_cmp_ge_f32_e64 s[6:7], 0, v100
	s_nop 1
	v_cndmask_b32_e64 v97, v97, v98, s[6:7]
	v_cmp_lt_f32_e64 s[6:7], 0, v101
	s_nop 1
	v_cndmask_b32_e64 v97, v97, v99, s[6:7]
	v_mul_f32_e32 v98, 0x37800000, v97
	v_cndmask_b32_e32 v97, v97, v98, vcc
	v_cmp_class_f32_e32 vcc, v96, v3
	s_nop 1
	v_cndmask_b32_e32 v96, v97, v96, vcc
	v_div_scale_f32 v97, s[6:7], v96, v96, 1.0
	v_rcp_f32_e32 v99, v97
	v_div_scale_f32 v98, vcc, 1.0, v96, 1.0
	v_fma_f32 v100, -v97, v99, 1.0
	v_fmac_f32_e32 v99, v100, v99
	v_mul_f32_e32 v100, v98, v99
	v_fma_f32 v101, -v97, v100, v98
	v_fmac_f32_e32 v100, v101, v99
	v_fma_f32 v97, -v97, v100, v98
	v_div_fmas_f32 v97, v97, v99, v100
	v_div_fixup_f32 v96, v97, v96, 1.0
	v_pk_mul_f32 v[84:85], v[84:85], v[96:97] op_sel_hi:[1,0]
	v_pk_mul_f32 v[96:97], v[86:87], v[96:97] op_sel_hi:[1,0]
	s_nop 0
	v_pk_fma_f32 v[102:103], v[8:9], v[84:85], v[12:13]
	v_pk_fma_f32 v[104:105], v[10:11], v[96:97], v[14:15]
	s_nop 0
	v_pk_fma_f32 v[102:103], v[78:79], v[88:89], v[102:103] op_sel_hi:[0,1,1]
	v_pk_fma_f32 v[104:105], v[78:79], v[90:91], v[104:105] op_sel_hi:[0,1,1]
	s_nop 0
	v_pk_mul_f32 v[104:105], v[104:105], v[94:95]
	v_pk_mul_f32 v[102:103], v[102:103], v[92:93]
	s_nop 0
	v_cvt_pk_bf16_f32 v102, v102, v103
	v_cvt_pk_bf16_f32 v103, v104, v105
	global_store_dwordx2 v1, v[102:103], s[14:15]
	s_add_u32 s14, s14, 0x1000
	s_addc_u32 s15, s15, 0
	s_sub_u32 s26, s26, 1
	s_cmp_lg_u32 s26, 0
	s_cbranch_scc1 .Lpost_loop
	s_branch .LBB0_764
.Lpost_orig:
	s_mov_b64 s[14:15], s[0:1]
	s_mov_b64 s[12:13], s[0:1]
	s_mov_b64 s[4:5], s[0:1]
	s_mov_b64 s[16:17], s[0:1]
	s_mov_b64 s[6:7], s[0:1]
	s_mov_b64 s[22:23], s[0:1]
	s_mov_b64 s[18:19], s[0:1]
	v_mov_b32_e32 v1, v190
	s_mov_b32 s8, s2
	s_lshl_b32 s8, s8, 9
	v_readfirstlane_b32 s3, v1
	s_andn2_b32 s3, s3, 63
	s_add_i32 s8, s8, s3
	v_and_or_b32 v2, v1, 63, s8
	s_mov_b32 s3, 0x800000
	v_cmp_gt_i32_e32 vcc, s3, v2
	s_and_saveexec_b64 s[8:9], vcc
	s_cbranch_execz .LBB0_763
	s_load_dwordx2 s[20:21], s[12:13], 0xe0
	s_load_dwordx2 s[10:11], s[14:15], 0xd8
	s_load_dwordx2 s[26:27], s[4:5], 0xe0
	s_load_dwordx2 s[28:29], s[16:17], 0xe0
	s_load_dwordx2 s[30:31], s[18:19], 0xe0
	s_waitcnt lgkmcnt(0)
	s_add_u32 s12, s20, 0x1c100000
	s_addc_u32 s13, s21, 0
	s_add_u32 s14, s26, 0x20100000
	s_addc_u32 s15, s27, 0
	s_add_u32 s16, s28, 0x24100000
	s_addc_u32 s17, s29, 0
	s_load_dwordx2 s[18:19], s[6:7], 0x70
	s_load_dwordx2 s[20:21], s[22:23], 0x78
	s_add_u32 s22, s30, 0x24300000
	s_addc_u32 s23, s31, 0
	s_lshl_b32 s28, s24, 9
	v_ashrrev_i32_e32 v3, 31, v2
	s_ashr_i32 s29, s28, 31
	s_waitcnt vmcnt(0)
	v_lshlrev_b64 v[4:5], 3, v[2:3]
	s_lshl_b64 s[30:31], s[28:29], 3
	s_mov_b64 s[34:35], 0
	v_mov_b32_e32 v7, 0
	v_mov_b32_e32 v1, 0x3a27c5ac
	s_mov_b32 s3, 0xf800000
	v_mov_b32_e32 v3, 0x260
	s_mov_b32 s4, 0x7fffff

.LBB0_850:
	ds_read_b128 v[154:157], v150
	ds_read_b128 v[158:161], v150 offset:1024
	ds_read_b128 v[162:165], v150 offset:2048
	ds_read_b128 v[166:169], v150 offset:3072
	s_add_u32 s44, s42, 0xfff80080
	s_addc_u32 s45, s43, -1
	s_cmp_eq_u32 s62, 28
	s_cselect_b32 s47, s4, s45
	s_cselect_b32 s46, s5, s44
	s_cselect_b32 s45, s26, s31
	s_cselect_b32 s44, s27, s29
	v_lshl_add_u64 v[146:147], s[42:43], 0, v[138:139]
	s_add_i32 m0, s39, 0xc000
	ds_read_b128 v[170:173], v151
	ds_read_b128 v[174:177], v151 offset:1024
	ds_read_b128 v[178:181], v151 offset:2048
	ds_read_b128 v[182:185], v151 offset:3072
	ds_read_b128 v[186:189], v151 offset:4096
	ds_read_b128 v[192:195], v151 offset:5120
	ds_read_b128 v[196:199], v151 offset:6144
	ds_read_b128 v[200:203], v151 offset:7168
	global_load_lds_dwordx4 v[146:147], off
	v_lshl_add_u64 v[146:147], s[42:43], 0, v[140:141]
	s_add_i32 m0, s39, 0xe000
	s_nop 0
	global_load_lds_dwordx4 v[146:147], off
	s_waitcnt lgkmcnt(8)
	s_barrier
	s_waitcnt lgkmcnt(0)
	s_setprio 1
	s_waitcnt lgkmcnt(0)
	v_mfma_f32_16x16x32_bf16 v[126:129], v[154:157], v[170:173], v[126:129]
	v_mfma_f32_16x16x32_bf16 v[122:125], v[162:165], v[170:173], v[122:125]
	v_mfma_f32_16x16x32_bf16 v[110:113], v[154:157], v[178:181], v[110:113]
	v_mfma_f32_16x16x32_bf16 v[106:109], v[162:165], v[178:181], v[106:109]
	v_mfma_f32_16x16x32_bf16 v[94:97], v[154:157], v[186:189], v[94:97]
	v_mfma_f32_16x16x32_bf16 v[90:93], v[162:165], v[186:189], v[90:93]
	v_mfma_f32_16x16x32_bf16 v[78:81], v[154:157], v[196:199], v[78:81]
	v_mfma_f32_16x16x32_bf16 v[74:77], v[162:165], v[196:199], v[74:77]
	v_mfma_f32_16x16x32_bf16 v[126:129], v[158:161], v[174:177], v[126:129]
	v_mfma_f32_16x16x32_bf16 v[122:125], v[166:169], v[174:177], v[122:125]
	v_mfma_f32_16x16x32_bf16 v[110:113], v[158:161], v[182:185], v[110:113]
	v_mfma_f32_16x16x32_bf16 v[106:109], v[166:169], v[182:185], v[106:109]
	v_mfma_f32_16x16x32_bf16 v[94:97], v[158:161], v[192:195], v[94:97]
	v_mfma_f32_16x16x32_bf16 v[90:93], v[166:169], v[192:195], v[90:93]
	v_mfma_f32_16x16x32_bf16 v[78:81], v[158:161], v[200:203], v[78:81]
	v_mfma_f32_16x16x32_bf16 v[74:77], v[166:169], v[200:203], v[74:77]
	s_setprio 0
	s_barrier
	s_add_i32 s63, s60, s52
	v_lshl_add_u64 v[146:147], s[44:45], 0, v[132:133]
	s_mov_b32 m0, s63
	ds_read_b128 v[204:207], v152
	ds_read_b128 v[208:211], v152 offset:1024
	ds_read_b128 v[212:215], v152 offset:2048
	ds_read_b128 v[216:219], v152 offset:3072
	global_load_lds_dwordx4 v[146:147], off
	v_lshl_add_u64 v[220:221], s[44:45], 0, v[136:137]
	s_add_i32 m0, s63, 0x2000
	s_nop 0
	global_load_lds_dwordx4 v[220:221], off
	s_barrier
	s_waitcnt lgkmcnt(0)
	s_setprio 1
	s_waitcnt lgkmcnt(0)
	v_mfma_f32_16x16x32_bf16 v[118:121], v[204:207], v[170:173], v[118:121]
	v_mfma_f32_16x16x32_bf16 v[114:117], v[212:215], v[170:173], v[114:117]
	v_mfma_f32_16x16x32_bf16 v[102:105], v[204:207], v[178:181], v[102:105]
	v_mfma_f32_16x16x32_bf16 v[98:101], v[212:215], v[178:181], v[98:101]
	v_mfma_f32_16x16x32_bf16 v[86:89], v[204:207], v[186:189], v[86:89]
	v_mfma_f32_16x16x32_bf16 v[82:85], v[212:215], v[186:189], v[82:85]
	v_mfma_f32_16x16x32_bf16 v[70:73], v[204:207], v[196:199], v[70:73]
	v_mfma_f32_16x16x32_bf16 v[66:69], v[212:215], v[196:199], v[66:69]
	v_mfma_f32_16x16x32_bf16 v[118:121], v[208:211], v[174:177], v[118:121]
	v_mfma_f32_16x16x32_bf16 v[114:117], v[216:219], v[174:177], v[114:117]
	v_mfma_f32_16x16x32_bf16 v[102:105], v[208:211], v[182:185], v[102:105]
	v_mfma_f32_16x16x32_bf16 v[98:101], v[216:219], v[182:185], v[98:101]
	v_mfma_f32_16x16x32_bf16 v[86:89], v[208:211], v[192:195], v[86:89]
	v_mfma_f32_16x16x32_bf16 v[82:85], v[216:219], v[192:195], v[82:85]
	v_mfma_f32_16x16x32_bf16 v[70:73], v[208:211], v[200:203], v[70:73]
	v_mfma_f32_16x16x32_bf16 v[66:69], v[216:219], v[200:203], v[66:69]
	s_setprio 0
	s_mov_b32 m0, s39
	v_lshl_add_u64 v[222:223], s[46:47], 0, v[130:131]
	s_barrier
	ds_read_b128 v[170:173], v151 offset:16384
	ds_read_b128 v[174:177], v151 offset:17408
	ds_read_b128 v[178:181], v151 offset:18432
	ds_read_b128 v[182:185], v151 offset:19456
	ds_read_b128 v[186:189], v151 offset:20480
	ds_read_b128 v[192:195], v151 offset:21504
	ds_read_b128 v[196:199], v151 offset:22528
	ds_read_b128 v[200:203], v151 offset:23552
	global_load_lds_dwordx4 v[222:223], off
	v_lshl_add_u64 v[224:225], s[46:47], 0, v[134:135]
	s_mov_b32 m0, s41
	s_nop 0
	global_load_lds_dwordx4 v[224:225], off
	s_barrier
	s_waitcnt lgkmcnt(0)
	s_setprio 1
	s_waitcnt lgkmcnt(0)
	v_mfma_f32_16x16x32_bf16 v[62:65], v[154:157], v[170:173], v[62:65]
	v_mfma_f32_16x16x32_bf16 v[58:61], v[162:165], v[170:173], v[58:61]
	v_mfma_f32_16x16x32_bf16 v[46:49], v[154:157], v[178:181], v[46:49]
	v_mfma_f32_16x16x32_bf16 v[42:45], v[162:165], v[178:181], v[42:45]
	v_mfma_f32_16x16x32_bf16 v[30:33], v[154:157], v[186:189], v[30:33]
	v_mfma_f32_16x16x32_bf16 v[26:29], v[162:165], v[186:189], v[26:29]
	v_mfma_f32_16x16x32_bf16 v[14:17], v[154:157], v[196:199], v[14:17]
	v_mfma_f32_16x16x32_bf16 v[10:13], v[162:165], v[196:199], v[10:13]
	v_mfma_f32_16x16x32_bf16 v[62:65], v[158:161], v[174:177], v[62:65]
	v_mfma_f32_16x16x32_bf16 v[58:61], v[166:169], v[174:177], v[58:61]
	v_mfma_f32_16x16x32_bf16 v[46:49], v[158:161], v[182:185], v[46:49]
	v_mfma_f32_16x16x32_bf16 v[42:45], v[166:169], v[182:185], v[42:45]
	v_mfma_f32_16x16x32_bf16 v[30:33], v[158:161], v[192:195], v[30:33]
	v_mfma_f32_16x16x32_bf16 v[26:29], v[166:169], v[192:195], v[26:29]
	v_mfma_f32_16x16x32_bf16 v[14:17], v[158:161], v[200:203], v[14:17]
	v_mfma_f32_16x16x32_bf16 v[10:13], v[166:169], v[200:203], v[10:13]
	s_setprio 0
	s_barrier
	s_add_u32 s64, s44, 0x80000
	s_addc_u32 s65, s45, 0
	s_add_i32 s63, s61, s52
	v_lshl_add_u64 v[154:155], s[64:65], 0, v[132:133]
	s_mov_b32 m0, s63
	s_nop 0
	global_load_lds_dwordx4 v[154:155], off
	v_lshl_add_u64 v[154:155], s[64:65], 0, v[136:137]
	s_add_i32 m0, s63, 0x2000
	s_nop 0
	global_load_lds_dwordx4 v[154:155], off
	s_waitcnt vmcnt(6)
	s_barrier
	s_setprio 1
	v_mfma_f32_16x16x32_bf16 v[54:57], v[204:207], v[170:173], v[54:57]
	v_mfma_f32_16x16x32_bf16 v[50:53], v[212:215], v[170:173], v[50:53]
	v_mfma_f32_16x16x32_bf16 v[38:41], v[204:207], v[178:181], v[38:41]
	v_mfma_f32_16x16x32_bf16 v[34:37], v[212:215], v[178:181], v[34:37]
	v_mfma_f32_16x16x32_bf16 v[22:25], v[204:207], v[186:189], v[22:25]
	v_mfma_f32_16x16x32_bf16 v[18:21], v[212:215], v[186:189], v[18:21]
	v_mfma_f32_16x16x32_bf16 v[6:9], v[204:207], v[196:199], v[6:9]
	v_mfma_f32_16x16x32_bf16 v[2:5], v[212:215], v[196:199], v[2:5]
	v_mfma_f32_16x16x32_bf16 v[54:57], v[208:211], v[174:177], v[54:57]
	v_mfma_f32_16x16x32_bf16 v[50:53], v[216:219], v[174:177], v[50:53]
	v_mfma_f32_16x16x32_bf16 v[38:41], v[208:211], v[182:185], v[38:41]
	v_mfma_f32_16x16x32_bf16 v[34:37], v[216:219], v[182:185], v[34:37]
	v_mfma_f32_16x16x32_bf16 v[22:25], v[208:211], v[192:195], v[22:25]
	v_mfma_f32_16x16x32_bf16 v[18:21], v[216:219], v[192:195], v[18:21]
	v_mfma_f32_16x16x32_bf16 v[6:9], v[208:211], v[200:203], v[6:9]
	v_mfma_f32_16x16x32_bf16 v[2:5], v[216:219], v[200:203], v[2:5]
	s_setprio 0
	s_add_i32 s63, 0, 0x18000
	v_add_u32_e32 v153, s63, v148
	s_barrier
	ds_read_b128 v[154:157], v153
	ds_read_b128 v[158:161], v153 offset:1024
	ds_read_b128 v[162:165], v153 offset:2048
	ds_read_b128 v[166:169], v153 offset:3072
	s_add_u32 s46, s46, 0x80000
	s_addc_u32 s47, s47, 0
	s_mov_b32 m0, s53
	v_lshl_add_u64 v[204:205], s[46:47], 0, v[130:131]
	ds_read_b128 v[170:173], v151 offset:32768
	ds_read_b128 v[174:177], v151 offset:33792
	ds_read_b128 v[178:181], v151 offset:34816
	ds_read_b128 v[182:185], v151 offset:35840
	ds_read_b128 v[186:189], v151 offset:36864
	ds_read_b128 v[192:195], v151 offset:37888
	ds_read_b128 v[196:199], v151 offset:38912
	ds_read_b128 v[200:203], v151 offset:39936
	global_load_lds_dwordx4 v[204:205], off
	v_lshl_add_u64 v[204:205], s[46:47], 0, v[134:135]
	s_mov_b32 m0, s54
	s_nop 0
	global_load_lds_dwordx4 v[204:205], off
	s_waitcnt lgkmcnt(8)
	s_barrier
	s_waitcnt lgkmcnt(0)
	s_setprio 1
	s_waitcnt lgkmcnt(0)
	v_mfma_f32_16x16x32_bf16 v[126:129], v[154:157], v[170:173], v[126:129]
	v_mfma_f32_16x16x32_bf16 v[122:125], v[162:165], v[170:173], v[122:125]
	v_mfma_f32_16x16x32_bf16 v[110:113], v[154:157], v[178:181], v[110:113]
	v_mfma_f32_16x16x32_bf16 v[106:109], v[162:165], v[178:181], v[106:109]
	v_mfma_f32_16x16x32_bf16 v[94:97], v[154:157], v[186:189], v[94:97]
	v_mfma_f32_16x16x32_bf16 v[90:93], v[162:165], v[186:189], v[90:93]
	v_mfma_f32_16x16x32_bf16 v[78:81], v[154:157], v[196:199], v[78:81]
	v_mfma_f32_16x16x32_bf16 v[74:77], v[162:165], v[196:199], v[74:77]
	v_mfma_f32_16x16x32_bf16 v[126:129], v[158:161], v[174:177], v[126:129]
	v_mfma_f32_16x16x32_bf16 v[122:125], v[166:169], v[174:177], v[122:125]
	v_mfma_f32_16x16x32_bf16 v[110:113], v[158:161], v[182:185], v[110:113]
	v_mfma_f32_16x16x32_bf16 v[106:109], v[166:169], v[182:185], v[106:109]
	v_mfma_f32_16x16x32_bf16 v[94:97], v[158:161], v[192:195], v[94:97]
	v_mfma_f32_16x16x32_bf16 v[90:93], v[166:169], v[192:195], v[90:93]
	v_mfma_f32_16x16x32_bf16 v[78:81], v[158:161], v[200:203], v[78:81]
	v_mfma_f32_16x16x32_bf16 v[74:77], v[166:169], v[200:203], v[74:77]
	s_setprio 0
	s_barrier
	s_add_i32 s46, 0, 0x1c000
	s_add_i32 s47, s63, s52
	v_add_u32_e32 v153, s46, v148
	v_lshl_add_u64 v[146:147], v[146:147], 0, s[12:13]
	s_mov_b32 m0, s47
	ds_read_b128 v[204:207], v153
	ds_read_b128 v[208:211], v153 offset:1024
	ds_read_b128 v[212:215], v153 offset:2048
	ds_read_b128 v[216:219], v153 offset:3072
	global_load_lds_dwordx4 v[146:147], off
	v_lshl_add_u64 v[146:147], v[220:221], 0, s[12:13]
	s_add_i32 m0, s47, 0x2000
	s_nop 0
	global_load_lds_dwordx4 v[146:147], off
	s_barrier
	s_waitcnt lgkmcnt(0)
	s_setprio 1
	s_waitcnt lgkmcnt(0)
	v_mfma_f32_16x16x32_bf16 v[118:121], v[204:207], v[170:173], v[118:121]
	v_mfma_f32_16x16x32_bf16 v[114:117], v[212:215], v[170:173], v[114:117]
	v_mfma_f32_16x16x32_bf16 v[102:105], v[204:207], v[178:181], v[102:105]
	v_mfma_f32_16x16x32_bf16 v[98:101], v[212:215], v[178:181], v[98:101]
	v_mfma_f32_16x16x32_bf16 v[86:89], v[204:207], v[186:189], v[86:89]
	v_mfma_f32_16x16x32_bf16 v[82:85], v[212:215], v[186:189], v[82:85]
	v_mfma_f32_16x16x32_bf16 v[70:73], v[204:207], v[196:199], v[70:73]
	v_mfma_f32_16x16x32_bf16 v[66:69], v[212:215], v[196:199], v[66:69]
	v_mfma_f32_16x16x32_bf16 v[118:121], v[208:211], v[174:177], v[118:121]
	v_mfma_f32_16x16x32_bf16 v[114:117], v[216:219], v[174:177], v[114:117]
	v_mfma_f32_16x16x32_bf16 v[102:105], v[208:211], v[182:185], v[102:105]
	v_mfma_f32_16x16x32_bf16 v[98:101], v[216:219], v[182:185], v[98:101]
	v_mfma_f32_16x16x32_bf16 v[86:89], v[208:211], v[192:195], v[86:89]
	v_mfma_f32_16x16x32_bf16 v[82:85], v[216:219], v[192:195], v[82:85]
	v_mfma_f32_16x16x32_bf16 v[70:73], v[208:211], v[200:203], v[70:73]
	v_mfma_f32_16x16x32_bf16 v[66:69], v[216:219], v[200:203], v[66:69]
	s_setprio 0
	s_mov_b32 m0, s56
	v_lshl_add_u64 v[146:147], v[222:223], 0, s[12:13]
	s_barrier
	ds_read_b128 v[170:173], v151 offset:49152
	ds_read_b128 v[174:177], v151 offset:50176
	ds_read_b128 v[178:181], v151 offset:51200
	ds_read_b128 v[182:185], v151 offset:52224
	ds_read_b128 v[186:189], v151 offset:53248
	ds_read_b128 v[192:195], v151 offset:54272
	ds_read_b128 v[196:199], v151 offset:55296
	ds_read_b128 v[200:203], v151 offset:56320
	global_load_lds_dwordx4 v[146:147], off
	v_lshl_add_u64 v[146:147], v[224:225], 0, s[12:13]
	s_mov_b32 m0, s57
	s_nop 0
	global_load_lds_dwordx4 v[146:147], off
	s_barrier
	s_waitcnt lgkmcnt(0)
	s_setprio 1
	s_waitcnt lgkmcnt(0)
	v_mfma_f32_16x16x32_bf16 v[62:65], v[154:157], v[170:173], v[62:65]
	v_mfma_f32_16x16x32_bf16 v[58:61], v[162:165], v[170:173], v[58:61]
	v_mfma_f32_16x16x32_bf16 v[46:49], v[154:157], v[178:181], v[46:49]
	v_mfma_f32_16x16x32_bf16 v[42:45], v[162:165], v[178:181], v[42:45]
	v_mfma_f32_16x16x32_bf16 v[30:33], v[154:157], v[186:189], v[30:33]
	v_mfma_f32_16x16x32_bf16 v[26:29], v[162:165], v[186:189], v[26:29]
	v_mfma_f32_16x16x32_bf16 v[14:17], v[154:157], v[196:199], v[14:17]
	v_mfma_f32_16x16x32_bf16 v[10:13], v[162:165], v[196:199], v[10:13]
	v_mfma_f32_16x16x32_bf16 v[62:65], v[158:161], v[174:177], v[62:65]
	v_mfma_f32_16x16x32_bf16 v[58:61], v[166:169], v[174:177], v[58:61]
	v_mfma_f32_16x16x32_bf16 v[46:49], v[158:161], v[182:185], v[46:49]
	v_mfma_f32_16x16x32_bf16 v[42:45], v[166:169], v[182:185], v[42:45]
	v_mfma_f32_16x16x32_bf16 v[30:33], v[158:161], v[192:195], v[30:33]
	v_mfma_f32_16x16x32_bf16 v[26:29], v[166:169], v[192:195], v[26:29]
	v_mfma_f32_16x16x32_bf16 v[14:17], v[158:161], v[200:203], v[14:17]
	v_mfma_f32_16x16x32_bf16 v[10:13], v[166:169], v[200:203], v[10:13]
	s_setprio 0
	s_barrier
	s_add_u32 s44, s44, 0x80080
	s_addc_u32 s45, s45, 0
	s_add_i32 s46, s46, s52
	v_lshl_add_u64 v[146:147], s[44:45], 0, v[132:133]
	s_mov_b32 m0, s46
	s_nop 0
	global_load_lds_dwordx4 v[146:147], off
	v_lshl_add_u64 v[146:147], s[44:45], 0, v[136:137]
	s_add_i32 m0, s46, 0x2000
	s_nop 0
	global_load_lds_dwordx4 v[146:147], off
	s_waitcnt vmcnt(6)
	s_barrier
	s_setprio 1
	v_mfma_f32_16x16x32_bf16 v[54:57], v[204:207], v[170:173], v[54:57]
	v_mfma_f32_16x16x32_bf16 v[50:53], v[212:215], v[170:173], v[50:53]
	v_mfma_f32_16x16x32_bf16 v[38:41], v[204:207], v[178:181], v[38:41]
	v_mfma_f32_16x16x32_bf16 v[34:37], v[212:215], v[178:181], v[34:37]
	v_mfma_f32_16x16x32_bf16 v[22:25], v[204:207], v[186:189], v[22:25]
	v_mfma_f32_16x16x32_bf16 v[18:21], v[212:215], v[186:189], v[18:21]
	v_mfma_f32_16x16x32_bf16 v[6:9], v[204:207], v[196:199], v[6:9]
	v_mfma_f32_16x16x32_bf16 v[2:5], v[212:215], v[196:199], v[2:5]
	v_mfma_f32_16x16x32_bf16 v[54:57], v[208:211], v[174:177], v[54:57]
	v_mfma_f32_16x16x32_bf16 v[50:53], v[216:219], v[174:177], v[50:53]
	v_mfma_f32_16x16x32_bf16 v[38:41], v[208:211], v[182:185], v[38:41]
	v_mfma_f32_16x16x32_bf16 v[34:37], v[216:219], v[182:185], v[34:37]
	v_mfma_f32_16x16x32_bf16 v[22:25], v[208:211], v[192:195], v[22:25]
	v_mfma_f32_16x16x32_bf16 v[18:21], v[216:219], v[192:195], v[18:21]
	v_mfma_f32_16x16x32_bf16 v[6:9], v[208:211], v[200:203], v[6:9]
	v_mfma_f32_16x16x32_bf16 v[2:5], v[216:219], v[200:203], v[2:5]
	s_setprio 0
	s_add_i32 s62, s62, 2
	s_add_u32 s42, s42, 0x100
	s_addc_u32 s43, s43, 0
	s_add_u32 s29, s29, 0x100
	s_addc_u32 s31, s31, 0
	s_cmp_gt_u32 s62, 29
	s_barrier
	s_cbranch_scc0 .LBB0_850
	s_lshl_b32 s4, s40, 8
	s_and_b32 s4, s4, 0x3f00
	v_add_u32_e32 v162, s4, v1
	s_ashr_i32 s4, s38, 31
	s_lshr_b32 s4, s4, 29
	s_add_i32 s4, s38, s4
	s_and_b32 s4, s4, 0xfffff8
	s_sub_i32 s4, s38, s4
	v_lshl_or_b32 v164, s4, 8, v149
	v_ashrrev_i32_e32 v163, 31, v162
	v_ashrrev_i32_e32 v165, 31, v164
	v_lshlrev_b32_e32 v146, 13, v162
	v_lshl_add_u32 v146, v164, 2, v146
	v_lshlrev_b32_e32 v147, 12, v162
	v_lshl_add_u32 v147, v164, 1, v147
	s_add_u32 s64, s8, 0x0
	s_addc_u32 s65, s9, 0
	global_load_dwordx4 v[176:179], v146, s[64:65]
	global_load_dwordx4 v[180:183], v146, s[64:65] offset:16
	s_add_u32 s64, s8, 0x200
	s_addc_u32 s65, s9, 0
	global_load_dwordx4 v[184:187], v146, s[64:65]
	global_load_dwordx4 v[192:195], v146, s[64:65] offset:16
	s_add_u32 s64, s8, 0x20000
	s_addc_u32 s65, s9, 0
	global_load_dwordx4 v[196:199], v146, s[64:65]
	global_load_dwordx4 v[200:203], v146, s[64:65] offset:16
	s_add_u32 s64, s8, 0x20200
	s_addc_u32 s65, s9, 0
	global_load_dwordx4 v[204:207], v146, s[64:65]
	global_load_dwordx4 v[208:211], v146, s[64:65] offset:16
	s_add_u32 s64, s8, 0x40000
	s_addc_u32 s65, s9, 0
	global_load_dwordx4 v[212:215], v146, s[64:65]
	global_load_dwordx4 v[216:219], v146, s[64:65] offset:16
	s_add_u32 s64, s8, 0x40200
	s_addc_u32 s65, s9, 0
	global_load_dwordx4 v[220:223], v146, s[64:65]
	global_load_dwordx4 v[224:227], v146, s[64:65] offset:16
	s_add_u32 s64, s8, 0x60000
	s_addc_u32 s65, s9, 0
	global_load_dwordx4 v[228:231], v146, s[64:65]
	global_load_dwordx4 v[232:235], v146, s[64:65] offset:16
	s_add_u32 s64, s8, 0x60200
	s_addc_u32 s65, s9, 0
	global_load_dwordx4 v[236:239], v146, s[64:65]
	global_load_dwordx4 v[240:243], v146, s[64:65] offset:16
	s_waitcnt vmcnt(14)
	v_pk_fma_f32 v[176:177], v[176:177], s[14:15], v[126:127] op_sel_hi:[1,0,1]
	v_pk_fma_f32 v[178:179], v[178:179], s[14:15], v[128:129] op_sel_hi:[1,0,1]
	v_pk_fma_f32 v[180:181], v[180:181], s[14:15], v[122:123] op_sel_hi:[1,0,1]
	v_pk_fma_f32 v[182:183], v[182:183], s[14:15], v[124:125] op_sel_hi:[1,0,1]
	v_cvt_pk_bf16_f32 v176, v176, v177
	v_cvt_pk_bf16_f32 v177, v178, v179
	v_cvt_pk_bf16_f32 v178, v180, v181
	v_cvt_pk_bf16_f32 v179, v182, v183
	s_add_u32 s66, s10, 0x0
	s_addc_u32 s67, s11, 0
	global_store_dwordx4 v147, v[176:179], s[66:67]
	s_waitcnt vmcnt(13)
	v_pk_fma_f32 v[184:185], v[184:185], s[14:15], v[118:119] op_sel_hi:[1,0,1]
	v_pk_fma_f32 v[186:187], v[186:187], s[14:15], v[120:121] op_sel_hi:[1,0,1]
	v_pk_fma_f32 v[192:193], v[192:193], s[14:15], v[114:115] op_sel_hi:[1,0,1]
	v_pk_fma_f32 v[194:195], v[194:195], s[14:15], v[116:117] op_sel_hi:[1,0,1]
	v_cvt_pk_bf16_f32 v184, v184, v185
	v_cvt_pk_bf16_f32 v185, v186, v187
	v_cvt_pk_bf16_f32 v186, v192, v193
	v_cvt_pk_bf16_f32 v187, v194, v195
	s_add_u32 s66, s10, 0x100
	s_addc_u32 s67, s11, 0
	global_store_dwordx4 v147, v[184:187], s[66:67]
	s_waitcnt vmcnt(12)
	v_pk_fma_f32 v[196:197], v[196:197], s[14:15], v[110:111] op_sel_hi:[1,0,1]
	v_pk_fma_f32 v[198:199], v[198:199], s[14:15], v[112:113] op_sel_hi:[1,0,1]
	v_pk_fma_f32 v[200:201], v[200:201], s[14:15], v[106:107] op_sel_hi:[1,0,1]
	v_pk_fma_f32 v[202:203], v[202:203], s[14:15], v[108:109] op_sel_hi:[1,0,1]
	v_cvt_pk_bf16_f32 v196, v196, v197
	v_cvt_pk_bf16_f32 v197, v198, v199
	v_cvt_pk_bf16_f32 v198, v200, v201
	v_cvt_pk_bf16_f32 v199, v202, v203
	s_add_u32 s66, s10, 0x10000
	s_addc_u32 s67, s11, 0
	global_store_dwordx4 v147, v[196:199], s[66:67]
	s_waitcnt vmcnt(11)
	v_pk_fma_f32 v[204:205], v[204:205], s[14:15], v[102:103] op_sel_hi:[1,0,1]
	v_pk_fma_f32 v[206:207], v[206:207], s[14:15], v[104:105] op_sel_hi:[1,0,1]
	v_pk_fma_f32 v[208:209], v[208:209], s[14:15], v[98:99] op_sel_hi:[1,0,1]
	v_pk_fma_f32 v[210:211], v[210:211], s[14:15], v[100:101] op_sel_hi:[1,0,1]
	v_cvt_pk_bf16_f32 v204, v204, v205
	v_cvt_pk_bf16_f32 v205, v206, v207
	v_cvt_pk_bf16_f32 v206, v208, v209
	v_cvt_pk_bf16_f32 v207, v210, v211
	s_add_u32 s66, s10, 0x10100
	s_addc_u32 s67, s11, 0
	global_store_dwordx4 v147, v[204:207], s[66:67]
	s_waitcnt vmcnt(10)
	v_pk_fma_f32 v[212:213], v[212:213], s[14:15], v[94:95] op_sel_hi:[1,0,1]
	v_pk_fma_f32 v[214:215], v[214:215], s[14:15], v[96:97] op_sel_hi:[1,0,1]
	v_pk_fma_f32 v[216:217], v[216:217], s[14:15], v[90:91] op_sel_hi:[1,0,1]
	v_pk_fma_f32 v[218:219], v[218:219], s[14:15], v[92:93] op_sel_hi:[1,0,1]
	v_cvt_pk_bf16_f32 v212, v212, v213
	v_cvt_pk_bf16_f32 v213, v214, v215
	v_cvt_pk_bf16_f32 v214, v216, v217
	v_cvt_pk_bf16_f32 v215, v218, v219
	s_add_u32 s66, s10, 0x20000
	s_addc_u32 s67, s11, 0
	global_store_dwordx4 v147, v[212:215], s[66:67]
	s_waitcnt vmcnt(9)
	v_pk_fma_f32 v[220:221], v[220:221], s[14:15], v[86:87] op_sel_hi:[1,0,1]
	v_pk_fma_f32 v[222:223], v[222:223], s[14:15], v[88:89] op_sel_hi:[1,0,1]
	v_pk_fma_f32 v[224:225], v[224:225], s[14:15], v[82:83] op_sel_hi:[1,0,1]
	v_pk_fma_f32 v[226:227], v[226:227], s[14:15], v[84:85] op_sel_hi:[1,0,1]
	v_cvt_pk_bf16_f32 v220, v220, v221
	v_cvt_pk_bf16_f32 v221, v222, v223
	v_cvt_pk_bf16_f32 v222, v224, v225
	v_cvt_pk_bf16_f32 v223, v226, v227
	s_add_u32 s66, s10, 0x20100
	s_addc_u32 s67, s11, 0
	global_store_dwordx4 v147, v[220:223], s[66:67]
	s_waitcnt vmcnt(8)
	v_pk_fma_f32 v[228:229], v[228:229], s[14:15], v[78:79] op_sel_hi:[1,0,1]
	v_pk_fma_f32 v[230:231], v[230:231], s[14:15], v[80:81] op_sel_hi:[1,0,1]
	v_pk_fma_f32 v[232:233], v[232:233], s[14:15], v[74:75] op_sel_hi:[1,0,1]
	v_pk_fma_f32 v[234:235], v[234:235], s[14:15], v[76:77] op_sel_hi:[1,0,1]
	v_cvt_pk_bf16_f32 v228, v228, v229
	v_cvt_pk_bf16_f32 v229, v230, v231
	v_cvt_pk_bf16_f32 v230, v232, v233
	v_cvt_pk_bf16_f32 v231, v234, v235
	s_add_u32 s66, s10, 0x30000
	s_addc_u32 s67, s11, 0
	global_store_dwordx4 v147, v[228:231], s[66:67]
	s_waitcnt vmcnt(7)
	v_pk_fma_f32 v[236:237], v[236:237], s[14:15], v[70:71] op_sel_hi:[1,0,1]
	v_pk_fma_f32 v[238:239], v[238:239], s[14:15], v[72:73] op_sel_hi:[1,0,1]
	v_pk_fma_f32 v[240:241], v[240:241], s[14:15], v[66:67] op_sel_hi:[1,0,1]
	v_pk_fma_f32 v[242:243], v[242:243], s[14:15], v[68:69] op_sel_hi:[1,0,1]
	v_cvt_pk_bf16_f32 v236, v236, v237
	v_cvt_pk_bf16_f32 v237, v238, v239
	v_cvt_pk_bf16_f32 v238, v240, v241
	v_cvt_pk_bf16_f32 v239, v242, v243
	s_add_u32 s66, s10, 0x30100
	s_addc_u32 s67, s11, 0
	global_store_dwordx4 v147, v[236:239], s[66:67]
	s_add_u32 s64, s8, 0x100000
	s_addc_u32 s65, s9, 0
	global_load_dwordx4 v[176:179], v146, s[64:65]
	global_load_dwordx4 v[180:183], v146, s[64:65] offset:16
	s_add_u32 s64, s8, 0x100200
	s_addc_u32 s65, s9, 0
	global_load_dwordx4 v[184:187], v146, s[64:65]
	global_load_dwordx4 v[192:195], v146, s[64:65] offset:16
	s_add_u32 s64, s8, 0x120000
	s_addc_u32 s65, s9, 0
	global_load_dwordx4 v[196:199], v146, s[64:65]
	global_load_dwordx4 v[200:203], v146, s[64:65] offset:16
	s_add_u32 s64, s8, 0x120200
	s_addc_u32 s65, s9, 0
	global_load_dwordx4 v[204:207], v146, s[64:65]
	global_load_dwordx4 v[208:211], v146, s[64:65] offset:16
	s_add_u32 s64, s8, 0x140000
	s_addc_u32 s65, s9, 0
	global_load_dwordx4 v[212:215], v146, s[64:65]
	global_load_dwordx4 v[216:219], v146, s[64:65] offset:16
	s_add_u32 s64, s8, 0x140200
	s_addc_u32 s65, s9, 0
	global_load_dwordx4 v[220:223], v146, s[64:65]
	global_load_dwordx4 v[224:227], v146, s[64:65] offset:16
	s_add_u32 s64, s8, 0x160000
	s_addc_u32 s65, s9, 0
	global_load_dwordx4 v[228:231], v146, s[64:65]
	global_load_dwordx4 v[232:235], v146, s[64:65] offset:16
	s_add_u32 s64, s8, 0x160200
	s_addc_u32 s65, s9, 0
	global_load_dwordx4 v[236:239], v146, s[64:65]
	global_load_dwordx4 v[240:243], v146, s[64:65] offset:16
	s_waitcnt vmcnt(14)
	v_pk_fma_f32 v[176:177], v[176:177], s[14:15], v[62:63] op_sel_hi:[1,0,1]
	v_pk_fma_f32 v[178:179], v[178:179], s[14:15], v[64:65] op_sel_hi:[1,0,1]
	v_pk_fma_f32 v[180:181], v[180:181], s[14:15], v[58:59] op_sel_hi:[1,0,1]
	v_pk_fma_f32 v[182:183], v[182:183], s[14:15], v[60:61] op_sel_hi:[1,0,1]
	v_cvt_pk_bf16_f32 v176, v176, v177
	v_cvt_pk_bf16_f32 v177, v178, v179
	v_cvt_pk_bf16_f32 v178, v180, v181
	v_cvt_pk_bf16_f32 v179, v182, v183
	s_add_u32 s66, s10, 0x80000
	s_addc_u32 s67, s11, 0
	global_store_dwordx4 v147, v[176:179], s[66:67]
	s_waitcnt vmcnt(13)
	v_pk_fma_f32 v[184:185], v[184:185], s[14:15], v[54:55] op_sel_hi:[1,0,1]
	v_pk_fma_f32 v[186:187], v[186:187], s[14:15], v[56:57] op_sel_hi:[1,0,1]
	v_pk_fma_f32 v[192:193], v[192:193], s[14:15], v[50:51] op_sel_hi:[1,0,1]
	v_pk_fma_f32 v[194:195], v[194:195], s[14:15], v[52:53] op_sel_hi:[1,0,1]
	v_cvt_pk_bf16_f32 v184, v184, v185
	v_cvt_pk_bf16_f32 v185, v186, v187
	v_cvt_pk_bf16_f32 v186, v192, v193
	v_cvt_pk_bf16_f32 v187, v194, v195
	s_add_u32 s66, s10, 0x80100
	s_addc_u32 s67, s11, 0
	global_store_dwordx4 v147, v[184:187], s[66:67]
	s_waitcnt vmcnt(12)
	v_pk_fma_f32 v[196:197], v[196:197], s[14:15], v[46:47] op_sel_hi:[1,0,1]
	v_pk_fma_f32 v[198:199], v[198:199], s[14:15], v[48:49] op_sel_hi:[1,0,1]
	v_pk_fma_f32 v[200:201], v[200:201], s[14:15], v[42:43] op_sel_hi:[1,0,1]
	v_pk_fma_f32 v[202:203], v[202:203], s[14:15], v[44:45] op_sel_hi:[1,0,1]
	v_cvt_pk_bf16_f32 v196, v196, v197
	v_cvt_pk_bf16_f32 v197, v198, v199
	v_cvt_pk_bf16_f32 v198, v200, v201
	v_cvt_pk_bf16_f32 v199, v202, v203
	s_add_u32 s66, s10, 0x90000
	s_addc_u32 s67, s11, 0
	global_store_dwordx4 v147, v[196:199], s[66:67]
	s_waitcnt vmcnt(11)
	v_pk_fma_f32 v[204:205], v[204:205], s[14:15], v[38:39] op_sel_hi:[1,0,1]
	v_pk_fma_f32 v[206:207], v[206:207], s[14:15], v[40:41] op_sel_hi:[1,0,1]
	v_pk_fma_f32 v[208:209], v[208:209], s[14:15], v[34:35] op_sel_hi:[1,0,1]
	v_pk_fma_f32 v[210:211], v[210:211], s[14:15], v[36:37] op_sel_hi:[1,0,1]
	v_cvt_pk_bf16_f32 v204, v204, v205
	v_cvt_pk_bf16_f32 v205, v206, v207
	v_cvt_pk_bf16_f32 v206, v208, v209
	v_cvt_pk_bf16_f32 v207, v210, v211
	s_add_u32 s66, s10, 0x90100
	s_addc_u32 s67, s11, 0
	global_store_dwordx4 v147, v[204:207], s[66:67]
	s_waitcnt vmcnt(10)
	v_pk_fma_f32 v[212:213], v[212:213], s[14:15], v[30:31] op_sel_hi:[1,0,1]
	v_pk_fma_f32 v[214:215], v[214:215], s[14:15], v[32:33] op_sel_hi:[1,0,1]
	v_pk_fma_f32 v[216:217], v[216:217], s[14:15], v[26:27] op_sel_hi:[1,0,1]
	v_pk_fma_f32 v[218:219], v[218:219], s[14:15], v[28:29] op_sel_hi:[1,0,1]
	v_cvt_pk_bf16_f32 v212, v212, v213
	v_cvt_pk_bf16_f32 v213, v214, v215
	v_cvt_pk_bf16_f32 v214, v216, v217
	v_cvt_pk_bf16_f32 v215, v218, v219
	s_add_u32 s66, s10, 0xa0000
	s_addc_u32 s67, s11, 0
	global_store_dwordx4 v147, v[212:215], s[66:67]
	s_waitcnt vmcnt(9)
	v_pk_fma_f32 v[220:221], v[220:221], s[14:15], v[22:23] op_sel_hi:[1,0,1]
	v_pk_fma_f32 v[222:223], v[222:223], s[14:15], v[24:25] op_sel_hi:[1,0,1]
	v_pk_fma_f32 v[224:225], v[224:225], s[14:15], v[18:19] op_sel_hi:[1,0,1]
	v_pk_fma_f32 v[226:227], v[226:227], s[14:15], v[20:21] op_sel_hi:[1,0,1]
	v_cvt_pk_bf16_f32 v220, v220, v221
	v_cvt_pk_bf16_f32 v221, v222, v223
	v_cvt_pk_bf16_f32 v222, v224, v225
	v_cvt_pk_bf16_f32 v223, v226, v227
	s_add_u32 s66, s10, 0xa0100
	s_addc_u32 s67, s11, 0
	global_store_dwordx4 v147, v[220:223], s[66:67]
	s_waitcnt vmcnt(8)
	v_pk_fma_f32 v[228:229], v[228:229], s[14:15], v[14:15] op_sel_hi:[1,0,1]
	v_pk_fma_f32 v[230:231], v[230:231], s[14:15], v[16:17] op_sel_hi:[1,0,1]
	v_pk_fma_f32 v[232:233], v[232:233], s[14:15], v[10:11] op_sel_hi:[1,0,1]
	v_pk_fma_f32 v[234:235], v[234:235], s[14:15], v[12:13] op_sel_hi:[1,0,1]
	v_cvt_pk_bf16_f32 v228, v228, v229
	v_cvt_pk_bf16_f32 v229, v230, v231
	v_cvt_pk_bf16_f32 v230, v232, v233
	v_cvt_pk_bf16_f32 v231, v234, v235
	s_add_u32 s66, s10, 0xb0000
	s_addc_u32 s67, s11, 0
	global_store_dwordx4 v147, v[228:231], s[66:67]
	s_waitcnt vmcnt(7)
	v_pk_fma_f32 v[236:237], v[236:237], s[14:15], v[6:7] op_sel_hi:[1,0,1]
	v_pk_fma_f32 v[238:239], v[238:239], s[14:15], v[8:9] op_sel_hi:[1,0,1]
	v_pk_fma_f32 v[240:241], v[240:241], s[14:15], v[2:3] op_sel_hi:[1,0,1]
	v_pk_fma_f32 v[242:243], v[242:243], s[14:15], v[4:5] op_sel_hi:[1,0,1]
	v_cvt_pk_bf16_f32 v236, v236, v237
	v_cvt_pk_bf16_f32 v237, v238, v239
	v_cvt_pk_bf16_f32 v238, v240, v241
	v_cvt_pk_bf16_f32 v239, v242, v243
	s_add_u32 s66, s10, 0xb0100
	s_addc_u32 s67, s11, 0
	global_store_dwordx4 v147, v[236:239], s[66:67]
	s_and_b64 vcc, exec, s[6:7]
	s_mov_b32 s40, s28
	s_mov_b32 s38, s30
	s_mov_b64 s[44:45], s[36:37]
	s_mov_b64 s[42:43], s[34:35]
	s_cbranch_vccz .LBB0_843
	s_waitcnt vmcnt(0)
	s_cmpk_gt_u32 s3, 0xff
	s_cbranch_scc1 .LBB0_854
	s_barrier

.LBB0_924:
	s_mov_b64 s[4:5], s[0:1]
	s_load_dword s3, s[4:5], 0xe8
	s_waitcnt lgkmcnt(0)
	s_cmp_gt_i32 s3, 8
	s_cbranch_scc1 .LBB0_933
	s_mov_b64 s[4:5], s[0:1]
	s_load_dword s3, s[4:5], 0xec
	s_waitcnt lgkmcnt(0)
	s_cmp_lt_i32 s3, 9
	s_cbranch_scc1 .LBB0_933
	s_mov_b64 s[10:11], s[0:1]
	s_mov_b64 s[6:7], s[0:1]
	s_mov_b64 s[12:13], s[0:1]
	s_mov_b64 s[16:17], s[0:1]
	s_mov_b64 s[4:5], s[0:1]
	v_mov_b32_e32 v1, v190
	s_mov_b32 s8, s2
	s_lshl_b32 s8, s8, 3
	v_readfirstlane_b32 s3, v1
	s_ashr_i32 s3, s3, 6
	s_add_i32 s8, s8, s3
	s_cmpk_gt_i32 s8, 0x3fff
	s_cbranch_scc1 .LBB0_933
	s_load_dwordx2 s[22:23], s[10:11], 0xe0
	s_ashr_i32 s9, s8, 31
	s_lshl_b32 s10, s24, 3
	s_lshl_b64 s[18:19], s[8:9], 12
	s_waitcnt vmcnt(0)
	v_and_b32_e32 v6, 63, v1
	s_waitcnt lgkmcnt(0)
	s_add_u32 s14, s22, s18
	s_addc_u32 s15, s23, s19
	v_lshlrev_b32_e32 v34, 4, v6
	v_mov_b32_e32 v35, 0
	v_lshl_add_u64 v[2:3], s[14:15], 0, v[34:35]
	s_mov_b64 s[14:15], 0x20100000
	s_mov_b32 s3, 0x20100000
	v_lshl_add_u64 v[4:5], v[2:3], 0, s[14:15]
	v_add_co_u32_e32 v2, vcc, s3, v2
	global_load_dwordx4 v[26:29], v[4:5], off offset:1024
	global_load_dwordx4 v[22:25], v[4:5], off offset:2048
	global_load_dwordx4 v[18:21], v[4:5], off offset:3072
	v_addc_co_u32_e32 v3, vcc, 0, v3, vcc
	global_load_dwordx4 v[30:33], v[2:3], off
	s_load_dwordx2 s[28:29], s[6:7], 0xb8
	s_load_dwordx2 s[30:31], s[12:13], 0xc0
	s_load_dwordx2 s[20:21], s[16:17], 0xe0
	s_load_dwordx2 s[14:15], s[4:5], 0xe0
	v_mbcnt_lo_u32_b32 v2, -1, 0
	v_mbcnt_hi_u32_b32 v10, -1, v2
	v_and_b32_e32 v12, 64, v10
	v_xor_b32_e32 v11, 16, v10
	v_add_u32_e32 v12, 64, v12
	v_xor_b32_e32 v13, 32, v10
	v_cmp_lt_i32_e64 s[6:7], v11, v12
	s_waitcnt lgkmcnt(0)
	s_cmp_lg_u64 s[14:15], 0
	v_cmp_eq_u32_e32 vcc, 0, v6
	v_cndmask_b32_e64 v11, v10, v11, s[6:7]
	v_cmp_lt_i32_e64 s[6:7], v13, v12
	s_cselect_b64 s[4:5], -1, 0
	s_and_b64 s[12:13], s[4:5], vcc
	v_cndmask_b32_e64 v10, v10, v13, s[6:7]
	s_lshl_b64 s[6:7], s[8:9], 3
	s_add_u32 s14, s14, s6
	s_addc_u32 s15, s15, s7
	s_ashr_i32 s11, s10, 31
	s_lshl_b64 s[16:17], s[10:11], 3
	s_add_u32 s18, s20, s18
	s_addc_u32 s19, s21, s19
	s_add_i32 s4, s8, s10
	v_lshlrev_b32_e32 v2, 5, v6
	s_ashr_i32 s5, s4, 31
	v_mov_b32_e32 v3, v35
	v_mov_b32_e32 v5, v35
	v_mov_b32_e32 v7, v35
	v_mov_b32_e32 v9, v35
	v_or_b32_e32 v4, 0x800, v2
	v_or_b32_e32 v6, 0x1000, v2
	v_or_b32_e32 v8, 0x1800, v2
	s_lshl_b64 s[20:21], s[10:11], 12
	s_lshl_b64 s[4:5], s[4:5], 12
	v_lshlrev_b32_e32 v70, 2, v11
	v_lshlrev_b32_e32 v71, 2, v10
	v_lshl_add_u64 v[36:37], s[28:29], 0, v[2:3]
	v_lshl_add_u64 v[38:39], s[30:31], 0, v[2:3]
	v_lshl_add_u64 v[40:41], s[28:29], 0, v[4:5]
	v_lshl_add_u64 v[42:43], s[30:31], 0, v[4:5]
	v_lshl_add_u64 v[44:45], s[28:29], 0, v[6:7]
	v_lshl_add_u64 v[46:47], s[30:31], 0, v[6:7]
	v_lshl_add_u64 v[48:49], s[28:29], 0, v[8:9]
	v_lshl_add_u64 v[50:51], s[30:31], 0, v[8:9]
	global_load_dwordx4 v[100:103], v[36:37], off
	global_load_dwordx4 v[104:107], v[36:37], off offset:16
	global_load_dwordx4 v[108:111], v[38:39], off
	global_load_dwordx4 v[112:115], v[38:39], off offset:16
	global_load_dwordx4 v[116:119], v[40:41], off
	global_load_dwordx4 v[120:123], v[40:41], off offset:16
	global_load_dwordx4 v[124:127], v[42:43], off
	global_load_dwordx4 v[128:131], v[42:43], off offset:16
	global_load_dwordx4 v[132:135], v[44:45], off
	global_load_dwordx4 v[136:139], v[44:45], off offset:16
	global_load_dwordx4 v[140:143], v[46:47], off
	global_load_dwordx4 v[144:147], v[46:47], off offset:16
	global_load_dwordx4 v[148:151], v[48:49], off
	global_load_dwordx4 v[152:155], v[48:49], off offset:16
	global_load_dwordx4 v[156:159], v[50:51], off
	global_load_dwordx4 v[160:163], v[50:51], off offset:16
	s_add_u32 s22, s22, s4
	v_mov_b32_e32 v1, 0x3727c5ac
	s_mov_b32 s3, 0xf800000
	v_mov_b32_e32 v69, 0x260
	s_mov_b32 s26, 0x8100000
	s_addc_u32 s23, s23, s5
	s_waitcnt vmcnt(0)
	v_mov_b64_e32 v[10:11], v[26:27]
	s_waitcnt vmcnt(2)
	v_mov_b64_e32 v[6:7], v[22:23]
	s_waitcnt vmcnt(1)
	v_mov_b64_e32 v[2:3], v[18:19]
	v_mov_b64_e32 v[4:5], v[20:21]
	v_mov_b64_e32 v[8:9], v[24:25]
	s_waitcnt vmcnt(0)
	v_mov_b64_e32 v[14:15], v[30:31]
	v_mov_b64_e32 v[12:13], v[28:29]
	v_mov_b64_e32 v[16:17], v[32:33]
	s_branch .LBB0_929
.LBB0_928:
	s_or_b64 exec, exec, s[4:5]
	v_pk_mul_f32 v[66:67], v[66:67], v[68:69] op_sel_hi:[1,0]
	v_pk_mul_f32 v[64:65], v[64:65], v[68:69] op_sel_hi:[1,0]
	v_pk_mul_f32 v[62:63], v[62:63], v[68:69] op_sel_hi:[1,0]
	v_pk_mul_f32 v[60:61], v[60:61], v[68:69] op_sel_hi:[1,0]
	v_lshl_add_u64 v[88:89], s[18:19], 0, v[34:35]
	v_add_co_u32_e32 v88, vcc, s26, v88
	v_pk_mul_f32 v[58:59], v[58:59], v[68:69] op_sel_hi:[1,0]
	s_nop 0
	v_addc_co_u32_e32 v89, vcc, 0, v89, vcc
	v_pk_mul_f32 v[56:57], v[56:57], v[68:69] op_sel_hi:[1,0]
	v_pk_mul_f32 v[54:55], v[54:55], v[68:69] op_sel_hi:[1,0]
	v_pk_mul_f32 v[52:53], v[52:53], v[68:69] op_sel_hi:[1,0]
	v_pk_mul_f32 v[32:33], v[32:33], v[68:69] op_sel_hi:[1,0]
	v_pk_mul_f32 v[30:31], v[30:31], v[68:69] op_sel_hi:[1,0]
	v_pk_mul_f32 v[28:29], v[28:29], v[68:69] op_sel_hi:[1,0]
	v_pk_mul_f32 v[26:27], v[26:27], v[68:69] op_sel_hi:[1,0]
	s_add_u32 s14, s14, s16
	s_addc_u32 s15, s15, s17
	s_add_u32 s18, s18, s20
	s_addc_u32 s19, s19, s21
	s_add_u32 s22, s22, s20
	s_addc_u32 s23, s23, s21
	s_andn2_b64 vcc, exec, s[28:29]
	v_pk_fma_f32 v[66:67], v[66:67], v[102:103], v[110:111]
	v_pk_fma_f32 v[64:65], v[64:65], v[100:101], v[108:109]
	v_pk_fma_f32 v[72:73], v[62:63], v[106:107], v[114:115]
	v_pk_fma_f32 v[62:63], v[60:61], v[104:105], v[112:113]
	v_cvt_pk_bf16_f32 v60, v64, v65
	v_cvt_pk_bf16_f32 v61, v66, v67
	v_cvt_pk_bf16_f32 v62, v62, v63
	v_cvt_pk_bf16_f32 v63, v72, v73
	global_store_dwordx4 v[88:89], v[60:63], off
	s_nop 1
	s_nop 0
	v_pk_fma_f32 v[58:59], v[58:59], v[118:119], v[126:127]
	v_pk_fma_f32 v[56:57], v[56:57], v[116:117], v[124:125]
	v_pk_fma_f32 v[60:61], v[54:55], v[122:123], v[130:131]
	v_pk_fma_f32 v[54:55], v[52:53], v[120:121], v[128:129]
	v_cvt_pk_bf16_f32 v52, v56, v57
	v_cvt_pk_bf16_f32 v53, v58, v59
	v_cvt_pk_bf16_f32 v54, v54, v55
	v_cvt_pk_bf16_f32 v55, v60, v61
	global_store_dwordx4 v[88:89], v[52:55], off offset:1024
	s_nop 1
	s_nop 0
	v_pk_mul_f32 v[72:73], v[20:21], v[68:69] op_sel_hi:[1,0]
	v_pk_mul_f32 v[74:75], v[18:19], v[68:69] op_sel_hi:[1,0]
	s_waitcnt vmcnt(2)
	v_mov_b64_e32 v[20:21], v[4:5]
	v_mov_b64_e32 v[18:19], v[2:3]
	v_pk_fma_f32 v[32:33], v[32:33], v[134:135], v[142:143]
	v_pk_fma_f32 v[30:31], v[30:31], v[132:133], v[140:141]
	v_pk_fma_f32 v[52:53], v[28:29], v[138:139], v[146:147]
	v_pk_fma_f32 v[28:29], v[26:27], v[136:137], v[144:145]
	v_cvt_pk_bf16_f32 v26, v30, v31
	v_cvt_pk_bf16_f32 v27, v32, v33
	v_cvt_pk_bf16_f32 v28, v28, v29
	v_cvt_pk_bf16_f32 v29, v52, v53
	global_store_dwordx4 v[88:89], v[26:29], off offset:2048
	s_nop 1
	v_pk_mul_f32 v[64:65], v[24:25], v[68:69] op_sel_hi:[1,0]
	v_pk_mul_f32 v[66:67], v[22:23], v[68:69] op_sel_hi:[1,0]
	v_mov_b64_e32 v[24:25], v[8:9]
	v_mov_b64_e32 v[28:29], v[12:13]
	v_mov_b64_e32 v[22:23], v[6:7]
	v_mov_b64_e32 v[26:27], v[10:11]
	v_pk_fma_f32 v[32:33], v[64:65], v[150:151], v[158:159]
	v_pk_fma_f32 v[30:31], v[66:67], v[148:149], v[156:157]
	v_pk_fma_f32 v[52:53], v[72:73], v[154:155], v[162:163]
	v_pk_fma_f32 v[54:55], v[74:75], v[152:153], v[160:161]
	v_cvt_pk_bf16_f32 v30, v30, v31
	v_cvt_pk_bf16_f32 v31, v32, v33
	v_cvt_pk_bf16_f32 v32, v54, v55
	v_cvt_pk_bf16_f32 v33, v52, v53
	global_store_dwordx4 v[88:89], v[30:33], off offset:3072
	s_nop 1
	s_nop 1
	v_mov_b64_e32 v[32:33], v[16:17]
	v_mov_b64_e32 v[30:31], v[14:15]
	s_cbranch_vccz .LBB0_933

.LBB0_1106:
	v_add3_u32 v66, v107, v175, s28
	s_andn2_b32 s4, 1, s14
	v_lshlrev_b32_e32 v66, s6, v66
	v_min_i32_e32 v164, 15, v163
	v_add_u32_e32 v138, s43, v66
	s_lshl_b32 s5, s4, 7
	s_and_b64 vcc, exec, s[94:95]
	s_cbranch_vccz .Lat_norm
	v_ashrrev_i32_e32 v219, 31, v138
	v_mov_b32_e32 v218, v138
	v_lshl_add_u64 v[220:221], s[96:97], 0, v[218:219]
	v_lshlrev_b64 v[222:223], 12, v[220:221]
	v_lshl_add_u64 v[222:223], v[136:137], 0, v[222:223]
	v_lshlrev_b64 v[220:221], 6, v[220:221]
	v_lshl_add_u64 v[224:225], s[64:65], 0, v[220:221]
	global_load_dwordx2 v[128:129], v[222:223], off
	global_load_dwordx2 v[126:127], v[222:223], off offset:32
	global_load_dwordx2 v[124:125], v[222:223], off offset:64
	global_load_dwordx2 v[122:123], v[222:223], off offset:96
	global_load_dwordx2 v[120:121], v[222:223], off offset:128
	global_load_dwordx2 v[118:119], v[222:223], off offset:160
	global_load_dwordx2 v[116:117], v[222:223], off offset:192
	global_load_dwordx2 v[114:115], v[222:223], off offset:224
	global_load_dword v226, v[224:225], off
.Lat_norm:
	v_lshlrev_b32_e32 v66, 4, v164
	v_bitop3_b32 v66, v66, v107, s5 bitop3:0xde
	v_mad_u64_u32 v[74:75], s[44:45], v66, s35, v[110:111]
	ds_read_b128 v[66:69], v74
	ds_read_b128 v[70:73], v74 offset:64
	v_min_i32_e32 v165, 14, v163
	v_add_u32_e32 v166, 2, v163
	s_waitcnt lgkmcnt(1)
	v_mfma_f32_16x16x32_bf16 v[66:69], v[66:69], v[62:65], 0
	v_min_i32_e32 v167, 15, v166
	v_add_u32_e32 v168, 4, v163
	v_min_i32_e32 v169, 15, v168
	s_waitcnt lgkmcnt(0)
	v_mfma_f32_16x16x32_bf16 v[66:69], v[70:73], v[58:61], v[66:69]
	ds_read_b128 v[70:73], v74 offset:128
	v_add_u32_e32 v170, 6, v163
	v_min_i32_e32 v171, 15, v170
	s_waitcnt lgkmcnt(0)
	v_mfma_f32_16x16x32_bf16 v[66:69], v[70:73], v[54:57], v[66:69]
	ds_read_b128 v[70:73], v74 offset:192
	v_add_u32_e32 v182, 9, v163
	s_cmp_gt_i32 s14, 0
	s_waitcnt lgkmcnt(0)
	v_mfma_f32_16x16x32_bf16 v[66:69], v[70:73], v[50:53], v[66:69]
	v_lshl_add_u32 v70, v165, 4, 16
	v_bitop3_b32 v70, v70, v107, s5 bitop3:0xde
	v_mad_u64_u32 v[78:79], s[44:45], v70, s35, v[110:111]
	ds_read_b128 v[70:73], v78
	ds_read_b128 v[74:77], v78 offset:64
	s_waitcnt lgkmcnt(1)
	v_mfma_f32_16x16x32_bf16 v[70:73], v[70:73], v[62:65], 0
	v_cmp_lt_i32_e64 s[14:15], 7, v163
	v_cmp_gt_i32_e32 vcc, 16, v163
	v_or_b32_e32 v174, v175, v107
	s_waitcnt lgkmcnt(0)
	v_mfma_f32_16x16x32_bf16 v[70:73], v[74:77], v[58:61], v[70:73]
	ds_read_b128 v[74:77], v78 offset:128
	v_ashrrev_i32_e32 v139, 31, v138
	s_waitcnt lgkmcnt(0)
	v_mfma_f32_16x16x32_bf16 v[70:73], v[74:77], v[54:57], v[70:73]
	ds_read_b128 v[74:77], v78 offset:192
	s_waitcnt lgkmcnt(0)
	v_mfma_f32_16x16x32_bf16 v[70:73], v[74:77], v[50:53], v[70:73]
	v_lshlrev_b32_e32 v74, 4, v167
	v_bitop3_b32 v74, v74, v107, s5 bitop3:0xde
	v_mad_u64_u32 v[82:83], s[44:45], v74, s35, v[110:111]
	ds_read_b128 v[74:77], v82
	ds_read_b128 v[78:81], v82 offset:64
	s_waitcnt lgkmcnt(1)
	v_mfma_f32_16x16x32_bf16 v[74:77], v[74:77], v[62:65], 0
	s_waitcnt lgkmcnt(0)
	v_mfma_f32_16x16x32_bf16 v[74:77], v[78:81], v[58:61], v[74:77]
	ds_read_b128 v[78:81], v82 offset:128
	s_waitcnt lgkmcnt(0)
	v_mfma_f32_16x16x32_bf16 v[74:77], v[78:81], v[54:57], v[74:77]
	ds_read_b128 v[78:81], v82 offset:192
	s_waitcnt lgkmcnt(0)
	v_mfma_f32_16x16x32_bf16 v[74:77], v[78:81], v[50:53], v[74:77]
	v_min_i32_e32 v78, 12, v163
	v_lshl_add_u32 v78, v78, 4, 48
	v_bitop3_b32 v78, v78, v107, s5 bitop3:0xde
	v_mad_u64_u32 v[86:87], s[44:45], v78, s35, v[110:111]
	ds_read_b128 v[78:81], v86
	ds_read_b128 v[82:85], v86 offset:64
	s_waitcnt lgkmcnt(1)
	v_mfma_f32_16x16x32_bf16 v[78:81], v[78:81], v[62:65], 0
	s_waitcnt lgkmcnt(0)
	v_mfma_f32_16x16x32_bf16 v[78:81], v[82:85], v[58:61], v[78:81]
	ds_read_b128 v[82:85], v86 offset:128
	s_waitcnt lgkmcnt(0)
	v_mfma_f32_16x16x32_bf16 v[78:81], v[82:85], v[54:57], v[78:81]
	ds_read_b128 v[82:85], v86 offset:192
	s_waitcnt lgkmcnt(0)
	v_mfma_f32_16x16x32_bf16 v[78:81], v[82:85], v[50:53], v[78:81]
	v_lshlrev_b32_e32 v82, 4, v169
	v_bitop3_b32 v82, v82, v107, s5 bitop3:0xde
	v_mad_u64_u32 v[90:91], s[44:45], v82, s35, v[110:111]
	ds_read_b128 v[82:85], v90
	ds_read_b128 v[86:89], v90 offset:64
	s_waitcnt lgkmcnt(1)
	v_mfma_f32_16x16x32_bf16 v[82:85], v[82:85], v[62:65], 0
	s_waitcnt lgkmcnt(0)
	v_mfma_f32_16x16x32_bf16 v[82:85], v[86:89], v[58:61], v[82:85]
	ds_read_b128 v[86:89], v90 offset:128
	s_waitcnt lgkmcnt(0)
	v_mfma_f32_16x16x32_bf16 v[82:85], v[86:89], v[54:57], v[82:85]
	ds_read_b128 v[86:89], v90 offset:192
	s_waitcnt lgkmcnt(0)
	v_mfma_f32_16x16x32_bf16 v[82:85], v[86:89], v[50:53], v[82:85]
	v_min_i32_e32 v86, 10, v163
	v_lshl_add_u32 v86, v86, 4, v201
	v_bitop3_b32 v86, v86, v107, s5 bitop3:0xde
	v_mad_u64_u32 v[94:95], s[44:45], v86, s35, v[110:111]
	ds_read_b128 v[86:89], v94
	ds_read_b128 v[90:93], v94 offset:64
	s_waitcnt lgkmcnt(1)
	v_mfma_f32_16x16x32_bf16 v[86:89], v[86:89], v[62:65], 0
	s_waitcnt lgkmcnt(0)
	v_mfma_f32_16x16x32_bf16 v[86:89], v[90:93], v[58:61], v[86:89]
	ds_read_b128 v[90:93], v94 offset:128
	s_waitcnt lgkmcnt(0)
	v_mfma_f32_16x16x32_bf16 v[86:89], v[90:93], v[54:57], v[86:89]
	ds_read_b128 v[90:93], v94 offset:192
	s_waitcnt lgkmcnt(0)
	v_mfma_f32_16x16x32_bf16 v[86:89], v[90:93], v[50:53], v[86:89]
	v_lshlrev_b32_e32 v90, 4, v171
	v_bitop3_b32 v90, v90, v107, s5 bitop3:0xde
	v_mad_u64_u32 v[98:99], s[44:45], v90, s35, v[110:111]
	ds_read_b128 v[90:93], v98
	ds_read_b128 v[94:97], v98 offset:64
	s_waitcnt lgkmcnt(1)
	v_mfma_f32_16x16x32_bf16 v[90:93], v[90:93], v[62:65], 0
	s_waitcnt lgkmcnt(0)
	v_mfma_f32_16x16x32_bf16 v[90:93], v[94:97], v[58:61], v[90:93]
	ds_read_b128 v[94:97], v98 offset:128
	s_waitcnt lgkmcnt(0)
	v_mfma_f32_16x16x32_bf16 v[90:93], v[94:97], v[54:57], v[90:93]
	ds_read_b128 v[94:97], v98 offset:192
	s_waitcnt lgkmcnt(0)
	v_mfma_f32_16x16x32_bf16 v[90:93], v[94:97], v[50:53], v[90:93]
	v_min_i32_e32 v94, 8, v163
	v_lshl_add_u32 v94, v94, 4, v202
	v_bitop3_b32 v94, v94, v107, s5 bitop3:0xde
	v_mad_u64_u32 v[172:173], s[44:45], v94, s35, v[110:111]
	ds_read_b128 v[94:97], v172
	ds_read_b128 v[98:101], v172 offset:64
	s_waitcnt lgkmcnt(1)
	v_mfma_f32_16x16x32_bf16 v[94:97], v[94:97], v[62:65], 0
	s_waitcnt lgkmcnt(0)
	v_mfma_f32_16x16x32_bf16 v[94:97], v[98:101], v[58:61], v[94:97]
	ds_read_b128 v[98:101], v172 offset:128
	s_waitcnt lgkmcnt(0)
	v_mfma_f32_16x16x32_bf16 v[94:97], v[98:101], v[54:57], v[94:97]
	ds_read_b128 v[98:101], v172 offset:192
	v_add_u32_e32 v172, 8, v163
	v_min_i32_e32 v173, 15, v172
	s_waitcnt lgkmcnt(0)
	v_mfma_f32_16x16x32_bf16 v[98:101], v[98:101], v[50:53], v[94:97]
	s_nop 2
	v_lshlrev_b32_e32 v94, 4, v173
	v_bitop3_b32 v94, v94, v107, s5 bitop3:0xde
	v_mad_u64_u32 v[180:181], s[44:45], v94, s35, v[110:111]
	ds_read_b128 v[94:97], v180
	ds_read_b128 v[176:179], v180 offset:64
	s_waitcnt lgkmcnt(1)
	v_mfma_f32_16x16x32_bf16 v[94:97], v[94:97], v[62:65], 0
	s_waitcnt lgkmcnt(0)
	v_mfma_f32_16x16x32_bf16 v[94:97], v[176:179], v[58:61], v[94:97]
	ds_read_b128 v[176:179], v180 offset:128
	s_waitcnt lgkmcnt(0)
	v_mfma_f32_16x16x32_bf16 v[94:97], v[176:179], v[54:57], v[94:97]
	ds_read_b128 v[176:179], v180 offset:192
	s_waitcnt lgkmcnt(0)
	v_mfma_f32_16x16x32_bf16 v[94:97], v[176:179], v[50:53], v[94:97]
	v_min_i32_e32 v176, 15, v182
	v_lshlrev_b32_e32 v176, 4, v176
	v_bitop3_b32 v176, v176, v107, s5 bitop3:0xde
	v_mad_u64_u32 v[180:181], s[44:45], v176, s35, v[110:111]
	ds_read_b128 v[176:179], v180
	s_waitcnt lgkmcnt(0)
	v_mfma_f32_16x16x32_bf16 v[62:65], v[176:179], v[62:65], 0
	ds_read_b128 v[176:179], v180 offset:64
	s_cselect_b64 s[44:45], -1, 0
	s_or_b64 s[14:15], s[44:45], s[14:15]
	s_waitcnt lgkmcnt(0)
	v_mfma_f32_16x16x32_bf16 v[58:61], v[176:179], v[58:61], v[62:65]
	s_nop 2
	ds_read_b128 v[62:65], v180 offset:128
	s_and_b64 s[14:15], vcc, s[14:15]
	s_xor_b64 s[50:51], s[14:15], -1
	s_waitcnt lgkmcnt(0)
	v_mfma_f32_16x16x32_bf16 v[54:57], v[62:65], v[54:57], v[58:61]
	s_nop 2
	ds_read_b128 v[58:61], v180 offset:192
	s_or_b64 s[52:53], s[50:51], s[12:13]
	v_mul_f32_e32 v62, 0x3e0293ee, v72
	s_waitcnt lgkmcnt(0)
	v_mfma_f32_16x16x32_bf16 v[50:53], v[58:61], v[50:53], v[54:57]
	s_nop 2
	v_add_u32_e32 v54, 0x80, v174
	v_or_b32_e32 v55, v175, v145
	v_cmp_gt_i32_e32 vcc, v55, v54
	s_or_b64 vcc, s[52:53], vcc
	v_mul_f32_e32 v56, 0x3e0293ee, v66
	v_or_b32_e32 v57, 1, v55
	v_cndmask_b32_e32 v56, v56, v203, vcc
	v_cmp_ge_i32_e32 vcc, v57, v174
	s_and_b64 s[14:15], s[14:15], vcc
	v_cmp_lt_i32_e32 vcc, v55, v54
	s_and_b64 vcc, s[14:15], vcc
	v_mul_f32_e32 v57, 0x3e0293ee, v67
	v_or_b32_e32 v59, 2, v55
	v_cndmask_b32_e32 v57, v203, v57, vcc
	v_cmp_lt_i32_e32 vcc, v59, v174
	s_or_b64 s[14:15], s[50:51], vcc
	v_cmp_gt_i32_e32 vcc, v59, v54
	s_or_b64 vcc, s[14:15], vcc
	v_mul_f32_e32 v59, 0x3e0293ee, v68
	v_or_b32_e32 v55, 3, v55
	v_cndmask_b32_e32 v59, v59, v203, vcc
	v_cmp_lt_i32_e32 vcc, v55, v174
	s_or_b64 s[14:15], s[50:51], vcc
	v_cmp_gt_i32_e32 vcc, v55, v54
	s_or_b64 vcc, s[14:15], vcc
	v_mul_f32_e32 v55, 0x3e0293ee, v69
	v_cmp_lt_i32_e64 s[14:15], 6, v163
	v_cndmask_b32_e32 v55, v55, v203, vcc
	v_cmp_gt_i32_e32 vcc, 15, v163
	s_or_b64 s[14:15], s[44:45], s[14:15]
	s_and_b64 vcc, vcc, s[14:15]
	v_mul_f32_e32 v60, 0x3e0293ee, v70
	v_mul_f32_e32 v61, 0x3e0293ee, v71
	v_mul_f32_e32 v63, 0x3e0293ee, v73
	v_cmp_lt_i32_e64 s[14:15], 5, v163
	v_cndmask_b32_e32 v60, v203, v60, vcc
	v_cndmask_b32_e32 v61, v203, v61, vcc
	v_cndmask_b32_e32 v62, v203, v62, vcc
	v_cndmask_b32_e32 v63, v203, v63, vcc
	v_cmp_gt_i32_e32 vcc, 14, v163
	s_or_b64 s[14:15], s[44:45], s[14:15]
	s_and_b64 vcc, vcc, s[14:15]
	v_mul_f32_e32 v64, 0x3e0293ee, v74
	v_mul_f32_e32 v65, 0x3e0293ee, v75
	v_mul_f32_e32 v66, 0x3e0293ee, v76
	v_mul_f32_e32 v67, 0x3e0293ee, v77
	v_cmp_lt_i32_e64 s[14:15], 4, v163
	v_cndmask_b32_e32 v64, v203, v64, vcc
	v_cndmask_b32_e32 v65, v203, v65, vcc
	v_cndmask_b32_e32 v66, v203, v66, vcc
	v_cndmask_b32_e32 v67, v203, v67, vcc
	v_cmp_gt_i32_e32 vcc, 13, v163
	s_or_b64 s[14:15], s[44:45], s[14:15]
	s_and_b64 vcc, vcc, s[14:15]
	v_mul_f32_e32 v68, 0x3e0293ee, v78
	v_mul_f32_e32 v69, 0x3e0293ee, v79
	v_mul_f32_e32 v70, 0x3e0293ee, v80
	v_mul_f32_e32 v71, 0x3e0293ee, v81
	v_cmp_lt_i32_e64 s[14:15], 3, v163
	v_cndmask_b32_e32 v68, v203, v68, vcc
	v_cndmask_b32_e32 v69, v203, v69, vcc
	v_cndmask_b32_e32 v70, v203, v70, vcc
	v_cndmask_b32_e32 v71, v203, v71, vcc
	v_cmp_gt_i32_e32 vcc, 12, v163
	s_or_b64 s[14:15], s[44:45], s[14:15]
	s_and_b64 vcc, vcc, s[14:15]
	v_mul_f32_e32 v72, 0x3e0293ee, v82
	v_mul_f32_e32 v73, 0x3e0293ee, v83
	v_mul_f32_e32 v74, 0x3e0293ee, v84
	v_mul_f32_e32 v75, 0x3e0293ee, v85
	v_cmp_lt_i32_e64 s[14:15], 2, v163
	v_cndmask_b32_e32 v72, v203, v72, vcc
	v_cndmask_b32_e32 v73, v203, v73, vcc
	v_cndmask_b32_e32 v74, v203, v74, vcc
	v_cndmask_b32_e32 v75, v203, v75, vcc
	v_cmp_gt_i32_e32 vcc, 11, v163
	s_or_b64 s[14:15], s[44:45], s[14:15]
	s_and_b64 vcc, vcc, s[14:15]
	v_mul_f32_e32 v77, 0x3e0293ee, v87
	v_cndmask_b32_e32 v84, v203, v77, vcc
	v_mul_f32_e32 v77, 0x3e0293ee, v88
	v_mul_f32_e32 v76, 0x3e0293ee, v86
	v_cndmask_b32_e32 v85, v203, v77, vcc
	v_mul_f32_e32 v77, 0x3e0293ee, v89
	v_cmp_lt_i32_e64 s[14:15], 1, v163
	v_cndmask_b32_e32 v76, v203, v76, vcc
	v_cndmask_b32_e32 v86, v203, v77, vcc
	v_cmp_gt_i32_e32 vcc, 10, v163
	s_or_b64 s[14:15], s[44:45], s[14:15]
	s_and_b64 vcc, vcc, s[14:15]
	v_mul_f32_e32 v77, 0x3e0293ee, v90
	v_cndmask_b32_e32 v87, v203, v77, vcc
	v_mul_f32_e32 v77, 0x3e0293ee, v91
	v_cndmask_b32_e32 v88, v203, v77, vcc
	v_mul_f32_e32 v77, 0x3e0293ee, v92
	v_cndmask_b32_e32 v89, v203, v77, vcc
	v_mul_f32_e32 v77, 0x3e0293ee, v93
	v_cmp_lt_i32_e64 s[14:15], 0, v163
	v_cndmask_b32_e32 v90, v203, v77, vcc
	v_cmp_gt_i32_e32 vcc, 9, v163
	s_or_b64 s[14:15], s[44:45], s[14:15]
	s_and_b64 vcc, vcc, s[14:15]
	v_mul_f32_e32 v77, 0x3e0293ee, v98
	v_cndmask_b32_e32 v91, v203, v77, vcc
	v_mul_f32_e32 v77, 0x3e0293ee, v99
	v_cndmask_b32_e32 v92, v203, v77, vcc
	v_mul_f32_e32 v77, 0x3e0293ee, v100
	v_cndmask_b32_e32 v93, v203, v77, vcc
	v_mul_f32_e32 v77, 0x3e0293ee, v101
	v_cmp_lt_i32_e64 s[14:15], -1, v163
	v_cndmask_b32_e32 v98, v203, v77, vcc
	v_cmp_gt_i32_e32 vcc, 8, v163
	s_or_b64 s[14:15], s[44:45], s[14:15]
	s_and_b64 s[14:15], vcc, s[14:15]
	v_lshl_or_b32 v77, v172, 4, v145
	v_cmp_lt_i32_e32 vcc, v77, v174
	s_xor_b64 s[50:51], s[14:15], -1
	s_or_b64 s[52:53], s[50:51], vcc
	v_cmp_gt_i32_e32 vcc, v77, v54
	s_or_b64 vcc, s[52:53], vcc
	v_mul_f32_e32 v78, 0x3e0293ee, v94
	v_cndmask_b32_e32 v99, v78, v203, vcc
	v_or_b32_e32 v78, 1, v77
	v_cmp_ge_i32_e32 vcc, v78, v174
	s_and_b64 s[14:15], s[14:15], vcc
	v_cmp_lt_i32_e32 vcc, v77, v54
	s_and_b64 vcc, s[14:15], vcc
	v_mul_f32_e32 v78, 0x3e0293ee, v95
	v_cndmask_b32_e32 v100, v203, v78, vcc
	v_or_b32_e32 v78, 2, v77
	v_cmp_lt_i32_e32 vcc, v78, v174
	s_or_b64 s[14:15], s[50:51], vcc
	v_cmp_gt_i32_e32 vcc, v78, v54
	s_or_b64 vcc, s[14:15], vcc
	v_mul_f32_e32 v78, 0x3e0293ee, v96
	v_or_b32_e32 v77, 3, v77
	v_cndmask_b32_e32 v101, v78, v203, vcc
	v_cmp_lt_i32_e32 vcc, v77, v174
	s_or_b64 s[14:15], s[50:51], vcc
	v_cmp_gt_i32_e32 vcc, v77, v54
	s_mov_b32 s5, 0xff61b1e6
	s_or_b64 vcc, s[14:15], vcc
	v_mul_f32_e32 v77, 0x3e0293ee, v97
	v_cmp_lt_i32_e64 s[14:15], -2, v163
	v_max3_f32 v58, v56, s5, v57
	v_cndmask_b32_e32 v175, v77, v203, vcc
	v_cmp_gt_i32_e32 vcc, 7, v163
	s_or_b64 s[14:15], s[44:45], s[14:15]
	v_max3_f32 v58, v58, v59, v55
	s_and_b64 s[14:15], vcc, s[14:15]
	v_lshl_or_b32 v77, v182, 4, v145
	v_max3_f32 v58, v58, v60, v61
	v_cmp_lt_i32_e32 vcc, v77, v174
	s_xor_b64 s[44:45], s[14:15], -1
	v_max3_f32 v58, v58, v62, v63
	s_or_b64 s[50:51], s[44:45], vcc
	v_cmp_gt_i32_e32 vcc, v77, v54
	v_max3_f32 v58, v58, v64, v65
	s_or_b64 vcc, s[50:51], vcc
	v_mul_f32_e32 v50, 0x3e0293ee, v50
	v_max3_f32 v58, v58, v66, v67
	v_cndmask_b32_e32 v176, v50, v203, vcc
	v_or_b32_e32 v50, 1, v77
	v_max3_f32 v58, v58, v68, v69
	v_cmp_ge_i32_e32 vcc, v50, v174
	v_max3_f32 v58, v58, v70, v71
	s_and_b64 s[14:15], s[14:15], vcc
	v_cmp_lt_i32_e32 vcc, v77, v54
	v_max3_f32 v58, v58, v72, v73
	s_and_b64 vcc, s[14:15], vcc
	v_mul_f32_e32 v50, 0x3e0293ee, v51
	v_or_b32_e32 v51, 2, v77
	v_max3_f32 v58, v58, v74, v75
	v_cndmask_b32_e32 v177, v203, v50, vcc
	v_cmp_lt_i32_e32 vcc, v51, v174
	v_max3_f32 v58, v58, v76, v84
	s_or_b64 s[14:15], s[44:45], vcc
	v_cmp_gt_i32_e32 vcc, v51, v54
	v_max3_f32 v58, v58, v85, v86
	s_or_b64 vcc, s[14:15], vcc
	v_mul_f32_e32 v51, 0x3e0293ee, v52
	v_max3_f32 v58, v58, v87, v88
	v_cndmask_b32_e32 v178, v51, v203, vcc
	v_or_b32_e32 v51, 3, v77
	v_max3_f32 v58, v58, v89, v90
	v_cmp_lt_i32_e32 vcc, v51, v174
	v_max3_f32 v58, v58, v91, v92
	s_or_b64 s[14:15], s[44:45], vcc
	v_cmp_gt_i32_e32 vcc, v51, v54
	v_max3_f32 v58, v58, v93, v98
	s_or_b64 vcc, s[14:15], vcc
	v_mul_f32_e32 v51, 0x3e0293ee, v53
	v_and_b32_e32 v52, 64, v197
	v_max3_f32 v58, v58, v99, v100
	v_cndmask_b32_e32 v174, v51, v203, vcc
	v_xor_b32_e32 v51, 16, v197
	v_add_u32_e32 v52, 64, v52
	v_max3_f32 v58, v58, v101, v175
	v_cmp_lt_i32_e32 vcc, v51, v52
	v_max3_f32 v50, v58, v176, v177
	v_max3_f32 v50, v50, v178, v174
	v_cndmask_b32_e32 v51, v197, v51, vcc
	v_lshlrev_b32_e32 v179, 2, v51
	ds_bpermute_b32 v51, v179, v50
	s_waitcnt lgkmcnt(0)
	v_max_f32_e32 v51, v51, v51
	v_max_f32_e32 v50, v50, v51
	v_xor_b32_e32 v51, 32, v197
	v_cmp_lt_i32_e32 vcc, v51, v52
	s_nop 1
	v_cndmask_b32_e32 v51, v197, v51, vcc
	v_lshlrev_b32_e32 v180, 2, v51
	ds_bpermute_b32 v51, v180, v50
	s_waitcnt lgkmcnt(0)
	v_max_f32_e32 v51, v51, v51
	v_max_f32_e32 v181, v50, v51
	v_sub_f32_e32 v50, v56, v181
	v_exp_f32_e32 v50, v50
	v_sub_f32_e32 v51, v57, v181
	v_exp_f32_e32 v51, v51
	v_add_f32_e32 v52, 0, v50
	v_add_f32_e32 v53, v51, v52
	v_sub_f32_e32 v52, v59, v181
	v_exp_f32_e32 v52, v52
	s_nop 0
	v_add_f32_e32 v54, v52, v53
	v_sub_f32_e32 v53, v55, v181
	v_exp_f32_e32 v53, v53
	s_nop 0
	v_add_f32_e32 v55, v53, v54
	v_sub_f32_e32 v54, v60, v181
	v_exp_f32_e32 v54, v54
	s_nop 0
	v_add_f32_e32 v56, v54, v55
	v_sub_f32_e32 v55, v61, v181
	v_exp_f32_e32 v55, v55
	s_nop 0
	v_add_f32_e32 v57, v55, v56
	v_sub_f32_e32 v56, v62, v181
	v_exp_f32_e32 v56, v56
	s_nop 0
	v_add_f32_e32 v58, v56, v57
	v_sub_f32_e32 v57, v63, v181
	v_exp_f32_e32 v57, v57
	v_sub_f32_e32 v63, v68, v181
	v_add_f32_e32 v59, v57, v58
	v_sub_f32_e32 v58, v64, v181
	v_exp_f32_e32 v58, v58
	v_exp_f32_e32 v64, v63
	v_sub_f32_e32 v63, v69, v181
	v_add_f32_e32 v60, v58, v59
	v_sub_f32_e32 v59, v65, v181
	v_exp_f32_e32 v59, v59
	v_exp_f32_e32 v65, v63
	v_sub_f32_e32 v63, v70, v181
	v_exp_f32_e32 v77, v63
	v_add_f32_e32 v61, v59, v60
	v_sub_f32_e32 v60, v66, v181
	v_exp_f32_e32 v60, v60
	v_sub_f32_e32 v63, v71, v181
	v_exp_f32_e32 v78, v63
	v_sub_f32_e32 v63, v72, v181
	v_add_f32_e32 v62, v60, v61
	v_sub_f32_e32 v61, v67, v181
	v_exp_f32_e32 v61, v61
	v_exp_f32_e32 v79, v63
	v_sub_f32_e32 v63, v73, v181
	v_exp_f32_e32 v80, v63
	v_add_f32_e32 v62, v61, v62
	v_add_f32_e32 v62, v64, v62
	v_add_f32_e32 v62, v65, v62
	v_sub_f32_e32 v63, v74, v181
	v_add_f32_e32 v62, v77, v62
	v_exp_f32_e32 v81, v63
	v_sub_f32_e32 v63, v75, v181
	v_add_f32_e32 v62, v78, v62
	v_exp_f32_e32 v82, v63
	v_sub_f32_e32 v63, v76, v181
	v_add_f32_e32 v62, v79, v62
	v_exp_f32_e32 v83, v63
	v_sub_f32_e32 v63, v84, v181
	v_add_f32_e32 v62, v80, v62
	v_exp_f32_e32 v84, v63
	v_sub_f32_e32 v63, v85, v181
	v_add_f32_e32 v62, v81, v62
	v_exp_f32_e32 v85, v63
	v_sub_f32_e32 v63, v86, v181
	v_add_f32_e32 v62, v82, v62
	v_exp_f32_e32 v86, v63
	v_sub_f32_e32 v63, v87, v181
	v_add_f32_e32 v62, v83, v62
	v_exp_f32_e32 v87, v63
	v_sub_f32_e32 v63, v88, v181
	v_add_f32_e32 v62, v84, v62
	v_exp_f32_e32 v88, v63
	v_sub_f32_e32 v63, v89, v181
	v_add_f32_e32 v62, v85, v62
	v_exp_f32_e32 v89, v63
	v_sub_f32_e32 v63, v90, v181
	v_add_f32_e32 v62, v86, v62
	v_exp_f32_e32 v90, v63
	v_sub_f32_e32 v63, v91, v181
	v_add_f32_e32 v62, v87, v62
	v_exp_f32_e32 v91, v63
	v_sub_f32_e32 v63, v92, v181
	v_add_f32_e32 v62, v88, v62
	v_exp_f32_e32 v92, v63
	v_sub_f32_e32 v63, v93, v181
	v_add_f32_e32 v62, v89, v62
	v_exp_f32_e32 v93, v63
	v_sub_f32_e32 v63, v98, v181
	v_add_f32_e32 v62, v90, v62
	v_exp_f32_e32 v94, v63
	v_sub_f32_e32 v63, v99, v181
	v_add_f32_e32 v62, v91, v62
	v_exp_f32_e32 v95, v63
	v_sub_f32_e32 v63, v100, v181
	v_add_f32_e32 v62, v92, v62
	v_exp_f32_e32 v96, v63
	v_sub_f32_e32 v63, v101, v181
	v_add_f32_e32 v62, v93, v62
	v_exp_f32_e32 v97, v63
	v_sub_f32_e32 v63, v175, v181
	v_add_f32_e32 v62, v94, v62
	v_exp_f32_e32 v98, v63
	v_sub_f32_e32 v63, v176, v181
	v_add_f32_e32 v62, v95, v62
	v_exp_f32_e32 v99, v63
	v_sub_f32_e32 v63, v177, v181
	v_add_f32_e32 v62, v96, v62
	v_exp_f32_e32 v100, v63
	v_sub_f32_e32 v63, v178, v181
	v_add_f32_e32 v62, v97, v62
	v_exp_f32_e32 v101, v63
	v_sub_f32_e32 v63, v174, v181
	v_add_f32_e32 v62, v98, v62
	v_exp_f32_e32 v174, v63
	v_add_f32_e32 v62, v99, v62
	v_add_f32_e32 v62, v100, v62
	v_add_f32_e32 v62, v101, v62
	v_add_f32_e32 v62, v174, v62
	ds_bpermute_b32 v63, v179, v62
	v_mov_b32_e32 v76, 0
	s_waitcnt lgkmcnt(0)
	v_add_f32_e32 v66, v62, v63
	ds_bpermute_b32 v67, v180, v66
	v_lshl_add_u64 v[62:63], s[96:97], 0, v[138:139]
	s_waitcnt lgkmcnt(0)
	v_add_f32_e32 v68, v66, v67
	v_div_scale_f32 v66, s[14:15], v68, v68, 1.0
	v_rcp_f32_e32 v67, v66
	s_nop 0
	v_fma_f32 v69, -v66, v67, 1.0
	v_fmac_f32_e32 v67, v69, v67
	v_div_scale_f32 v69, vcc, 1.0, v68, 1.0
	v_mul_f32_e32 v70, v69, v67
	v_fma_f32 v71, -v66, v70, v69
	v_fmac_f32_e32 v70, v71, v67
	v_fma_f32 v66, -v66, v70, v69
	v_div_fmas_f32 v66, v66, v67, v70
	v_div_fixup_f32 v72, v66, v68, 1.0
	v_lshlrev_b64 v[66:67], 12, v[62:63]
	v_lshl_add_u64 v[70:71], v[136:137], 0, v[66:67]
	v_log_f32_e32 v66, v68
	v_lshlrev_b64 v[62:63], 6, v[62:63]
	s_andn2_b64 vcc, exec, s[94:95]
	v_lshl_add_u64 v[74:75], s[64:65], 0, v[62:63]
	v_add_f32_e32 v66, v181, v66
	v_mul_f32_e32 v73, 0x3f317218, v66
	s_cbranch_vccnz .LBB0_1108
	v_max_f32_e32 v66, v73, v73
	s_mov_b32 s5, 0x800000
	s_waitcnt vmcnt(0)
	v_max_f32_e32 v63, v226, v226
	v_max_f32_e32 v63, v63, v66
	v_sub_f32_e32 v62, v226, v63
	v_sub_f32_e32 v66, v73, v63
	v_mul_f32_e32 v62, 0x3fb8aa3b, v62
	v_mul_f32_e32 v66, 0x3fb8aa3b, v66
	v_exp_f32_e32 v62, v62
	v_exp_f32_e32 v66, v66
	s_nop 0
	v_add_f32_e32 v67, v62, v66
	v_div_scale_f32 v68, s[14:15], v67, v67, 1.0
	v_rcp_f32_e32 v69, v68
	s_nop 0
	v_fma_f32 v73, -v68, v69, 1.0
	v_fmac_f32_e32 v69, v73, v69
	v_div_scale_f32 v73, vcc, 1.0, v67, 1.0
	v_mul_f32_e32 v76, v73, v69
	v_fma_f32 v138, -v68, v76, v73
	v_fmac_f32_e32 v76, v138, v69
	v_fma_f32 v68, -v68, v76, v73
	v_div_fmas_f32 v68, v68, v69, v76
	v_div_fixup_f32 v68, v68, v67, 1.0
	v_mul_f32_e32 v76, v62, v68
	v_mul_f32_e32 v62, v66, v68
	v_cmp_gt_f32_e32 vcc, s5, v67
	v_mul_f32_e32 v72, v72, v62
	s_mov_b32 s5, 0x3f317217
	v_cndmask_b32_e64 v62, 0, 32, vcc
	v_ldexp_f32 v62, v67, v62
	v_log_f32_e32 v62, v62
	s_nop 0
	v_mul_f32_e32 v66, 0x3f317217, v62
	v_fma_f32 v66, v62, s5, -v66
	v_fmac_f32_e32 v66, 0x3377d1cf, v62
	s_mov_b32 s5, 0x7f800000
	v_fmac_f32_e32 v66, 0x3f317217, v62
	v_cmp_lt_f32_e64 s[14:15], |v62|, s5
	s_nop 1
	v_cndmask_b32_e64 v62, v62, v66, s[14:15]
	v_cndmask_b32_e32 v66, 0, v204, vcc
	v_sub_f32_e32 v62, v62, v66
	v_add_f32_e32 v73, v63, v62

.LBB0_1256:
	s_add_u32 s44, s64, 0xfff80080
	s_addc_u32 s45, s65, -1
	s_add_i32 s48, 0, 0x10000
	v_add_u32_e32 v102, s48, v187
	ds_read_b128 v[90:93], v102
	ds_read_b128 v[94:97], v102 offset:1024
	ds_read_b128 v[98:101], v102 offset:2048
	ds_read_b128 v[102:105], v102 offset:3072
	s_cmp_eq_u32 s47, 28
	s_cselect_b32 s69, s4, s45
	s_cselect_b32 s68, s5, s44
	s_cselect_b32 s45, s6, s19
	s_cselect_b32 s44, s7, s18
	v_lshl_add_u64 v[184:185], s[64:65], 0, v[164:165]
	s_add_i32 m0, s27, 0xc000
	ds_read_b128 v[168:171], v189
	ds_read_b128 v[172:175], v189 offset:1024
	ds_read_b128 v[176:179], v189 offset:2048
	ds_read_b128 v[180:183], v189 offset:3072
	ds_read_b128 v[206:209], v189 offset:4096
	ds_read_b128 v[210:213], v189 offset:5120
	ds_read_b128 v[214:217], v189 offset:6144
	ds_read_b128 v[218:221], v189 offset:7168
	global_load_lds_dwordx4 v[184:185], off
	v_lshl_add_u64 v[184:185], s[64:65], 0, v[166:167]
	s_add_i32 m0, s27, 0xe000
	s_nop 0
	global_load_lds_dwordx4 v[184:185], off
	s_waitcnt lgkmcnt(8)
	s_barrier
	s_waitcnt lgkmcnt(0)
	s_setprio 1
	s_waitcnt lgkmcnt(0)
	v_mfma_f32_16x16x32_bf16 v[142:145], v[90:93], v[168:171], v[142:145]
	v_mfma_f32_16x16x32_bf16 v[138:141], v[98:101], v[168:171], v[138:141]
	v_mfma_f32_16x16x32_bf16 v[134:137], v[90:93], v[176:179], v[134:137]
	v_mfma_f32_16x16x32_bf16 v[130:133], v[98:101], v[176:179], v[130:133]
	v_mfma_f32_16x16x32_bf16 v[126:129], v[90:93], v[206:209], v[126:129]
	v_mfma_f32_16x16x32_bf16 v[122:125], v[98:101], v[206:209], v[122:125]
	v_mfma_f32_16x16x32_bf16 v[118:121], v[90:93], v[214:217], v[118:121]
	v_mfma_f32_16x16x32_bf16 v[114:117], v[98:101], v[214:217], v[114:117]
	v_mfma_f32_16x16x32_bf16 v[142:145], v[94:97], v[172:175], v[142:145]
	v_mfma_f32_16x16x32_bf16 v[138:141], v[102:105], v[172:175], v[138:141]
	v_mfma_f32_16x16x32_bf16 v[134:137], v[94:97], v[180:183], v[134:137]
	v_mfma_f32_16x16x32_bf16 v[130:133], v[102:105], v[180:183], v[130:133]
	v_mfma_f32_16x16x32_bf16 v[126:129], v[94:97], v[210:213], v[126:129]
	v_mfma_f32_16x16x32_bf16 v[122:125], v[102:105], v[210:213], v[122:125]
	v_mfma_f32_16x16x32_bf16 v[118:121], v[94:97], v[218:221], v[118:121]
	v_mfma_f32_16x16x32_bf16 v[114:117], v[102:105], v[218:221], v[114:117]
	s_setprio 0
	s_barrier
	s_add_i32 s50, 0, 0x14000
	v_add_u32_e32 v184, s50, v187
	s_add_i32 s48, s48, s22
	ds_read_b128 v[222:225], v184
	ds_read_b128 v[226:229], v184 offset:1024
	ds_read_b128 v[230:233], v184 offset:2048
	ds_read_b128 v[234:237], v184 offset:3072
	v_lshl_add_u64 v[184:185], s[44:45], 0, v[0:1]
	s_mov_b32 m0, s48
	v_lshl_add_u64 v[238:239], s[44:45], 0, v[158:159]
	global_load_lds_dwordx4 v[184:185], off
	s_add_i32 m0, s48, 0x2000
	s_nop 0
	global_load_lds_dwordx4 v[238:239], off
	s_barrier
	s_waitcnt lgkmcnt(0)
	s_setprio 1
	s_waitcnt lgkmcnt(0)
	v_mfma_f32_16x16x32_bf16 v[62:65], v[222:225], v[168:171], v[62:65]
	v_mfma_f32_16x16x32_bf16 v[58:61], v[230:233], v[168:171], v[58:61]
	v_mfma_f32_16x16x32_bf16 v[54:57], v[222:225], v[176:179], v[54:57]
	v_mfma_f32_16x16x32_bf16 v[50:53], v[230:233], v[176:179], v[50:53]
	v_mfma_f32_16x16x32_bf16 v[46:49], v[222:225], v[206:209], v[46:49]
	v_mfma_f32_16x16x32_bf16 v[42:45], v[230:233], v[206:209], v[42:45]
	v_mfma_f32_16x16x32_bf16 v[38:41], v[222:225], v[214:217], v[38:41]
	v_mfma_f32_16x16x32_bf16 v[34:37], v[230:233], v[214:217], v[34:37]
	v_mfma_f32_16x16x32_bf16 v[62:65], v[226:229], v[172:175], v[62:65]
	v_mfma_f32_16x16x32_bf16 v[58:61], v[234:237], v[172:175], v[58:61]
	v_mfma_f32_16x16x32_bf16 v[54:57], v[226:229], v[180:183], v[54:57]
	v_mfma_f32_16x16x32_bf16 v[50:53], v[234:237], v[180:183], v[50:53]
	v_mfma_f32_16x16x32_bf16 v[46:49], v[226:229], v[210:213], v[46:49]
	v_mfma_f32_16x16x32_bf16 v[42:45], v[234:237], v[210:213], v[42:45]
	v_mfma_f32_16x16x32_bf16 v[38:41], v[226:229], v[218:221], v[38:41]
	v_mfma_f32_16x16x32_bf16 v[34:37], v[234:237], v[218:221], v[34:37]
	s_setprio 0
	s_mov_b32 m0, s27
	v_lshl_add_u64 v[240:241], s[68:69], 0, v[162:163]
	s_barrier
	ds_read_b128 v[168:171], v189 offset:16384
	ds_read_b128 v[172:175], v189 offset:17408
	ds_read_b128 v[176:179], v189 offset:18432
	ds_read_b128 v[180:183], v189 offset:19456
	ds_read_b128 v[206:209], v189 offset:20480
	ds_read_b128 v[210:213], v189 offset:21504
	ds_read_b128 v[214:217], v189 offset:22528
	ds_read_b128 v[218:221], v189 offset:23552
	global_load_lds_dwordx4 v[240:241], off
	v_lshl_add_u64 v[242:243], s[68:69], 0, v[160:161]
	s_mov_b32 m0, s28
	s_nop 0
	global_load_lds_dwordx4 v[242:243], off
	s_barrier
	s_waitcnt lgkmcnt(0)
	s_setprio 1
	s_waitcnt lgkmcnt(0)
	v_mfma_f32_16x16x32_bf16 v[110:113], v[90:93], v[168:171], v[110:113]
	v_mfma_f32_16x16x32_bf16 v[106:109], v[98:101], v[168:171], v[106:109]
	v_mfma_f32_16x16x32_bf16 v[86:89], v[90:93], v[176:179], v[86:89]
	v_mfma_f32_16x16x32_bf16 v[82:85], v[98:101], v[176:179], v[82:85]
	v_mfma_f32_16x16x32_bf16 v[78:81], v[90:93], v[206:209], v[78:81]
	v_mfma_f32_16x16x32_bf16 v[74:77], v[98:101], v[206:209], v[74:77]
	v_mfma_f32_16x16x32_bf16 v[70:73], v[90:93], v[214:217], v[70:73]
	v_mfma_f32_16x16x32_bf16 v[66:69], v[98:101], v[214:217], v[66:69]
	v_mfma_f32_16x16x32_bf16 v[110:113], v[94:97], v[172:175], v[110:113]
	v_mfma_f32_16x16x32_bf16 v[106:109], v[102:105], v[172:175], v[106:109]
	v_mfma_f32_16x16x32_bf16 v[86:89], v[94:97], v[180:183], v[86:89]
	v_mfma_f32_16x16x32_bf16 v[82:85], v[102:105], v[180:183], v[82:85]
	v_mfma_f32_16x16x32_bf16 v[78:81], v[94:97], v[210:213], v[78:81]
	v_mfma_f32_16x16x32_bf16 v[74:77], v[102:105], v[210:213], v[74:77]
	v_mfma_f32_16x16x32_bf16 v[70:73], v[94:97], v[218:221], v[70:73]
	v_mfma_f32_16x16x32_bf16 v[66:69], v[102:105], v[218:221], v[66:69]
	s_setprio 0
	s_barrier
	s_add_u32 s48, s44, 0x80000
	s_addc_u32 s49, s45, 0
	s_add_i32 s50, s50, s22
	v_lshl_add_u64 v[90:91], s[48:49], 0, v[0:1]
	s_mov_b32 m0, s50
	s_nop 0
	global_load_lds_dwordx4 v[90:91], off
	v_lshl_add_u64 v[90:91], s[48:49], 0, v[158:159]
	s_add_i32 m0, s50, 0x2000
	s_nop 0
	global_load_lds_dwordx4 v[90:91], off
	s_waitcnt vmcnt(6)
	s_barrier
	s_setprio 1
	v_mfma_f32_16x16x32_bf16 v[30:33], v[222:225], v[168:171], v[30:33]
	v_mfma_f32_16x16x32_bf16 v[26:29], v[230:233], v[168:171], v[26:29]
	v_mfma_f32_16x16x32_bf16 v[22:25], v[222:225], v[176:179], v[22:25]
	v_mfma_f32_16x16x32_bf16 v[18:21], v[230:233], v[176:179], v[18:21]
	v_mfma_f32_16x16x32_bf16 v[14:17], v[222:225], v[206:209], v[14:17]
	v_mfma_f32_16x16x32_bf16 v[10:13], v[230:233], v[206:209], v[10:13]
	v_mfma_f32_16x16x32_bf16 v[6:9], v[222:225], v[214:217], v[6:9]
	v_mfma_f32_16x16x32_bf16 v[2:5], v[230:233], v[214:217], v[2:5]
	v_mfma_f32_16x16x32_bf16 v[30:33], v[226:229], v[172:175], v[30:33]
	v_mfma_f32_16x16x32_bf16 v[26:29], v[234:237], v[172:175], v[26:29]
	v_mfma_f32_16x16x32_bf16 v[22:25], v[226:229], v[180:183], v[22:25]
	v_mfma_f32_16x16x32_bf16 v[18:21], v[234:237], v[180:183], v[18:21]
	v_mfma_f32_16x16x32_bf16 v[14:17], v[226:229], v[210:213], v[14:17]
	v_mfma_f32_16x16x32_bf16 v[10:13], v[234:237], v[210:213], v[10:13]
	v_mfma_f32_16x16x32_bf16 v[6:9], v[226:229], v[218:221], v[6:9]
	v_mfma_f32_16x16x32_bf16 v[2:5], v[234:237], v[218:221], v[2:5]
	s_setprio 0
	s_add_i32 s50, 0, 0x18000
	v_add_u32_e32 v102, s50, v187
	s_barrier
	ds_read_b128 v[90:93], v102
	ds_read_b128 v[94:97], v102 offset:1024
	ds_read_b128 v[98:101], v102 offset:2048
	ds_read_b128 v[102:105], v102 offset:3072
	s_add_u32 s48, s68, 0x80000
	s_addc_u32 s49, s69, 0
	s_mov_b32 m0, s36
	v_lshl_add_u64 v[222:223], s[48:49], 0, v[162:163]
	ds_read_b128 v[168:171], v189 offset:32768
	ds_read_b128 v[172:175], v189 offset:33792
	ds_read_b128 v[176:179], v189 offset:34816
	ds_read_b128 v[180:183], v189 offset:35840
	ds_read_b128 v[206:209], v189 offset:36864
	ds_read_b128 v[210:213], v189 offset:37888
	ds_read_b128 v[214:217], v189 offset:38912
	ds_read_b128 v[218:221], v189 offset:39936
	global_load_lds_dwordx4 v[222:223], off
	v_lshl_add_u64 v[222:223], s[48:49], 0, v[160:161]
	s_mov_b32 m0, s37
	s_nop 0
	global_load_lds_dwordx4 v[222:223], off
	s_waitcnt lgkmcnt(8)
	s_barrier
	s_waitcnt lgkmcnt(0)
	s_setprio 1
	s_waitcnt lgkmcnt(0)
	v_mfma_f32_16x16x32_bf16 v[142:145], v[90:93], v[168:171], v[142:145]
	v_mfma_f32_16x16x32_bf16 v[138:141], v[98:101], v[168:171], v[138:141]
	v_mfma_f32_16x16x32_bf16 v[134:137], v[90:93], v[176:179], v[134:137]
	v_mfma_f32_16x16x32_bf16 v[130:133], v[98:101], v[176:179], v[130:133]
	v_mfma_f32_16x16x32_bf16 v[126:129], v[90:93], v[206:209], v[126:129]
	v_mfma_f32_16x16x32_bf16 v[122:125], v[98:101], v[206:209], v[122:125]
	v_mfma_f32_16x16x32_bf16 v[118:121], v[90:93], v[214:217], v[118:121]
	v_mfma_f32_16x16x32_bf16 v[114:117], v[98:101], v[214:217], v[114:117]
	v_mfma_f32_16x16x32_bf16 v[142:145], v[94:97], v[172:175], v[142:145]
	v_mfma_f32_16x16x32_bf16 v[138:141], v[102:105], v[172:175], v[138:141]
	v_mfma_f32_16x16x32_bf16 v[134:137], v[94:97], v[180:183], v[134:137]
	v_mfma_f32_16x16x32_bf16 v[130:133], v[102:105], v[180:183], v[130:133]
	v_mfma_f32_16x16x32_bf16 v[126:129], v[94:97], v[210:213], v[126:129]
	v_mfma_f32_16x16x32_bf16 v[122:125], v[102:105], v[210:213], v[122:125]
	v_mfma_f32_16x16x32_bf16 v[118:121], v[94:97], v[218:221], v[118:121]
	v_mfma_f32_16x16x32_bf16 v[114:117], v[102:105], v[218:221], v[114:117]
	s_setprio 0
	s_barrier
	s_add_i32 s48, 0, 0x1c000
	s_add_i32 s49, s50, s22
	v_add_u32_e32 v205, s48, v187
	v_lshl_add_u64 v[184:185], v[184:185], 0, s[62:63]
	s_mov_b32 m0, s49
	ds_read_b128 v[222:225], v205
	ds_read_b128 v[226:229], v205 offset:1024
	ds_read_b128 v[230:233], v205 offset:2048
	ds_read_b128 v[234:237], v205 offset:3072
	global_load_lds_dwordx4 v[184:185], off
	v_lshl_add_u64 v[184:185], v[238:239], 0, s[62:63]
	s_add_i32 m0, s49, 0x2000
	s_nop 0
	global_load_lds_dwordx4 v[184:185], off
	s_barrier
	s_waitcnt lgkmcnt(0)
	s_setprio 1
	s_waitcnt lgkmcnt(0)
	v_mfma_f32_16x16x32_bf16 v[62:65], v[222:225], v[168:171], v[62:65]
	v_mfma_f32_16x16x32_bf16 v[58:61], v[230:233], v[168:171], v[58:61]
	v_mfma_f32_16x16x32_bf16 v[54:57], v[222:225], v[176:179], v[54:57]
	v_mfma_f32_16x16x32_bf16 v[50:53], v[230:233], v[176:179], v[50:53]
	v_mfma_f32_16x16x32_bf16 v[46:49], v[222:225], v[206:209], v[46:49]
	v_mfma_f32_16x16x32_bf16 v[42:45], v[230:233], v[206:209], v[42:45]
	v_mfma_f32_16x16x32_bf16 v[38:41], v[222:225], v[214:217], v[38:41]
	v_mfma_f32_16x16x32_bf16 v[34:37], v[230:233], v[214:217], v[34:37]
	v_mfma_f32_16x16x32_bf16 v[62:65], v[226:229], v[172:175], v[62:65]
	v_mfma_f32_16x16x32_bf16 v[58:61], v[234:237], v[172:175], v[58:61]
	v_mfma_f32_16x16x32_bf16 v[54:57], v[226:229], v[180:183], v[54:57]
	v_mfma_f32_16x16x32_bf16 v[50:53], v[234:237], v[180:183], v[50:53]
	v_mfma_f32_16x16x32_bf16 v[46:49], v[226:229], v[210:213], v[46:49]
	v_mfma_f32_16x16x32_bf16 v[42:45], v[234:237], v[210:213], v[42:45]
	v_mfma_f32_16x16x32_bf16 v[38:41], v[226:229], v[218:221], v[38:41]
	v_mfma_f32_16x16x32_bf16 v[34:37], v[234:237], v[218:221], v[34:37]
	s_setprio 0
	s_mov_b32 m0, s40
	v_lshl_add_u64 v[184:185], v[240:241], 0, s[62:63]
	s_barrier
	ds_read_b128 v[168:171], v189 offset:49152
	ds_read_b128 v[172:175], v189 offset:50176
	ds_read_b128 v[176:179], v189 offset:51200
	ds_read_b128 v[180:183], v189 offset:52224
	ds_read_b128 v[206:209], v189 offset:53248
	ds_read_b128 v[210:213], v189 offset:54272
	ds_read_b128 v[214:217], v189 offset:55296
	ds_read_b128 v[218:221], v189 offset:56320
	global_load_lds_dwordx4 v[184:185], off
	v_lshl_add_u64 v[184:185], v[242:243], 0, s[62:63]
	s_mov_b32 m0, s41
	s_nop 0
	global_load_lds_dwordx4 v[184:185], off
	s_barrier
	s_waitcnt lgkmcnt(0)
	s_setprio 1
	s_waitcnt lgkmcnt(0)
	v_mfma_f32_16x16x32_bf16 v[110:113], v[90:93], v[168:171], v[110:113]
	v_mfma_f32_16x16x32_bf16 v[106:109], v[98:101], v[168:171], v[106:109]
	v_mfma_f32_16x16x32_bf16 v[86:89], v[90:93], v[176:179], v[86:89]
	v_mfma_f32_16x16x32_bf16 v[82:85], v[98:101], v[176:179], v[82:85]
	v_mfma_f32_16x16x32_bf16 v[78:81], v[90:93], v[206:209], v[78:81]
	v_mfma_f32_16x16x32_bf16 v[74:77], v[98:101], v[206:209], v[74:77]
	v_mfma_f32_16x16x32_bf16 v[70:73], v[90:93], v[214:217], v[70:73]
	v_mfma_f32_16x16x32_bf16 v[66:69], v[98:101], v[214:217], v[66:69]
	v_mfma_f32_16x16x32_bf16 v[110:113], v[94:97], v[172:175], v[110:113]
	v_mfma_f32_16x16x32_bf16 v[106:109], v[102:105], v[172:175], v[106:109]
	v_mfma_f32_16x16x32_bf16 v[86:89], v[94:97], v[180:183], v[86:89]
	v_mfma_f32_16x16x32_bf16 v[82:85], v[102:105], v[180:183], v[82:85]
	v_mfma_f32_16x16x32_bf16 v[78:81], v[94:97], v[210:213], v[78:81]
	v_mfma_f32_16x16x32_bf16 v[74:77], v[102:105], v[210:213], v[74:77]
	v_mfma_f32_16x16x32_bf16 v[70:73], v[94:97], v[218:221], v[70:73]
	v_mfma_f32_16x16x32_bf16 v[66:69], v[102:105], v[218:221], v[66:69]
	s_setprio 0
	s_barrier
	s_add_u32 s44, s44, 0x80080
	s_addc_u32 s45, s45, 0
	s_add_i32 s48, s48, s22
	v_lshl_add_u64 v[90:91], s[44:45], 0, v[0:1]
	s_mov_b32 m0, s48
	s_nop 0
	global_load_lds_dwordx4 v[90:91], off
	v_lshl_add_u64 v[90:91], s[44:45], 0, v[158:159]
	s_add_i32 m0, s48, 0x2000
	s_nop 0
	global_load_lds_dwordx4 v[90:91], off
	s_waitcnt vmcnt(6)
	s_barrier
	s_setprio 1
	v_mfma_f32_16x16x32_bf16 v[30:33], v[222:225], v[168:171], v[30:33]
	v_mfma_f32_16x16x32_bf16 v[26:29], v[230:233], v[168:171], v[26:29]
	v_mfma_f32_16x16x32_bf16 v[22:25], v[222:225], v[176:179], v[22:25]
	v_mfma_f32_16x16x32_bf16 v[18:21], v[230:233], v[176:179], v[18:21]
	v_mfma_f32_16x16x32_bf16 v[14:17], v[222:225], v[206:209], v[14:17]
	v_mfma_f32_16x16x32_bf16 v[10:13], v[230:233], v[206:209], v[10:13]
	v_mfma_f32_16x16x32_bf16 v[6:9], v[222:225], v[214:217], v[6:9]
	v_mfma_f32_16x16x32_bf16 v[2:5], v[230:233], v[214:217], v[2:5]
	v_mfma_f32_16x16x32_bf16 v[30:33], v[226:229], v[172:175], v[30:33]
	v_mfma_f32_16x16x32_bf16 v[26:29], v[234:237], v[172:175], v[26:29]
	v_mfma_f32_16x16x32_bf16 v[22:25], v[226:229], v[180:183], v[22:25]
	v_mfma_f32_16x16x32_bf16 v[18:21], v[234:237], v[180:183], v[18:21]
	v_mfma_f32_16x16x32_bf16 v[14:17], v[226:229], v[210:213], v[14:17]
	v_mfma_f32_16x16x32_bf16 v[10:13], v[234:237], v[210:213], v[10:13]
	v_mfma_f32_16x16x32_bf16 v[6:9], v[226:229], v[218:221], v[6:9]
	v_mfma_f32_16x16x32_bf16 v[2:5], v[234:237], v[218:221], v[2:5]
	s_setprio 0
	s_add_i32 s47, s47, 2
	s_add_u32 s64, s64, 0x100
	s_addc_u32 s65, s65, 0
	s_add_u32 s18, s18, 0x100
	s_addc_u32 s19, s19, 0
	s_cmp_gt_u32 s47, 29
	s_barrier
	s_cbranch_scc0 .LBB0_1256
	s_lshl_b32 s4, s46, 8
	s_and_b32 s4, s4, 0x3f00
	v_add_u32_e32 v178, s4, v186
	s_ashr_i32 s4, s43, 31
	s_lshr_b32 s4, s4, 29
	s_add_i32 s4, s43, s4
	s_and_b32 s4, s4, 0xfffff8
	s_sub_i32 s4, s43, s4
	v_lshl_or_b32 v172, s4, 8, v188
	v_ashrrev_i32_e32 v173, 31, v172
	v_ashrrev_i32_e32 v179, 31, v178
	v_lshlrev_b32_e32 v170, 12, v178
	v_lshl_add_u32 v170, v172, 1, v170
	v_lshlrev_b32_e32 v171, 3, v178
	v_lshlrev_b32_e32 v174, 2, v172
	global_load_dwordx4 v[98:101], v174, s[12:13]
	global_load_dwordx4 v[90:93], v174, s[12:13] offset:16
	global_load_dwordx4 v[102:105], v174, s[14:15]
	global_load_dwordx4 v[94:97], v174, s[14:15] offset:16
	s_add_u32 s48, s82, 0x0
	s_addc_u32 s49, s83, 0
	global_load_dwordx4 v[220:223], v170, s[48:49]
	s_add_u32 s50, s10, 0x0
	s_addc_u32 s51, s11, 0
	global_load_dwordx2 v[176:177], v171, s[50:51]
	s_add_u32 s48, s82, 0x10000
	s_addc_u32 s49, s83, 0
	global_load_dwordx4 v[224:227], v170, s[48:49]
	s_add_u32 s50, s10, 0x80
	s_addc_u32 s51, s11, 0
	global_load_dwordx2 v[180:181], v171, s[50:51]
	s_add_u32 s48, s82, 0x20000
	s_addc_u32 s49, s83, 0
	global_load_dwordx4 v[228:231], v170, s[48:49]
	s_add_u32 s50, s10, 0x100
	s_addc_u32 s51, s11, 0
	global_load_dwordx2 v[182:183], v171, s[50:51]
	s_add_u32 s48, s82, 0x30000
	s_addc_u32 s49, s83, 0
	global_load_dwordx4 v[232:235], v170, s[48:49]
	s_add_u32 s50, s10, 0x180
	s_addc_u32 s51, s11, 0
	global_load_dwordx2 v[184:185], v171, s[50:51]
	s_add_u32 s48, s82, 0x80000
	s_addc_u32 s49, s83, 0
	global_load_dwordx4 v[236:239], v170, s[48:49]
	s_add_u32 s50, s10, 0x400
	s_addc_u32 s51, s11, 0
	global_load_dwordx2 v[168:169], v171, s[50:51]
	s_add_u32 s48, s82, 0x90000
	s_addc_u32 s49, s83, 0
	global_load_dwordx4 v[240:243], v170, s[48:49]
	s_add_u32 s50, s10, 0x480
	s_addc_u32 s51, s11, 0
	global_load_dwordx2 v[252:253], v171, s[50:51]
	s_add_u32 s48, s82, 0xa0000
	s_addc_u32 s49, s83, 0
	global_load_dwordx4 v[244:247], v170, s[48:49]
	s_add_u32 s50, s10, 0x500
	s_addc_u32 s51, s11, 0
	global_load_dwordx2 v[214:215], v171, s[50:51]
	s_add_u32 s48, s82, 0xb0000
	s_addc_u32 s49, s83, 0
	global_load_dwordx4 v[248:251], v170, s[48:49]
	s_add_u32 s50, s10, 0x580
	s_addc_u32 s51, s11, 0
	global_load_dwordx2 v[216:217], v171, s[50:51]
	s_waitcnt vmcnt(14)
	v_lshlrev_b32_e32 v206, 16, v220
	v_and_b32_e32 v207, 0xffff0000, v220
	v_lshlrev_b32_e32 v208, 16, v221
	v_and_b32_e32 v209, 0xffff0000, v221
	v_lshlrev_b32_e32 v210, 16, v222
	v_and_b32_e32 v211, 0xffff0000, v222
	v_lshlrev_b32_e32 v212, 16, v223
	v_and_b32_e32 v213, 0xffff0000, v223
	v_sub_f32_e32 v206, v206, v176
	v_sub_f32_e32 v207, v207, v176
	v_sub_f32_e32 v208, v208, v176
	v_sub_f32_e32 v209, v209, v176
	v_sub_f32_e32 v210, v210, v176
	v_sub_f32_e32 v211, v211, v176
	v_sub_f32_e32 v212, v212, v176
	v_sub_f32_e32 v213, v213, v176
	v_pk_mul_f32 v[206:207], v[176:177], v[206:207] op_sel:[1,0]
	v_pk_mul_f32 v[208:209], v[176:177], v[208:209] op_sel:[1,0]
	v_pk_mul_f32 v[210:211], v[176:177], v[210:211] op_sel:[1,0]
	v_pk_mul_f32 v[212:213], v[176:177], v[212:213] op_sel:[1,0]
	v_pk_fma_f32 v[206:207], v[98:99], v[206:207], v[102:103]
	v_pk_fma_f32 v[208:209], v[100:101], v[208:209], v[104:105]
	v_pk_fma_f32 v[210:211], v[90:91], v[210:211], v[94:95]
	v_pk_fma_f32 v[212:213], v[92:93], v[212:213], v[96:97]
	v_pk_fma_f32 v[206:207], v[206:207], s[66:67], v[142:143] op_sel_hi:[1,0,1]
	v_pk_fma_f32 v[208:209], v[208:209], s[66:67], v[144:145] op_sel_hi:[1,0,1]
	v_pk_fma_f32 v[210:211], v[210:211], s[66:67], v[138:139] op_sel_hi:[1,0,1]
	v_pk_fma_f32 v[212:213], v[212:213], s[66:67], v[140:141] op_sel_hi:[1,0,1]
	v_cvt_pk_bf16_f32 v220, v206, v207
	v_cvt_pk_bf16_f32 v221, v208, v209
	v_cvt_pk_bf16_f32 v222, v210, v211
	v_cvt_pk_bf16_f32 v223, v212, v213
	s_add_u32 s48, s82, 0x0
	s_addc_u32 s49, s83, 0
	global_store_dwordx4 v170, v[220:223], s[48:49]
	s_waitcnt vmcnt(13)
	v_lshlrev_b32_e32 v206, 16, v224
	v_and_b32_e32 v207, 0xffff0000, v224
	v_lshlrev_b32_e32 v208, 16, v225
	v_and_b32_e32 v209, 0xffff0000, v225
	v_lshlrev_b32_e32 v210, 16, v226
	v_and_b32_e32 v211, 0xffff0000, v226
	v_lshlrev_b32_e32 v212, 16, v227
	v_and_b32_e32 v213, 0xffff0000, v227
	v_sub_f32_e32 v206, v206, v180
	v_sub_f32_e32 v207, v207, v180
	v_sub_f32_e32 v208, v208, v180
	v_sub_f32_e32 v209, v209, v180
	v_sub_f32_e32 v210, v210, v180
	v_sub_f32_e32 v211, v211, v180
	v_sub_f32_e32 v212, v212, v180
	v_sub_f32_e32 v213, v213, v180
	v_pk_mul_f32 v[206:207], v[180:181], v[206:207] op_sel:[1,0]
	v_pk_mul_f32 v[208:209], v[180:181], v[208:209] op_sel:[1,0]
	v_pk_mul_f32 v[210:211], v[180:181], v[210:211] op_sel:[1,0]
	v_pk_mul_f32 v[212:213], v[180:181], v[212:213] op_sel:[1,0]
	v_pk_fma_f32 v[206:207], v[98:99], v[206:207], v[102:103]
	v_pk_fma_f32 v[208:209], v[100:101], v[208:209], v[104:105]
	v_pk_fma_f32 v[210:211], v[90:91], v[210:211], v[94:95]
	v_pk_fma_f32 v[212:213], v[92:93], v[212:213], v[96:97]
	v_pk_fma_f32 v[206:207], v[206:207], s[66:67], v[134:135] op_sel_hi:[1,0,1]
	v_pk_fma_f32 v[208:209], v[208:209], s[66:67], v[136:137] op_sel_hi:[1,0,1]
	v_pk_fma_f32 v[210:211], v[210:211], s[66:67], v[130:131] op_sel_hi:[1,0,1]
	v_pk_fma_f32 v[212:213], v[212:213], s[66:67], v[132:133] op_sel_hi:[1,0,1]
	v_cvt_pk_bf16_f32 v224, v206, v207
	v_cvt_pk_bf16_f32 v225, v208, v209
	v_cvt_pk_bf16_f32 v226, v210, v211
	v_cvt_pk_bf16_f32 v227, v212, v213
	s_add_u32 s48, s82, 0x10000
	s_addc_u32 s49, s83, 0
	global_store_dwordx4 v170, v[224:227], s[48:49]
	s_waitcnt vmcnt(12)
	v_lshlrev_b32_e32 v206, 16, v228
	v_and_b32_e32 v207, 0xffff0000, v228
	v_lshlrev_b32_e32 v208, 16, v229
	v_and_b32_e32 v209, 0xffff0000, v229
	v_lshlrev_b32_e32 v210, 16, v230
	v_and_b32_e32 v211, 0xffff0000, v230
	v_lshlrev_b32_e32 v212, 16, v231
	v_and_b32_e32 v213, 0xffff0000, v231
	v_sub_f32_e32 v206, v206, v182
	v_sub_f32_e32 v207, v207, v182
	v_sub_f32_e32 v208, v208, v182
	v_sub_f32_e32 v209, v209, v182
	v_sub_f32_e32 v210, v210, v182
	v_sub_f32_e32 v211, v211, v182
	v_sub_f32_e32 v212, v212, v182
	v_sub_f32_e32 v213, v213, v182
	v_pk_mul_f32 v[206:207], v[182:183], v[206:207] op_sel:[1,0]
	v_pk_mul_f32 v[208:209], v[182:183], v[208:209] op_sel:[1,0]
	v_pk_mul_f32 v[210:211], v[182:183], v[210:211] op_sel:[1,0]
	v_pk_mul_f32 v[212:213], v[182:183], v[212:213] op_sel:[1,0]
	v_pk_fma_f32 v[206:207], v[98:99], v[206:207], v[102:103]
	v_pk_fma_f32 v[208:209], v[100:101], v[208:209], v[104:105]
	v_pk_fma_f32 v[210:211], v[90:91], v[210:211], v[94:95]
	v_pk_fma_f32 v[212:213], v[92:93], v[212:213], v[96:97]
	v_pk_fma_f32 v[206:207], v[206:207], s[66:67], v[126:127] op_sel_hi:[1,0,1]
	v_pk_fma_f32 v[208:209], v[208:209], s[66:67], v[128:129] op_sel_hi:[1,0,1]
	v_pk_fma_f32 v[210:211], v[210:211], s[66:67], v[122:123] op_sel_hi:[1,0,1]
	v_pk_fma_f32 v[212:213], v[212:213], s[66:67], v[124:125] op_sel_hi:[1,0,1]
	v_cvt_pk_bf16_f32 v228, v206, v207
	v_cvt_pk_bf16_f32 v229, v208, v209
	v_cvt_pk_bf16_f32 v230, v210, v211
	v_cvt_pk_bf16_f32 v231, v212, v213
	s_add_u32 s48, s82, 0x20000
	s_addc_u32 s49, s83, 0
	global_store_dwordx4 v170, v[228:231], s[48:49]
	s_waitcnt vmcnt(11)
	v_lshlrev_b32_e32 v206, 16, v232
	v_and_b32_e32 v207, 0xffff0000, v232
	v_lshlrev_b32_e32 v208, 16, v233
	v_and_b32_e32 v209, 0xffff0000, v233
	v_lshlrev_b32_e32 v210, 16, v234
	v_and_b32_e32 v211, 0xffff0000, v234
	v_lshlrev_b32_e32 v212, 16, v235
	v_and_b32_e32 v213, 0xffff0000, v235
	v_sub_f32_e32 v206, v206, v184
	v_sub_f32_e32 v207, v207, v184
	v_sub_f32_e32 v208, v208, v184
	v_sub_f32_e32 v209, v209, v184
	v_sub_f32_e32 v210, v210, v184
	v_sub_f32_e32 v211, v211, v184
	v_sub_f32_e32 v212, v212, v184
	v_sub_f32_e32 v213, v213, v184
	v_pk_mul_f32 v[206:207], v[184:185], v[206:207] op_sel:[1,0]
	v_pk_mul_f32 v[208:209], v[184:185], v[208:209] op_sel:[1,0]
	v_pk_mul_f32 v[210:211], v[184:185], v[210:211] op_sel:[1,0]
	v_pk_mul_f32 v[212:213], v[184:185], v[212:213] op_sel:[1,0]
	v_pk_fma_f32 v[206:207], v[98:99], v[206:207], v[102:103]
	v_pk_fma_f32 v[208:209], v[100:101], v[208:209], v[104:105]
	v_pk_fma_f32 v[210:211], v[90:91], v[210:211], v[94:95]
	v_pk_fma_f32 v[212:213], v[92:93], v[212:213], v[96:97]
	v_pk_fma_f32 v[206:207], v[206:207], s[66:67], v[118:119] op_sel_hi:[1,0,1]
	v_pk_fma_f32 v[208:209], v[208:209], s[66:67], v[120:121] op_sel_hi:[1,0,1]
	v_pk_fma_f32 v[210:211], v[210:211], s[66:67], v[114:115] op_sel_hi:[1,0,1]
	v_pk_fma_f32 v[212:213], v[212:213], s[66:67], v[116:117] op_sel_hi:[1,0,1]
	v_cvt_pk_bf16_f32 v232, v206, v207
	v_cvt_pk_bf16_f32 v233, v208, v209
	v_cvt_pk_bf16_f32 v234, v210, v211
	v_cvt_pk_bf16_f32 v235, v212, v213
	s_add_u32 s48, s82, 0x30000
	s_addc_u32 s49, s83, 0
	global_store_dwordx4 v170, v[232:235], s[48:49]
	s_waitcnt vmcnt(10)
	v_lshlrev_b32_e32 v206, 16, v236
	v_and_b32_e32 v207, 0xffff0000, v236
	v_lshlrev_b32_e32 v208, 16, v237
	v_and_b32_e32 v209, 0xffff0000, v237
	v_lshlrev_b32_e32 v210, 16, v238
	v_and_b32_e32 v211, 0xffff0000, v238
	v_lshlrev_b32_e32 v212, 16, v239
	v_and_b32_e32 v213, 0xffff0000, v239
	v_sub_f32_e32 v206, v206, v168
	v_sub_f32_e32 v207, v207, v168
	v_sub_f32_e32 v208, v208, v168
	v_sub_f32_e32 v209, v209, v168
	v_sub_f32_e32 v210, v210, v168
	v_sub_f32_e32 v211, v211, v168
	v_sub_f32_e32 v212, v212, v168
	v_sub_f32_e32 v213, v213, v168
	v_pk_mul_f32 v[206:207], v[168:169], v[206:207] op_sel:[1,0]
	v_pk_mul_f32 v[208:209], v[168:169], v[208:209] op_sel:[1,0]
	v_pk_mul_f32 v[210:211], v[168:169], v[210:211] op_sel:[1,0]
	v_pk_mul_f32 v[212:213], v[168:169], v[212:213] op_sel:[1,0]
	v_pk_fma_f32 v[206:207], v[98:99], v[206:207], v[102:103]
	v_pk_fma_f32 v[208:209], v[100:101], v[208:209], v[104:105]
	v_pk_fma_f32 v[210:211], v[90:91], v[210:211], v[94:95]
	v_pk_fma_f32 v[212:213], v[92:93], v[212:213], v[96:97]
	v_pk_fma_f32 v[206:207], v[206:207], s[66:67], v[110:111] op_sel_hi:[1,0,1]
	v_pk_fma_f32 v[208:209], v[208:209], s[66:67], v[112:113] op_sel_hi:[1,0,1]
	v_pk_fma_f32 v[210:211], v[210:211], s[66:67], v[106:107] op_sel_hi:[1,0,1]
	v_pk_fma_f32 v[212:213], v[212:213], s[66:67], v[108:109] op_sel_hi:[1,0,1]
	v_cvt_pk_bf16_f32 v236, v206, v207
	v_cvt_pk_bf16_f32 v237, v208, v209
	v_cvt_pk_bf16_f32 v238, v210, v211
	v_cvt_pk_bf16_f32 v239, v212, v213
	s_add_u32 s48, s82, 0x80000
	s_addc_u32 s49, s83, 0
	global_store_dwordx4 v170, v[236:239], s[48:49]
	s_waitcnt vmcnt(9)
	v_lshlrev_b32_e32 v206, 16, v240
	v_and_b32_e32 v207, 0xffff0000, v240
	v_lshlrev_b32_e32 v208, 16, v241
	v_and_b32_e32 v209, 0xffff0000, v241
	v_lshlrev_b32_e32 v210, 16, v242
	v_and_b32_e32 v211, 0xffff0000, v242
	v_lshlrev_b32_e32 v212, 16, v243
	v_and_b32_e32 v213, 0xffff0000, v243
	v_sub_f32_e32 v206, v206, v252
	v_sub_f32_e32 v207, v207, v252
	v_sub_f32_e32 v208, v208, v252
	v_sub_f32_e32 v209, v209, v252
	v_sub_f32_e32 v210, v210, v252
	v_sub_f32_e32 v211, v211, v252
	v_sub_f32_e32 v212, v212, v252
	v_sub_f32_e32 v213, v213, v252
	v_pk_mul_f32 v[206:207], v[252:253], v[206:207] op_sel:[1,0]
	v_pk_mul_f32 v[208:209], v[252:253], v[208:209] op_sel:[1,0]
	v_pk_mul_f32 v[210:211], v[252:253], v[210:211] op_sel:[1,0]
	v_pk_mul_f32 v[212:213], v[252:253], v[212:213] op_sel:[1,0]
	v_pk_fma_f32 v[206:207], v[98:99], v[206:207], v[102:103]
	v_pk_fma_f32 v[208:209], v[100:101], v[208:209], v[104:105]
	v_pk_fma_f32 v[210:211], v[90:91], v[210:211], v[94:95]
	v_pk_fma_f32 v[212:213], v[92:93], v[212:213], v[96:97]
	v_pk_fma_f32 v[206:207], v[206:207], s[66:67], v[86:87] op_sel_hi:[1,0,1]
	v_pk_fma_f32 v[208:209], v[208:209], s[66:67], v[88:89] op_sel_hi:[1,0,1]
	v_pk_fma_f32 v[210:211], v[210:211], s[66:67], v[82:83] op_sel_hi:[1,0,1]
	v_pk_fma_f32 v[212:213], v[212:213], s[66:67], v[84:85] op_sel_hi:[1,0,1]
	v_cvt_pk_bf16_f32 v240, v206, v207
	v_cvt_pk_bf16_f32 v241, v208, v209
	v_cvt_pk_bf16_f32 v242, v210, v211
	v_cvt_pk_bf16_f32 v243, v212, v213
	s_add_u32 s48, s82, 0x90000
	s_addc_u32 s49, s83, 0
	global_store_dwordx4 v170, v[240:243], s[48:49]
	s_waitcnt vmcnt(8)
	v_lshlrev_b32_e32 v206, 16, v244
	v_and_b32_e32 v207, 0xffff0000, v244
	v_lshlrev_b32_e32 v208, 16, v245
	v_and_b32_e32 v209, 0xffff0000, v245
	v_lshlrev_b32_e32 v210, 16, v246
	v_and_b32_e32 v211, 0xffff0000, v246
	v_lshlrev_b32_e32 v212, 16, v247
	v_and_b32_e32 v213, 0xffff0000, v247
	v_sub_f32_e32 v206, v206, v214
	v_sub_f32_e32 v207, v207, v214
	v_sub_f32_e32 v208, v208, v214
	v_sub_f32_e32 v209, v209, v214
	v_sub_f32_e32 v210, v210, v214
	v_sub_f32_e32 v211, v211, v214
	v_sub_f32_e32 v212, v212, v214
	v_sub_f32_e32 v213, v213, v214
	v_pk_mul_f32 v[206:207], v[214:215], v[206:207] op_sel:[1,0]
	v_pk_mul_f32 v[208:209], v[214:215], v[208:209] op_sel:[1,0]
	v_pk_mul_f32 v[210:211], v[214:215], v[210:211] op_sel:[1,0]
	v_pk_mul_f32 v[212:213], v[214:215], v[212:213] op_sel:[1,0]
	v_pk_fma_f32 v[206:207], v[98:99], v[206:207], v[102:103]
	v_pk_fma_f32 v[208:209], v[100:101], v[208:209], v[104:105]
	v_pk_fma_f32 v[210:211], v[90:91], v[210:211], v[94:95]
	v_pk_fma_f32 v[212:213], v[92:93], v[212:213], v[96:97]
	v_pk_fma_f32 v[206:207], v[206:207], s[66:67], v[78:79] op_sel_hi:[1,0,1]
	v_pk_fma_f32 v[208:209], v[208:209], s[66:67], v[80:81] op_sel_hi:[1,0,1]
	v_pk_fma_f32 v[210:211], v[210:211], s[66:67], v[74:75] op_sel_hi:[1,0,1]
	v_pk_fma_f32 v[212:213], v[212:213], s[66:67], v[76:77] op_sel_hi:[1,0,1]
	v_cvt_pk_bf16_f32 v244, v206, v207
	v_cvt_pk_bf16_f32 v245, v208, v209
	v_cvt_pk_bf16_f32 v246, v210, v211
	v_cvt_pk_bf16_f32 v247, v212, v213
	s_add_u32 s48, s82, 0xa0000
	s_addc_u32 s49, s83, 0
	global_store_dwordx4 v170, v[244:247], s[48:49]
	s_waitcnt vmcnt(7)
	v_lshlrev_b32_e32 v206, 16, v248
	v_and_b32_e32 v207, 0xffff0000, v248
	v_lshlrev_b32_e32 v208, 16, v249
	v_and_b32_e32 v209, 0xffff0000, v249
	v_lshlrev_b32_e32 v210, 16, v250
	v_and_b32_e32 v211, 0xffff0000, v250
	v_lshlrev_b32_e32 v212, 16, v251
	v_and_b32_e32 v213, 0xffff0000, v251
	v_sub_f32_e32 v206, v206, v216
	v_sub_f32_e32 v207, v207, v216
	v_sub_f32_e32 v208, v208, v216
	v_sub_f32_e32 v209, v209, v216
	v_sub_f32_e32 v210, v210, v216
	v_sub_f32_e32 v211, v211, v216
	v_sub_f32_e32 v212, v212, v216
	v_sub_f32_e32 v213, v213, v216
	v_pk_mul_f32 v[206:207], v[216:217], v[206:207] op_sel:[1,0]
	v_pk_mul_f32 v[208:209], v[216:217], v[208:209] op_sel:[1,0]
	v_pk_mul_f32 v[210:211], v[216:217], v[210:211] op_sel:[1,0]
	v_pk_mul_f32 v[212:213], v[216:217], v[212:213] op_sel:[1,0]
	v_pk_fma_f32 v[206:207], v[98:99], v[206:207], v[102:103]
	v_pk_fma_f32 v[208:209], v[100:101], v[208:209], v[104:105]
	v_pk_fma_f32 v[210:211], v[90:91], v[210:211], v[94:95]
	v_pk_fma_f32 v[212:213], v[92:93], v[212:213], v[96:97]
	v_pk_fma_f32 v[206:207], v[206:207], s[66:67], v[70:71] op_sel_hi:[1,0,1]
	v_pk_fma_f32 v[208:209], v[208:209], s[66:67], v[72:73] op_sel_hi:[1,0,1]
	v_pk_fma_f32 v[210:211], v[210:211], s[66:67], v[66:67] op_sel_hi:[1,0,1]
	v_pk_fma_f32 v[212:213], v[212:213], s[66:67], v[68:69] op_sel_hi:[1,0,1]
	v_cvt_pk_bf16_f32 v248, v206, v207
	v_cvt_pk_bf16_f32 v249, v208, v209
	v_cvt_pk_bf16_f32 v250, v210, v211
	v_cvt_pk_bf16_f32 v251, v212, v213
	s_add_u32 s48, s82, 0xb0000
	s_addc_u32 s49, s83, 0
	global_store_dwordx4 v170, v[248:251], s[48:49]
	global_load_dwordx4 v[98:101], v174, s[12:13] offset:512
	global_load_dwordx4 v[90:93], v174, s[12:13] offset:528
	global_load_dwordx4 v[102:105], v174, s[14:15] offset:512
	global_load_dwordx4 v[94:97], v174, s[14:15] offset:528
	s_add_u32 s48, s82, 0x100
	s_addc_u32 s49, s83, 0
	global_load_dwordx4 v[220:223], v170, s[48:49]
	s_add_u32 s50, s10, 0x0
	s_addc_u32 s51, s11, 0
	global_load_dwordx2 v[176:177], v171, s[50:51]
	s_add_u32 s48, s82, 0x10100
	s_addc_u32 s49, s83, 0
	global_load_dwordx4 v[224:227], v170, s[48:49]
	s_add_u32 s50, s10, 0x80
	s_addc_u32 s51, s11, 0
	global_load_dwordx2 v[180:181], v171, s[50:51]
	s_add_u32 s48, s82, 0x20100
	s_addc_u32 s49, s83, 0
	global_load_dwordx4 v[228:231], v170, s[48:49]
	s_add_u32 s50, s10, 0x100
	s_addc_u32 s51, s11, 0
	global_load_dwordx2 v[182:183], v171, s[50:51]
	s_add_u32 s48, s82, 0x30100
	s_addc_u32 s49, s83, 0
	global_load_dwordx4 v[232:235], v170, s[48:49]
	s_add_u32 s50, s10, 0x180
	s_addc_u32 s51, s11, 0
	global_load_dwordx2 v[184:185], v171, s[50:51]
	s_add_u32 s48, s82, 0x80100
	s_addc_u32 s49, s83, 0
	global_load_dwordx4 v[236:239], v170, s[48:49]
	s_add_u32 s50, s10, 0x400
	s_addc_u32 s51, s11, 0
	global_load_dwordx2 v[168:169], v171, s[50:51]
	s_add_u32 s48, s82, 0x90100
	s_addc_u32 s49, s83, 0
	global_load_dwordx4 v[240:243], v170, s[48:49]
	s_add_u32 s50, s10, 0x480
	s_addc_u32 s51, s11, 0
	global_load_dwordx2 v[252:253], v171, s[50:51]
	s_add_u32 s48, s82, 0xa0100
	s_addc_u32 s49, s83, 0
	global_load_dwordx4 v[244:247], v170, s[48:49]
	s_add_u32 s50, s10, 0x500
	s_addc_u32 s51, s11, 0
	global_load_dwordx2 v[214:215], v171, s[50:51]
	s_add_u32 s48, s82, 0xb0100
	s_addc_u32 s49, s83, 0
	global_load_dwordx4 v[248:251], v170, s[48:49]
	s_add_u32 s50, s10, 0x580
	s_addc_u32 s51, s11, 0
	global_load_dwordx2 v[216:217], v171, s[50:51]
	s_waitcnt vmcnt(14)
	v_lshlrev_b32_e32 v206, 16, v220
	v_and_b32_e32 v207, 0xffff0000, v220
	v_lshlrev_b32_e32 v208, 16, v221
	v_and_b32_e32 v209, 0xffff0000, v221
	v_lshlrev_b32_e32 v210, 16, v222
	v_and_b32_e32 v211, 0xffff0000, v222
	v_lshlrev_b32_e32 v212, 16, v223
	v_and_b32_e32 v213, 0xffff0000, v223
	v_sub_f32_e32 v206, v206, v176
	v_sub_f32_e32 v207, v207, v176
	v_sub_f32_e32 v208, v208, v176
	v_sub_f32_e32 v209, v209, v176
	v_sub_f32_e32 v210, v210, v176
	v_sub_f32_e32 v211, v211, v176
	v_sub_f32_e32 v212, v212, v176
	v_sub_f32_e32 v213, v213, v176
	v_pk_mul_f32 v[206:207], v[176:177], v[206:207] op_sel:[1,0]
	v_pk_mul_f32 v[208:209], v[176:177], v[208:209] op_sel:[1,0]
	v_pk_mul_f32 v[210:211], v[176:177], v[210:211] op_sel:[1,0]
	v_pk_mul_f32 v[212:213], v[176:177], v[212:213] op_sel:[1,0]
	v_pk_fma_f32 v[206:207], v[98:99], v[206:207], v[102:103]
	v_pk_fma_f32 v[208:209], v[100:101], v[208:209], v[104:105]
	v_pk_fma_f32 v[210:211], v[90:91], v[210:211], v[94:95]
	v_pk_fma_f32 v[212:213], v[92:93], v[212:213], v[96:97]
	v_pk_fma_f32 v[206:207], v[206:207], s[66:67], v[62:63] op_sel_hi:[1,0,1]
	v_pk_fma_f32 v[208:209], v[208:209], s[66:67], v[64:65] op_sel_hi:[1,0,1]
	v_pk_fma_f32 v[210:211], v[210:211], s[66:67], v[58:59] op_sel_hi:[1,0,1]
	v_pk_fma_f32 v[212:213], v[212:213], s[66:67], v[60:61] op_sel_hi:[1,0,1]
	v_cvt_pk_bf16_f32 v220, v206, v207
	v_cvt_pk_bf16_f32 v221, v208, v209
	v_cvt_pk_bf16_f32 v222, v210, v211
	v_cvt_pk_bf16_f32 v223, v212, v213
	s_add_u32 s48, s82, 0x100
	s_addc_u32 s49, s83, 0
	global_store_dwordx4 v170, v[220:223], s[48:49]
	s_waitcnt vmcnt(13)
	v_lshlrev_b32_e32 v206, 16, v224
	v_and_b32_e32 v207, 0xffff0000, v224
	v_lshlrev_b32_e32 v208, 16, v225
	v_and_b32_e32 v209, 0xffff0000, v225
	v_lshlrev_b32_e32 v210, 16, v226
	v_and_b32_e32 v211, 0xffff0000, v226
	v_lshlrev_b32_e32 v212, 16, v227
	v_and_b32_e32 v213, 0xffff0000, v227
	v_sub_f32_e32 v206, v206, v180
	v_sub_f32_e32 v207, v207, v180
	v_sub_f32_e32 v208, v208, v180
	v_sub_f32_e32 v209, v209, v180
	v_sub_f32_e32 v210, v210, v180
	v_sub_f32_e32 v211, v211, v180
	v_sub_f32_e32 v212, v212, v180
	v_sub_f32_e32 v213, v213, v180
	v_pk_mul_f32 v[206:207], v[180:181], v[206:207] op_sel:[1,0]
	v_pk_mul_f32 v[208:209], v[180:181], v[208:209] op_sel:[1,0]
	v_pk_mul_f32 v[210:211], v[180:181], v[210:211] op_sel:[1,0]
	v_pk_mul_f32 v[212:213], v[180:181], v[212:213] op_sel:[1,0]
	v_pk_fma_f32 v[206:207], v[98:99], v[206:207], v[102:103]
	v_pk_fma_f32 v[208:209], v[100:101], v[208:209], v[104:105]
	v_pk_fma_f32 v[210:211], v[90:91], v[210:211], v[94:95]
	v_pk_fma_f32 v[212:213], v[92:93], v[212:213], v[96:97]
	v_pk_fma_f32 v[206:207], v[206:207], s[66:67], v[54:55] op_sel_hi:[1,0,1]
	v_pk_fma_f32 v[208:209], v[208:209], s[66:67], v[56:57] op_sel_hi:[1,0,1]
	v_pk_fma_f32 v[210:211], v[210:211], s[66:67], v[50:51] op_sel_hi:[1,0,1]
	v_pk_fma_f32 v[212:213], v[212:213], s[66:67], v[52:53] op_sel_hi:[1,0,1]
	v_cvt_pk_bf16_f32 v224, v206, v207
	v_cvt_pk_bf16_f32 v225, v208, v209
	v_cvt_pk_bf16_f32 v226, v210, v211
	v_cvt_pk_bf16_f32 v227, v212, v213
	s_add_u32 s48, s82, 0x10100
	s_addc_u32 s49, s83, 0
	global_store_dwordx4 v170, v[224:227], s[48:49]
	s_waitcnt vmcnt(12)
	v_lshlrev_b32_e32 v206, 16, v228
	v_and_b32_e32 v207, 0xffff0000, v228
	v_lshlrev_b32_e32 v208, 16, v229
	v_and_b32_e32 v209, 0xffff0000, v229
	v_lshlrev_b32_e32 v210, 16, v230
	v_and_b32_e32 v211, 0xffff0000, v230
	v_lshlrev_b32_e32 v212, 16, v231
	v_and_b32_e32 v213, 0xffff0000, v231
	v_sub_f32_e32 v206, v206, v182
	v_sub_f32_e32 v207, v207, v182
	v_sub_f32_e32 v208, v208, v182
	v_sub_f32_e32 v209, v209, v182
	v_sub_f32_e32 v210, v210, v182
	v_sub_f32_e32 v211, v211, v182
	v_sub_f32_e32 v212, v212, v182
	v_sub_f32_e32 v213, v213, v182
	v_pk_mul_f32 v[206:207], v[182:183], v[206:207] op_sel:[1,0]
	v_pk_mul_f32 v[208:209], v[182:183], v[208:209] op_sel:[1,0]
	v_pk_mul_f32 v[210:211], v[182:183], v[210:211] op_sel:[1,0]
	v_pk_mul_f32 v[212:213], v[182:183], v[212:213] op_sel:[1,0]
	v_pk_fma_f32 v[206:207], v[98:99], v[206:207], v[102:103]
	v_pk_fma_f32 v[208:209], v[100:101], v[208:209], v[104:105]
	v_pk_fma_f32 v[210:211], v[90:91], v[210:211], v[94:95]
	v_pk_fma_f32 v[212:213], v[92:93], v[212:213], v[96:97]
	v_pk_fma_f32 v[206:207], v[206:207], s[66:67], v[46:47] op_sel_hi:[1,0,1]
	v_pk_fma_f32 v[208:209], v[208:209], s[66:67], v[48:49] op_sel_hi:[1,0,1]
	v_pk_fma_f32 v[210:211], v[210:211], s[66:67], v[42:43] op_sel_hi:[1,0,1]
	v_pk_fma_f32 v[212:213], v[212:213], s[66:67], v[44:45] op_sel_hi:[1,0,1]
	v_cvt_pk_bf16_f32 v228, v206, v207
	v_cvt_pk_bf16_f32 v229, v208, v209
	v_cvt_pk_bf16_f32 v230, v210, v211
	v_cvt_pk_bf16_f32 v231, v212, v213
	s_add_u32 s48, s82, 0x20100
	s_addc_u32 s49, s83, 0
	global_store_dwordx4 v170, v[228:231], s[48:49]
	s_waitcnt vmcnt(11)
	v_lshlrev_b32_e32 v206, 16, v232
	v_and_b32_e32 v207, 0xffff0000, v232
	v_lshlrev_b32_e32 v208, 16, v233
	v_and_b32_e32 v209, 0xffff0000, v233
	v_lshlrev_b32_e32 v210, 16, v234
	v_and_b32_e32 v211, 0xffff0000, v234
	v_lshlrev_b32_e32 v212, 16, v235
	v_and_b32_e32 v213, 0xffff0000, v235
	v_sub_f32_e32 v206, v206, v184
	v_sub_f32_e32 v207, v207, v184
	v_sub_f32_e32 v208, v208, v184
	v_sub_f32_e32 v209, v209, v184
	v_sub_f32_e32 v210, v210, v184
	v_sub_f32_e32 v211, v211, v184
	v_sub_f32_e32 v212, v212, v184
	v_sub_f32_e32 v213, v213, v184
	v_pk_mul_f32 v[206:207], v[184:185], v[206:207] op_sel:[1,0]
	v_pk_mul_f32 v[208:209], v[184:185], v[208:209] op_sel:[1,0]
	v_pk_mul_f32 v[210:211], v[184:185], v[210:211] op_sel:[1,0]
	v_pk_mul_f32 v[212:213], v[184:185], v[212:213] op_sel:[1,0]
	v_pk_fma_f32 v[206:207], v[98:99], v[206:207], v[102:103]
	v_pk_fma_f32 v[208:209], v[100:101], v[208:209], v[104:105]
	v_pk_fma_f32 v[210:211], v[90:91], v[210:211], v[94:95]
	v_pk_fma_f32 v[212:213], v[92:93], v[212:213], v[96:97]
	v_pk_fma_f32 v[206:207], v[206:207], s[66:67], v[38:39] op_sel_hi:[1,0,1]
	v_pk_fma_f32 v[208:209], v[208:209], s[66:67], v[40:41] op_sel_hi:[1,0,1]
	v_pk_fma_f32 v[210:211], v[210:211], s[66:67], v[34:35] op_sel_hi:[1,0,1]
	v_pk_fma_f32 v[212:213], v[212:213], s[66:67], v[36:37] op_sel_hi:[1,0,1]
	v_cvt_pk_bf16_f32 v232, v206, v207
	v_cvt_pk_bf16_f32 v233, v208, v209
	v_cvt_pk_bf16_f32 v234, v210, v211
	v_cvt_pk_bf16_f32 v235, v212, v213
	s_add_u32 s48, s82, 0x30100
	s_addc_u32 s49, s83, 0
	global_store_dwordx4 v170, v[232:235], s[48:49]
	s_waitcnt vmcnt(10)
	v_lshlrev_b32_e32 v206, 16, v236
	v_and_b32_e32 v207, 0xffff0000, v236
	v_lshlrev_b32_e32 v208, 16, v237
	v_and_b32_e32 v209, 0xffff0000, v237
	v_lshlrev_b32_e32 v210, 16, v238
	v_and_b32_e32 v211, 0xffff0000, v238
	v_lshlrev_b32_e32 v212, 16, v239
	v_and_b32_e32 v213, 0xffff0000, v239
	v_sub_f32_e32 v206, v206, v168
	v_sub_f32_e32 v207, v207, v168
	v_sub_f32_e32 v208, v208, v168
	v_sub_f32_e32 v209, v209, v168
	v_sub_f32_e32 v210, v210, v168
	v_sub_f32_e32 v211, v211, v168
	v_sub_f32_e32 v212, v212, v168
	v_sub_f32_e32 v213, v213, v168
	v_pk_mul_f32 v[206:207], v[168:169], v[206:207] op_sel:[1,0]
	v_pk_mul_f32 v[208:209], v[168:169], v[208:209] op_sel:[1,0]
	v_pk_mul_f32 v[210:211], v[168:169], v[210:211] op_sel:[1,0]
	v_pk_mul_f32 v[212:213], v[168:169], v[212:213] op_sel:[1,0]
	v_pk_fma_f32 v[206:207], v[98:99], v[206:207], v[102:103]
	v_pk_fma_f32 v[208:209], v[100:101], v[208:209], v[104:105]
	v_pk_fma_f32 v[210:211], v[90:91], v[210:211], v[94:95]
	v_pk_fma_f32 v[212:213], v[92:93], v[212:213], v[96:97]
	v_pk_fma_f32 v[206:207], v[206:207], s[66:67], v[30:31] op_sel_hi:[1,0,1]
	v_pk_fma_f32 v[208:209], v[208:209], s[66:67], v[32:33] op_sel_hi:[1,0,1]
	v_pk_fma_f32 v[210:211], v[210:211], s[66:67], v[26:27] op_sel_hi:[1,0,1]
	v_pk_fma_f32 v[212:213], v[212:213], s[66:67], v[28:29] op_sel_hi:[1,0,1]
	v_cvt_pk_bf16_f32 v236, v206, v207
	v_cvt_pk_bf16_f32 v237, v208, v209
	v_cvt_pk_bf16_f32 v238, v210, v211
	v_cvt_pk_bf16_f32 v239, v212, v213
	s_add_u32 s48, s82, 0x80100
	s_addc_u32 s49, s83, 0
	global_store_dwordx4 v170, v[236:239], s[48:49]
	s_waitcnt vmcnt(9)
	v_lshlrev_b32_e32 v206, 16, v240
	v_and_b32_e32 v207, 0xffff0000, v240
	v_lshlrev_b32_e32 v208, 16, v241
	v_and_b32_e32 v209, 0xffff0000, v241
	v_lshlrev_b32_e32 v210, 16, v242
	v_and_b32_e32 v211, 0xffff0000, v242
	v_lshlrev_b32_e32 v212, 16, v243
	v_and_b32_e32 v213, 0xffff0000, v243
	v_sub_f32_e32 v206, v206, v252
	v_sub_f32_e32 v207, v207, v252
	v_sub_f32_e32 v208, v208, v252
	v_sub_f32_e32 v209, v209, v252
	v_sub_f32_e32 v210, v210, v252
	v_sub_f32_e32 v211, v211, v252
	v_sub_f32_e32 v212, v212, v252
	v_sub_f32_e32 v213, v213, v252
	v_pk_mul_f32 v[206:207], v[252:253], v[206:207] op_sel:[1,0]
	v_pk_mul_f32 v[208:209], v[252:253], v[208:209] op_sel:[1,0]
	v_pk_mul_f32 v[210:211], v[252:253], v[210:211] op_sel:[1,0]
	v_pk_mul_f32 v[212:213], v[252:253], v[212:213] op_sel:[1,0]
	v_pk_fma_f32 v[206:207], v[98:99], v[206:207], v[102:103]
	v_pk_fma_f32 v[208:209], v[100:101], v[208:209], v[104:105]
	v_pk_fma_f32 v[210:211], v[90:91], v[210:211], v[94:95]
	v_pk_fma_f32 v[212:213], v[92:93], v[212:213], v[96:97]
	v_pk_fma_f32 v[206:207], v[206:207], s[66:67], v[22:23] op_sel_hi:[1,0,1]
	v_pk_fma_f32 v[208:209], v[208:209], s[66:67], v[24:25] op_sel_hi:[1,0,1]
	v_pk_fma_f32 v[210:211], v[210:211], s[66:67], v[18:19] op_sel_hi:[1,0,1]
	v_pk_fma_f32 v[212:213], v[212:213], s[66:67], v[20:21] op_sel_hi:[1,0,1]
	v_cvt_pk_bf16_f32 v240, v206, v207
	v_cvt_pk_bf16_f32 v241, v208, v209
	v_cvt_pk_bf16_f32 v242, v210, v211
	v_cvt_pk_bf16_f32 v243, v212, v213
	s_add_u32 s48, s82, 0x90100
	s_addc_u32 s49, s83, 0
	global_store_dwordx4 v170, v[240:243], s[48:49]
	s_waitcnt vmcnt(8)
	v_lshlrev_b32_e32 v206, 16, v244
	v_and_b32_e32 v207, 0xffff0000, v244
	v_lshlrev_b32_e32 v208, 16, v245
	v_and_b32_e32 v209, 0xffff0000, v245
	v_lshlrev_b32_e32 v210, 16, v246
	v_and_b32_e32 v211, 0xffff0000, v246
	v_lshlrev_b32_e32 v212, 16, v247
	v_and_b32_e32 v213, 0xffff0000, v247
	v_sub_f32_e32 v206, v206, v214
	v_sub_f32_e32 v207, v207, v214
	v_sub_f32_e32 v208, v208, v214
	v_sub_f32_e32 v209, v209, v214
	v_sub_f32_e32 v210, v210, v214
	v_sub_f32_e32 v211, v211, v214
	v_sub_f32_e32 v212, v212, v214
	v_sub_f32_e32 v213, v213, v214
	v_pk_mul_f32 v[206:207], v[214:215], v[206:207] op_sel:[1,0]
	v_pk_mul_f32 v[208:209], v[214:215], v[208:209] op_sel:[1,0]
	v_pk_mul_f32 v[210:211], v[214:215], v[210:211] op_sel:[1,0]
	v_pk_mul_f32 v[212:213], v[214:215], v[212:213] op_sel:[1,0]
	v_pk_fma_f32 v[206:207], v[98:99], v[206:207], v[102:103]
	v_pk_fma_f32 v[208:209], v[100:101], v[208:209], v[104:105]
	v_pk_fma_f32 v[210:211], v[90:91], v[210:211], v[94:95]
	v_pk_fma_f32 v[212:213], v[92:93], v[212:213], v[96:97]
	v_pk_fma_f32 v[206:207], v[206:207], s[66:67], v[14:15] op_sel_hi:[1,0,1]
	v_pk_fma_f32 v[208:209], v[208:209], s[66:67], v[16:17] op_sel_hi:[1,0,1]
	v_pk_fma_f32 v[210:211], v[210:211], s[66:67], v[10:11] op_sel_hi:[1,0,1]
	v_pk_fma_f32 v[212:213], v[212:213], s[66:67], v[12:13] op_sel_hi:[1,0,1]
	v_cvt_pk_bf16_f32 v244, v206, v207
	v_cvt_pk_bf16_f32 v245, v208, v209
	v_cvt_pk_bf16_f32 v246, v210, v211
	v_cvt_pk_bf16_f32 v247, v212, v213
	s_add_u32 s48, s82, 0xa0100
	s_addc_u32 s49, s83, 0
	global_store_dwordx4 v170, v[244:247], s[48:49]
	s_waitcnt vmcnt(7)
	v_lshlrev_b32_e32 v206, 16, v248
	v_and_b32_e32 v207, 0xffff0000, v248
	v_lshlrev_b32_e32 v208, 16, v249
	v_and_b32_e32 v209, 0xffff0000, v249
	v_lshlrev_b32_e32 v210, 16, v250
	v_and_b32_e32 v211, 0xffff0000, v250
	v_lshlrev_b32_e32 v212, 16, v251
	v_and_b32_e32 v213, 0xffff0000, v251
	v_sub_f32_e32 v206, v206, v216
	v_sub_f32_e32 v207, v207, v216
	v_sub_f32_e32 v208, v208, v216
	v_sub_f32_e32 v209, v209, v216
	v_sub_f32_e32 v210, v210, v216
	v_sub_f32_e32 v211, v211, v216
	v_sub_f32_e32 v212, v212, v216
	v_sub_f32_e32 v213, v213, v216
	v_pk_mul_f32 v[206:207], v[216:217], v[206:207] op_sel:[1,0]
	v_pk_mul_f32 v[208:209], v[216:217], v[208:209] op_sel:[1,0]
	v_pk_mul_f32 v[210:211], v[216:217], v[210:211] op_sel:[1,0]
	v_pk_mul_f32 v[212:213], v[216:217], v[212:213] op_sel:[1,0]
	v_pk_fma_f32 v[206:207], v[98:99], v[206:207], v[102:103]
	v_pk_fma_f32 v[208:209], v[100:101], v[208:209], v[104:105]
	v_pk_fma_f32 v[210:211], v[90:91], v[210:211], v[94:95]
	v_pk_fma_f32 v[212:213], v[92:93], v[212:213], v[96:97]
	v_pk_fma_f32 v[206:207], v[206:207], s[66:67], v[6:7] op_sel_hi:[1,0,1]
	v_pk_fma_f32 v[208:209], v[208:209], s[66:67], v[8:9] op_sel_hi:[1,0,1]
	v_pk_fma_f32 v[210:211], v[210:211], s[66:67], v[2:3] op_sel_hi:[1,0,1]
	v_pk_fma_f32 v[212:213], v[212:213], s[66:67], v[4:5] op_sel_hi:[1,0,1]
	v_cvt_pk_bf16_f32 v248, v206, v207
	v_cvt_pk_bf16_f32 v249, v208, v209
	v_cvt_pk_bf16_f32 v250, v210, v211
	v_cvt_pk_bf16_f32 v251, v212, v213
	s_add_u32 s48, s82, 0xb0100
	s_addc_u32 s49, s83, 0
	global_store_dwordx4 v170, v[248:251], s[48:49]
	s_and_b64 vcc, exec, s[8:9]
	s_mov_b32 s43, s86
	s_mov_b32 s46, s84
	s_mov_b64 s[68:69], s[90:91]
	s_mov_b64 s[64:65], s[88:89]
	s_cbranch_vccz .LBB0_1249
	s_waitcnt vmcnt(0)
	v_readlane_b32 s86, v254, 39
	s_cmpk_gt_u32 s21, 0xff
	s_mov_b32 s84, 0xf800000
	s_mov_b32 s85, 0x100000
	v_readlane_b32 s87, v254, 40
	s_cbranch_scc1 .LBB0_1260
	s_barrier

.LBB0_1617:
	s_add_u32 s68, s64, 0x100
	s_addc_u32 s69, s65, 0
	s_add_i32 s48, 0, 0x10000
	v_add_u32_e32 v102, s48, v187
	ds_read_b128 v[90:93], v102
	ds_read_b128 v[94:97], v102 offset:1024
	ds_read_b128 v[98:101], v102 offset:2048
	ds_read_b128 v[102:105], v102 offset:3072
	s_cmpk_eq_i32 s47, 0x54
	s_cselect_b32 s81, s11, s69
	s_cselect_b32 s80, s10, s68
	s_cselect_b32 s45, s13, s5
	s_cselect_b32 s44, s12, s4
	v_lshl_add_u64 v[184:185], s[64:65], 0, v[164:165]
	s_add_i32 m0, s27, 0xc000
	ds_read_b128 v[168:171], v189
	ds_read_b128 v[172:175], v189 offset:1024
	ds_read_b128 v[176:179], v189 offset:2048
	ds_read_b128 v[180:183], v189 offset:3072
	ds_read_b128 v[206:209], v189 offset:4096
	ds_read_b128 v[210:213], v189 offset:5120
	ds_read_b128 v[214:217], v189 offset:6144
	ds_read_b128 v[218:221], v189 offset:7168
	global_load_lds_dwordx4 v[184:185], off
	v_lshl_add_u64 v[184:185], s[64:65], 0, v[166:167]
	s_add_i32 m0, s27, 0xe000
	s_nop 0
	global_load_lds_dwordx4 v[184:185], off
	s_waitcnt lgkmcnt(8)
	s_barrier
	s_waitcnt lgkmcnt(0)
	s_setprio 1
	s_waitcnt lgkmcnt(0)
	v_mfma_f32_16x16x32_bf16 v[142:145], v[90:93], v[168:171], v[142:145]
	v_mfma_f32_16x16x32_bf16 v[138:141], v[98:101], v[168:171], v[138:141]
	v_mfma_f32_16x16x32_bf16 v[134:137], v[90:93], v[176:179], v[134:137]
	v_mfma_f32_16x16x32_bf16 v[130:133], v[98:101], v[176:179], v[130:133]
	v_mfma_f32_16x16x32_bf16 v[126:129], v[90:93], v[206:209], v[126:129]
	v_mfma_f32_16x16x32_bf16 v[122:125], v[98:101], v[206:209], v[122:125]
	v_mfma_f32_16x16x32_bf16 v[118:121], v[90:93], v[214:217], v[118:121]
	v_mfma_f32_16x16x32_bf16 v[114:117], v[98:101], v[214:217], v[114:117]
	v_mfma_f32_16x16x32_bf16 v[142:145], v[94:97], v[172:175], v[142:145]
	v_mfma_f32_16x16x32_bf16 v[138:141], v[102:105], v[172:175], v[138:141]
	v_mfma_f32_16x16x32_bf16 v[134:137], v[94:97], v[180:183], v[134:137]
	v_mfma_f32_16x16x32_bf16 v[130:133], v[102:105], v[180:183], v[130:133]
	v_mfma_f32_16x16x32_bf16 v[126:129], v[94:97], v[210:213], v[126:129]
	v_mfma_f32_16x16x32_bf16 v[122:125], v[102:105], v[210:213], v[122:125]
	v_mfma_f32_16x16x32_bf16 v[118:121], v[94:97], v[218:221], v[118:121]
	v_mfma_f32_16x16x32_bf16 v[114:117], v[102:105], v[218:221], v[114:117]
	s_setprio 0
	s_barrier
	s_add_i32 s50, 0, 0x14000
	v_add_u32_e32 v184, s50, v187
	s_add_i32 s48, s48, s22
	ds_read_b128 v[222:225], v184
	ds_read_b128 v[226:229], v184 offset:1024
	ds_read_b128 v[230:233], v184 offset:2048
	ds_read_b128 v[234:237], v184 offset:3072
	v_lshl_add_u64 v[184:185], s[44:45], 0, v[0:1]
	s_mov_b32 m0, s48
	v_lshl_add_u64 v[238:239], s[44:45], 0, v[158:159]
	global_load_lds_dwordx4 v[184:185], off
	s_add_i32 m0, s48, 0x2000
	s_nop 0
	global_load_lds_dwordx4 v[238:239], off
	s_barrier
	s_waitcnt lgkmcnt(0)
	s_setprio 1
	s_waitcnt lgkmcnt(0)
	v_mfma_f32_16x16x32_bf16 v[62:65], v[222:225], v[168:171], v[62:65]
	v_mfma_f32_16x16x32_bf16 v[58:61], v[230:233], v[168:171], v[58:61]
	v_mfma_f32_16x16x32_bf16 v[54:57], v[222:225], v[176:179], v[54:57]
	v_mfma_f32_16x16x32_bf16 v[50:53], v[230:233], v[176:179], v[50:53]
	v_mfma_f32_16x16x32_bf16 v[46:49], v[222:225], v[206:209], v[46:49]
	v_mfma_f32_16x16x32_bf16 v[42:45], v[230:233], v[206:209], v[42:45]
	v_mfma_f32_16x16x32_bf16 v[38:41], v[222:225], v[214:217], v[38:41]
	v_mfma_f32_16x16x32_bf16 v[34:37], v[230:233], v[214:217], v[34:37]
	v_mfma_f32_16x16x32_bf16 v[62:65], v[226:229], v[172:175], v[62:65]
	v_mfma_f32_16x16x32_bf16 v[58:61], v[234:237], v[172:175], v[58:61]
	v_mfma_f32_16x16x32_bf16 v[54:57], v[226:229], v[180:183], v[54:57]
	v_mfma_f32_16x16x32_bf16 v[50:53], v[234:237], v[180:183], v[50:53]
	v_mfma_f32_16x16x32_bf16 v[46:49], v[226:229], v[210:213], v[46:49]
	v_mfma_f32_16x16x32_bf16 v[42:45], v[234:237], v[210:213], v[42:45]
	v_mfma_f32_16x16x32_bf16 v[38:41], v[226:229], v[218:221], v[38:41]
	v_mfma_f32_16x16x32_bf16 v[34:37], v[234:237], v[218:221], v[34:37]
	s_setprio 0
	s_mov_b32 m0, s27
	v_lshl_add_u64 v[240:241], s[80:81], 0, v[162:163]
	s_barrier
	ds_read_b128 v[168:171], v189 offset:16384
	ds_read_b128 v[172:175], v189 offset:17408
	ds_read_b128 v[176:179], v189 offset:18432
	ds_read_b128 v[180:183], v189 offset:19456
	ds_read_b128 v[206:209], v189 offset:20480
	ds_read_b128 v[210:213], v189 offset:21504
	ds_read_b128 v[214:217], v189 offset:22528
	ds_read_b128 v[218:221], v189 offset:23552
	global_load_lds_dwordx4 v[240:241], off
	v_lshl_add_u64 v[242:243], s[80:81], 0, v[160:161]
	s_mov_b32 m0, s36
	s_nop 0
	global_load_lds_dwordx4 v[242:243], off
	s_barrier
	s_waitcnt lgkmcnt(0)
	s_setprio 1
	s_waitcnt lgkmcnt(0)
	v_mfma_f32_16x16x32_bf16 v[110:113], v[90:93], v[168:171], v[110:113]
	v_mfma_f32_16x16x32_bf16 v[106:109], v[98:101], v[168:171], v[106:109]
	v_mfma_f32_16x16x32_bf16 v[86:89], v[90:93], v[176:179], v[86:89]
	v_mfma_f32_16x16x32_bf16 v[82:85], v[98:101], v[176:179], v[82:85]
	v_mfma_f32_16x16x32_bf16 v[78:81], v[90:93], v[206:209], v[78:81]
	v_mfma_f32_16x16x32_bf16 v[74:77], v[98:101], v[206:209], v[74:77]
	v_mfma_f32_16x16x32_bf16 v[70:73], v[90:93], v[214:217], v[70:73]
	v_mfma_f32_16x16x32_bf16 v[66:69], v[98:101], v[214:217], v[66:69]
	v_mfma_f32_16x16x32_bf16 v[110:113], v[94:97], v[172:175], v[110:113]
	v_mfma_f32_16x16x32_bf16 v[106:109], v[102:105], v[172:175], v[106:109]
	v_mfma_f32_16x16x32_bf16 v[86:89], v[94:97], v[180:183], v[86:89]
	v_mfma_f32_16x16x32_bf16 v[82:85], v[102:105], v[180:183], v[82:85]
	v_mfma_f32_16x16x32_bf16 v[78:81], v[94:97], v[210:213], v[78:81]
	v_mfma_f32_16x16x32_bf16 v[74:77], v[102:105], v[210:213], v[74:77]
	v_mfma_f32_16x16x32_bf16 v[70:73], v[94:97], v[218:221], v[70:73]
	v_mfma_f32_16x16x32_bf16 v[66:69], v[102:105], v[218:221], v[66:69]
	s_setprio 0
	s_barrier
	s_add_u32 s48, s44, 0x160000
	s_addc_u32 s49, s45, 0
	s_add_i32 s50, s50, s22
	v_lshl_add_u64 v[90:91], s[48:49], 0, v[0:1]
	s_mov_b32 m0, s50
	s_nop 0
	global_load_lds_dwordx4 v[90:91], off
	v_lshl_add_u64 v[90:91], s[48:49], 0, v[158:159]
	s_add_i32 m0, s50, 0x2000
	s_nop 0
	global_load_lds_dwordx4 v[90:91], off
	s_waitcnt vmcnt(6)
	s_barrier
	s_setprio 1
	v_mfma_f32_16x16x32_bf16 v[30:33], v[222:225], v[168:171], v[30:33]
	v_mfma_f32_16x16x32_bf16 v[26:29], v[230:233], v[168:171], v[26:29]
	v_mfma_f32_16x16x32_bf16 v[22:25], v[222:225], v[176:179], v[22:25]
	v_mfma_f32_16x16x32_bf16 v[18:21], v[230:233], v[176:179], v[18:21]
	v_mfma_f32_16x16x32_bf16 v[14:17], v[222:225], v[206:209], v[14:17]
	v_mfma_f32_16x16x32_bf16 v[10:13], v[230:233], v[206:209], v[10:13]
	v_mfma_f32_16x16x32_bf16 v[6:9], v[222:225], v[214:217], v[6:9]
	v_mfma_f32_16x16x32_bf16 v[2:5], v[230:233], v[214:217], v[2:5]
	v_mfma_f32_16x16x32_bf16 v[30:33], v[226:229], v[172:175], v[30:33]
	v_mfma_f32_16x16x32_bf16 v[26:29], v[234:237], v[172:175], v[26:29]
	v_mfma_f32_16x16x32_bf16 v[22:25], v[226:229], v[180:183], v[22:25]
	v_mfma_f32_16x16x32_bf16 v[18:21], v[234:237], v[180:183], v[18:21]
	v_mfma_f32_16x16x32_bf16 v[14:17], v[226:229], v[210:213], v[14:17]
	v_mfma_f32_16x16x32_bf16 v[10:13], v[234:237], v[210:213], v[10:13]
	v_mfma_f32_16x16x32_bf16 v[6:9], v[226:229], v[218:221], v[6:9]
	v_mfma_f32_16x16x32_bf16 v[2:5], v[234:237], v[218:221], v[2:5]
	s_setprio 0
	s_add_i32 s50, 0, 0x18000
	v_add_u32_e32 v102, s50, v187
	s_barrier
	ds_read_b128 v[90:93], v102
	ds_read_b128 v[94:97], v102 offset:1024
	ds_read_b128 v[98:101], v102 offset:2048
	ds_read_b128 v[102:105], v102 offset:3072
	s_add_u32 s48, s80, 0x160000
	s_addc_u32 s49, s81, 0
	s_mov_b32 m0, s37
	v_lshl_add_u64 v[222:223], s[48:49], 0, v[162:163]
	ds_read_b128 v[168:171], v189 offset:32768
	ds_read_b128 v[172:175], v189 offset:33792
	ds_read_b128 v[176:179], v189 offset:34816
	ds_read_b128 v[180:183], v189 offset:35840
	ds_read_b128 v[206:209], v189 offset:36864
	ds_read_b128 v[210:213], v189 offset:37888
	ds_read_b128 v[214:217], v189 offset:38912
	ds_read_b128 v[218:221], v189 offset:39936
	global_load_lds_dwordx4 v[222:223], off
	v_lshl_add_u64 v[222:223], s[48:49], 0, v[160:161]
	s_mov_b32 m0, s40
	s_nop 0
	global_load_lds_dwordx4 v[222:223], off
	s_waitcnt lgkmcnt(8)
	s_barrier
	s_waitcnt lgkmcnt(0)
	s_setprio 1
	s_waitcnt lgkmcnt(0)
	v_mfma_f32_16x16x32_bf16 v[142:145], v[90:93], v[168:171], v[142:145]
	v_mfma_f32_16x16x32_bf16 v[138:141], v[98:101], v[168:171], v[138:141]
	v_mfma_f32_16x16x32_bf16 v[134:137], v[90:93], v[176:179], v[134:137]
	v_mfma_f32_16x16x32_bf16 v[130:133], v[98:101], v[176:179], v[130:133]
	v_mfma_f32_16x16x32_bf16 v[126:129], v[90:93], v[206:209], v[126:129]
	v_mfma_f32_16x16x32_bf16 v[122:125], v[98:101], v[206:209], v[122:125]
	v_mfma_f32_16x16x32_bf16 v[118:121], v[90:93], v[214:217], v[118:121]
	v_mfma_f32_16x16x32_bf16 v[114:117], v[98:101], v[214:217], v[114:117]
	v_mfma_f32_16x16x32_bf16 v[142:145], v[94:97], v[172:175], v[142:145]
	v_mfma_f32_16x16x32_bf16 v[138:141], v[102:105], v[172:175], v[138:141]
	v_mfma_f32_16x16x32_bf16 v[134:137], v[94:97], v[180:183], v[134:137]
	v_mfma_f32_16x16x32_bf16 v[130:133], v[102:105], v[180:183], v[130:133]
	v_mfma_f32_16x16x32_bf16 v[126:129], v[94:97], v[210:213], v[126:129]
	v_mfma_f32_16x16x32_bf16 v[122:125], v[102:105], v[210:213], v[122:125]
	v_mfma_f32_16x16x32_bf16 v[118:121], v[94:97], v[218:221], v[118:121]
	v_mfma_f32_16x16x32_bf16 v[114:117], v[102:105], v[218:221], v[114:117]
	s_setprio 0
	s_barrier
	s_add_i32 s48, 0, 0x1c000
	s_add_i32 s49, s50, s22
	v_add_u32_e32 v205, s48, v187
	v_lshl_add_u64 v[184:185], v[184:185], 0, s[62:63]
	s_mov_b32 m0, s49
	ds_read_b128 v[222:225], v205
	ds_read_b128 v[226:229], v205 offset:1024
	ds_read_b128 v[230:233], v205 offset:2048
	ds_read_b128 v[234:237], v205 offset:3072
	global_load_lds_dwordx4 v[184:185], off
	v_lshl_add_u64 v[184:185], v[238:239], 0, s[62:63]
	s_add_i32 m0, s49, 0x2000
	s_nop 0
	global_load_lds_dwordx4 v[184:185], off
	s_barrier
	s_waitcnt lgkmcnt(0)
	s_setprio 1
	s_waitcnt lgkmcnt(0)
	v_mfma_f32_16x16x32_bf16 v[62:65], v[222:225], v[168:171], v[62:65]
	v_mfma_f32_16x16x32_bf16 v[58:61], v[230:233], v[168:171], v[58:61]
	v_mfma_f32_16x16x32_bf16 v[54:57], v[222:225], v[176:179], v[54:57]
	v_mfma_f32_16x16x32_bf16 v[50:53], v[230:233], v[176:179], v[50:53]
	v_mfma_f32_16x16x32_bf16 v[46:49], v[222:225], v[206:209], v[46:49]
	v_mfma_f32_16x16x32_bf16 v[42:45], v[230:233], v[206:209], v[42:45]
	v_mfma_f32_16x16x32_bf16 v[38:41], v[222:225], v[214:217], v[38:41]
	v_mfma_f32_16x16x32_bf16 v[34:37], v[230:233], v[214:217], v[34:37]
	v_mfma_f32_16x16x32_bf16 v[62:65], v[226:229], v[172:175], v[62:65]
	v_mfma_f32_16x16x32_bf16 v[58:61], v[234:237], v[172:175], v[58:61]
	v_mfma_f32_16x16x32_bf16 v[54:57], v[226:229], v[180:183], v[54:57]
	v_mfma_f32_16x16x32_bf16 v[50:53], v[234:237], v[180:183], v[50:53]
	v_mfma_f32_16x16x32_bf16 v[46:49], v[226:229], v[210:213], v[46:49]
	v_mfma_f32_16x16x32_bf16 v[42:45], v[234:237], v[210:213], v[42:45]
	v_mfma_f32_16x16x32_bf16 v[38:41], v[226:229], v[218:221], v[38:41]
	v_mfma_f32_16x16x32_bf16 v[34:37], v[234:237], v[218:221], v[34:37]
	s_setprio 0
	s_mov_b32 m0, s28
	v_lshl_add_u64 v[184:185], v[240:241], 0, s[62:63]
	s_barrier
	ds_read_b128 v[168:171], v189 offset:49152
	ds_read_b128 v[172:175], v189 offset:50176
	ds_read_b128 v[176:179], v189 offset:51200
	ds_read_b128 v[180:183], v189 offset:52224
	ds_read_b128 v[206:209], v189 offset:53248
	ds_read_b128 v[210:213], v189 offset:54272
	ds_read_b128 v[214:217], v189 offset:55296
	ds_read_b128 v[218:221], v189 offset:56320
	global_load_lds_dwordx4 v[184:185], off
	v_lshl_add_u64 v[184:185], v[242:243], 0, s[62:63]
	s_mov_b32 m0, s41
	s_nop 0
	global_load_lds_dwordx4 v[184:185], off
	s_barrier
	s_waitcnt lgkmcnt(0)
	s_setprio 1
	s_waitcnt lgkmcnt(0)
	v_mfma_f32_16x16x32_bf16 v[110:113], v[90:93], v[168:171], v[110:113]
	v_mfma_f32_16x16x32_bf16 v[106:109], v[98:101], v[168:171], v[106:109]
	v_mfma_f32_16x16x32_bf16 v[86:89], v[90:93], v[176:179], v[86:89]
	v_mfma_f32_16x16x32_bf16 v[82:85], v[98:101], v[176:179], v[82:85]
	v_mfma_f32_16x16x32_bf16 v[78:81], v[90:93], v[206:209], v[78:81]
	v_mfma_f32_16x16x32_bf16 v[74:77], v[98:101], v[206:209], v[74:77]
	v_mfma_f32_16x16x32_bf16 v[70:73], v[90:93], v[214:217], v[70:73]
	v_mfma_f32_16x16x32_bf16 v[66:69], v[98:101], v[214:217], v[66:69]
	v_mfma_f32_16x16x32_bf16 v[110:113], v[94:97], v[172:175], v[110:113]
	v_mfma_f32_16x16x32_bf16 v[106:109], v[102:105], v[172:175], v[106:109]
	v_mfma_f32_16x16x32_bf16 v[86:89], v[94:97], v[180:183], v[86:89]
	v_mfma_f32_16x16x32_bf16 v[82:85], v[102:105], v[180:183], v[82:85]
	v_mfma_f32_16x16x32_bf16 v[78:81], v[94:97], v[210:213], v[78:81]
	v_mfma_f32_16x16x32_bf16 v[74:77], v[102:105], v[210:213], v[74:77]
	v_mfma_f32_16x16x32_bf16 v[70:73], v[94:97], v[218:221], v[70:73]
	v_mfma_f32_16x16x32_bf16 v[66:69], v[102:105], v[218:221], v[66:69]
	s_setprio 0
	s_barrier
	s_add_u32 s44, s44, 0x160080
	s_addc_u32 s45, s45, 0
	s_add_i32 s48, s48, s22
	v_lshl_add_u64 v[90:91], s[44:45], 0, v[0:1]
	s_mov_b32 m0, s48
	s_nop 0
	global_load_lds_dwordx4 v[90:91], off
	v_lshl_add_u64 v[90:91], s[44:45], 0, v[158:159]
	s_add_i32 m0, s48, 0x2000
	s_nop 0
	global_load_lds_dwordx4 v[90:91], off
	s_waitcnt vmcnt(6)
	s_barrier
	s_setprio 1
	v_mfma_f32_16x16x32_bf16 v[30:33], v[222:225], v[168:171], v[30:33]
	v_mfma_f32_16x16x32_bf16 v[26:29], v[230:233], v[168:171], v[26:29]
	v_mfma_f32_16x16x32_bf16 v[22:25], v[222:225], v[176:179], v[22:25]
	v_mfma_f32_16x16x32_bf16 v[18:21], v[230:233], v[176:179], v[18:21]
	v_mfma_f32_16x16x32_bf16 v[14:17], v[222:225], v[206:209], v[14:17]
	v_mfma_f32_16x16x32_bf16 v[10:13], v[230:233], v[206:209], v[10:13]
	v_mfma_f32_16x16x32_bf16 v[6:9], v[222:225], v[214:217], v[6:9]
	v_mfma_f32_16x16x32_bf16 v[2:5], v[230:233], v[214:217], v[2:5]
	v_mfma_f32_16x16x32_bf16 v[30:33], v[226:229], v[172:175], v[30:33]
	v_mfma_f32_16x16x32_bf16 v[26:29], v[234:237], v[172:175], v[26:29]
	v_mfma_f32_16x16x32_bf16 v[22:25], v[226:229], v[180:183], v[22:25]
	v_mfma_f32_16x16x32_bf16 v[18:21], v[234:237], v[180:183], v[18:21]
	v_mfma_f32_16x16x32_bf16 v[14:17], v[226:229], v[210:213], v[14:17]
	v_mfma_f32_16x16x32_bf16 v[10:13], v[234:237], v[210:213], v[10:13]
	v_mfma_f32_16x16x32_bf16 v[6:9], v[226:229], v[218:221], v[6:9]
	v_mfma_f32_16x16x32_bf16 v[2:5], v[234:237], v[218:221], v[2:5]
	s_setprio 0
	s_add_i32 s47, s47, 2
	s_add_u32 s4, s4, 0x100
	s_addc_u32 s5, s5, 0
	s_cmpk_gt_u32 s47, 0x55
	s_mov_b64 s[64:65], s[68:69]
	s_barrier
	s_cbranch_scc0 .LBB0_1617
	s_lshl_b32 s4, s46, 8
	s_and_b32 s4, s4, 0x3f00
	v_add_u32_e32 v178, s4, v186
	s_ashr_i32 s4, s43, 31
	s_lshr_b32 s4, s4, 29
	s_add_i32 s4, s43, s4
	s_and_b32 s4, s4, 0xfffff8
	s_sub_i32 s4, s43, s4
	v_lshl_or_b32 v172, s4, 8, v188
	v_ashrrev_i32_e32 v173, 31, v172
	v_ashrrev_i32_e32 v179, 31, v178
	v_lshlrev_b32_e32 v170, 12, v178
	v_lshl_add_u32 v170, v172, 1, v170
	v_lshlrev_b32_e32 v171, 3, v178
	v_lshlrev_b32_e32 v174, 2, v172
	global_load_dwordx4 v[98:101], v174, s[74:75]
	global_load_dwordx4 v[90:93], v174, s[74:75] offset:16
	global_load_dwordx4 v[102:105], v174, s[76:77]
	global_load_dwordx4 v[94:97], v174, s[76:77] offset:16
	s_add_u32 s48, s72, 0x0
	s_addc_u32 s49, s73, 0
	global_load_dwordx4 v[220:223], v170, s[48:49]
	s_add_u32 s50, s14, 0x0
	s_addc_u32 s51, s15, 0
	global_load_dwordx2 v[176:177], v171, s[50:51]
	s_add_u32 s48, s72, 0x10000
	s_addc_u32 s49, s73, 0
	global_load_dwordx4 v[224:227], v170, s[48:49]
	s_add_u32 s50, s14, 0x80
	s_addc_u32 s51, s15, 0
	global_load_dwordx2 v[180:181], v171, s[50:51]
	s_add_u32 s48, s72, 0x20000
	s_addc_u32 s49, s73, 0
	global_load_dwordx4 v[228:231], v170, s[48:49]
	s_add_u32 s50, s14, 0x100
	s_addc_u32 s51, s15, 0
	global_load_dwordx2 v[182:183], v171, s[50:51]
	s_add_u32 s48, s72, 0x30000
	s_addc_u32 s49, s73, 0
	global_load_dwordx4 v[232:235], v170, s[48:49]
	s_add_u32 s50, s14, 0x180
	s_addc_u32 s51, s15, 0
	global_load_dwordx2 v[184:185], v171, s[50:51]
	s_add_u32 s48, s72, 0x80000
	s_addc_u32 s49, s73, 0
	global_load_dwordx4 v[236:239], v170, s[48:49]
	s_add_u32 s50, s14, 0x400
	s_addc_u32 s51, s15, 0
	global_load_dwordx2 v[168:169], v171, s[50:51]
	s_add_u32 s48, s72, 0x90000
	s_addc_u32 s49, s73, 0
	global_load_dwordx4 v[240:243], v170, s[48:49]
	s_add_u32 s50, s14, 0x480
	s_addc_u32 s51, s15, 0
	global_load_dwordx2 v[252:253], v171, s[50:51]
	s_add_u32 s48, s72, 0xa0000
	s_addc_u32 s49, s73, 0
	global_load_dwordx4 v[244:247], v170, s[48:49]
	s_add_u32 s50, s14, 0x500
	s_addc_u32 s51, s15, 0
	global_load_dwordx2 v[214:215], v171, s[50:51]
	s_add_u32 s48, s72, 0xb0000
	s_addc_u32 s49, s73, 0
	global_load_dwordx4 v[248:251], v170, s[48:49]
	s_add_u32 s50, s14, 0x580
	s_addc_u32 s51, s15, 0
	global_load_dwordx2 v[216:217], v171, s[50:51]
	s_waitcnt vmcnt(14)
	v_lshlrev_b32_e32 v206, 16, v220
	v_and_b32_e32 v207, 0xffff0000, v220
	v_lshlrev_b32_e32 v208, 16, v221
	v_and_b32_e32 v209, 0xffff0000, v221
	v_lshlrev_b32_e32 v210, 16, v222
	v_and_b32_e32 v211, 0xffff0000, v222
	v_lshlrev_b32_e32 v212, 16, v223
	v_and_b32_e32 v213, 0xffff0000, v223
	v_sub_f32_e32 v206, v206, v176
	v_sub_f32_e32 v207, v207, v176
	v_sub_f32_e32 v208, v208, v176
	v_sub_f32_e32 v209, v209, v176
	v_sub_f32_e32 v210, v210, v176
	v_sub_f32_e32 v211, v211, v176
	v_sub_f32_e32 v212, v212, v176
	v_sub_f32_e32 v213, v213, v176
	v_pk_mul_f32 v[206:207], v[176:177], v[206:207] op_sel:[1,0]
	v_pk_mul_f32 v[208:209], v[176:177], v[208:209] op_sel:[1,0]
	v_pk_mul_f32 v[210:211], v[176:177], v[210:211] op_sel:[1,0]
	v_pk_mul_f32 v[212:213], v[176:177], v[212:213] op_sel:[1,0]
	v_pk_fma_f32 v[206:207], v[98:99], v[206:207], v[102:103]
	v_pk_fma_f32 v[208:209], v[100:101], v[208:209], v[104:105]
	v_pk_fma_f32 v[210:211], v[90:91], v[210:211], v[94:95]
	v_pk_fma_f32 v[212:213], v[92:93], v[212:213], v[96:97]
	v_pk_fma_f32 v[206:207], v[206:207], s[66:67], v[142:143] op_sel_hi:[1,0,1]
	v_pk_fma_f32 v[208:209], v[208:209], s[66:67], v[144:145] op_sel_hi:[1,0,1]
	v_pk_fma_f32 v[210:211], v[210:211], s[66:67], v[138:139] op_sel_hi:[1,0,1]
	v_pk_fma_f32 v[212:213], v[212:213], s[66:67], v[140:141] op_sel_hi:[1,0,1]
	v_cvt_pk_bf16_f32 v220, v206, v207
	v_cvt_pk_bf16_f32 v221, v208, v209
	v_cvt_pk_bf16_f32 v222, v210, v211
	v_cvt_pk_bf16_f32 v223, v212, v213
	s_add_u32 s48, s72, 0x0
	s_addc_u32 s49, s73, 0
	global_store_dwordx4 v170, v[220:223], s[48:49]
	s_waitcnt vmcnt(13)
	v_lshlrev_b32_e32 v206, 16, v224
	v_and_b32_e32 v207, 0xffff0000, v224
	v_lshlrev_b32_e32 v208, 16, v225
	v_and_b32_e32 v209, 0xffff0000, v225
	v_lshlrev_b32_e32 v210, 16, v226
	v_and_b32_e32 v211, 0xffff0000, v226
	v_lshlrev_b32_e32 v212, 16, v227
	v_and_b32_e32 v213, 0xffff0000, v227
	v_sub_f32_e32 v206, v206, v180
	v_sub_f32_e32 v207, v207, v180
	v_sub_f32_e32 v208, v208, v180
	v_sub_f32_e32 v209, v209, v180
	v_sub_f32_e32 v210, v210, v180
	v_sub_f32_e32 v211, v211, v180
	v_sub_f32_e32 v212, v212, v180
	v_sub_f32_e32 v213, v213, v180
	v_pk_mul_f32 v[206:207], v[180:181], v[206:207] op_sel:[1,0]
	v_pk_mul_f32 v[208:209], v[180:181], v[208:209] op_sel:[1,0]
	v_pk_mul_f32 v[210:211], v[180:181], v[210:211] op_sel:[1,0]
	v_pk_mul_f32 v[212:213], v[180:181], v[212:213] op_sel:[1,0]
	v_pk_fma_f32 v[206:207], v[98:99], v[206:207], v[102:103]
	v_pk_fma_f32 v[208:209], v[100:101], v[208:209], v[104:105]
	v_pk_fma_f32 v[210:211], v[90:91], v[210:211], v[94:95]
	v_pk_fma_f32 v[212:213], v[92:93], v[212:213], v[96:97]
	v_pk_fma_f32 v[206:207], v[206:207], s[66:67], v[134:135] op_sel_hi:[1,0,1]
	v_pk_fma_f32 v[208:209], v[208:209], s[66:67], v[136:137] op_sel_hi:[1,0,1]
	v_pk_fma_f32 v[210:211], v[210:211], s[66:67], v[130:131] op_sel_hi:[1,0,1]
	v_pk_fma_f32 v[212:213], v[212:213], s[66:67], v[132:133] op_sel_hi:[1,0,1]
	v_cvt_pk_bf16_f32 v224, v206, v207
	v_cvt_pk_bf16_f32 v225, v208, v209
	v_cvt_pk_bf16_f32 v226, v210, v211
	v_cvt_pk_bf16_f32 v227, v212, v213
	s_add_u32 s48, s72, 0x10000
	s_addc_u32 s49, s73, 0
	global_store_dwordx4 v170, v[224:227], s[48:49]
	s_waitcnt vmcnt(12)
	v_lshlrev_b32_e32 v206, 16, v228
	v_and_b32_e32 v207, 0xffff0000, v228
	v_lshlrev_b32_e32 v208, 16, v229
	v_and_b32_e32 v209, 0xffff0000, v229
	v_lshlrev_b32_e32 v210, 16, v230
	v_and_b32_e32 v211, 0xffff0000, v230
	v_lshlrev_b32_e32 v212, 16, v231
	v_and_b32_e32 v213, 0xffff0000, v231
	v_sub_f32_e32 v206, v206, v182
	v_sub_f32_e32 v207, v207, v182
	v_sub_f32_e32 v208, v208, v182
	v_sub_f32_e32 v209, v209, v182
	v_sub_f32_e32 v210, v210, v182
	v_sub_f32_e32 v211, v211, v182
	v_sub_f32_e32 v212, v212, v182
	v_sub_f32_e32 v213, v213, v182
	v_pk_mul_f32 v[206:207], v[182:183], v[206:207] op_sel:[1,0]
	v_pk_mul_f32 v[208:209], v[182:183], v[208:209] op_sel:[1,0]
	v_pk_mul_f32 v[210:211], v[182:183], v[210:211] op_sel:[1,0]
	v_pk_mul_f32 v[212:213], v[182:183], v[212:213] op_sel:[1,0]
	v_pk_fma_f32 v[206:207], v[98:99], v[206:207], v[102:103]
	v_pk_fma_f32 v[208:209], v[100:101], v[208:209], v[104:105]
	v_pk_fma_f32 v[210:211], v[90:91], v[210:211], v[94:95]
	v_pk_fma_f32 v[212:213], v[92:93], v[212:213], v[96:97]
	v_pk_fma_f32 v[206:207], v[206:207], s[66:67], v[126:127] op_sel_hi:[1,0,1]
	v_pk_fma_f32 v[208:209], v[208:209], s[66:67], v[128:129] op_sel_hi:[1,0,1]
	v_pk_fma_f32 v[210:211], v[210:211], s[66:67], v[122:123] op_sel_hi:[1,0,1]
	v_pk_fma_f32 v[212:213], v[212:213], s[66:67], v[124:125] op_sel_hi:[1,0,1]
	v_cvt_pk_bf16_f32 v228, v206, v207
	v_cvt_pk_bf16_f32 v229, v208, v209
	v_cvt_pk_bf16_f32 v230, v210, v211
	v_cvt_pk_bf16_f32 v231, v212, v213
	s_add_u32 s48, s72, 0x20000
	s_addc_u32 s49, s73, 0
	global_store_dwordx4 v170, v[228:231], s[48:49]
	s_waitcnt vmcnt(11)
	v_lshlrev_b32_e32 v206, 16, v232
	v_and_b32_e32 v207, 0xffff0000, v232
	v_lshlrev_b32_e32 v208, 16, v233
	v_and_b32_e32 v209, 0xffff0000, v233
	v_lshlrev_b32_e32 v210, 16, v234
	v_and_b32_e32 v211, 0xffff0000, v234
	v_lshlrev_b32_e32 v212, 16, v235
	v_and_b32_e32 v213, 0xffff0000, v235
	v_sub_f32_e32 v206, v206, v184
	v_sub_f32_e32 v207, v207, v184
	v_sub_f32_e32 v208, v208, v184
	v_sub_f32_e32 v209, v209, v184
	v_sub_f32_e32 v210, v210, v184
	v_sub_f32_e32 v211, v211, v184
	v_sub_f32_e32 v212, v212, v184
	v_sub_f32_e32 v213, v213, v184
	v_pk_mul_f32 v[206:207], v[184:185], v[206:207] op_sel:[1,0]
	v_pk_mul_f32 v[208:209], v[184:185], v[208:209] op_sel:[1,0]
	v_pk_mul_f32 v[210:211], v[184:185], v[210:211] op_sel:[1,0]
	v_pk_mul_f32 v[212:213], v[184:185], v[212:213] op_sel:[1,0]
	v_pk_fma_f32 v[206:207], v[98:99], v[206:207], v[102:103]
	v_pk_fma_f32 v[208:209], v[100:101], v[208:209], v[104:105]
	v_pk_fma_f32 v[210:211], v[90:91], v[210:211], v[94:95]
	v_pk_fma_f32 v[212:213], v[92:93], v[212:213], v[96:97]
	v_pk_fma_f32 v[206:207], v[206:207], s[66:67], v[118:119] op_sel_hi:[1,0,1]
	v_pk_fma_f32 v[208:209], v[208:209], s[66:67], v[120:121] op_sel_hi:[1,0,1]
	v_pk_fma_f32 v[210:211], v[210:211], s[66:67], v[114:115] op_sel_hi:[1,0,1]
	v_pk_fma_f32 v[212:213], v[212:213], s[66:67], v[116:117] op_sel_hi:[1,0,1]
	v_cvt_pk_bf16_f32 v232, v206, v207
	v_cvt_pk_bf16_f32 v233, v208, v209
	v_cvt_pk_bf16_f32 v234, v210, v211
	v_cvt_pk_bf16_f32 v235, v212, v213
	s_add_u32 s48, s72, 0x30000
	s_addc_u32 s49, s73, 0
	global_store_dwordx4 v170, v[232:235], s[48:49]
	s_waitcnt vmcnt(10)
	v_lshlrev_b32_e32 v206, 16, v236
	v_and_b32_e32 v207, 0xffff0000, v236
	v_lshlrev_b32_e32 v208, 16, v237
	v_and_b32_e32 v209, 0xffff0000, v237
	v_lshlrev_b32_e32 v210, 16, v238
	v_and_b32_e32 v211, 0xffff0000, v238
	v_lshlrev_b32_e32 v212, 16, v239
	v_and_b32_e32 v213, 0xffff0000, v239
	v_sub_f32_e32 v206, v206, v168
	v_sub_f32_e32 v207, v207, v168
	v_sub_f32_e32 v208, v208, v168
	v_sub_f32_e32 v209, v209, v168
	v_sub_f32_e32 v210, v210, v168
	v_sub_f32_e32 v211, v211, v168
	v_sub_f32_e32 v212, v212, v168
	v_sub_f32_e32 v213, v213, v168
	v_pk_mul_f32 v[206:207], v[168:169], v[206:207] op_sel:[1,0]
	v_pk_mul_f32 v[208:209], v[168:169], v[208:209] op_sel:[1,0]
	v_pk_mul_f32 v[210:211], v[168:169], v[210:211] op_sel:[1,0]
	v_pk_mul_f32 v[212:213], v[168:169], v[212:213] op_sel:[1,0]
	v_pk_fma_f32 v[206:207], v[98:99], v[206:207], v[102:103]
	v_pk_fma_f32 v[208:209], v[100:101], v[208:209], v[104:105]
	v_pk_fma_f32 v[210:211], v[90:91], v[210:211], v[94:95]
	v_pk_fma_f32 v[212:213], v[92:93], v[212:213], v[96:97]
	v_pk_fma_f32 v[206:207], v[206:207], s[66:67], v[110:111] op_sel_hi:[1,0,1]
	v_pk_fma_f32 v[208:209], v[208:209], s[66:67], v[112:113] op_sel_hi:[1,0,1]
	v_pk_fma_f32 v[210:211], v[210:211], s[66:67], v[106:107] op_sel_hi:[1,0,1]
	v_pk_fma_f32 v[212:213], v[212:213], s[66:67], v[108:109] op_sel_hi:[1,0,1]
	v_cvt_pk_bf16_f32 v236, v206, v207
	v_cvt_pk_bf16_f32 v237, v208, v209
	v_cvt_pk_bf16_f32 v238, v210, v211
	v_cvt_pk_bf16_f32 v239, v212, v213
	s_add_u32 s48, s72, 0x80000
	s_addc_u32 s49, s73, 0
	global_store_dwordx4 v170, v[236:239], s[48:49]
	s_waitcnt vmcnt(9)
	v_lshlrev_b32_e32 v206, 16, v240
	v_and_b32_e32 v207, 0xffff0000, v240
	v_lshlrev_b32_e32 v208, 16, v241
	v_and_b32_e32 v209, 0xffff0000, v241
	v_lshlrev_b32_e32 v210, 16, v242
	v_and_b32_e32 v211, 0xffff0000, v242
	v_lshlrev_b32_e32 v212, 16, v243
	v_and_b32_e32 v213, 0xffff0000, v243
	v_sub_f32_e32 v206, v206, v252
	v_sub_f32_e32 v207, v207, v252
	v_sub_f32_e32 v208, v208, v252
	v_sub_f32_e32 v209, v209, v252
	v_sub_f32_e32 v210, v210, v252
	v_sub_f32_e32 v211, v211, v252
	v_sub_f32_e32 v212, v212, v252
	v_sub_f32_e32 v213, v213, v252
	v_pk_mul_f32 v[206:207], v[252:253], v[206:207] op_sel:[1,0]
	v_pk_mul_f32 v[208:209], v[252:253], v[208:209] op_sel:[1,0]
	v_pk_mul_f32 v[210:211], v[252:253], v[210:211] op_sel:[1,0]
	v_pk_mul_f32 v[212:213], v[252:253], v[212:213] op_sel:[1,0]
	v_pk_fma_f32 v[206:207], v[98:99], v[206:207], v[102:103]
	v_pk_fma_f32 v[208:209], v[100:101], v[208:209], v[104:105]
	v_pk_fma_f32 v[210:211], v[90:91], v[210:211], v[94:95]
	v_pk_fma_f32 v[212:213], v[92:93], v[212:213], v[96:97]
	v_pk_fma_f32 v[206:207], v[206:207], s[66:67], v[86:87] op_sel_hi:[1,0,1]
	v_pk_fma_f32 v[208:209], v[208:209], s[66:67], v[88:89] op_sel_hi:[1,0,1]
	v_pk_fma_f32 v[210:211], v[210:211], s[66:67], v[82:83] op_sel_hi:[1,0,1]
	v_pk_fma_f32 v[212:213], v[212:213], s[66:67], v[84:85] op_sel_hi:[1,0,1]
	v_cvt_pk_bf16_f32 v240, v206, v207
	v_cvt_pk_bf16_f32 v241, v208, v209
	v_cvt_pk_bf16_f32 v242, v210, v211
	v_cvt_pk_bf16_f32 v243, v212, v213
	s_add_u32 s48, s72, 0x90000
	s_addc_u32 s49, s73, 0
	global_store_dwordx4 v170, v[240:243], s[48:49]
	s_waitcnt vmcnt(8)
	v_lshlrev_b32_e32 v206, 16, v244
	v_and_b32_e32 v207, 0xffff0000, v244
	v_lshlrev_b32_e32 v208, 16, v245
	v_and_b32_e32 v209, 0xffff0000, v245
	v_lshlrev_b32_e32 v210, 16, v246
	v_and_b32_e32 v211, 0xffff0000, v246
	v_lshlrev_b32_e32 v212, 16, v247
	v_and_b32_e32 v213, 0xffff0000, v247
	v_sub_f32_e32 v206, v206, v214
	v_sub_f32_e32 v207, v207, v214
	v_sub_f32_e32 v208, v208, v214
	v_sub_f32_e32 v209, v209, v214
	v_sub_f32_e32 v210, v210, v214
	v_sub_f32_e32 v211, v211, v214
	v_sub_f32_e32 v212, v212, v214
	v_sub_f32_e32 v213, v213, v214
	v_pk_mul_f32 v[206:207], v[214:215], v[206:207] op_sel:[1,0]
	v_pk_mul_f32 v[208:209], v[214:215], v[208:209] op_sel:[1,0]
	v_pk_mul_f32 v[210:211], v[214:215], v[210:211] op_sel:[1,0]
	v_pk_mul_f32 v[212:213], v[214:215], v[212:213] op_sel:[1,0]
	v_pk_fma_f32 v[206:207], v[98:99], v[206:207], v[102:103]
	v_pk_fma_f32 v[208:209], v[100:101], v[208:209], v[104:105]
	v_pk_fma_f32 v[210:211], v[90:91], v[210:211], v[94:95]
	v_pk_fma_f32 v[212:213], v[92:93], v[212:213], v[96:97]
	v_pk_fma_f32 v[206:207], v[206:207], s[66:67], v[78:79] op_sel_hi:[1,0,1]
	v_pk_fma_f32 v[208:209], v[208:209], s[66:67], v[80:81] op_sel_hi:[1,0,1]
	v_pk_fma_f32 v[210:211], v[210:211], s[66:67], v[74:75] op_sel_hi:[1,0,1]
	v_pk_fma_f32 v[212:213], v[212:213], s[66:67], v[76:77] op_sel_hi:[1,0,1]
	v_cvt_pk_bf16_f32 v244, v206, v207
	v_cvt_pk_bf16_f32 v245, v208, v209
	v_cvt_pk_bf16_f32 v246, v210, v211
	v_cvt_pk_bf16_f32 v247, v212, v213
	s_add_u32 s48, s72, 0xa0000
	s_addc_u32 s49, s73, 0
	global_store_dwordx4 v170, v[244:247], s[48:49]
	s_waitcnt vmcnt(7)
	v_lshlrev_b32_e32 v206, 16, v248
	v_and_b32_e32 v207, 0xffff0000, v248
	v_lshlrev_b32_e32 v208, 16, v249
	v_and_b32_e32 v209, 0xffff0000, v249
	v_lshlrev_b32_e32 v210, 16, v250
	v_and_b32_e32 v211, 0xffff0000, v250
	v_lshlrev_b32_e32 v212, 16, v251
	v_and_b32_e32 v213, 0xffff0000, v251
	v_sub_f32_e32 v206, v206, v216
	v_sub_f32_e32 v207, v207, v216
	v_sub_f32_e32 v208, v208, v216
	v_sub_f32_e32 v209, v209, v216
	v_sub_f32_e32 v210, v210, v216
	v_sub_f32_e32 v211, v211, v216
	v_sub_f32_e32 v212, v212, v216
	v_sub_f32_e32 v213, v213, v216
	v_pk_mul_f32 v[206:207], v[216:217], v[206:207] op_sel:[1,0]
	v_pk_mul_f32 v[208:209], v[216:217], v[208:209] op_sel:[1,0]
	v_pk_mul_f32 v[210:211], v[216:217], v[210:211] op_sel:[1,0]
	v_pk_mul_f32 v[212:213], v[216:217], v[212:213] op_sel:[1,0]
	v_pk_fma_f32 v[206:207], v[98:99], v[206:207], v[102:103]
	v_pk_fma_f32 v[208:209], v[100:101], v[208:209], v[104:105]
	v_pk_fma_f32 v[210:211], v[90:91], v[210:211], v[94:95]
	v_pk_fma_f32 v[212:213], v[92:93], v[212:213], v[96:97]
	v_pk_fma_f32 v[206:207], v[206:207], s[66:67], v[70:71] op_sel_hi:[1,0,1]
	v_pk_fma_f32 v[208:209], v[208:209], s[66:67], v[72:73] op_sel_hi:[1,0,1]
	v_pk_fma_f32 v[210:211], v[210:211], s[66:67], v[66:67] op_sel_hi:[1,0,1]
	v_pk_fma_f32 v[212:213], v[212:213], s[66:67], v[68:69] op_sel_hi:[1,0,1]
	v_cvt_pk_bf16_f32 v248, v206, v207
	v_cvt_pk_bf16_f32 v249, v208, v209
	v_cvt_pk_bf16_f32 v250, v210, v211
	v_cvt_pk_bf16_f32 v251, v212, v213
	s_add_u32 s48, s72, 0xb0000
	s_addc_u32 s49, s73, 0
	global_store_dwordx4 v170, v[248:251], s[48:49]
	global_load_dwordx4 v[98:101], v174, s[74:75] offset:512
	global_load_dwordx4 v[90:93], v174, s[74:75] offset:528
	global_load_dwordx4 v[102:105], v174, s[76:77] offset:512
	global_load_dwordx4 v[94:97], v174, s[76:77] offset:528
	s_add_u32 s48, s72, 0x100
	s_addc_u32 s49, s73, 0
	global_load_dwordx4 v[220:223], v170, s[48:49]
	s_add_u32 s50, s14, 0x0
	s_addc_u32 s51, s15, 0
	global_load_dwordx2 v[176:177], v171, s[50:51]
	s_add_u32 s48, s72, 0x10100
	s_addc_u32 s49, s73, 0
	global_load_dwordx4 v[224:227], v170, s[48:49]
	s_add_u32 s50, s14, 0x80
	s_addc_u32 s51, s15, 0
	global_load_dwordx2 v[180:181], v171, s[50:51]
	s_add_u32 s48, s72, 0x20100
	s_addc_u32 s49, s73, 0
	global_load_dwordx4 v[228:231], v170, s[48:49]
	s_add_u32 s50, s14, 0x100
	s_addc_u32 s51, s15, 0
	global_load_dwordx2 v[182:183], v171, s[50:51]
	s_add_u32 s48, s72, 0x30100
	s_addc_u32 s49, s73, 0
	global_load_dwordx4 v[232:235], v170, s[48:49]
	s_add_u32 s50, s14, 0x180
	s_addc_u32 s51, s15, 0
	global_load_dwordx2 v[184:185], v171, s[50:51]
	s_add_u32 s48, s72, 0x80100
	s_addc_u32 s49, s73, 0
	global_load_dwordx4 v[236:239], v170, s[48:49]
	s_add_u32 s50, s14, 0x400
	s_addc_u32 s51, s15, 0
	global_load_dwordx2 v[168:169], v171, s[50:51]
	s_add_u32 s48, s72, 0x90100
	s_addc_u32 s49, s73, 0
	global_load_dwordx4 v[240:243], v170, s[48:49]
	s_add_u32 s50, s14, 0x480
	s_addc_u32 s51, s15, 0
	global_load_dwordx2 v[252:253], v171, s[50:51]
	s_add_u32 s48, s72, 0xa0100
	s_addc_u32 s49, s73, 0
	global_load_dwordx4 v[244:247], v170, s[48:49]
	s_add_u32 s50, s14, 0x500
	s_addc_u32 s51, s15, 0
	global_load_dwordx2 v[214:215], v171, s[50:51]
	s_add_u32 s48, s72, 0xb0100
	s_addc_u32 s49, s73, 0
	global_load_dwordx4 v[248:251], v170, s[48:49]
	s_add_u32 s50, s14, 0x580
	s_addc_u32 s51, s15, 0
	global_load_dwordx2 v[216:217], v171, s[50:51]
	s_waitcnt vmcnt(14)
	v_lshlrev_b32_e32 v206, 16, v220
	v_and_b32_e32 v207, 0xffff0000, v220
	v_lshlrev_b32_e32 v208, 16, v221
	v_and_b32_e32 v209, 0xffff0000, v221
	v_lshlrev_b32_e32 v210, 16, v222
	v_and_b32_e32 v211, 0xffff0000, v222
	v_lshlrev_b32_e32 v212, 16, v223
	v_and_b32_e32 v213, 0xffff0000, v223
	v_sub_f32_e32 v206, v206, v176
	v_sub_f32_e32 v207, v207, v176
	v_sub_f32_e32 v208, v208, v176
	v_sub_f32_e32 v209, v209, v176
	v_sub_f32_e32 v210, v210, v176
	v_sub_f32_e32 v211, v211, v176
	v_sub_f32_e32 v212, v212, v176
	v_sub_f32_e32 v213, v213, v176
	v_pk_mul_f32 v[206:207], v[176:177], v[206:207] op_sel:[1,0]
	v_pk_mul_f32 v[208:209], v[176:177], v[208:209] op_sel:[1,0]
	v_pk_mul_f32 v[210:211], v[176:177], v[210:211] op_sel:[1,0]
	v_pk_mul_f32 v[212:213], v[176:177], v[212:213] op_sel:[1,0]
	v_pk_fma_f32 v[206:207], v[98:99], v[206:207], v[102:103]
	v_pk_fma_f32 v[208:209], v[100:101], v[208:209], v[104:105]
	v_pk_fma_f32 v[210:211], v[90:91], v[210:211], v[94:95]
	v_pk_fma_f32 v[212:213], v[92:93], v[212:213], v[96:97]
	v_pk_fma_f32 v[206:207], v[206:207], s[66:67], v[62:63] op_sel_hi:[1,0,1]
	v_pk_fma_f32 v[208:209], v[208:209], s[66:67], v[64:65] op_sel_hi:[1,0,1]
	v_pk_fma_f32 v[210:211], v[210:211], s[66:67], v[58:59] op_sel_hi:[1,0,1]
	v_pk_fma_f32 v[212:213], v[212:213], s[66:67], v[60:61] op_sel_hi:[1,0,1]
	v_cvt_pk_bf16_f32 v220, v206, v207
	v_cvt_pk_bf16_f32 v221, v208, v209
	v_cvt_pk_bf16_f32 v222, v210, v211
	v_cvt_pk_bf16_f32 v223, v212, v213
	s_add_u32 s48, s72, 0x100
	s_addc_u32 s49, s73, 0
	global_store_dwordx4 v170, v[220:223], s[48:49]
	s_waitcnt vmcnt(13)
	v_lshlrev_b32_e32 v206, 16, v224
	v_and_b32_e32 v207, 0xffff0000, v224
	v_lshlrev_b32_e32 v208, 16, v225
	v_and_b32_e32 v209, 0xffff0000, v225
	v_lshlrev_b32_e32 v210, 16, v226
	v_and_b32_e32 v211, 0xffff0000, v226
	v_lshlrev_b32_e32 v212, 16, v227
	v_and_b32_e32 v213, 0xffff0000, v227
	v_sub_f32_e32 v206, v206, v180
	v_sub_f32_e32 v207, v207, v180
	v_sub_f32_e32 v208, v208, v180
	v_sub_f32_e32 v209, v209, v180
	v_sub_f32_e32 v210, v210, v180
	v_sub_f32_e32 v211, v211, v180
	v_sub_f32_e32 v212, v212, v180
	v_sub_f32_e32 v213, v213, v180
	v_pk_mul_f32 v[206:207], v[180:181], v[206:207] op_sel:[1,0]
	v_pk_mul_f32 v[208:209], v[180:181], v[208:209] op_sel:[1,0]
	v_pk_mul_f32 v[210:211], v[180:181], v[210:211] op_sel:[1,0]
	v_pk_mul_f32 v[212:213], v[180:181], v[212:213] op_sel:[1,0]
	v_pk_fma_f32 v[206:207], v[98:99], v[206:207], v[102:103]
	v_pk_fma_f32 v[208:209], v[100:101], v[208:209], v[104:105]
	v_pk_fma_f32 v[210:211], v[90:91], v[210:211], v[94:95]
	v_pk_fma_f32 v[212:213], v[92:93], v[212:213], v[96:97]
	v_pk_fma_f32 v[206:207], v[206:207], s[66:67], v[54:55] op_sel_hi:[1,0,1]
	v_pk_fma_f32 v[208:209], v[208:209], s[66:67], v[56:57] op_sel_hi:[1,0,1]
	v_pk_fma_f32 v[210:211], v[210:211], s[66:67], v[50:51] op_sel_hi:[1,0,1]
	v_pk_fma_f32 v[212:213], v[212:213], s[66:67], v[52:53] op_sel_hi:[1,0,1]
	v_cvt_pk_bf16_f32 v224, v206, v207
	v_cvt_pk_bf16_f32 v225, v208, v209
	v_cvt_pk_bf16_f32 v226, v210, v211
	v_cvt_pk_bf16_f32 v227, v212, v213
	s_add_u32 s48, s72, 0x10100
	s_addc_u32 s49, s73, 0
	global_store_dwordx4 v170, v[224:227], s[48:49]
	s_waitcnt vmcnt(12)
	v_lshlrev_b32_e32 v206, 16, v228
	v_and_b32_e32 v207, 0xffff0000, v228
	v_lshlrev_b32_e32 v208, 16, v229
	v_and_b32_e32 v209, 0xffff0000, v229
	v_lshlrev_b32_e32 v210, 16, v230
	v_and_b32_e32 v211, 0xffff0000, v230
	v_lshlrev_b32_e32 v212, 16, v231
	v_and_b32_e32 v213, 0xffff0000, v231
	v_sub_f32_e32 v206, v206, v182
	v_sub_f32_e32 v207, v207, v182
	v_sub_f32_e32 v208, v208, v182
	v_sub_f32_e32 v209, v209, v182
	v_sub_f32_e32 v210, v210, v182
	v_sub_f32_e32 v211, v211, v182
	v_sub_f32_e32 v212, v212, v182
	v_sub_f32_e32 v213, v213, v182
	v_pk_mul_f32 v[206:207], v[182:183], v[206:207] op_sel:[1,0]
	v_pk_mul_f32 v[208:209], v[182:183], v[208:209] op_sel:[1,0]
	v_pk_mul_f32 v[210:211], v[182:183], v[210:211] op_sel:[1,0]
	v_pk_mul_f32 v[212:213], v[182:183], v[212:213] op_sel:[1,0]
	v_pk_fma_f32 v[206:207], v[98:99], v[206:207], v[102:103]
	v_pk_fma_f32 v[208:209], v[100:101], v[208:209], v[104:105]
	v_pk_fma_f32 v[210:211], v[90:91], v[210:211], v[94:95]
	v_pk_fma_f32 v[212:213], v[92:93], v[212:213], v[96:97]
	v_pk_fma_f32 v[206:207], v[206:207], s[66:67], v[46:47] op_sel_hi:[1,0,1]
	v_pk_fma_f32 v[208:209], v[208:209], s[66:67], v[48:49] op_sel_hi:[1,0,1]
	v_pk_fma_f32 v[210:211], v[210:211], s[66:67], v[42:43] op_sel_hi:[1,0,1]
	v_pk_fma_f32 v[212:213], v[212:213], s[66:67], v[44:45] op_sel_hi:[1,0,1]
	v_cvt_pk_bf16_f32 v228, v206, v207
	v_cvt_pk_bf16_f32 v229, v208, v209
	v_cvt_pk_bf16_f32 v230, v210, v211
	v_cvt_pk_bf16_f32 v231, v212, v213
	s_add_u32 s48, s72, 0x20100
	s_addc_u32 s49, s73, 0
	global_store_dwordx4 v170, v[228:231], s[48:49]
	s_waitcnt vmcnt(11)
	v_lshlrev_b32_e32 v206, 16, v232
	v_and_b32_e32 v207, 0xffff0000, v232
	v_lshlrev_b32_e32 v208, 16, v233
	v_and_b32_e32 v209, 0xffff0000, v233
	v_lshlrev_b32_e32 v210, 16, v234
	v_and_b32_e32 v211, 0xffff0000, v234
	v_lshlrev_b32_e32 v212, 16, v235
	v_and_b32_e32 v213, 0xffff0000, v235
	v_sub_f32_e32 v206, v206, v184
	v_sub_f32_e32 v207, v207, v184
	v_sub_f32_e32 v208, v208, v184
	v_sub_f32_e32 v209, v209, v184
	v_sub_f32_e32 v210, v210, v184
	v_sub_f32_e32 v211, v211, v184
	v_sub_f32_e32 v212, v212, v184
	v_sub_f32_e32 v213, v213, v184
	v_pk_mul_f32 v[206:207], v[184:185], v[206:207] op_sel:[1,0]
	v_pk_mul_f32 v[208:209], v[184:185], v[208:209] op_sel:[1,0]
	v_pk_mul_f32 v[210:211], v[184:185], v[210:211] op_sel:[1,0]
	v_pk_mul_f32 v[212:213], v[184:185], v[212:213] op_sel:[1,0]
	v_pk_fma_f32 v[206:207], v[98:99], v[206:207], v[102:103]
	v_pk_fma_f32 v[208:209], v[100:101], v[208:209], v[104:105]
	v_pk_fma_f32 v[210:211], v[90:91], v[210:211], v[94:95]
	v_pk_fma_f32 v[212:213], v[92:93], v[212:213], v[96:97]
	v_pk_fma_f32 v[206:207], v[206:207], s[66:67], v[38:39] op_sel_hi:[1,0,1]
	v_pk_fma_f32 v[208:209], v[208:209], s[66:67], v[40:41] op_sel_hi:[1,0,1]
	v_pk_fma_f32 v[210:211], v[210:211], s[66:67], v[34:35] op_sel_hi:[1,0,1]
	v_pk_fma_f32 v[212:213], v[212:213], s[66:67], v[36:37] op_sel_hi:[1,0,1]
	v_cvt_pk_bf16_f32 v232, v206, v207
	v_cvt_pk_bf16_f32 v233, v208, v209
	v_cvt_pk_bf16_f32 v234, v210, v211
	v_cvt_pk_bf16_f32 v235, v212, v213
	s_add_u32 s48, s72, 0x30100
	s_addc_u32 s49, s73, 0
	global_store_dwordx4 v170, v[232:235], s[48:49]
	s_waitcnt vmcnt(10)
	v_lshlrev_b32_e32 v206, 16, v236
	v_and_b32_e32 v207, 0xffff0000, v236
	v_lshlrev_b32_e32 v208, 16, v237
	v_and_b32_e32 v209, 0xffff0000, v237
	v_lshlrev_b32_e32 v210, 16, v238
	v_and_b32_e32 v211, 0xffff0000, v238
	v_lshlrev_b32_e32 v212, 16, v239
	v_and_b32_e32 v213, 0xffff0000, v239
	v_sub_f32_e32 v206, v206, v168
	v_sub_f32_e32 v207, v207, v168
	v_sub_f32_e32 v208, v208, v168
	v_sub_f32_e32 v209, v209, v168
	v_sub_f32_e32 v210, v210, v168
	v_sub_f32_e32 v211, v211, v168
	v_sub_f32_e32 v212, v212, v168
	v_sub_f32_e32 v213, v213, v168
	v_pk_mul_f32 v[206:207], v[168:169], v[206:207] op_sel:[1,0]
	v_pk_mul_f32 v[208:209], v[168:169], v[208:209] op_sel:[1,0]
	v_pk_mul_f32 v[210:211], v[168:169], v[210:211] op_sel:[1,0]
	v_pk_mul_f32 v[212:213], v[168:169], v[212:213] op_sel:[1,0]
	v_pk_fma_f32 v[206:207], v[98:99], v[206:207], v[102:103]
	v_pk_fma_f32 v[208:209], v[100:101], v[208:209], v[104:105]
	v_pk_fma_f32 v[210:211], v[90:91], v[210:211], v[94:95]
	v_pk_fma_f32 v[212:213], v[92:93], v[212:213], v[96:97]
	v_pk_fma_f32 v[206:207], v[206:207], s[66:67], v[30:31] op_sel_hi:[1,0,1]
	v_pk_fma_f32 v[208:209], v[208:209], s[66:67], v[32:33] op_sel_hi:[1,0,1]
	v_pk_fma_f32 v[210:211], v[210:211], s[66:67], v[26:27] op_sel_hi:[1,0,1]
	v_pk_fma_f32 v[212:213], v[212:213], s[66:67], v[28:29] op_sel_hi:[1,0,1]
	v_cvt_pk_bf16_f32 v236, v206, v207
	v_cvt_pk_bf16_f32 v237, v208, v209
	v_cvt_pk_bf16_f32 v238, v210, v211
	v_cvt_pk_bf16_f32 v239, v212, v213
	s_add_u32 s48, s72, 0x80100
	s_addc_u32 s49, s73, 0
	global_store_dwordx4 v170, v[236:239], s[48:49]
	s_waitcnt vmcnt(9)
	v_lshlrev_b32_e32 v206, 16, v240
	v_and_b32_e32 v207, 0xffff0000, v240
	v_lshlrev_b32_e32 v208, 16, v241
	v_and_b32_e32 v209, 0xffff0000, v241
	v_lshlrev_b32_e32 v210, 16, v242
	v_and_b32_e32 v211, 0xffff0000, v242
	v_lshlrev_b32_e32 v212, 16, v243
	v_and_b32_e32 v213, 0xffff0000, v243
	v_sub_f32_e32 v206, v206, v252
	v_sub_f32_e32 v207, v207, v252
	v_sub_f32_e32 v208, v208, v252
	v_sub_f32_e32 v209, v209, v252
	v_sub_f32_e32 v210, v210, v252
	v_sub_f32_e32 v211, v211, v252
	v_sub_f32_e32 v212, v212, v252
	v_sub_f32_e32 v213, v213, v252
	v_pk_mul_f32 v[206:207], v[252:253], v[206:207] op_sel:[1,0]
	v_pk_mul_f32 v[208:209], v[252:253], v[208:209] op_sel:[1,0]
	v_pk_mul_f32 v[210:211], v[252:253], v[210:211] op_sel:[1,0]
	v_pk_mul_f32 v[212:213], v[252:253], v[212:213] op_sel:[1,0]
	v_pk_fma_f32 v[206:207], v[98:99], v[206:207], v[102:103]
	v_pk_fma_f32 v[208:209], v[100:101], v[208:209], v[104:105]
	v_pk_fma_f32 v[210:211], v[90:91], v[210:211], v[94:95]
	v_pk_fma_f32 v[212:213], v[92:93], v[212:213], v[96:97]
	v_pk_fma_f32 v[206:207], v[206:207], s[66:67], v[22:23] op_sel_hi:[1,0,1]
	v_pk_fma_f32 v[208:209], v[208:209], s[66:67], v[24:25] op_sel_hi:[1,0,1]
	v_pk_fma_f32 v[210:211], v[210:211], s[66:67], v[18:19] op_sel_hi:[1,0,1]
	v_pk_fma_f32 v[212:213], v[212:213], s[66:67], v[20:21] op_sel_hi:[1,0,1]
	v_cvt_pk_bf16_f32 v240, v206, v207
	v_cvt_pk_bf16_f32 v241, v208, v209
	v_cvt_pk_bf16_f32 v242, v210, v211
	v_cvt_pk_bf16_f32 v243, v212, v213
	s_add_u32 s48, s72, 0x90100
	s_addc_u32 s49, s73, 0
	global_store_dwordx4 v170, v[240:243], s[48:49]
	s_waitcnt vmcnt(8)
	v_lshlrev_b32_e32 v206, 16, v244
	v_and_b32_e32 v207, 0xffff0000, v244
	v_lshlrev_b32_e32 v208, 16, v245
	v_and_b32_e32 v209, 0xffff0000, v245
	v_lshlrev_b32_e32 v210, 16, v246
	v_and_b32_e32 v211, 0xffff0000, v246
	v_lshlrev_b32_e32 v212, 16, v247
	v_and_b32_e32 v213, 0xffff0000, v247
	v_sub_f32_e32 v206, v206, v214
	v_sub_f32_e32 v207, v207, v214
	v_sub_f32_e32 v208, v208, v214
	v_sub_f32_e32 v209, v209, v214
	v_sub_f32_e32 v210, v210, v214
	v_sub_f32_e32 v211, v211, v214
	v_sub_f32_e32 v212, v212, v214
	v_sub_f32_e32 v213, v213, v214
	v_pk_mul_f32 v[206:207], v[214:215], v[206:207] op_sel:[1,0]
	v_pk_mul_f32 v[208:209], v[214:215], v[208:209] op_sel:[1,0]
	v_pk_mul_f32 v[210:211], v[214:215], v[210:211] op_sel:[1,0]
	v_pk_mul_f32 v[212:213], v[214:215], v[212:213] op_sel:[1,0]
	v_pk_fma_f32 v[206:207], v[98:99], v[206:207], v[102:103]
	v_pk_fma_f32 v[208:209], v[100:101], v[208:209], v[104:105]
	v_pk_fma_f32 v[210:211], v[90:91], v[210:211], v[94:95]
	v_pk_fma_f32 v[212:213], v[92:93], v[212:213], v[96:97]
	v_pk_fma_f32 v[206:207], v[206:207], s[66:67], v[14:15] op_sel_hi:[1,0,1]
	v_pk_fma_f32 v[208:209], v[208:209], s[66:67], v[16:17] op_sel_hi:[1,0,1]
	v_pk_fma_f32 v[210:211], v[210:211], s[66:67], v[10:11] op_sel_hi:[1,0,1]
	v_pk_fma_f32 v[212:213], v[212:213], s[66:67], v[12:13] op_sel_hi:[1,0,1]
	v_cvt_pk_bf16_f32 v244, v206, v207
	v_cvt_pk_bf16_f32 v245, v208, v209
	v_cvt_pk_bf16_f32 v246, v210, v211
	v_cvt_pk_bf16_f32 v247, v212, v213
	s_add_u32 s48, s72, 0xa0100
	s_addc_u32 s49, s73, 0
	global_store_dwordx4 v170, v[244:247], s[48:49]
	s_waitcnt vmcnt(7)
	v_lshlrev_b32_e32 v206, 16, v248
	v_and_b32_e32 v207, 0xffff0000, v248
	v_lshlrev_b32_e32 v208, 16, v249
	v_and_b32_e32 v209, 0xffff0000, v249
	v_lshlrev_b32_e32 v210, 16, v250
	v_and_b32_e32 v211, 0xffff0000, v250
	v_lshlrev_b32_e32 v212, 16, v251
	v_and_b32_e32 v213, 0xffff0000, v251
	v_sub_f32_e32 v206, v206, v216
	v_sub_f32_e32 v207, v207, v216
	v_sub_f32_e32 v208, v208, v216
	v_sub_f32_e32 v209, v209, v216
	v_sub_f32_e32 v210, v210, v216
	v_sub_f32_e32 v211, v211, v216
	v_sub_f32_e32 v212, v212, v216
	v_sub_f32_e32 v213, v213, v216
	v_pk_mul_f32 v[206:207], v[216:217], v[206:207] op_sel:[1,0]
	v_pk_mul_f32 v[208:209], v[216:217], v[208:209] op_sel:[1,0]
	v_pk_mul_f32 v[210:211], v[216:217], v[210:211] op_sel:[1,0]
	v_pk_mul_f32 v[212:213], v[216:217], v[212:213] op_sel:[1,0]
	v_pk_fma_f32 v[206:207], v[98:99], v[206:207], v[102:103]
	v_pk_fma_f32 v[208:209], v[100:101], v[208:209], v[104:105]
	v_pk_fma_f32 v[210:211], v[90:91], v[210:211], v[94:95]
	v_pk_fma_f32 v[212:213], v[92:93], v[212:213], v[96:97]
	v_pk_fma_f32 v[206:207], v[206:207], s[66:67], v[6:7] op_sel_hi:[1,0,1]
	v_pk_fma_f32 v[208:209], v[208:209], s[66:67], v[8:9] op_sel_hi:[1,0,1]
	v_pk_fma_f32 v[210:211], v[210:211], s[66:67], v[2:3] op_sel_hi:[1,0,1]
	v_pk_fma_f32 v[212:213], v[212:213], s[66:67], v[4:5] op_sel_hi:[1,0,1]
	v_cvt_pk_bf16_f32 v248, v206, v207
	v_cvt_pk_bf16_f32 v249, v208, v209
	v_cvt_pk_bf16_f32 v250, v210, v211
	v_cvt_pk_bf16_f32 v251, v212, v213
	s_add_u32 s48, s72, 0xb0100
	s_addc_u32 s49, s73, 0
	global_store_dwordx4 v170, v[248:251], s[48:49]
	s_and_b64 vcc, exec, s[8:9]
	s_mov_b32 s43, s6
	s_mov_b32 s46, s7
	s_mov_b64 s[68:69], s[12:13]
	s_mov_b64 s[64:65], s[10:11]
	s_cbranch_vccz .LBB0_1606
	s_waitcnt vmcnt(0)
	s_cmpk_gt_u32 s19, 0xff
	s_cbranch_scc1 .LBB0_1621
	s_barrier
